# sigmoid/silu divisions (denominator 1+exp, in [1,2^96)): drop the range-scaling and special-value fix-up steps of the IEEE division expansion, keep every Newton/refinement fma; bit-identical outputs
# speedup vs baseline: 1.0032x; 1.0032x over previous
; DEVI float b2f(bfu b) { return __uint_as_float(((unsigned)b) << 16); }
; DEVI float sigmoidf_(float x) { return 1.f / (1.f + __expf(-x)); }
; DEVI void h1_item(const Params& P, int l, int ck, int h, char* smem, int tid) {
;     ...
; #pragma unroll 8
;   for (int i = 0; i < Lh; ++i) {
;     float f = lb + (1.f - lb) * sigmoidf_(b2f(FS[(hf * Lh + i) * 136 + d]));
;     tot += __logf(f);
;   }
.LBB0_397:
	ds_read_u16 v2, v0
	s_add_i32 s26, s26, -8
	s_cmp_eq_u32 s26, 0
	s_waitcnt lgkmcnt(0)
	v_lshlrev_b32_e32 v2, 16, v2
	v_mul_f32_e32 v2, 0xbfb8aa3b, v2
	v_exp_f32_e32 v2, v2
	s_nop 0
	v_add_f32_e32 v2, 1.0, v2
	v_min_f32_e32 v3, 0x7f7fffff, v2
	v_rcp_f32_e32 v5, v3
	s_nop 0
	v_fma_f32 v6, -v3, v5, 1.0
	v_fmac_f32_e32 v5, v6, v5
	v_fma_f32 v8, -v3, v5, 1.0
	v_fma_f32 v7, v8, v5, v5
	v_fma_f32 v3, -v3, v7, 1.0
	v_fma_f32 v2, v3, v5, v7
	v_fma_f32 v2, v4, v2, v20
	v_cmp_gt_f32_e32 vcc, s34, v2
	s_nop 1
	v_cndmask_b32_e64 v3, 0, 32, vcc
	v_ldexp_f32 v2, v2, v3
	v_log_f32_e32 v2, v2
	s_nop 0
	v_mul_f32_e32 v3, 0x3f317217, v2
	v_fma_f32 v3, v2, s38, -v3
	v_fmac_f32_e32 v3, 0x3377d1cf, v2
	v_fmac_f32_e32 v3, 0x3f317217, v2
	v_cmp_lt_f32_e64 s[42:43], |v2|, s20
	s_nop 1
	v_cndmask_b32_e64 v2, v2, v3, s[42:43]
	v_cndmask_b32_e32 v3, 0, v193, vcc
	v_sub_f32_e32 v2, v2, v3
	v_add_f32_e32 v1, v1, v2
	ds_read_u16 v2, v0 offset:272
	s_waitcnt lgkmcnt(0)
	v_lshlrev_b32_e32 v2, 16, v2
	v_mul_f32_e32 v2, 0xbfb8aa3b, v2
	v_exp_f32_e32 v2, v2
	s_nop 0
	v_add_f32_e32 v2, 1.0, v2
	v_min_f32_e32 v3, 0x7f7fffff, v2
	v_rcp_f32_e32 v5, v3
	s_nop 0
	v_fma_f32 v6, -v3, v5, 1.0
	v_fmac_f32_e32 v5, v6, v5
	v_fma_f32 v8, -v3, v5, 1.0
	v_fma_f32 v7, v8, v5, v5
	v_fma_f32 v3, -v3, v7, 1.0
	v_fma_f32 v2, v3, v5, v7
	v_fma_f32 v2, v4, v2, v20
	v_cmp_gt_f32_e32 vcc, s34, v2
	s_nop 1
	v_cndmask_b32_e64 v3, 0, 32, vcc
	v_ldexp_f32 v2, v2, v3
	v_log_f32_e32 v2, v2
	s_nop 0
	v_mul_f32_e32 v3, 0x3f317217, v2
	v_fma_f32 v3, v2, s38, -v3
	v_fmac_f32_e32 v3, 0x3377d1cf, v2
	v_fmac_f32_e32 v3, 0x3f317217, v2
	v_cmp_lt_f32_e64 s[42:43], |v2|, s20
	s_nop 1
	v_cndmask_b32_e64 v2, v2, v3, s[42:43]
	v_cndmask_b32_e32 v3, 0, v193, vcc
	v_sub_f32_e32 v2, v2, v3
	v_add_f32_e32 v1, v1, v2
	ds_read_u16 v2, v0 offset:544
	s_waitcnt lgkmcnt(0)
	v_lshlrev_b32_e32 v2, 16, v2
	v_mul_f32_e32 v2, 0xbfb8aa3b, v2
	v_exp_f32_e32 v2, v2
	s_nop 0
	v_add_f32_e32 v2, 1.0, v2
	v_min_f32_e32 v3, 0x7f7fffff, v2
	v_rcp_f32_e32 v5, v3
	s_nop 0
	v_fma_f32 v6, -v3, v5, 1.0
	v_fmac_f32_e32 v5, v6, v5
	v_fma_f32 v8, -v3, v5, 1.0
	v_fma_f32 v7, v8, v5, v5
	v_fma_f32 v3, -v3, v7, 1.0
	v_fma_f32 v2, v3, v5, v7
	v_fma_f32 v2, v4, v2, v20
	v_cmp_gt_f32_e32 vcc, s34, v2
	s_nop 1
	v_cndmask_b32_e64 v3, 0, 32, vcc
	v_ldexp_f32 v2, v2, v3
	v_log_f32_e32 v2, v2
	s_nop 0
	v_mul_f32_e32 v3, 0x3f317217, v2
	v_fma_f32 v3, v2, s38, -v3
	v_fmac_f32_e32 v3, 0x3377d1cf, v2
	v_fmac_f32_e32 v3, 0x3f317217, v2
	v_cmp_lt_f32_e64 s[42:43], |v2|, s20
	s_nop 1
	v_cndmask_b32_e64 v2, v2, v3, s[42:43]
	v_cndmask_b32_e32 v3, 0, v193, vcc
	v_sub_f32_e32 v2, v2, v3
	v_add_f32_e32 v1, v1, v2
	ds_read_u16 v2, v0 offset:816
	s_waitcnt lgkmcnt(0)
	v_lshlrev_b32_e32 v2, 16, v2
	v_mul_f32_e32 v2, 0xbfb8aa3b, v2
	v_exp_f32_e32 v2, v2
	s_nop 0
	v_add_f32_e32 v2, 1.0, v2
	v_min_f32_e32 v3, 0x7f7fffff, v2
	v_rcp_f32_e32 v5, v3
	s_nop 0
	v_fma_f32 v6, -v3, v5, 1.0
	v_fmac_f32_e32 v5, v6, v5
	v_fma_f32 v8, -v3, v5, 1.0
	v_fma_f32 v7, v8, v5, v5
	v_fma_f32 v3, -v3, v7, 1.0
	v_fma_f32 v2, v3, v5, v7
	v_fma_f32 v2, v4, v2, v20
	v_cmp_gt_f32_e32 vcc, s34, v2
	s_nop 1
	v_cndmask_b32_e64 v3, 0, 32, vcc
	v_ldexp_f32 v2, v2, v3
	v_log_f32_e32 v2, v2
	s_nop 0
	v_mul_f32_e32 v3, 0x3f317217, v2
	v_fma_f32 v3, v2, s38, -v3
	v_fmac_f32_e32 v3, 0x3377d1cf, v2
	v_fmac_f32_e32 v3, 0x3f317217, v2
	v_cmp_lt_f32_e64 s[42:43], |v2|, s20
	s_nop 1
	v_cndmask_b32_e64 v2, v2, v3, s[42:43]
	v_cndmask_b32_e32 v3, 0, v193, vcc
	v_sub_f32_e32 v2, v2, v3
	v_add_f32_e32 v1, v1, v2
	ds_read_u16 v2, v0 offset:1088
	s_waitcnt lgkmcnt(0)
	v_lshlrev_b32_e32 v2, 16, v2
	v_mul_f32_e32 v2, 0xbfb8aa3b, v2
	v_exp_f32_e32 v2, v2
	s_nop 0
	v_add_f32_e32 v2, 1.0, v2
	v_min_f32_e32 v3, 0x7f7fffff, v2
	v_rcp_f32_e32 v5, v3
	s_nop 0
	v_fma_f32 v6, -v3, v5, 1.0
	v_fmac_f32_e32 v5, v6, v5
	v_fma_f32 v8, -v3, v5, 1.0
	v_fma_f32 v7, v8, v5, v5
	v_fma_f32 v3, -v3, v7, 1.0
	v_fma_f32 v2, v3, v5, v7
	v_fma_f32 v2, v4, v2, v20
	v_cmp_gt_f32_e32 vcc, s34, v2
	s_nop 1
	v_cndmask_b32_e64 v3, 0, 32, vcc
	v_ldexp_f32 v2, v2, v3
	v_log_f32_e32 v2, v2
	s_nop 0
	v_mul_f32_e32 v3, 0x3f317217, v2
	v_fma_f32 v3, v2, s38, -v3
	v_fmac_f32_e32 v3, 0x3377d1cf, v2
	v_fmac_f32_e32 v3, 0x3f317217, v2
	v_cmp_lt_f32_e64 s[42:43], |v2|, s20
	s_nop 1
	v_cndmask_b32_e64 v2, v2, v3, s[42:43]
	v_cndmask_b32_e32 v3, 0, v193, vcc
	v_sub_f32_e32 v2, v2, v3
	v_add_f32_e32 v1, v1, v2
	ds_read_u16 v2, v0 offset:1360
	s_waitcnt lgkmcnt(0)
	v_lshlrev_b32_e32 v2, 16, v2
	v_mul_f32_e32 v2, 0xbfb8aa3b, v2
	v_exp_f32_e32 v2, v2
	s_nop 0
	v_add_f32_e32 v2, 1.0, v2
	v_min_f32_e32 v3, 0x7f7fffff, v2
	v_rcp_f32_e32 v5, v3
	s_nop 0
	v_fma_f32 v6, -v3, v5, 1.0
	v_fmac_f32_e32 v5, v6, v5
	v_fma_f32 v8, -v3, v5, 1.0
	v_fma_f32 v7, v8, v5, v5
	v_fma_f32 v3, -v3, v7, 1.0
	v_fma_f32 v2, v3, v5, v7
	v_fma_f32 v2, v4, v2, v20
	v_cmp_gt_f32_e32 vcc, s34, v2
	s_nop 1
	v_cndmask_b32_e64 v3, 0, 32, vcc
	v_ldexp_f32 v2, v2, v3
	v_log_f32_e32 v2, v2
	s_nop 0
	v_mul_f32_e32 v3, 0x3f317217, v2
	v_fma_f32 v3, v2, s38, -v3
	v_fmac_f32_e32 v3, 0x3377d1cf, v2
	v_fmac_f32_e32 v3, 0x3f317217, v2
	v_cmp_lt_f32_e64 s[42:43], |v2|, s20
	s_nop 1
	v_cndmask_b32_e64 v2, v2, v3, s[42:43]
	v_cndmask_b32_e32 v3, 0, v193, vcc
	v_sub_f32_e32 v2, v2, v3
	v_add_f32_e32 v1, v1, v2
	ds_read_u16 v2, v0 offset:1632
	s_waitcnt lgkmcnt(0)
	v_lshlrev_b32_e32 v2, 16, v2
	v_mul_f32_e32 v2, 0xbfb8aa3b, v2
	v_exp_f32_e32 v2, v2
	s_nop 0
	v_add_f32_e32 v2, 1.0, v2
	v_min_f32_e32 v3, 0x7f7fffff, v2
	v_rcp_f32_e32 v5, v3
	s_nop 0
	v_fma_f32 v6, -v3, v5, 1.0
	v_fmac_f32_e32 v5, v6, v5
	v_fma_f32 v8, -v3, v5, 1.0
	v_fma_f32 v7, v8, v5, v5
	v_fma_f32 v3, -v3, v7, 1.0
	v_fma_f32 v2, v3, v5, v7
	v_fma_f32 v2, v4, v2, v20
	v_cmp_gt_f32_e32 vcc, s34, v2
	s_nop 1
	v_cndmask_b32_e64 v3, 0, 32, vcc
	v_ldexp_f32 v2, v2, v3
	v_log_f32_e32 v2, v2
	s_nop 0
	v_mul_f32_e32 v3, 0x3f317217, v2
	v_fma_f32 v3, v2, s38, -v3
	v_fmac_f32_e32 v3, 0x3377d1cf, v2
	v_fmac_f32_e32 v3, 0x3f317217, v2
	v_cmp_lt_f32_e64 s[42:43], |v2|, s20
	s_nop 1
	v_cndmask_b32_e64 v2, v2, v3, s[42:43]
	v_cndmask_b32_e32 v3, 0, v193, vcc
	v_sub_f32_e32 v2, v2, v3
	v_add_f32_e32 v1, v1, v2
	ds_read_u16 v2, v0 offset:1904
	v_add_u32_e32 v0, 0x880, v0
	s_waitcnt lgkmcnt(0)
	v_lshlrev_b32_e32 v2, 16, v2
	v_mul_f32_e32 v2, 0xbfb8aa3b, v2
	v_exp_f32_e32 v2, v2
	s_nop 0
	v_add_f32_e32 v2, 1.0, v2
	v_min_f32_e32 v3, 0x7f7fffff, v2
	v_rcp_f32_e32 v5, v3
	s_nop 0
	v_fma_f32 v6, -v3, v5, 1.0
	v_fmac_f32_e32 v5, v6, v5
	v_fma_f32 v8, -v3, v5, 1.0
	v_fma_f32 v7, v8, v5, v5
	v_fma_f32 v3, -v3, v7, 1.0
	v_fma_f32 v2, v3, v5, v7
	v_fma_f32 v2, v4, v2, v20
	v_cmp_gt_f32_e32 vcc, s34, v2
	s_nop 1
	v_cndmask_b32_e64 v3, 0, 32, vcc
	v_ldexp_f32 v2, v2, v3
	v_log_f32_e32 v2, v2
	s_nop 0
	v_mul_f32_e32 v3, 0x3f317217, v2
	v_fma_f32 v3, v2, s38, -v3
	v_fmac_f32_e32 v3, 0x3377d1cf, v2
	v_fmac_f32_e32 v3, 0x3f317217, v2
	v_cmp_lt_f32_e64 s[42:43], |v2|, s20
	s_nop 1
	v_cndmask_b32_e64 v2, v2, v3, s[42:43]
	v_cndmask_b32_e32 v3, 0, v193, vcc
	v_sub_f32_e32 v2, v2, v3
	v_add_f32_e32 v1, v1, v2
	s_cbranch_scc0 .LBB0_397
; DEVI float b2f(bfu b) { return __uint_as_float(((unsigned)b) << 16); }
; DEVI float sigmoidf_(float x) { return 1.f / (1.f + __expf(-x)); }
; DEVI void h1_item(const Params& P, int l, int ck, int h, char* smem, int tid) {
;     ...
;   tots[hf * 128 + d] = tot;
;   __syncthreads();
;   float run = hf ? 0.f : tots[128 + d];
; #pragma unroll 8
;   for (int i = Lh - 1; i >= 0; --i) {
;     const int sr = hf * Lh + i;
;     float f = lb + (1.f - lb) * sigmoidf_(b2f(FS[sr * 136 + d]));
;     KT[d * 72 + sr] = f2b((1.f - f) * __expf(run));
;     run += __logf(f);
;   }
	v_mov_b32_e32 v5, 0
	ds_write_b32 v100, v1 offset:54272
	s_waitcnt lgkmcnt(0)
	s_barrier
	s_and_saveexec_b64 s[26:27], s[40:41]
	ds_read_b32 v5, v100 offset:54784
	s_or_b64 exec, exec, s[26:27]
	v_mad_u64_u32 v[0:1], s[26:27], v164, s24, v[138:139]
	v_mad_u64_u32 v[2:3], s[26:27], v165, s24, v[140:141]
.LBB0_401:
	ds_read_u16 v1, v0 offset:1904
	s_waitcnt lgkmcnt(1)
	v_mul_f32_e32 v3, 0x3fb8aa3b, v5
	v_exp_f32_e32 v3, v3
	s_add_i32 s24, s24, -8
	s_cmp_eq_u32 s24, 0
	s_waitcnt lgkmcnt(0)
	v_lshlrev_b32_e32 v1, 16, v1
	v_mul_f32_e32 v1, 0xbfb8aa3b, v1
	v_exp_f32_e32 v1, v1
	s_nop 0
	v_add_f32_e32 v1, 1.0, v1
	v_min_f32_e32 v6, 0x7f7fffff, v1
	v_rcp_f32_e32 v8, v6
	s_nop 0
	v_fma_f32 v9, -v6, v8, 1.0
	v_fmac_f32_e32 v8, v9, v8
	v_fma_f32 v10, -v6, v8, 1.0
	v_fma_f32 v9, v10, v8, v8
	v_fma_f32 v6, -v6, v9, 1.0
	v_fma_f32 v1, v6, v8, v9
	v_fma_f32 v1, v4, v1, v20
	v_sub_f32_e32 v6, 1.0, v1
	v_cmp_gt_f32_e32 vcc, s34, v1
	v_mul_f32_e32 v3, v3, v6
	s_nop 0
	v_cndmask_b32_e64 v7, 0, 32, vcc
	v_ldexp_f32 v1, v1, v7
	v_bfe_u32 v7, v3, 16, 1
	v_add3_u32 v3, v3, v7, s39
	ds_write_b16_d16_hi v2, v3 offset:14
	ds_read_u16 v3, v0 offset:1632
	v_log_f32_e32 v1, v1
	v_cndmask_b32_e32 v6, 0, v193, vcc
	s_waitcnt lgkmcnt(0)
	v_lshlrev_b32_e32 v3, 16, v3
	v_mul_f32_e32 v3, 0xbfb8aa3b, v3
	v_mul_f32_e32 v7, 0x3f317217, v1
	v_exp_f32_e32 v3, v3
	v_fma_f32 v7, v1, s38, -v7
	v_fmac_f32_e32 v7, 0x3377d1cf, v1
	v_fmac_f32_e32 v7, 0x3f317217, v1
	v_cmp_lt_f32_e64 vcc, |v1|, s20
	v_add_f32_e32 v3, 1.0, v3
	s_nop 0
	v_cndmask_b32_e32 v1, v1, v7, vcc
	v_sub_f32_e32 v1, v1, v6
	v_min_f32_e32 v6, 0x7f7fffff, v3
	v_rcp_f32_e32 v8, v6
	s_nop 0
	v_add_f32_e32 v1, v5, v1
	v_fma_f32 v9, -v6, v8, 1.0
	v_fmac_f32_e32 v8, v9, v8
	v_fma_f32 v10, -v6, v8, 1.0
	v_fma_f32 v9, v10, v8, v8
	v_mul_f32_e32 v5, 0x3fb8aa3b, v1
	v_fma_f32 v6, -v6, v9, 1.0
	v_exp_f32_e32 v5, v5
	s_nop 0
	v_fma_f32 v3, v6, v8, v9
	v_fma_f32 v3, v4, v3, v20
	v_sub_f32_e32 v6, 1.0, v3
	v_cmp_gt_f32_e32 vcc, s34, v3
	v_mul_f32_e32 v5, v5, v6
	s_nop 0
	v_cndmask_b32_e64 v7, 0, 32, vcc
	v_ldexp_f32 v3, v3, v7
	v_bfe_u32 v7, v5, 16, 1
	v_add3_u32 v5, v5, v7, s39
	ds_write_b16_d16_hi v2, v5 offset:12
	ds_read_u16 v5, v0 offset:1360
	v_log_f32_e32 v3, v3
	v_cndmask_b32_e32 v6, 0, v193, vcc
	s_waitcnt lgkmcnt(0)
	v_lshlrev_b32_e32 v5, 16, v5
	v_mul_f32_e32 v5, 0xbfb8aa3b, v5
	v_mul_f32_e32 v7, 0x3f317217, v3
	v_exp_f32_e32 v5, v5
	v_fma_f32 v7, v3, s38, -v7
	v_fmac_f32_e32 v7, 0x3377d1cf, v3
	v_fmac_f32_e32 v7, 0x3f317217, v3
	v_cmp_lt_f32_e64 vcc, |v3|, s20
	v_add_f32_e32 v5, 1.0, v5
	s_nop 0
	v_cndmask_b32_e32 v3, v3, v7, vcc
	v_sub_f32_e32 v3, v3, v6
	v_min_f32_e32 v6, 0x7f7fffff, v5
	v_rcp_f32_e32 v8, v6
	s_nop 0
	v_add_f32_e32 v1, v1, v3
	v_fma_f32 v9, -v6, v8, 1.0
	v_fmac_f32_e32 v8, v9, v8
	v_fma_f32 v10, -v6, v8, 1.0
	v_fma_f32 v9, v10, v8, v8
	v_mul_f32_e32 v3, 0x3fb8aa3b, v1
	v_fma_f32 v6, -v6, v9, 1.0
	v_exp_f32_e32 v3, v3
	s_nop 0
	v_fma_f32 v5, v6, v8, v9
	v_fma_f32 v5, v4, v5, v20
	v_sub_f32_e32 v6, 1.0, v5
	v_cmp_gt_f32_e32 vcc, s34, v5
	v_mul_f32_e32 v3, v3, v6
	s_nop 0
	v_cndmask_b32_e64 v7, 0, 32, vcc
	v_ldexp_f32 v5, v5, v7
	v_bfe_u32 v7, v3, 16, 1
	v_add3_u32 v3, v3, v7, s39
	ds_write_b16_d16_hi v2, v3 offset:10
	ds_read_u16 v3, v0 offset:1088
	v_log_f32_e32 v5, v5
	v_cndmask_b32_e32 v6, 0, v193, vcc
	s_waitcnt lgkmcnt(0)
	v_lshlrev_b32_e32 v3, 16, v3
	v_mul_f32_e32 v3, 0xbfb8aa3b, v3
	v_mul_f32_e32 v7, 0x3f317217, v5
	v_exp_f32_e32 v3, v3
	v_fma_f32 v7, v5, s38, -v7
	v_fmac_f32_e32 v7, 0x3377d1cf, v5
	v_fmac_f32_e32 v7, 0x3f317217, v5
	v_cmp_lt_f32_e64 vcc, |v5|, s20
	v_add_f32_e32 v3, 1.0, v3
	s_nop 0
	v_cndmask_b32_e32 v5, v5, v7, vcc
	v_sub_f32_e32 v5, v5, v6
	v_min_f32_e32 v6, 0x7f7fffff, v3
	v_rcp_f32_e32 v8, v6
	s_nop 0
	v_add_f32_e32 v1, v1, v5
	v_fma_f32 v9, -v6, v8, 1.0
	v_fmac_f32_e32 v8, v9, v8
	v_fma_f32 v10, -v6, v8, 1.0
	v_fma_f32 v9, v10, v8, v8
	v_mul_f32_e32 v5, 0x3fb8aa3b, v1
	v_fma_f32 v6, -v6, v9, 1.0
	v_exp_f32_e32 v5, v5
	s_nop 0
	v_fma_f32 v3, v6, v8, v9
	v_fma_f32 v3, v4, v3, v20
	v_sub_f32_e32 v6, 1.0, v3
	v_cmp_gt_f32_e32 vcc, s34, v3
	v_mul_f32_e32 v5, v5, v6
	s_nop 0
	v_cndmask_b32_e64 v7, 0, 32, vcc
	v_ldexp_f32 v3, v3, v7
	v_bfe_u32 v7, v5, 16, 1
	v_add3_u32 v5, v5, v7, s39
	ds_write_b16_d16_hi v2, v5 offset:8
	ds_read_u16 v5, v0 offset:816
	v_log_f32_e32 v3, v3
	v_cndmask_b32_e32 v6, 0, v193, vcc
	s_waitcnt lgkmcnt(0)
; DEVI float b2f(bfu b) { return __uint_as_float(((unsigned)b) << 16); }
; DEVI float sigmoidf_(float x) { return 1.f / (1.f + __expf(-x)); }
; DEVI void h1_item(const Params& P, int l, int ck, int h, char* smem, int tid) {
;     ...
; #pragma unroll 8
;   for (int i = Lh - 1; i >= 0; --i) {
;     const int sr = hf * Lh + i;
;     float f = lb + (1.f - lb) * sigmoidf_(b2f(FS[sr * 136 + d]));
;     KT[d * 72 + sr] = f2b((1.f - f) * __expf(run));
;     run += __logf(f);
;   }
;   if (L == 32) {
;     for (int sr = 32 + hf * 16; sr < 48 + hf * 16; ++sr) KT[d * 72 + sr] = 0;
;   }
	v_lshlrev_b32_e32 v5, 16, v5
	v_mul_f32_e32 v5, 0xbfb8aa3b, v5
	v_mul_f32_e32 v7, 0x3f317217, v3
	v_exp_f32_e32 v5, v5
	v_fma_f32 v7, v3, s38, -v7
	v_fmac_f32_e32 v7, 0x3377d1cf, v3
	v_fmac_f32_e32 v7, 0x3f317217, v3
	v_cmp_lt_f32_e64 vcc, |v3|, s20
	v_add_f32_e32 v5, 1.0, v5
	s_nop 0
	v_cndmask_b32_e32 v3, v3, v7, vcc
	v_sub_f32_e32 v3, v3, v6
	v_min_f32_e32 v6, 0x7f7fffff, v5
	v_rcp_f32_e32 v8, v6
	s_nop 0
	v_add_f32_e32 v1, v1, v3
	v_fma_f32 v9, -v6, v8, 1.0
	v_fmac_f32_e32 v8, v9, v8
	v_fma_f32 v10, -v6, v8, 1.0
	v_fma_f32 v9, v10, v8, v8
	v_mul_f32_e32 v3, 0x3fb8aa3b, v1
	v_fma_f32 v6, -v6, v9, 1.0
	v_exp_f32_e32 v3, v3
	s_nop 0
	v_fma_f32 v5, v6, v8, v9
	v_fma_f32 v5, v4, v5, v20
	v_sub_f32_e32 v6, 1.0, v5
	v_cmp_gt_f32_e32 vcc, s34, v5
	v_mul_f32_e32 v3, v3, v6
	s_nop 0
	v_cndmask_b32_e64 v7, 0, 32, vcc
	v_ldexp_f32 v5, v5, v7
	v_bfe_u32 v7, v3, 16, 1
	v_add3_u32 v3, v3, v7, s39
	ds_write_b16_d16_hi v2, v3 offset:6
	ds_read_u16 v3, v0 offset:544
	v_log_f32_e32 v5, v5
	v_cndmask_b32_e32 v6, 0, v193, vcc
	s_waitcnt lgkmcnt(0)
	v_lshlrev_b32_e32 v3, 16, v3
	v_mul_f32_e32 v3, 0xbfb8aa3b, v3
	v_mul_f32_e32 v7, 0x3f317217, v5
	v_exp_f32_e32 v3, v3
	v_fma_f32 v7, v5, s38, -v7
	v_fmac_f32_e32 v7, 0x3377d1cf, v5
	v_fmac_f32_e32 v7, 0x3f317217, v5
	v_cmp_lt_f32_e64 vcc, |v5|, s20
	v_add_f32_e32 v3, 1.0, v3
	s_nop 0
	v_cndmask_b32_e32 v5, v5, v7, vcc
	v_sub_f32_e32 v5, v5, v6
	v_min_f32_e32 v6, 0x7f7fffff, v3
	v_rcp_f32_e32 v8, v6
	s_nop 0
	v_add_f32_e32 v1, v1, v5
	v_fma_f32 v9, -v6, v8, 1.0
	v_fmac_f32_e32 v8, v9, v8
	v_fma_f32 v10, -v6, v8, 1.0
	v_fma_f32 v9, v10, v8, v8
	v_mul_f32_e32 v5, 0x3fb8aa3b, v1
	v_fma_f32 v6, -v6, v9, 1.0
	v_exp_f32_e32 v5, v5
	s_nop 0
	v_fma_f32 v3, v6, v8, v9
	v_fma_f32 v3, v4, v3, v20
	v_sub_f32_e32 v6, 1.0, v3
	v_cmp_gt_f32_e32 vcc, s34, v3
	v_mul_f32_e32 v5, v5, v6
	s_nop 0
	v_cndmask_b32_e64 v7, 0, 32, vcc
	v_ldexp_f32 v3, v3, v7
	v_bfe_u32 v7, v5, 16, 1
	v_add3_u32 v5, v5, v7, s39
	ds_write_b16_d16_hi v2, v5 offset:4
	ds_read_u16 v5, v0 offset:272
	v_log_f32_e32 v3, v3
	v_cndmask_b32_e32 v6, 0, v193, vcc
	s_waitcnt lgkmcnt(0)
	v_lshlrev_b32_e32 v5, 16, v5
	v_mul_f32_e32 v5, 0xbfb8aa3b, v5
	v_mul_f32_e32 v7, 0x3f317217, v3
	v_exp_f32_e32 v5, v5
	v_fma_f32 v7, v3, s38, -v7
	v_fmac_f32_e32 v7, 0x3377d1cf, v3
	v_fmac_f32_e32 v7, 0x3f317217, v3
	v_cmp_lt_f32_e64 vcc, |v3|, s20
	v_add_f32_e32 v5, 1.0, v5
	s_nop 0
	v_cndmask_b32_e32 v3, v3, v7, vcc
	v_sub_f32_e32 v3, v3, v6
	v_min_f32_e32 v6, 0x7f7fffff, v5
	v_rcp_f32_e32 v8, v6
	s_nop 0
	v_add_f32_e32 v1, v1, v3
	v_fma_f32 v9, -v6, v8, 1.0
	v_fmac_f32_e32 v8, v9, v8
	v_fma_f32 v10, -v6, v8, 1.0
	v_fma_f32 v9, v10, v8, v8
	v_mul_f32_e32 v3, 0x3fb8aa3b, v1
	v_fma_f32 v6, -v6, v9, 1.0
	v_exp_f32_e32 v3, v3
	s_nop 0
	v_fma_f32 v5, v6, v8, v9
	v_fma_f32 v5, v4, v5, v20
	v_sub_f32_e32 v6, 1.0, v5
	v_cmp_gt_f32_e32 vcc, s34, v5
	v_mul_f32_e32 v3, v3, v6
	s_nop 0
	v_cndmask_b32_e64 v7, 0, 32, vcc
	v_ldexp_f32 v5, v5, v7
	v_bfe_u32 v7, v3, 16, 1
	v_add3_u32 v3, v3, v7, s39
	ds_write_b16_d16_hi v2, v3 offset:2
	ds_read_u16 v3, v0
	v_log_f32_e32 v5, v5
	v_cndmask_b32_e32 v6, 0, v193, vcc
	v_add_u32_e32 v0, 0xfffff780, v0
	s_waitcnt lgkmcnt(0)
	v_lshlrev_b32_e32 v3, 16, v3
	v_mul_f32_e32 v3, 0xbfb8aa3b, v3
	v_mul_f32_e32 v7, 0x3f317217, v5
	v_exp_f32_e32 v3, v3
	v_fma_f32 v7, v5, s38, -v7
	v_fmac_f32_e32 v7, 0x3377d1cf, v5
	v_fmac_f32_e32 v7, 0x3f317217, v5
	v_cmp_lt_f32_e64 vcc, |v5|, s20
	v_add_f32_e32 v3, 1.0, v3
	s_nop 0
	v_cndmask_b32_e32 v5, v5, v7, vcc
	v_sub_f32_e32 v5, v5, v6
	v_min_f32_e32 v6, 0x7f7fffff, v3
	v_rcp_f32_e32 v8, v6
	s_nop 0
	v_add_f32_e32 v1, v1, v5
	v_fma_f32 v9, -v6, v8, 1.0
	v_fmac_f32_e32 v8, v9, v8
	v_fma_f32 v10, -v6, v8, 1.0
	v_fma_f32 v9, v10, v8, v8
	v_fma_f32 v6, -v6, v9, 1.0
	v_fma_f32 v3, v6, v8, v9
	v_mul_f32_e32 v5, 0x3fb8aa3b, v1
	v_fma_f32 v3, v4, v3, v20
	v_exp_f32_e32 v5, v5
	v_cmp_gt_f32_e32 vcc, s34, v3
	v_sub_f32_e32 v6, 1.0, v3
	v_mul_f32_e32 v5, v5, v6
	v_cndmask_b32_e64 v7, 0, 32, vcc
	v_ldexp_f32 v3, v3, v7
	v_log_f32_e32 v3, v3
	v_bfe_u32 v7, v5, 16, 1
	v_add3_u32 v5, v5, v7, s39
	ds_write_b16_d16_hi v2, v5
	v_mul_f32_e32 v5, 0x3f317217, v3
	v_fma_f32 v5, v3, s38, -v5
	v_fmac_f32_e32 v5, 0x3377d1cf, v3
	v_cndmask_b32_e32 v6, 0, v193, vcc
	v_fmac_f32_e32 v5, 0x3f317217, v3
	v_cmp_lt_f32_e64 vcc, |v3|, s20
	v_add_u32_e32 v2, -16, v2
	s_nop 0
	v_cndmask_b32_e32 v3, v3, v5, vcc
	v_sub_f32_e32 v3, v3, v6
	v_add_f32_e32 v5, v1, v3
	s_cbranch_scc0 .LBB0_401
	s_and_b64 vcc, exec, s[46:47]
	s_cbranch_vccz .LBB0_404
	s_mov_b32 s24, s25
	s_mov_b32 s26, s25
	s_mov_b32 s27, s25
	v_mov_b64_e32 v[0:1], s[24:25]
	v_mov_b64_e32 v[2:3], s[26:27]
	ds_write_b128 v166, v[0:3] offset:18496
	ds_write_b128 v166, v[0:3] offset:18512

; DEVI float sigmoidf_(float x) { return 1.f / (1.f + __expf(-x)); }
; DEVI void gate_tile(const Params& P, int l, int pm, int q, char* smem, int tid) {
;     ...
;   for (int q = 0; q < 8; ++q) {
;     const int id = tid + 256 * q, row = id >> 4, g4 = id & 15;
;     const int cl = g4 * 4, wcc = cl >> 5, c32 = cl & 31;
;     const long grow = (long)pm * 128 + row;
;     const int col = nb * 128 + hb * 64 + cl;
;     float4 rp = *reinterpret_cast<const float4*>(T + row * 128 + wcc * 64 + c32);
;     float4 gp = *reinterpret_cast<const float4*>(T + row * 128 + wcc * 64 + 32 + c32);
;     float xv[4], bav[4], bxv[4], lmv[4];
;     load4bf(cb + grow * 1024 + col, xv);
;     ld4f(ba + col, bav); ld4f(bx + col, bxv); ld4f(lam + col, lmv);
;     const float rpa[4] = {rp.x, rp.y, rp.z, rp.w}, gpa[4] = {gp.x, gp.y, gp.z, gp.w};
;     float av[4], uv[4];
; #pragma unroll
;     for (int i = 0; i < 4; ++i) {
;       float r = sigmoidf_(rpa[i] + bav[i]);
;       float gi = sigmoidf_(gpa[i] + bxv[i]);
;       float a = __expf(-8.f * log1pf(__expf(-lmv[i])) * r);
;       av[i] = a;
;       uv[i] = sqrtf(fmaxf(1.f - a * a, 0.f)) * gi * xv[i];
;     }
;     *reinterpret_cast<float4*>(au0 + grow * 1024 + col) = make_float4(av[0], av[1], av[2], av[3]);
;     *reinterpret_cast<float4*>(au1 + grow * 1024 + col) = make_float4(uv[0], uv[1], uv[2], uv[3]);
;     *reinterpret_cast<float4*>(Tw + row * 128 + wcc * 64 + c32) = make_float4(av[0], av[1], av[2], av[3]);
;     *reinterpret_cast<float4*>(Tw + row * 128 + wcc * 64 + 32 + c32) = make_float4(uv[0], uv[1], uv[2], uv[3]);
;   }
.LBB0_459:
	v_add_u32_e32 v173, s61, v20
	v_ashrrev_i32_e32 v170, 4, v173
	v_ashrrev_i32_e32 v171, 31, v170
	v_lshlrev_b64 v[170:171], 10, v[170:171]
	v_lshl_add_u64 v[174:175], v[170:171], 0, s[54:55]
	v_lshl_add_u64 v[170:171], v[174:175], 1, v[48:49]
	global_load_dwordx2 v[208:209], v[170:171], off
	global_load_dwordx4 v[212:215], v[50:51], off
	global_load_dwordx4 v[216:219], v[52:53], off
	global_load_dwordx4 v[220:223], v[54:55], off
	v_add_u32_e32 v175, s61, v20
	v_add_u32_e32 v170, 0x100, v175
	v_ashrrev_i32_e32 v172, 4, v170
	v_ashrrev_i32_e32 v173, 31, v172
	v_lshlrev_b64 v[172:173], 10, v[172:173]
	v_lshl_add_u64 v[176:177], v[172:173], 0, s[54:55]
	v_lshl_add_u64 v[172:173], v[176:177], 1, v[48:49]
	global_load_dwordx2 v[210:211], v[172:173], off
	v_add_u32_e32 v175, s61, v20
	v_add_u32_e32 v170, 0x200, v175
	v_ashrrev_i32_e32 v172, 4, v170
	v_ashrrev_i32_e32 v173, 31, v172
	v_lshlrev_b64 v[172:173], 10, v[172:173]
	v_lshl_add_u64 v[176:177], v[172:173], 0, s[54:55]
	v_lshl_add_u64 v[172:173], v[176:177], 1, v[48:49]
	global_load_dwordx2 v[224:225], v[172:173], off
	v_add_u32_e32 v175, s61, v20
	v_add_u32_e32 v170, 0x300, v175
	v_ashrrev_i32_e32 v172, 4, v170
	v_ashrrev_i32_e32 v173, 31, v172
	v_lshlrev_b64 v[172:173], 10, v[172:173]
	v_lshl_add_u64 v[176:177], v[172:173], 0, s[54:55]
	v_lshl_add_u64 v[172:173], v[176:177], 1, v[48:49]
	global_load_dwordx2 v[226:227], v[172:173], off
	s_waitcnt vmcnt(0)
	v_add_u32_e32 v41, s61, v20
	v_ashrrev_i32_e32 v8, 4, v41
	v_ashrrev_i32_e32 v9, 31, v8
	v_lshl_or_b32 v43, v8, 9, v112
	v_lshlrev_b64 v[8:9], 10, v[8:9]
	v_lshl_add_u64 v[100:101], v[8:9], 0, s[54:55]
	v_lshl_add_u64 v[8:9], v[100:101], 1, v[48:49]
	ds_read_b128 v[4:7], v43
	ds_read_b128 v[0:3], v43 offset:128
	v_mov_b32_e32 v8, v208
	v_mov_b32_e32 v9, v209
	s_addk_i32 s61, 0x400
	s_cmpk_eq_i32 s61, 0x800
	v_lshlrev_b32_e32 v62, 16, v8
	v_and_b32_e32 v63, 0xffff0000, v8
	v_lshlrev_b32_e32 v60, 16, v9
	v_and_b32_e32 v61, 0xffff0000, v9
	v_mov_b32_e32 v16, v212
	v_mov_b32_e32 v17, v213
	v_mov_b32_e32 v18, v214
	v_mov_b32_e32 v19, v215
	v_mov_b32_e32 v12, v216
	v_mov_b32_e32 v13, v217
	v_mov_b32_e32 v14, v218
	v_mov_b32_e32 v15, v219
	v_mov_b32_e32 v8, v220
	v_mov_b32_e32 v9, v221
	v_mov_b32_e32 v10, v222
	v_mov_b32_e32 v11, v223
	s_waitcnt lgkmcnt(1)
	v_add_f32_e32 v4, v4, v16
	v_mul_f32_e32 v4, 0xbfb8aa3b, v4
	v_exp_f32_e32 v4, v4
	s_waitcnt lgkmcnt(0)
	v_add_f32_e32 v0, v0, v12
	v_mul_f32_e32 v0, 0xbfb8aa3b, v0
	v_add_f32_e32 v5, v5, v17
	v_add_f32_e32 v4, 1.0, v4
	v_min_f32_e32 v16, 0x7f7fffff, v4
	v_rcp_f32_e32 v45, v16
	v_mul_f32_e32 v5, 0xbfb8aa3b, v5
	v_exp_f32_e32 v5, v5
	v_add_f32_e32 v1, v1, v13
	v_fma_f32 v47, -v16, v45, 1.0
	v_fmac_f32_e32 v45, v47, v45
	v_fma_f32 v114, -v16, v45, 1.0
	v_fma_f32 v113, v114, v45, v45
	v_fma_f32 v16, -v16, v113, 1.0
	v_fma_f32 v16, v16, v45, v113
	v_exp_f32_e32 v4, v0
	v_add_f32_e32 v5, 1.0, v5
	v_mul_f32_e32 v1, 0xbfb8aa3b, v1
	v_add_f32_e32 v6, v6, v18
	v_mul_f32_e32 v6, 0xbfb8aa3b, v6
	v_exp_f32_e32 v6, v6
	s_nop 0
	v_add_f32_e32 v6, 1.0, v6
	v_add_f32_e32 v2, v2, v14
	v_mul_f32_e32 v2, 0xbfb8aa3b, v2
	v_add_f32_e32 v7, v7, v19
	v_mul_f32_e32 v7, 0xbfb8aa3b, v7
	v_exp_f32_e32 v7, v7
	v_mov_b32_e32 v0, v240
	v_mul_f32_e32 v0, v16, v0
	v_mul_f32_e32 v0, 0x3fb8aa3b, v0
	v_exp_f32_e32 v0, v0
	v_add_f32_e32 v7, 1.0, v7
	v_add_f32_e32 v3, v3, v15
	v_mul_f32_e32 v3, 0xbfb8aa3b, v3
	v_fma_f32 v8, -v0, v0, 1.0
	v_max_f32_e32 v8, 0, v8
	v_cmp_gt_f32_e32 vcc, s69, v8
	v_mul_f32_e32 v12, 0x4f800000, v8
	s_nop 0
	v_cndmask_b32_e32 v8, v8, v12, vcc
	v_sqrt_f32_e32 v12, v8
	s_nop 0
	v_add_u32_e32 v16, -1, v12
	v_fma_f32 v45, -v16, v12, v8
	v_cmp_ge_f32_e64 s[46:47], 0, v45
	v_add_u32_e32 v45, 1, v12
	s_nop 0
	v_cndmask_b32_e64 v16, v12, v16, s[46:47]
	v_fma_f32 v12, -v45, v12, v8
	v_cmp_lt_f32_e64 s[46:47], 0, v12
	s_nop 1
	v_cndmask_b32_e64 v12, v16, v45, s[46:47]
	v_mul_f32_e32 v16, 0x37800000, v12
	v_cndmask_b32_e32 v12, v12, v16, vcc
	v_cmp_class_f32_e32 vcc, v8, v186
	s_nop 1
	v_cndmask_b32_e32 v8, v12, v8, vcc
	v_min_f32_e32 v12, 0x7f7fffff, v5
	v_rcp_f32_e32 v16, v12
	s_nop 0
	v_fma_f32 v17, -v12, v16, 1.0
	v_fmac_f32_e32 v16, v17, v16
	v_fma_f32 v47, -v12, v16, 1.0
	v_fma_f32 v45, v47, v16, v16
	v_fma_f32 v12, -v12, v45, 1.0
	v_fma_f32 v16, v12, v16, v45
	v_exp_f32_e32 v5, v1
	s_nop 0
	v_pk_add_f32 v[4:5], v[4:5], 1.0 op_sel_hi:[1,0]
	s_nop 1
	s_nop 1
	s_nop 1
	v_mov_b32_e32 v1, v241
	v_mul_f32_e32 v1, v16, v1
	v_mul_f32_e32 v1, 0x3fb8aa3b, v1
	v_exp_f32_e32 v1, v1
	s_nop 0
	v_fma_f32 v9, -v1, v1, 1.0
	v_max_f32_e32 v9, 0, v9
	v_cmp_gt_f32_e32 vcc, s69, v9
	v_mul_f32_e32 v12, 0x4f800000, v9
	s_nop 0
	v_cndmask_b32_e32 v9, v9, v12, vcc
	v_sqrt_f32_e32 v12, v9
	s_nop 0
	v_add_u32_e32 v13, -1, v12
	v_fma_f32 v16, -v13, v12, v9
	v_cmp_ge_f32_e64 s[46:47], 0, v16
	v_add_u32_e32 v16, 1, v12
	s_nop 0
	v_cndmask_b32_e64 v13, v12, v13, s[46:47]
	v_fma_f32 v12, -v16, v12, v9
	v_cmp_lt_f32_e64 s[46:47], 0, v12
	s_nop 1
	v_cndmask_b32_e64 v12, v13, v16, s[46:47]
	v_mul_f32_e32 v13, 0x37800000, v12
	v_cndmask_b32_e32 v12, v12, v13, vcc
	v_cmp_class_f32_e32 vcc, v9, v186
	s_nop 1
	v_cndmask_b32_e32 v9, v12, v9, vcc
	v_min_f32_e32 v12, 0x7f7fffff, v6
	v_rcp_f32_e32 v13, v12
	s_nop 0
	v_fma_f32 v16, -v12, v13, 1.0
	v_fmac_f32_e32 v13, v16, v13
	v_fma_f32 v18, -v12, v13, 1.0
	v_fma_f32 v17, v18, v13, v13
	v_fma_f32 v12, -v12, v17, 1.0
	v_fma_f32 v16, v12, v13, v17
	v_exp_f32_e32 v6, v2
	s_nop 0
	s_nop 1
	s_nop 1
	s_nop 1
	v_mov_b32_e32 v2, v242
	v_mul_f32_e32 v2, v16, v2
	v_mul_f32_e32 v2, 0x3fb8aa3b, v2
	v_exp_f32_e32 v2, v2
	s_nop 0
	v_fma_f32 v10, -v2, v2, 1.0
	v_max_f32_e32 v10, 0, v10
; DEVI float sigmoidf_(float x) { return 1.f / (1.f + __expf(-x)); }
; DEVI void gate_tile(const Params& P, int l, int pm, int q, char* smem, int tid) {
;     ...
;   for (int q = 0; q < 8; ++q) {
;     const int id = tid + 256 * q, row = id >> 4, g4 = id & 15;
;     const int cl = g4 * 4, wcc = cl >> 5, c32 = cl & 31;
;     const long grow = (long)pm * 128 + row;
;     const int col = nb * 128 + hb * 64 + cl;
;     float4 rp = *reinterpret_cast<const float4*>(T + row * 128 + wcc * 64 + c32);
;     float4 gp = *reinterpret_cast<const float4*>(T + row * 128 + wcc * 64 + 32 + c32);
;     float xv[4], bav[4], bxv[4], lmv[4];
;     load4bf(cb + grow * 1024 + col, xv);
;     ld4f(ba + col, bav); ld4f(bx + col, bxv); ld4f(lam + col, lmv);
;     const float rpa[4] = {rp.x, rp.y, rp.z, rp.w}, gpa[4] = {gp.x, gp.y, gp.z, gp.w};
;     float av[4], uv[4];
; #pragma unroll
;     for (int i = 0; i < 4; ++i) {
;       float r = sigmoidf_(rpa[i] + bav[i]);
;       float gi = sigmoidf_(gpa[i] + bxv[i]);
;       float a = __expf(-8.f * log1pf(__expf(-lmv[i])) * r);
;       av[i] = a;
;       uv[i] = sqrtf(fmaxf(1.f - a * a, 0.f)) * gi * xv[i];
;     }
;     *reinterpret_cast<float4*>(au0 + grow * 1024 + col) = make_float4(av[0], av[1], av[2], av[3]);
;     *reinterpret_cast<float4*>(au1 + grow * 1024 + col) = make_float4(uv[0], uv[1], uv[2], uv[3]);
;     *reinterpret_cast<float4*>(Tw + row * 128 + wcc * 64 + c32) = make_float4(av[0], av[1], av[2], av[3]);
;     *reinterpret_cast<float4*>(Tw + row * 128 + wcc * 64 + 32 + c32) = make_float4(uv[0], uv[1], uv[2], uv[3]);
;   }
	v_cmp_gt_f32_e32 vcc, s69, v10
	v_mul_f32_e32 v12, 0x4f800000, v10
	s_nop 0
	v_cndmask_b32_e32 v10, v10, v12, vcc
	v_sqrt_f32_e32 v12, v10
	s_nop 0
	v_add_u32_e32 v13, -1, v12
	v_fma_f32 v14, -v13, v12, v10
	v_cmp_ge_f32_e64 s[46:47], 0, v14
	v_add_u32_e32 v14, 1, v12
	s_nop 0
	v_cndmask_b32_e64 v13, v12, v13, s[46:47]
	v_fma_f32 v12, -v14, v12, v10
	v_cmp_lt_f32_e64 s[46:47], 0, v12
	s_nop 1
	v_cndmask_b32_e64 v12, v13, v14, s[46:47]
	v_mul_f32_e32 v13, 0x37800000, v12
	v_cndmask_b32_e32 v12, v12, v13, vcc
	v_cmp_class_f32_e32 vcc, v10, v186
	s_nop 1
	v_cndmask_b32_e32 v10, v12, v10, vcc
	v_min_f32_e32 v12, 0x7f7fffff, v7
	v_rcp_f32_e32 v13, v12
	s_nop 0
	v_fma_f32 v14, -v12, v13, 1.0
	v_fmac_f32_e32 v13, v14, v13
	v_fma_f32 v17, -v12, v13, 1.0
	v_fma_f32 v16, v17, v13, v13
	v_fma_f32 v12, -v12, v16, 1.0
	v_fma_f32 v14, v12, v13, v16
	v_exp_f32_e32 v7, v3
	s_nop 0
	v_pk_add_f32 v[6:7], v[6:7], 1.0 op_sel_hi:[1,0]
	s_nop 1
	s_nop 1
	s_nop 1
	v_mov_b32_e32 v3, v243
	v_mul_f32_e32 v3, v14, v3
	v_mul_f32_e32 v3, 0x3fb8aa3b, v3
	v_exp_f32_e32 v3, v3
	s_nop 0
	v_fma_f32 v11, -v3, v3, 1.0
	v_max_f32_e32 v11, 0, v11
	v_cmp_gt_f32_e32 vcc, s69, v11
	v_mul_f32_e32 v12, 0x4f800000, v11
	s_nop 0
	v_cndmask_b32_e32 v11, v11, v12, vcc
	v_sqrt_f32_e32 v12, v11
	s_nop 0
	v_add_u32_e32 v13, -1, v12
	v_fma_f32 v14, -v13, v12, v11
	v_cmp_ge_f32_e64 s[46:47], 0, v14
	v_add_u32_e32 v14, 1, v12
	s_nop 0
	v_cndmask_b32_e64 v13, v12, v13, s[46:47]
	v_fma_f32 v12, -v14, v12, v11
	v_cmp_lt_f32_e64 s[46:47], 0, v12
	s_nop 1
	v_cndmask_b32_e64 v12, v13, v14, s[46:47]
	v_mul_f32_e32 v13, 0x37800000, v12
	v_cndmask_b32_e32 v12, v12, v13, vcc
	v_cmp_class_f32_e32 vcc, v11, v186
	s_nop 1
	v_cndmask_b32_e32 v11, v12, v11, vcc
	v_lshlrev_b64 v[12:13], 2, v[100:101]
	v_lshl_add_u64 v[14:15], v[56:57], 0, v[12:13]
	global_store_dwordx4 v[14:15], v[0:3], off
	v_min_f32_e32 v14, 0x7f7fffff, v5
	v_rcp_f32_e32 v15, v14
	v_lshl_add_u64 v[12:13], v[58:59], 0, v[12:13]
	v_fma_f32 v16, -v14, v15, 1.0
	v_fmac_f32_e32 v15, v16, v15
	v_fma_f32 v18, -v14, v15, 1.0
	v_fma_f32 v17, v18, v15, v15
	v_fma_f32 v14, -v14, v17, 1.0
	v_fma_f32 v5, v14, v15, v17
	v_min_f32_e32 v14, 0x7f7fffff, v4
	v_rcp_f32_e32 v15, v14
	s_nop 0
	v_fma_f32 v16, -v14, v15, 1.0
	v_fmac_f32_e32 v15, v16, v15
	v_fma_f32 v18, -v14, v15, 1.0
	v_fma_f32 v17, v18, v15, v15
	v_fma_f32 v14, -v14, v17, 1.0
	v_fma_f32 v4, v14, v15, v17
	v_pk_mul_f32 v[4:5], v[4:5], v[8:9]
	v_min_f32_e32 v8, 0x7f7fffff, v7
	v_rcp_f32_e32 v9, v8
	v_pk_mul_f32 v[4:5], v[4:5], v[62:63]
	v_fma_f32 v14, -v8, v9, 1.0
	v_fmac_f32_e32 v9, v14, v9
	v_fma_f32 v16, -v8, v9, 1.0
	v_fma_f32 v15, v16, v9, v9
	v_fma_f32 v8, -v8, v15, 1.0
	v_fma_f32 v7, v8, v9, v15
	v_min_f32_e32 v8, 0x7f7fffff, v6
	v_rcp_f32_e32 v9, v8
	s_nop 0
	v_fma_f32 v14, -v8, v9, 1.0
	v_fmac_f32_e32 v9, v14, v9
	v_fma_f32 v16, -v8, v9, 1.0
	v_fma_f32 v15, v16, v9, v9
	v_fma_f32 v8, -v8, v15, 1.0
	v_fma_f32 v6, v8, v9, v15
	v_pk_mul_f32 v[6:7], v[6:7], v[10:11]
	s_nop 0
	v_pk_mul_f32 v[6:7], v[6:7], v[60:61]
	global_store_dwordx4 v[12:13], v[4:7], off
	ds_write_b128 v43, v[0:3]
	ds_write_b128 v43, v[4:7] offset:128
	v_add_u32_e32 v0, 0x100, v41
	v_ashrrev_i32_e32 v4, 4, v0
	v_ashrrev_i32_e32 v5, 31, v4
	v_lshl_or_b32 v43, v4, 9, v112
	v_lshlrev_b64 v[4:5], 10, v[4:5]
	v_lshl_add_u64 v[100:101], v[4:5], 0, s[54:55]
	v_lshl_add_u64 v[4:5], v[100:101], 1, v[48:49]
	ds_read_b128 v[12:15], v43
	ds_read_b128 v[0:3], v43 offset:128
	v_mov_b32_e32 v4, v210
	v_mov_b32_e32 v5, v211
	v_lshlrev_b32_e32 v62, 16, v4
	v_and_b32_e32 v63, 0xffff0000, v4
	v_lshlrev_b32_e32 v60, 16, v5
	v_and_b32_e32 v61, 0xffff0000, v5
	v_mov_b32_e32 v16, v212
	v_mov_b32_e32 v17, v213
	v_mov_b32_e32 v18, v214
	v_mov_b32_e32 v19, v215
	v_mov_b32_e32 v8, v216
	v_mov_b32_e32 v9, v217
	v_mov_b32_e32 v10, v218
	v_mov_b32_e32 v11, v219
	v_mov_b32_e32 v4, v220
	v_mov_b32_e32 v5, v221
	v_mov_b32_e32 v6, v222
	v_mov_b32_e32 v7, v223
	s_waitcnt lgkmcnt(1)
	v_add_f32_e32 v12, v12, v16
	v_mul_f32_e32 v12, 0xbfb8aa3b, v12
	v_exp_f32_e32 v12, v12
	s_waitcnt lgkmcnt(0)
	v_add_f32_e32 v0, v0, v8
	v_mul_f32_e32 v0, 0xbfb8aa3b, v0
	v_exp_f32_e32 v8, v0
	v_add_f32_e32 v12, 1.0, v12
	v_min_f32_e32 v16, 0x7f7fffff, v12
	v_rcp_f32_e32 v45, v16
	v_add_f32_e32 v1, v1, v9
	v_fma_f32 v47, -v16, v45, 1.0
	v_fmac_f32_e32 v45, v47, v45
	v_fma_f32 v114, -v16, v45, 1.0
	v_fma_f32 v113, v114, v45, v45
	v_fma_f32 v16, -v16, v113, 1.0
	v_fma_f32 v12, v16, v45, v113
	v_mul_f32_e32 v1, 0xbfb8aa3b, v1
	v_exp_f32_e32 v9, v1
	v_add_f32_e32 v2, v2, v10
	v_mul_f32_e32 v2, 0xbfb8aa3b, v2
	v_exp_f32_e32 v10, v2
	v_mov_b32_e32 v0, v240
	v_mul_f32_e32 v0, v12, v0
	v_mul_f32_e32 v0, 0x3fb8aa3b, v0
	v_exp_f32_e32 v0, v0
	v_add_f32_e32 v3, v3, v11
	v_fma_f32 v4, -v0, v0, 1.0
	v_max_f32_e32 v4, 0, v4
	v_cmp_gt_f32_e32 vcc, s69, v4
	v_mul_f32_e32 v12, 0x4f800000, v4
	s_nop 0
	v_cndmask_b32_e32 v4, v4, v12, vcc
	v_sqrt_f32_e32 v12, v4
	v_mul_f32_e32 v3, 0xbfb8aa3b, v3
	v_exp_f32_e32 v11, v3
	v_add_u32_e32 v16, -1, v12
	v_fma_f32 v45, -v16, v12, v4
	v_cmp_ge_f32_e64 s[46:47], 0, v45
	v_add_u32_e32 v45, 1, v12
	s_nop 0
	v_cndmask_b32_e64 v16, v12, v16, s[46:47]
	v_fma_f32 v12, -v45, v12, v4
	v_cmp_lt_f32_e64 s[46:47], 0, v12
	v_pk_add_f32 v[8:9], v[8:9], 1.0 op_sel_hi:[1,0]
	s_nop 0
	v_cndmask_b32_e64 v12, v16, v45, s[46:47]
	v_mul_f32_e32 v16, 0x37800000, v12
	v_cndmask_b32_e32 v12, v12, v16, vcc
	v_cmp_class_f32_e32 vcc, v4, v186
	s_nop 1
	v_cndmask_b32_e32 v4, v12, v4, vcc
	v_add_f32_e32 v12, v13, v17
	v_mul_f32_e32 v12, 0xbfb8aa3b, v12
	v_exp_f32_e32 v12, v12
	s_nop 0
	v_add_f32_e32 v12, 1.0, v12
	v_min_f32_e32 v13, 0x7f7fffff, v12
	v_rcp_f32_e32 v16, v13
	s_nop 0
; DEVI float sigmoidf_(float x) { return 1.f / (1.f + __expf(-x)); }
; DEVI void gate_tile(const Params& P, int l, int pm, int q, char* smem, int tid) {
;     ...
;   for (int q = 0; q < 8; ++q) {
;     const int id = tid + 256 * q, row = id >> 4, g4 = id & 15;
;     const int cl = g4 * 4, wcc = cl >> 5, c32 = cl & 31;
;     const long grow = (long)pm * 128 + row;
;     const int col = nb * 128 + hb * 64 + cl;
;     float4 rp = *reinterpret_cast<const float4*>(T + row * 128 + wcc * 64 + c32);
;     float4 gp = *reinterpret_cast<const float4*>(T + row * 128 + wcc * 64 + 32 + c32);
;     float xv[4], bav[4], bxv[4], lmv[4];
;     load4bf(cb + grow * 1024 + col, xv);
;     ld4f(ba + col, bav); ld4f(bx + col, bxv); ld4f(lam + col, lmv);
;     const float rpa[4] = {rp.x, rp.y, rp.z, rp.w}, gpa[4] = {gp.x, gp.y, gp.z, gp.w};
;     float av[4], uv[4];
; #pragma unroll
;     for (int i = 0; i < 4; ++i) {
;       float r = sigmoidf_(rpa[i] + bav[i]);
;       float gi = sigmoidf_(gpa[i] + bxv[i]);
;       float a = __expf(-8.f * log1pf(__expf(-lmv[i])) * r);
;       av[i] = a;
;       uv[i] = sqrtf(fmaxf(1.f - a * a, 0.f)) * gi * xv[i];
;     }
;     *reinterpret_cast<float4*>(au0 + grow * 1024 + col) = make_float4(av[0], av[1], av[2], av[3]);
;     *reinterpret_cast<float4*>(au1 + grow * 1024 + col) = make_float4(uv[0], uv[1], uv[2], uv[3]);
;     *reinterpret_cast<float4*>(Tw + row * 128 + wcc * 64 + c32) = make_float4(av[0], av[1], av[2], av[3]);
;     *reinterpret_cast<float4*>(Tw + row * 128 + wcc * 64 + 32 + c32) = make_float4(uv[0], uv[1], uv[2], uv[3]);
;   }
	v_fma_f32 v17, -v13, v16, 1.0
	v_fmac_f32_e32 v16, v17, v16
	v_fma_f32 v47, -v13, v16, 1.0
	v_fma_f32 v45, v47, v16, v16
	v_fma_f32 v13, -v13, v45, 1.0
	v_fma_f32 v16, v13, v16, v45
	s_nop 1
	s_nop 1
	s_nop 1
	v_mov_b32_e32 v1, v241
	v_mul_f32_e32 v1, v16, v1
	v_mul_f32_e32 v1, 0x3fb8aa3b, v1
	v_exp_f32_e32 v1, v1
	s_nop 0
	v_fma_f32 v5, -v1, v1, 1.0
	v_max_f32_e32 v5, 0, v5
	v_cmp_gt_f32_e32 vcc, s69, v5
	v_mul_f32_e32 v12, 0x4f800000, v5
	s_nop 0
	v_cndmask_b32_e32 v5, v5, v12, vcc
	v_sqrt_f32_e32 v12, v5
	s_nop 0
	v_add_u32_e32 v13, -1, v12
	v_fma_f32 v16, -v13, v12, v5
	v_cmp_ge_f32_e64 s[46:47], 0, v16
	v_add_u32_e32 v16, 1, v12
	s_nop 0
	v_cndmask_b32_e64 v13, v12, v13, s[46:47]
	v_fma_f32 v12, -v16, v12, v5
	v_cmp_lt_f32_e64 s[46:47], 0, v12
	s_nop 1
	v_cndmask_b32_e64 v12, v13, v16, s[46:47]
	v_mul_f32_e32 v13, 0x37800000, v12
	v_cndmask_b32_e32 v12, v12, v13, vcc
	v_cmp_class_f32_e32 vcc, v5, v186
	s_nop 1
	v_cndmask_b32_e32 v5, v12, v5, vcc
	v_add_f32_e32 v12, v14, v18
	v_mul_f32_e32 v12, 0xbfb8aa3b, v12
	v_exp_f32_e32 v12, v12
	s_nop 0
	v_add_f32_e32 v12, 1.0, v12
	v_min_f32_e32 v13, 0x7f7fffff, v12
	v_rcp_f32_e32 v14, v13
	s_nop 0
	v_fma_f32 v16, -v13, v14, 1.0
	v_fmac_f32_e32 v14, v16, v14
	v_fma_f32 v18, -v13, v14, 1.0
	v_fma_f32 v17, v18, v14, v14
	v_fma_f32 v13, -v13, v17, 1.0
	v_fma_f32 v14, v13, v14, v17
	s_nop 1
	s_nop 1
	s_nop 1
	v_mov_b32_e32 v2, v242
	v_mul_f32_e32 v2, v14, v2
	v_mul_f32_e32 v2, 0x3fb8aa3b, v2
	v_exp_f32_e32 v2, v2
	s_nop 0
	v_fma_f32 v6, -v2, v2, 1.0
	v_max_f32_e32 v6, 0, v6
	v_cmp_gt_f32_e32 vcc, s69, v6
	v_mul_f32_e32 v12, 0x4f800000, v6
	s_nop 0
	v_cndmask_b32_e32 v6, v6, v12, vcc
	v_sqrt_f32_e32 v12, v6
	s_nop 0
	v_add_u32_e32 v13, -1, v12
	v_fma_f32 v14, -v13, v12, v6
	v_cmp_ge_f32_e64 s[46:47], 0, v14
	v_add_u32_e32 v14, 1, v12
	s_nop 0
	v_cndmask_b32_e64 v13, v12, v13, s[46:47]
	v_fma_f32 v12, -v14, v12, v6
	v_cmp_lt_f32_e64 s[46:47], 0, v12
	s_nop 1
	v_cndmask_b32_e64 v12, v13, v14, s[46:47]
	v_mul_f32_e32 v13, 0x37800000, v12
	v_cndmask_b32_e32 v12, v12, v13, vcc
	v_cmp_class_f32_e32 vcc, v6, v186
	s_nop 1
	v_cndmask_b32_e32 v6, v12, v6, vcc
	v_add_f32_e32 v12, v15, v19
	v_mul_f32_e32 v12, 0xbfb8aa3b, v12
	v_exp_f32_e32 v12, v12
	s_nop 0
	v_add_f32_e32 v12, 1.0, v12
	v_min_f32_e32 v13, 0x7f7fffff, v12
	v_rcp_f32_e32 v14, v13
	s_nop 0
	v_fma_f32 v15, -v13, v14, 1.0
	v_fmac_f32_e32 v14, v15, v14
	v_fma_f32 v17, -v13, v14, 1.0
	v_fma_f32 v16, v17, v14, v14
	v_fma_f32 v13, -v13, v16, 1.0
	v_fma_f32 v14, v13, v14, v16
	s_nop 1
	s_nop 1
	s_nop 1
	v_mov_b32_e32 v3, v243
	v_mul_f32_e32 v3, v14, v3
	v_mul_f32_e32 v3, 0x3fb8aa3b, v3
	v_exp_f32_e32 v3, v3
	s_nop 0
	v_fma_f32 v7, -v3, v3, 1.0
	v_max_f32_e32 v7, 0, v7
	v_cmp_gt_f32_e32 vcc, s69, v7
	v_mul_f32_e32 v12, 0x4f800000, v7
	s_nop 0
	v_cndmask_b32_e32 v7, v7, v12, vcc
	v_sqrt_f32_e32 v12, v7
	s_nop 0
	v_add_u32_e32 v13, -1, v12
	v_fma_f32 v14, -v13, v12, v7
	v_cmp_ge_f32_e64 s[46:47], 0, v14
	v_add_u32_e32 v14, 1, v12
	s_nop 0
	v_cndmask_b32_e64 v13, v12, v13, s[46:47]
	v_fma_f32 v12, -v14, v12, v7
	v_cmp_lt_f32_e64 s[46:47], 0, v12
	s_nop 1
	v_cndmask_b32_e64 v12, v13, v14, s[46:47]
	v_mul_f32_e32 v13, 0x37800000, v12
	v_cndmask_b32_e32 v12, v12, v13, vcc
	v_cmp_class_f32_e32 vcc, v7, v186
	s_nop 1
	v_cndmask_b32_e32 v7, v12, v7, vcc
	v_lshlrev_b64 v[12:13], 2, v[100:101]
	v_lshl_add_u64 v[14:15], v[56:57], 0, v[12:13]
	global_store_dwordx4 v[14:15], v[0:3], off
	v_min_f32_e32 v14, 0x7f7fffff, v9
	v_rcp_f32_e32 v15, v14
	v_lshl_add_u64 v[12:13], v[58:59], 0, v[12:13]
	v_fma_f32 v16, -v14, v15, 1.0
	v_fmac_f32_e32 v15, v16, v15
	v_fma_f32 v18, -v14, v15, 1.0
	v_fma_f32 v17, v18, v15, v15
	v_fma_f32 v14, -v14, v17, 1.0
	v_fma_f32 v9, v14, v15, v17
	v_min_f32_e32 v14, 0x7f7fffff, v8
	v_rcp_f32_e32 v15, v14
	s_nop 0
	v_fma_f32 v16, -v14, v15, 1.0
	v_fmac_f32_e32 v15, v16, v15
	v_fma_f32 v18, -v14, v15, 1.0
	v_fma_f32 v17, v18, v15, v15
	v_fma_f32 v14, -v14, v17, 1.0
	v_fma_f32 v8, v14, v15, v17
	v_pk_mul_f32 v[4:5], v[8:9], v[4:5]
	v_pk_add_f32 v[8:9], v[10:11], 1.0 op_sel_hi:[1,0]
	v_pk_mul_f32 v[4:5], v[4:5], v[62:63]
	v_min_f32_e32 v10, 0x7f7fffff, v9
	v_rcp_f32_e32 v11, v10
	s_nop 0
	v_fma_f32 v14, -v10, v11, 1.0
	v_fmac_f32_e32 v11, v14, v11
	v_fma_f32 v16, -v10, v11, 1.0
	v_fma_f32 v15, v16, v11, v11
	v_fma_f32 v10, -v10, v15, 1.0
	v_fma_f32 v9, v10, v11, v15
	v_min_f32_e32 v10, 0x7f7fffff, v8
	v_rcp_f32_e32 v11, v10
	s_nop 0
	v_fma_f32 v14, -v10, v11, 1.0
	v_fmac_f32_e32 v11, v14, v11
	v_fma_f32 v16, -v10, v11, 1.0
	v_fma_f32 v15, v16, v11, v11
	v_fma_f32 v10, -v10, v15, 1.0
	v_fma_f32 v8, v10, v11, v15
	v_pk_mul_f32 v[6:7], v[8:9], v[6:7]
	s_nop 0
	v_pk_mul_f32 v[6:7], v[6:7], v[60:61]
	global_store_dwordx4 v[12:13], v[4:7], off
	ds_write_b128 v43, v[0:3]
	ds_write_b128 v43, v[4:7] offset:128
	v_add_u32_e32 v0, 0x200, v41
	v_ashrrev_i32_e32 v4, 4, v0
	v_ashrrev_i32_e32 v5, 31, v4
	v_lshl_or_b32 v43, v4, 9, v112
	v_lshlrev_b64 v[4:5], 10, v[4:5]
	v_lshl_add_u64 v[100:101], v[4:5], 0, s[54:55]
	v_lshl_add_u64 v[4:5], v[100:101], 1, v[48:49]
	ds_read_b128 v[12:15], v43
	ds_read_b128 v[0:3], v43 offset:128
	v_mov_b32_e32 v4, v224
	v_mov_b32_e32 v5, v225
	v_lshlrev_b32_e32 v62, 16, v4
	v_and_b32_e32 v63, 0xffff0000, v4
	v_lshlrev_b32_e32 v60, 16, v5
	v_and_b32_e32 v61, 0xffff0000, v5
	v_mov_b32_e32 v16, v212
	v_mov_b32_e32 v17, v213
	v_mov_b32_e32 v18, v214
	v_mov_b32_e32 v19, v215
	v_mov_b32_e32 v8, v216
	v_mov_b32_e32 v9, v217
	v_mov_b32_e32 v10, v218
	v_mov_b32_e32 v11, v219
	v_mov_b32_e32 v4, v220
	v_mov_b32_e32 v5, v221
	v_mov_b32_e32 v6, v222
	v_mov_b32_e32 v7, v223
	s_waitcnt lgkmcnt(1)
; DEVI float sigmoidf_(float x) { return 1.f / (1.f + __expf(-x)); }
; DEVI void gate_tile(const Params& P, int l, int pm, int q, char* smem, int tid) {
;     ...
;   for (int q = 0; q < 8; ++q) {
;     const int id = tid + 256 * q, row = id >> 4, g4 = id & 15;
;     const int cl = g4 * 4, wcc = cl >> 5, c32 = cl & 31;
;     const long grow = (long)pm * 128 + row;
;     const int col = nb * 128 + hb * 64 + cl;
;     float4 rp = *reinterpret_cast<const float4*>(T + row * 128 + wcc * 64 + c32);
;     float4 gp = *reinterpret_cast<const float4*>(T + row * 128 + wcc * 64 + 32 + c32);
;     float xv[4], bav[4], bxv[4], lmv[4];
;     load4bf(cb + grow * 1024 + col, xv);
;     ld4f(ba + col, bav); ld4f(bx + col, bxv); ld4f(lam + col, lmv);
;     const float rpa[4] = {rp.x, rp.y, rp.z, rp.w}, gpa[4] = {gp.x, gp.y, gp.z, gp.w};
;     float av[4], uv[4];
; #pragma unroll
;     for (int i = 0; i < 4; ++i) {
;       float r = sigmoidf_(rpa[i] + bav[i]);
;       float gi = sigmoidf_(gpa[i] + bxv[i]);
;       float a = __expf(-8.f * log1pf(__expf(-lmv[i])) * r);
;       av[i] = a;
;       uv[i] = sqrtf(fmaxf(1.f - a * a, 0.f)) * gi * xv[i];
;     }
;     *reinterpret_cast<float4*>(au0 + grow * 1024 + col) = make_float4(av[0], av[1], av[2], av[3]);
;     *reinterpret_cast<float4*>(au1 + grow * 1024 + col) = make_float4(uv[0], uv[1], uv[2], uv[3]);
;     *reinterpret_cast<float4*>(Tw + row * 128 + wcc * 64 + c32) = make_float4(av[0], av[1], av[2], av[3]);
;     *reinterpret_cast<float4*>(Tw + row * 128 + wcc * 64 + 32 + c32) = make_float4(uv[0], uv[1], uv[2], uv[3]);
;   }
	v_add_f32_e32 v12, v12, v16
	v_mul_f32_e32 v12, 0xbfb8aa3b, v12
	v_exp_f32_e32 v12, v12
	s_waitcnt lgkmcnt(0)
	v_add_f32_e32 v0, v0, v8
	v_mul_f32_e32 v0, 0xbfb8aa3b, v0
	v_exp_f32_e32 v8, v0
	v_add_f32_e32 v12, 1.0, v12
	v_min_f32_e32 v16, 0x7f7fffff, v12
	v_rcp_f32_e32 v45, v16
	v_add_f32_e32 v1, v1, v9
	v_fma_f32 v47, -v16, v45, 1.0
	v_fmac_f32_e32 v45, v47, v45
	v_fma_f32 v114, -v16, v45, 1.0
	v_fma_f32 v113, v114, v45, v45
	v_fma_f32 v16, -v16, v113, 1.0
	v_fma_f32 v12, v16, v45, v113
	v_mul_f32_e32 v1, 0xbfb8aa3b, v1
	v_exp_f32_e32 v9, v1
	v_add_f32_e32 v2, v2, v10
	v_mul_f32_e32 v2, 0xbfb8aa3b, v2
	v_exp_f32_e32 v10, v2
	v_mov_b32_e32 v0, v240
	v_mul_f32_e32 v0, v12, v0
	v_mul_f32_e32 v0, 0x3fb8aa3b, v0
	v_exp_f32_e32 v0, v0
	v_add_f32_e32 v3, v3, v11
	v_fma_f32 v4, -v0, v0, 1.0
	v_max_f32_e32 v4, 0, v4
	v_cmp_gt_f32_e32 vcc, s69, v4
	v_mul_f32_e32 v12, 0x4f800000, v4
	s_nop 0
	v_cndmask_b32_e32 v4, v4, v12, vcc
	v_sqrt_f32_e32 v12, v4
	v_mul_f32_e32 v3, 0xbfb8aa3b, v3
	v_exp_f32_e32 v11, v3
	v_add_u32_e32 v16, -1, v12
	v_fma_f32 v45, -v16, v12, v4
	v_cmp_ge_f32_e64 s[46:47], 0, v45
	v_add_u32_e32 v45, 1, v12
	s_nop 0
	v_cndmask_b32_e64 v16, v12, v16, s[46:47]
	v_fma_f32 v12, -v45, v12, v4
	v_cmp_lt_f32_e64 s[46:47], 0, v12
	v_pk_add_f32 v[8:9], v[8:9], 1.0 op_sel_hi:[1,0]
	s_nop 0
	v_cndmask_b32_e64 v12, v16, v45, s[46:47]
	v_mul_f32_e32 v16, 0x37800000, v12
	v_cndmask_b32_e32 v12, v12, v16, vcc
	v_cmp_class_f32_e32 vcc, v4, v186
	s_nop 1
	v_cndmask_b32_e32 v4, v12, v4, vcc
	v_add_f32_e32 v12, v13, v17
	v_mul_f32_e32 v12, 0xbfb8aa3b, v12
	v_exp_f32_e32 v12, v12
	s_nop 0
	v_add_f32_e32 v12, 1.0, v12
	v_min_f32_e32 v13, 0x7f7fffff, v12
	v_rcp_f32_e32 v16, v13
	s_nop 0
	v_fma_f32 v17, -v13, v16, 1.0
	v_fmac_f32_e32 v16, v17, v16
	v_fma_f32 v47, -v13, v16, 1.0
	v_fma_f32 v45, v47, v16, v16
	v_fma_f32 v13, -v13, v45, 1.0
	v_fma_f32 v16, v13, v16, v45
	s_nop 1
	s_nop 1
	s_nop 1
	v_mov_b32_e32 v1, v241
	v_mul_f32_e32 v1, v16, v1
	v_mul_f32_e32 v1, 0x3fb8aa3b, v1
	v_exp_f32_e32 v1, v1
	s_nop 0
	v_fma_f32 v5, -v1, v1, 1.0
	v_max_f32_e32 v5, 0, v5
	v_cmp_gt_f32_e32 vcc, s69, v5
	v_mul_f32_e32 v12, 0x4f800000, v5
	s_nop 0
	v_cndmask_b32_e32 v5, v5, v12, vcc
	v_sqrt_f32_e32 v12, v5
	s_nop 0
	v_add_u32_e32 v13, -1, v12
	v_fma_f32 v16, -v13, v12, v5
	v_cmp_ge_f32_e64 s[46:47], 0, v16
	v_add_u32_e32 v16, 1, v12
	s_nop 0
	v_cndmask_b32_e64 v13, v12, v13, s[46:47]
	v_fma_f32 v12, -v16, v12, v5
	v_cmp_lt_f32_e64 s[46:47], 0, v12
	s_nop 1
	v_cndmask_b32_e64 v12, v13, v16, s[46:47]
	v_mul_f32_e32 v13, 0x37800000, v12
	v_cndmask_b32_e32 v12, v12, v13, vcc
	v_cmp_class_f32_e32 vcc, v5, v186
	s_nop 1
	v_cndmask_b32_e32 v5, v12, v5, vcc
	v_add_f32_e32 v12, v14, v18
	v_mul_f32_e32 v12, 0xbfb8aa3b, v12
	v_exp_f32_e32 v12, v12
	s_nop 0
	v_add_f32_e32 v12, 1.0, v12
	v_min_f32_e32 v13, 0x7f7fffff, v12
	v_rcp_f32_e32 v14, v13
	s_nop 0
	v_fma_f32 v16, -v13, v14, 1.0
	v_fmac_f32_e32 v14, v16, v14
	v_fma_f32 v18, -v13, v14, 1.0
	v_fma_f32 v17, v18, v14, v14
	v_fma_f32 v13, -v13, v17, 1.0
	v_fma_f32 v14, v13, v14, v17
	s_nop 1
	s_nop 1
	s_nop 1
	v_mov_b32_e32 v2, v242
	v_mul_f32_e32 v2, v14, v2
	v_mul_f32_e32 v2, 0x3fb8aa3b, v2
	v_exp_f32_e32 v2, v2
	s_nop 0
	v_fma_f32 v6, -v2, v2, 1.0
	v_max_f32_e32 v6, 0, v6
	v_cmp_gt_f32_e32 vcc, s69, v6
	v_mul_f32_e32 v12, 0x4f800000, v6
	s_nop 0
	v_cndmask_b32_e32 v6, v6, v12, vcc
	v_sqrt_f32_e32 v12, v6
	s_nop 0
	v_add_u32_e32 v13, -1, v12
	v_fma_f32 v14, -v13, v12, v6
	v_cmp_ge_f32_e64 s[46:47], 0, v14
	v_add_u32_e32 v14, 1, v12
	s_nop 0
	v_cndmask_b32_e64 v13, v12, v13, s[46:47]
	v_fma_f32 v12, -v14, v12, v6
	v_cmp_lt_f32_e64 s[46:47], 0, v12
	s_nop 1
	v_cndmask_b32_e64 v12, v13, v14, s[46:47]
	v_mul_f32_e32 v13, 0x37800000, v12
	v_cndmask_b32_e32 v12, v12, v13, vcc
	v_cmp_class_f32_e32 vcc, v6, v186
	s_nop 1
	v_cndmask_b32_e32 v6, v12, v6, vcc
	v_add_f32_e32 v12, v15, v19
	v_mul_f32_e32 v12, 0xbfb8aa3b, v12
	v_exp_f32_e32 v12, v12
	s_nop 0
	v_add_f32_e32 v12, 1.0, v12
	v_min_f32_e32 v13, 0x7f7fffff, v12
	v_rcp_f32_e32 v14, v13
	s_nop 0
	v_fma_f32 v15, -v13, v14, 1.0
	v_fmac_f32_e32 v14, v15, v14
	v_fma_f32 v17, -v13, v14, 1.0
	v_fma_f32 v16, v17, v14, v14
	v_fma_f32 v13, -v13, v16, 1.0
	v_fma_f32 v14, v13, v14, v16
	s_nop 1
	s_nop 1
	s_nop 1
	v_mov_b32_e32 v3, v243
	v_mul_f32_e32 v3, v14, v3
	v_mul_f32_e32 v3, 0x3fb8aa3b, v3
	v_exp_f32_e32 v3, v3
	s_nop 0
	v_fma_f32 v7, -v3, v3, 1.0
	v_max_f32_e32 v7, 0, v7
	v_cmp_gt_f32_e32 vcc, s69, v7
	v_mul_f32_e32 v12, 0x4f800000, v7
	s_nop 0
	v_cndmask_b32_e32 v7, v7, v12, vcc
	v_sqrt_f32_e32 v12, v7
	s_nop 0
	v_add_u32_e32 v13, -1, v12
	v_fma_f32 v14, -v13, v12, v7
	v_cmp_ge_f32_e64 s[46:47], 0, v14
	v_add_u32_e32 v14, 1, v12
	s_nop 0
	v_cndmask_b32_e64 v13, v12, v13, s[46:47]
	v_fma_f32 v12, -v14, v12, v7
	v_cmp_lt_f32_e64 s[46:47], 0, v12
	s_nop 1
	v_cndmask_b32_e64 v12, v13, v14, s[46:47]
	v_mul_f32_e32 v13, 0x37800000, v12
	v_cndmask_b32_e32 v12, v12, v13, vcc
	v_cmp_class_f32_e32 vcc, v7, v186
	s_nop 1
	v_cndmask_b32_e32 v7, v12, v7, vcc
	v_lshlrev_b64 v[12:13], 2, v[100:101]
	v_lshl_add_u64 v[14:15], v[56:57], 0, v[12:13]
	global_store_dwordx4 v[14:15], v[0:3], off
	v_min_f32_e32 v14, 0x7f7fffff, v9
	v_rcp_f32_e32 v15, v14
	v_lshl_add_u64 v[12:13], v[58:59], 0, v[12:13]
	v_fma_f32 v16, -v14, v15, 1.0
	v_fmac_f32_e32 v15, v16, v15
	v_fma_f32 v18, -v14, v15, 1.0
	v_fma_f32 v17, v18, v15, v15
	v_fma_f32 v14, -v14, v17, 1.0
	v_fma_f32 v9, v14, v15, v17
	v_min_f32_e32 v14, 0x7f7fffff, v8
	v_rcp_f32_e32 v15, v14
	s_nop 0
	v_fma_f32 v16, -v14, v15, 1.0
	v_fmac_f32_e32 v15, v16, v15
	v_fma_f32 v18, -v14, v15, 1.0
	v_fma_f32 v17, v18, v15, v15
	v_fma_f32 v14, -v14, v17, 1.0
; DEVI float sigmoidf_(float x) { return 1.f / (1.f + __expf(-x)); }
; DEVI void gate_tile(const Params& P, int l, int pm, int q, char* smem, int tid) {
;     ...
;   for (int q = 0; q < 8; ++q) {
;     const int id = tid + 256 * q, row = id >> 4, g4 = id & 15;
;     const int cl = g4 * 4, wcc = cl >> 5, c32 = cl & 31;
;     const long grow = (long)pm * 128 + row;
;     const int col = nb * 128 + hb * 64 + cl;
;     float4 rp = *reinterpret_cast<const float4*>(T + row * 128 + wcc * 64 + c32);
;     float4 gp = *reinterpret_cast<const float4*>(T + row * 128 + wcc * 64 + 32 + c32);
;     float xv[4], bav[4], bxv[4], lmv[4];
;     load4bf(cb + grow * 1024 + col, xv);
;     ld4f(ba + col, bav); ld4f(bx + col, bxv); ld4f(lam + col, lmv);
;     const float rpa[4] = {rp.x, rp.y, rp.z, rp.w}, gpa[4] = {gp.x, gp.y, gp.z, gp.w};
;     float av[4], uv[4];
; #pragma unroll
;     for (int i = 0; i < 4; ++i) {
;       float r = sigmoidf_(rpa[i] + bav[i]);
;       float gi = sigmoidf_(gpa[i] + bxv[i]);
;       float a = __expf(-8.f * log1pf(__expf(-lmv[i])) * r);
;       av[i] = a;
;       uv[i] = sqrtf(fmaxf(1.f - a * a, 0.f)) * gi * xv[i];
;     }
;     *reinterpret_cast<float4*>(au0 + grow * 1024 + col) = make_float4(av[0], av[1], av[2], av[3]);
;     *reinterpret_cast<float4*>(au1 + grow * 1024 + col) = make_float4(uv[0], uv[1], uv[2], uv[3]);
;     *reinterpret_cast<float4*>(Tw + row * 128 + wcc * 64 + c32) = make_float4(av[0], av[1], av[2], av[3]);
;     *reinterpret_cast<float4*>(Tw + row * 128 + wcc * 64 + 32 + c32) = make_float4(uv[0], uv[1], uv[2], uv[3]);
;   }
	v_fma_f32 v8, v14, v15, v17
	v_pk_mul_f32 v[4:5], v[8:9], v[4:5]
	v_pk_add_f32 v[8:9], v[10:11], 1.0 op_sel_hi:[1,0]
	v_pk_mul_f32 v[4:5], v[4:5], v[62:63]
	v_min_f32_e32 v10, 0x7f7fffff, v9
	v_rcp_f32_e32 v11, v10
	s_nop 0
	v_fma_f32 v14, -v10, v11, 1.0
	v_fmac_f32_e32 v11, v14, v11
	v_fma_f32 v16, -v10, v11, 1.0
	v_fma_f32 v15, v16, v11, v11
	v_fma_f32 v10, -v10, v15, 1.0
	v_fma_f32 v9, v10, v11, v15
	v_min_f32_e32 v10, 0x7f7fffff, v8
	v_rcp_f32_e32 v11, v10
	s_nop 0
	v_fma_f32 v14, -v10, v11, 1.0
	v_fmac_f32_e32 v11, v14, v11
	v_fma_f32 v16, -v10, v11, 1.0
	v_fma_f32 v15, v16, v11, v11
	v_fma_f32 v10, -v10, v15, 1.0
	v_fma_f32 v8, v10, v11, v15
	v_pk_mul_f32 v[6:7], v[8:9], v[6:7]
	s_nop 0
	v_pk_mul_f32 v[6:7], v[6:7], v[60:61]
	global_store_dwordx4 v[12:13], v[4:7], off
	ds_write_b128 v43, v[0:3]
	ds_write_b128 v43, v[4:7] offset:128
	v_add_u32_e32 v0, 0x300, v41
	v_ashrrev_i32_e32 v4, 4, v0
	v_ashrrev_i32_e32 v5, 31, v4
	v_lshl_or_b32 v41, v4, 9, v112
	v_lshlrev_b64 v[4:5], 10, v[4:5]
	v_lshl_add_u64 v[100:101], v[4:5], 0, s[54:55]
	v_lshl_add_u64 v[4:5], v[100:101], 1, v[48:49]
	ds_read_b128 v[12:15], v41
	ds_read_b128 v[0:3], v41 offset:128
	v_mov_b32_e32 v4, v226
	v_mov_b32_e32 v5, v227
	v_lshlrev_b32_e32 v62, 16, v4
	v_and_b32_e32 v63, 0xffff0000, v4
	v_lshlrev_b32_e32 v60, 16, v5
	v_and_b32_e32 v61, 0xffff0000, v5
	v_mov_b32_e32 v16, v212
	v_mov_b32_e32 v17, v213
	v_mov_b32_e32 v18, v214
	v_mov_b32_e32 v19, v215
	v_mov_b32_e32 v8, v216
	v_mov_b32_e32 v9, v217
	v_mov_b32_e32 v10, v218
	v_mov_b32_e32 v11, v219
	v_mov_b32_e32 v4, v220
	v_mov_b32_e32 v5, v221
	v_mov_b32_e32 v6, v222
	v_mov_b32_e32 v7, v223
	s_waitcnt lgkmcnt(1)
	v_add_f32_e32 v12, v12, v16
	v_mul_f32_e32 v12, 0xbfb8aa3b, v12
	v_exp_f32_e32 v12, v12
	s_waitcnt lgkmcnt(0)
; DEVI float sigmoidf_(float x) { return 1.f / (1.f + __expf(-x)); }
; DEVI void gate_tile(const Params& P, int l, int pm, int q, char* smem, int tid) {
;     ...
;   for (int q = 0; q < 8; ++q) {
;     const int id = tid + 256 * q, row = id >> 4, g4 = id & 15;
;     const int cl = g4 * 4, wcc = cl >> 5, c32 = cl & 31;
;     const long grow = (long)pm * 128 + row;
;     const int col = nb * 128 + hb * 64 + cl;
;     float4 rp = *reinterpret_cast<const float4*>(T + row * 128 + wcc * 64 + c32);
;     float4 gp = *reinterpret_cast<const float4*>(T + row * 128 + wcc * 64 + 32 + c32);
;     float xv[4], bav[4], bxv[4], lmv[4];
;     load4bf(cb + grow * 1024 + col, xv);
;     ld4f(ba + col, bav); ld4f(bx + col, bxv); ld4f(lam + col, lmv);
;     const float rpa[4] = {rp.x, rp.y, rp.z, rp.w}, gpa[4] = {gp.x, gp.y, gp.z, gp.w};
;     float av[4], uv[4];
; #pragma unroll
;     for (int i = 0; i < 4; ++i) {
;       float r = sigmoidf_(rpa[i] + bav[i]);
;       float gi = sigmoidf_(gpa[i] + bxv[i]);
;       float a = __expf(-8.f * log1pf(__expf(-lmv[i])) * r);
;       av[i] = a;
;       uv[i] = sqrtf(fmaxf(1.f - a * a, 0.f)) * gi * xv[i];
;     }
;     *reinterpret_cast<float4*>(au0 + grow * 1024 + col) = make_float4(av[0], av[1], av[2], av[3]);
;     *reinterpret_cast<float4*>(au1 + grow * 1024 + col) = make_float4(uv[0], uv[1], uv[2], uv[3]);
;     *reinterpret_cast<float4*>(Tw + row * 128 + wcc * 64 + c32) = make_float4(av[0], av[1], av[2], av[3]);
;     *reinterpret_cast<float4*>(Tw + row * 128 + wcc * 64 + 32 + c32) = make_float4(uv[0], uv[1], uv[2], uv[3]);
;   }
	v_add_f32_e32 v0, v0, v8
	v_mul_f32_e32 v0, 0xbfb8aa3b, v0
	v_exp_f32_e32 v8, v0
	v_add_f32_e32 v12, 1.0, v12
	v_min_f32_e32 v16, 0x7f7fffff, v12
	v_rcp_f32_e32 v43, v16
	v_add_f32_e32 v1, v1, v9
	v_fma_f32 v45, -v16, v43, 1.0
	v_fmac_f32_e32 v43, v45, v43
	v_fma_f32 v113, -v16, v43, 1.0
	v_fma_f32 v47, v113, v43, v43
	v_fma_f32 v16, -v16, v47, 1.0
	v_fma_f32 v12, v16, v43, v47
	v_mul_f32_e32 v1, 0xbfb8aa3b, v1
	v_exp_f32_e32 v9, v1
	v_add_f32_e32 v2, v2, v10
	v_mul_f32_e32 v2, 0xbfb8aa3b, v2
	v_exp_f32_e32 v10, v2
	v_mov_b32_e32 v0, v240
	v_mul_f32_e32 v0, v12, v0
	v_mul_f32_e32 v0, 0x3fb8aa3b, v0
	v_exp_f32_e32 v0, v0
	v_add_f32_e32 v3, v3, v11
	v_fma_f32 v4, -v0, v0, 1.0
	v_max_f32_e32 v4, 0, v4
	v_cmp_gt_f32_e32 vcc, s69, v4
	v_mul_f32_e32 v12, 0x4f800000, v4
	s_nop 0
	v_cndmask_b32_e32 v4, v4, v12, vcc
	v_sqrt_f32_e32 v12, v4
	v_mul_f32_e32 v3, 0xbfb8aa3b, v3
	v_exp_f32_e32 v11, v3
	v_add_u32_e32 v16, -1, v12
	v_fma_f32 v43, -v16, v12, v4
	v_cmp_ge_f32_e64 s[46:47], 0, v43
	v_add_u32_e32 v43, 1, v12
	s_nop 0
	v_cndmask_b32_e64 v16, v12, v16, s[46:47]
	v_fma_f32 v12, -v43, v12, v4
	v_cmp_lt_f32_e64 s[46:47], 0, v12
	v_pk_add_f32 v[8:9], v[8:9], 1.0 op_sel_hi:[1,0]
	s_nop 0
	v_cndmask_b32_e64 v12, v16, v43, s[46:47]
	v_mul_f32_e32 v16, 0x37800000, v12
	v_cndmask_b32_e32 v12, v12, v16, vcc
	v_cmp_class_f32_e32 vcc, v4, v186
	s_nop 1
	v_cndmask_b32_e32 v4, v12, v4, vcc
	v_add_f32_e32 v12, v13, v17
	v_mul_f32_e32 v12, 0xbfb8aa3b, v12
	v_exp_f32_e32 v12, v12
	s_nop 0
	v_add_f32_e32 v12, 1.0, v12
	v_min_f32_e32 v13, 0x7f7fffff, v12
	v_rcp_f32_e32 v16, v13
	s_nop 0
	v_fma_f32 v17, -v13, v16, 1.0
	v_fmac_f32_e32 v16, v17, v16
	v_fma_f32 v45, -v13, v16, 1.0
	v_fma_f32 v43, v45, v16, v16
	v_fma_f32 v13, -v13, v43, 1.0
	v_fma_f32 v16, v13, v16, v43
	s_nop 1
	s_nop 1
	s_nop 1
	v_mov_b32_e32 v1, v241
	v_mul_f32_e32 v1, v16, v1
	v_mul_f32_e32 v1, 0x3fb8aa3b, v1
	v_exp_f32_e32 v1, v1
	s_nop 0
	v_fma_f32 v5, -v1, v1, 1.0
	v_max_f32_e32 v5, 0, v5
	v_cmp_gt_f32_e32 vcc, s69, v5
	v_mul_f32_e32 v12, 0x4f800000, v5
	s_nop 0
	v_cndmask_b32_e32 v5, v5, v12, vcc
	v_sqrt_f32_e32 v12, v5
	s_nop 0
	v_add_u32_e32 v13, -1, v12
	v_fma_f32 v16, -v13, v12, v5
	v_cmp_ge_f32_e64 s[46:47], 0, v16
	v_add_u32_e32 v16, 1, v12
	s_nop 0
	v_cndmask_b32_e64 v13, v12, v13, s[46:47]
	v_fma_f32 v12, -v16, v12, v5
	v_cmp_lt_f32_e64 s[46:47], 0, v12
	s_nop 1
	v_cndmask_b32_e64 v12, v13, v16, s[46:47]
	v_mul_f32_e32 v13, 0x37800000, v12
	v_cndmask_b32_e32 v12, v12, v13, vcc
	v_cmp_class_f32_e32 vcc, v5, v186
	s_nop 1
	v_cndmask_b32_e32 v5, v12, v5, vcc
	v_add_f32_e32 v12, v14, v18
	v_mul_f32_e32 v12, 0xbfb8aa3b, v12
	v_exp_f32_e32 v12, v12
	s_nop 0
	v_add_f32_e32 v12, 1.0, v12
	v_min_f32_e32 v13, 0x7f7fffff, v12
	v_rcp_f32_e32 v14, v13
	s_nop 0
	v_fma_f32 v16, -v13, v14, 1.0
	v_fmac_f32_e32 v14, v16, v14
	v_fma_f32 v18, -v13, v14, 1.0
	v_fma_f32 v17, v18, v14, v14
	v_fma_f32 v13, -v13, v17, 1.0
	v_fma_f32 v14, v13, v14, v17
	s_nop 1
	s_nop 1
	s_nop 1
	v_mov_b32_e32 v2, v242
	v_mul_f32_e32 v2, v14, v2
	v_mul_f32_e32 v2, 0x3fb8aa3b, v2
	v_exp_f32_e32 v2, v2
	s_nop 0
	v_fma_f32 v6, -v2, v2, 1.0
	v_max_f32_e32 v6, 0, v6
	v_cmp_gt_f32_e32 vcc, s69, v6
	v_mul_f32_e32 v12, 0x4f800000, v6
	s_nop 0
	v_cndmask_b32_e32 v6, v6, v12, vcc
	v_sqrt_f32_e32 v12, v6
	s_nop 0
	v_add_u32_e32 v13, -1, v12
	v_fma_f32 v14, -v13, v12, v6
	v_cmp_ge_f32_e64 s[46:47], 0, v14
	v_add_u32_e32 v14, 1, v12
	s_nop 0
	v_cndmask_b32_e64 v13, v12, v13, s[46:47]
	v_fma_f32 v12, -v14, v12, v6
	v_cmp_lt_f32_e64 s[46:47], 0, v12
	s_nop 1
	v_cndmask_b32_e64 v12, v13, v14, s[46:47]
	v_mul_f32_e32 v13, 0x37800000, v12
	v_cndmask_b32_e32 v12, v12, v13, vcc
	v_cmp_class_f32_e32 vcc, v6, v186
	s_nop 1
	v_cndmask_b32_e32 v6, v12, v6, vcc
	v_add_f32_e32 v12, v15, v19
	v_mul_f32_e32 v12, 0xbfb8aa3b, v12
	v_exp_f32_e32 v12, v12
	s_nop 0
	v_add_f32_e32 v12, 1.0, v12
	v_min_f32_e32 v13, 0x7f7fffff, v12
	v_rcp_f32_e32 v14, v13
	s_nop 0
	v_fma_f32 v15, -v13, v14, 1.0
	v_fmac_f32_e32 v14, v15, v14
	v_fma_f32 v17, -v13, v14, 1.0
	v_fma_f32 v16, v17, v14, v14
	v_fma_f32 v13, -v13, v16, 1.0
	v_fma_f32 v14, v13, v14, v16
	s_nop 1
	s_nop 1
	s_nop 1
	v_mov_b32_e32 v3, v243
	v_mul_f32_e32 v3, v14, v3
	v_mul_f32_e32 v3, 0x3fb8aa3b, v3
	v_exp_f32_e32 v3, v3
	s_nop 0
	v_fma_f32 v7, -v3, v3, 1.0
	v_max_f32_e32 v7, 0, v7
	v_cmp_gt_f32_e32 vcc, s69, v7
	v_mul_f32_e32 v12, 0x4f800000, v7
	s_nop 0
	v_cndmask_b32_e32 v7, v7, v12, vcc
	v_sqrt_f32_e32 v12, v7
	s_nop 0
	v_add_u32_e32 v13, -1, v12
	v_fma_f32 v14, -v13, v12, v7
	v_cmp_ge_f32_e64 s[46:47], 0, v14
	v_add_u32_e32 v14, 1, v12
	s_nop 0
	v_cndmask_b32_e64 v13, v12, v13, s[46:47]
	v_fma_f32 v12, -v14, v12, v7
	v_cmp_lt_f32_e64 s[46:47], 0, v12
	s_nop 1
	v_cndmask_b32_e64 v12, v13, v14, s[46:47]
	v_mul_f32_e32 v13, 0x37800000, v12
	v_cndmask_b32_e32 v12, v12, v13, vcc
	v_cmp_class_f32_e32 vcc, v7, v186
	s_nop 1
	v_cndmask_b32_e32 v7, v12, v7, vcc
	v_lshlrev_b64 v[12:13], 2, v[100:101]
	v_lshl_add_u64 v[14:15], v[56:57], 0, v[12:13]
	global_store_dwordx4 v[14:15], v[0:3], off
	v_min_f32_e32 v14, 0x7f7fffff, v9
	v_rcp_f32_e32 v15, v14
	v_lshl_add_u64 v[12:13], v[58:59], 0, v[12:13]
	v_fma_f32 v16, -v14, v15, 1.0
	v_fmac_f32_e32 v15, v16, v15
	v_fma_f32 v18, -v14, v15, 1.0
	v_fma_f32 v17, v18, v15, v15
	v_fma_f32 v14, -v14, v17, 1.0
	v_fma_f32 v9, v14, v15, v17
	v_min_f32_e32 v14, 0x7f7fffff, v8
	v_rcp_f32_e32 v15, v14
	s_nop 0
	v_fma_f32 v16, -v14, v15, 1.0
	v_fmac_f32_e32 v15, v16, v15
	v_fma_f32 v18, -v14, v15, 1.0
	v_fma_f32 v17, v18, v15, v15
	v_fma_f32 v14, -v14, v17, 1.0
	v_fma_f32 v8, v14, v15, v17
	v_pk_mul_f32 v[4:5], v[8:9], v[4:5]
	v_pk_add_f32 v[8:9], v[10:11], 1.0 op_sel_hi:[1,0]
	v_pk_mul_f32 v[4:5], v[4:5], v[62:63]
	v_min_f32_e32 v10, 0x7f7fffff, v9
	v_rcp_f32_e32 v11, v10
	s_nop 0
	v_fma_f32 v14, -v10, v11, 1.0
	v_fmac_f32_e32 v11, v14, v11
	v_fma_f32 v16, -v10, v11, 1.0
	v_fma_f32 v15, v16, v11, v11
	v_fma_f32 v10, -v10, v15, 1.0
	v_fma_f32 v9, v10, v11, v15
	v_min_f32_e32 v10, 0x7f7fffff, v8
	v_rcp_f32_e32 v11, v10
	s_nop 0
	v_fma_f32 v14, -v10, v11, 1.0
	v_fmac_f32_e32 v11, v14, v11
	v_fma_f32 v16, -v10, v11, 1.0
	v_fma_f32 v15, v16, v11, v11
	v_fma_f32 v10, -v10, v15, 1.0
	v_fma_f32 v8, v10, v11, v15
	v_pk_mul_f32 v[6:7], v[8:9], v[6:7]
	s_nop 0
	v_pk_mul_f32 v[6:7], v[6:7], v[60:61]
	global_store_dwordx4 v[12:13], v[4:7], off
	ds_write_b128 v41, v[0:3]
	ds_write_b128 v41, v[4:7] offset:128
	s_cbranch_scc0 .LBB0_459
	s_waitcnt lgkmcnt(0)
	s_barrier
	s_and_saveexec_b64 s[46:47], s[44:45]
	s_cbranch_execz .LBB0_451
	v_mov_b32_e32 v1, 1.0
	v_mov_b32_e32 v2, 0
	s_mov_b32 s54, -16
	v_mov_b32_e32 v4, v111

; DEVI float sigmoidf_(float x) { return 1.f / (1.f + __expf(-x)); }
; template <int BR, int IN, int OUT>
; DEVI void p6_branch(const Params& P, int pm, int pn, float* macc, char* smem, int tid) {
;     ...
; #pragma unroll 8
;   for (int q = 0; q < 16; ++q) {
;     const int id = tid + 256 * q, row = id >> 5, c4 = id & 31;
;     const long grow = (long)pm * 128 + row;
;     const int gcol = pn * 128 + c4 * 4;
;     float4 a = *reinterpret_cast<const float4*>(T + row * 128 + c4 * 4);
;     float g[4];
;     load4bf(Z + grow * NCOL + (9 + BR) * 1024 + gcol, g);
;     float v[4] = {sigmoidf_(g[0]) * a.x, sigmoidf_(g[1]) * a.y, sigmoidf_(g[2]) * a.z, sigmoidf_(g[3]) * a.w};
;     if (IN == 1) {
;       float mo[4]; load4bf(M + grow * 1024 + gcol, mo);
;       v[0] += mo[0]; v[1] += mo[1]; v[2] += mo[2]; v[3] += mo[3];
;     }
;     if (IN == 2) {
;       float4 mo = *reinterpret_cast<const float4*>(macc + grow * 1024 + gcol);
;       v[0] += mo.x; v[1] += mo.y; v[2] += mo.z; v[3] += mo.w;
;     }
;     if (OUT == 1) *reinterpret_cast<float4*>(macc + grow * 1024 + gcol) = make_float4(v[0], v[1], v[2], v[3]);
;     else store4bf(M + grow * 1024 + gcol, v);
.LBB0_513:
	v_add_u32_e32 v238, s24, v91
	v_ashrrev_i32_e32 v236, 5, v238
	v_ashrrev_i32_e32 v237, 31, v236
	v_lshl_add_u64 v[240:241], s[74:75], 0, v[236:237]
	v_mov_b64_e32 v[236:237], s[26:27]
	v_mad_u64_u32 v[242:243], s[50:51], v240, s22, v[236:237]
	v_mad_i32_i24 v243, v241, s22, v243
	v_lshl_add_u64 v[242:243], v[242:243], 0, v[2:3]
	v_add_co_u32_e32 v242, vcc, 0x4000, v242
	s_nop 1
	v_addc_co_u32_e32 v243, vcc, 0, v243, vcc
	global_load_dwordx2 v[220:221], v[242:243], off offset:2048
	v_add_u32_e32 v238, s24, v91
	v_mov_b64_e32 v[236:237], s[26:27]
	v_add_u32_e32 v239, 0x100, v238
	v_ashrrev_i32_e32 v240, 5, v239
	v_ashrrev_i32_e32 v241, 31, v240
	v_lshl_add_u64 v[242:243], s[74:75], 0, v[240:241]
	v_mad_u64_u32 v[240:241], s[50:51], v242, s22, v[236:237]
	v_mad_i32_i24 v241, v243, s22, v241
	v_lshl_add_u64 v[240:241], v[240:241], 0, v[2:3]
	v_add_co_u32_e32 v240, vcc, s36, v240
	s_nop 1
	v_addc_co_u32_e32 v241, vcc, 0, v241, vcc
	global_load_dwordx2 v[222:223], v[240:241], off offset:2048
	v_add_u32_e32 v238, s24, v91
	v_mov_b64_e32 v[236:237], s[26:27]
	v_add_u32_e32 v239, 0x200, v238
	v_ashrrev_i32_e32 v240, 5, v239
	v_ashrrev_i32_e32 v241, 31, v240
	v_lshl_add_u64 v[242:243], s[74:75], 0, v[240:241]
	v_mad_u64_u32 v[240:241], s[50:51], v242, s22, v[236:237]
	v_mad_i32_i24 v241, v243, s22, v241
	v_lshl_add_u64 v[240:241], v[240:241], 0, v[2:3]
	v_add_co_u32_e32 v240, vcc, s36, v240
	s_nop 1
	v_addc_co_u32_e32 v241, vcc, 0, v241, vcc
	global_load_dwordx2 v[224:225], v[240:241], off offset:2048
	v_add_u32_e32 v238, s24, v91
	v_mov_b64_e32 v[236:237], s[26:27]
	v_add_u32_e32 v239, 0x300, v238
	v_ashrrev_i32_e32 v240, 5, v239
	v_ashrrev_i32_e32 v241, 31, v240
	v_lshl_add_u64 v[242:243], s[74:75], 0, v[240:241]
	v_mad_u64_u32 v[240:241], s[50:51], v242, s22, v[236:237]
	v_mad_i32_i24 v241, v243, s22, v241
	v_lshl_add_u64 v[240:241], v[240:241], 0, v[2:3]
	v_add_co_u32_e32 v240, vcc, s36, v240
	s_nop 1
	v_addc_co_u32_e32 v241, vcc, 0, v241, vcc
	global_load_dwordx2 v[226:227], v[240:241], off offset:2048
	v_add_u32_e32 v238, s24, v91
	v_mov_b64_e32 v[236:237], s[26:27]
	v_add_u32_e32 v239, 0x400, v238
	v_ashrrev_i32_e32 v240, 5, v239
	v_ashrrev_i32_e32 v241, 31, v240
	v_lshl_add_u64 v[242:243], s[74:75], 0, v[240:241]
	v_mad_u64_u32 v[240:241], s[50:51], v242, s22, v[236:237]
	v_mad_i32_i24 v241, v243, s22, v241
	v_lshl_add_u64 v[240:241], v[240:241], 0, v[2:3]
	v_add_co_u32_e32 v240, vcc, s36, v240
	s_nop 1
	v_addc_co_u32_e32 v241, vcc, 0, v241, vcc
	global_load_dwordx2 v[228:229], v[240:241], off offset:2048
	v_add_u32_e32 v238, s24, v91
	v_mov_b64_e32 v[236:237], s[26:27]
	v_add_u32_e32 v239, 0x500, v238
	v_ashrrev_i32_e32 v240, 5, v239
	v_ashrrev_i32_e32 v241, 31, v240
	v_lshl_add_u64 v[242:243], s[74:75], 0, v[240:241]
	v_mad_u64_u32 v[240:241], s[50:51], v242, s22, v[236:237]
	v_mad_i32_i24 v241, v243, s22, v241
	v_lshl_add_u64 v[240:241], v[240:241], 0, v[2:3]
	v_add_co_u32_e32 v240, vcc, s36, v240
	s_nop 1
	v_addc_co_u32_e32 v241, vcc, 0, v241, vcc
	global_load_dwordx2 v[230:231], v[240:241], off offset:2048
	v_add_u32_e32 v238, s24, v91
	v_mov_b64_e32 v[236:237], s[26:27]
	v_add_u32_e32 v239, 0x600, v238
	v_ashrrev_i32_e32 v240, 5, v239
	v_ashrrev_i32_e32 v241, 31, v240
	v_lshl_add_u64 v[242:243], s[74:75], 0, v[240:241]
	v_mad_u64_u32 v[240:241], s[50:51], v242, s22, v[236:237]
	v_mad_i32_i24 v241, v243, s22, v241
	v_lshl_add_u64 v[240:241], v[240:241], 0, v[2:3]
	v_add_co_u32_e32 v240, vcc, s36, v240
	s_nop 1
	v_addc_co_u32_e32 v241, vcc, 0, v241, vcc
	global_load_dwordx2 v[232:233], v[240:241], off offset:2048
	v_add_u32_e32 v238, s24, v91
	v_mov_b64_e32 v[236:237], s[26:27]
	v_add_u32_e32 v238, 0x700, v238
	v_ashrrev_i32_e32 v240, 5, v238
	v_ashrrev_i32_e32 v241, 31, v240
	v_lshl_add_u64 v[238:239], s[74:75], 0, v[240:241]
	v_mad_u64_u32 v[236:237], s[50:51], v238, s22, v[236:237]
	v_mad_i32_i24 v237, v239, s22, v237
	v_lshl_add_u64 v[236:237], v[236:237], 0, v[2:3]
	v_add_co_u32_e32 v236, vcc, s36, v236
	s_nop 1
	v_addc_co_u32_e32 v237, vcc, 0, v237, vcc
	global_load_dwordx2 v[234:235], v[236:237], off offset:2048
	s_waitcnt vmcnt(0)
	v_add_u32_e32 v6, s24, v91
	v_ashrrev_i32_e32 v4, 5, v6
	v_ashrrev_i32_e32 v5, 31, v4
	v_lshl_add_u64 v[8:9], s[74:75], 0, v[4:5]
	v_lshl_or_b32 v7, v4, 9, v169
	v_mov_b64_e32 v[4:5], s[26:27]
	v_mad_u64_u32 v[10:11], s[50:51], v8, s22, v[4:5]
	v_mad_i32_i24 v11, v9, s22, v11
	v_lshl_add_u64 v[10:11], v[10:11], 0, v[2:3]
	v_add_co_u32_e32 v10, vcc, 0x4000, v10
	v_lshlrev_b64 v[8:9], 11, v[8:9]
	s_nop 0
	v_addc_co_u32_e32 v11, vcc, 0, v11, vcc
	v_mov_b32_e32 v10, v220
	v_mov_b32_e32 v11, v221
	v_lshl_add_u64 v[16:17], v[0:1], 0, v[8:9]
	s_addk_i32 s24, 0x800
	s_cmpk_lg_i32 s24, 0x1000
	v_lshlrev_b32_e32 v12, 16, v10
	v_and_b32_e32 v10, 0xffff0000, v10
	v_lshlrev_b32_e32 v13, 16, v11
	v_mul_f32_e32 v10, 0xbfb8aa3b, v10
	v_mul_f32_e32 v12, 0xbfb8aa3b, v12
	v_exp_f32_e32 v14, v10
	v_mul_f32_e32 v10, 0xbfb8aa3b, v13
	v_exp_f32_e32 v12, v12
	v_exp_f32_e32 v13, v10
	v_and_b32_e32 v11, 0xffff0000, v11
	v_mul_f32_e32 v10, 0xbfb8aa3b, v11
	v_exp_f32_e32 v15, v10
	v_pk_add_f32 v[12:13], v[12:13], 1.0 op_sel_hi:[1,0]
	ds_read_b128 v[8:11], v7
	v_min_f32_e32 v7, 0x7f7fffff, v13
	v_rcp_f32_e32 v18, v7
	v_pk_add_f32 v[14:15], v[14:15], 1.0 op_sel_hi:[1,0]
	v_fma_f32 v19, -v7, v18, 1.0
	v_fmac_f32_e32 v18, v19, v18
	v_fma_f32 v21, -v7, v18, 1.0
	v_fma_f32 v20, v21, v18, v18
	v_fma_f32 v7, -v7, v20, 1.0
	v_fma_f32 v13, v7, v18, v20
	v_min_f32_e32 v7, 0x7f7fffff, v12
	v_rcp_f32_e32 v18, v7
	s_nop 0
	v_fma_f32 v19, -v7, v18, 1.0
	v_fmac_f32_e32 v18, v19, v18
	v_fma_f32 v21, -v7, v18, 1.0
	v_fma_f32 v20, v21, v18, v18
	v_fma_f32 v7, -v7, v20, 1.0
	v_fma_f32 v12, v7, v18, v20
	v_min_f32_e32 v7, 0x7f7fffff, v15
	s_waitcnt lgkmcnt(0)
; DEVI float sigmoidf_(float x) { return 1.f / (1.f + __expf(-x)); }
; template <int BR, int IN, int OUT>
; DEVI void p6_branch(const Params& P, int pm, int pn, float* macc, char* smem, int tid) {
;     ...
; #pragma unroll 8
;   for (int q = 0; q < 16; ++q) {
;     const int id = tid + 256 * q, row = id >> 5, c4 = id & 31;
;     const long grow = (long)pm * 128 + row;
;     const int gcol = pn * 128 + c4 * 4;
;     float4 a = *reinterpret_cast<const float4*>(T + row * 128 + c4 * 4);
;     float g[4];
;     load4bf(Z + grow * NCOL + (9 + BR) * 1024 + gcol, g);
;     float v[4] = {sigmoidf_(g[0]) * a.x, sigmoidf_(g[1]) * a.y, sigmoidf_(g[2]) * a.z, sigmoidf_(g[3]) * a.w};
;     if (IN == 1) {
;       float mo[4]; load4bf(M + grow * 1024 + gcol, mo);
;       v[0] += mo[0]; v[1] += mo[1]; v[2] += mo[2]; v[3] += mo[3];
;     }
;     if (IN == 2) {
;       float4 mo = *reinterpret_cast<const float4*>(macc + grow * 1024 + gcol);
;       v[0] += mo.x; v[1] += mo.y; v[2] += mo.z; v[3] += mo.w;
;     }
;     if (OUT == 1) *reinterpret_cast<float4*>(macc + grow * 1024 + gcol) = make_float4(v[0], v[1], v[2], v[3]);
;     else store4bf(M + grow * 1024 + gcol, v);
	v_mov_b32_e32 v18, v8
	v_rcp_f32_e32 v8, v7
	v_mov_b32_e32 v19, v10
	v_pk_mul_f32 v[12:13], v[18:19], v[12:13]
	v_fma_f32 v10, -v7, v8, 1.0
	v_fmac_f32_e32 v8, v10, v8
	v_fma_f32 v19, -v7, v8, 1.0
	v_fma_f32 v18, v19, v8, v8
	v_fma_f32 v7, -v7, v18, 1.0
	v_fma_f32 v15, v7, v8, v18
	v_min_f32_e32 v7, 0x7f7fffff, v14
	v_rcp_f32_e32 v8, v7
	s_nop 0
	v_fma_f32 v10, -v7, v8, 1.0
	v_fmac_f32_e32 v8, v10, v8
	v_fma_f32 v19, -v7, v8, 1.0
	v_fma_f32 v18, v19, v8, v8
	v_fma_f32 v7, -v7, v18, 1.0
	v_fma_f32 v14, v7, v8, v18
	v_mov_b32_e32 v10, v9
	v_pk_mul_f32 v[8:9], v[10:11], v[14:15]
	v_and_b32_sdwa v10, v12, v95 dst_sel:DWORD dst_unused:UNUSED_PAD src0_sel:WORD_1 src1_sel:DWORD
	v_add3_u32 v10, v12, v10, s39
	v_and_b32_sdwa v11, v9, v95 dst_sel:DWORD dst_unused:UNUSED_PAD src0_sel:WORD_1 src1_sel:DWORD
	v_and_b32_sdwa v12, v8, v95 dst_sel:DWORD dst_unused:UNUSED_PAD src0_sel:WORD_1 src1_sel:DWORD
	v_and_b32_sdwa v7, v13, v95 dst_sel:DWORD dst_unused:UNUSED_PAD src0_sel:WORD_1 src1_sel:DWORD
	v_add3_u32 v9, v9, v11, s39
	v_add3_u32 v8, v8, v12, s39
	v_add3_u32 v7, v13, v7, s39
	v_and_b32_e32 v9, 0xffff0000, v9
	v_and_b32_e32 v8, 0xffff0000, v8
	v_or_b32_sdwa v9, v9, v7 dst_sel:DWORD dst_unused:UNUSED_PAD src0_sel:DWORD src1_sel:WORD_1
	v_or_b32_sdwa v8, v8, v10 dst_sel:DWORD dst_unused:UNUSED_PAD src0_sel:DWORD src1_sel:WORD_1
	v_add_u32_e32 v7, 0x100, v6
	global_store_dwordx2 v[16:17], v[8:9], off
	v_ashrrev_i32_e32 v8, 5, v7
	v_ashrrev_i32_e32 v9, 31, v8
	v_lshl_add_u64 v[10:11], s[74:75], 0, v[8:9]
	v_lshl_or_b32 v7, v8, 9, v169
	v_mad_u64_u32 v[8:9], s[50:51], v10, s22, v[4:5]
	v_mad_i32_i24 v9, v11, s22, v9
	v_lshl_add_u64 v[8:9], v[8:9], 0, v[2:3]
	v_add_co_u32_e32 v8, vcc, s36, v8
	s_nop 1
	v_addc_co_u32_e32 v9, vcc, 0, v9, vcc
	v_mov_b32_e32 v8, v222
	v_mov_b32_e32 v9, v223
	v_lshlrev_b32_e32 v12, 16, v8
	v_and_b32_e32 v8, 0xffff0000, v8
	v_lshlrev_b32_e32 v13, 16, v9
	v_mul_f32_e32 v8, 0xbfb8aa3b, v8
	v_mul_f32_e32 v12, 0xbfb8aa3b, v12
	v_exp_f32_e32 v14, v8
	v_mul_f32_e32 v8, 0xbfb8aa3b, v13
	v_exp_f32_e32 v12, v12
	v_exp_f32_e32 v13, v8
	v_and_b32_e32 v9, 0xffff0000, v9
	v_mul_f32_e32 v8, 0xbfb8aa3b, v9
	v_exp_f32_e32 v15, v8
	v_lshlrev_b64 v[8:9], 11, v[10:11]
	v_pk_add_f32 v[12:13], v[12:13], 1.0 op_sel_hi:[1,0]
	v_lshl_add_u64 v[16:17], v[0:1], 0, v[8:9]
	ds_read_b128 v[8:11], v7
	v_min_f32_e32 v7, 0x7f7fffff, v13
	v_rcp_f32_e32 v18, v7
	v_pk_add_f32 v[14:15], v[14:15], 1.0 op_sel_hi:[1,0]
	v_fma_f32 v19, -v7, v18, 1.0
	v_fmac_f32_e32 v18, v19, v18
	v_fma_f32 v21, -v7, v18, 1.0
	v_fma_f32 v20, v21, v18, v18
	v_fma_f32 v7, -v7, v20, 1.0
	v_fma_f32 v13, v7, v18, v20
	v_min_f32_e32 v7, 0x7f7fffff, v12
	v_rcp_f32_e32 v18, v7
	s_nop 0
	v_fma_f32 v19, -v7, v18, 1.0
	v_fmac_f32_e32 v18, v19, v18
	v_fma_f32 v21, -v7, v18, 1.0
	v_fma_f32 v20, v21, v18, v18
	v_fma_f32 v7, -v7, v20, 1.0
	v_fma_f32 v12, v7, v18, v20
	v_min_f32_e32 v7, 0x7f7fffff, v15
	s_waitcnt lgkmcnt(0)
	v_mov_b32_e32 v18, v8
	v_rcp_f32_e32 v8, v7
	v_mov_b32_e32 v19, v10
	v_pk_mul_f32 v[12:13], v[18:19], v[12:13]
	v_fma_f32 v10, -v7, v8, 1.0
	v_fmac_f32_e32 v8, v10, v8
	v_fma_f32 v19, -v7, v8, 1.0
	v_fma_f32 v18, v19, v8, v8
	v_fma_f32 v7, -v7, v18, 1.0
	v_fma_f32 v15, v7, v8, v18
	v_min_f32_e32 v7, 0x7f7fffff, v14
	v_rcp_f32_e32 v8, v7
	s_nop 0
	v_fma_f32 v10, -v7, v8, 1.0
	v_fmac_f32_e32 v8, v10, v8
	v_fma_f32 v19, -v7, v8, 1.0
	v_fma_f32 v18, v19, v8, v8
	v_fma_f32 v7, -v7, v18, 1.0
	v_fma_f32 v14, v7, v8, v18
	v_mov_b32_e32 v10, v9
	v_pk_mul_f32 v[8:9], v[10:11], v[14:15]
	v_and_b32_sdwa v10, v12, v95 dst_sel:DWORD dst_unused:UNUSED_PAD src0_sel:WORD_1 src1_sel:DWORD
	v_add3_u32 v10, v12, v10, s39
	v_and_b32_sdwa v11, v9, v95 dst_sel:DWORD dst_unused:UNUSED_PAD src0_sel:WORD_1 src1_sel:DWORD
	v_and_b32_sdwa v12, v8, v95 dst_sel:DWORD dst_unused:UNUSED_PAD src0_sel:WORD_1 src1_sel:DWORD
	v_and_b32_sdwa v7, v13, v95 dst_sel:DWORD dst_unused:UNUSED_PAD src0_sel:WORD_1 src1_sel:DWORD
	v_add3_u32 v9, v9, v11, s39
	v_add3_u32 v8, v8, v12, s39
	v_add3_u32 v7, v13, v7, s39
	v_and_b32_e32 v9, 0xffff0000, v9
	v_and_b32_e32 v8, 0xffff0000, v8
	v_or_b32_sdwa v9, v9, v7 dst_sel:DWORD dst_unused:UNUSED_PAD src0_sel:DWORD src1_sel:WORD_1
	v_or_b32_sdwa v8, v8, v10 dst_sel:DWORD dst_unused:UNUSED_PAD src0_sel:DWORD src1_sel:WORD_1
	v_add_u32_e32 v7, 0x200, v6
	global_store_dwordx2 v[16:17], v[8:9], off
	v_ashrrev_i32_e32 v8, 5, v7
	v_ashrrev_i32_e32 v9, 31, v8
	v_lshl_add_u64 v[10:11], s[74:75], 0, v[8:9]
	v_lshl_or_b32 v7, v8, 9, v169
	v_mad_u64_u32 v[8:9], s[50:51], v10, s22, v[4:5]
	v_mad_i32_i24 v9, v11, s22, v9
	v_lshl_add_u64 v[8:9], v[8:9], 0, v[2:3]
	v_add_co_u32_e32 v8, vcc, s36, v8
	s_nop 1
	v_addc_co_u32_e32 v9, vcc, 0, v9, vcc
	v_mov_b32_e32 v8, v224
	v_mov_b32_e32 v9, v225
	v_lshlrev_b32_e32 v12, 16, v8
	v_and_b32_e32 v8, 0xffff0000, v8
	v_lshlrev_b32_e32 v13, 16, v9
	v_mul_f32_e32 v8, 0xbfb8aa3b, v8
	v_mul_f32_e32 v12, 0xbfb8aa3b, v12
	v_exp_f32_e32 v14, v8
	v_mul_f32_e32 v8, 0xbfb8aa3b, v13
	v_exp_f32_e32 v12, v12
	v_exp_f32_e32 v13, v8
	v_and_b32_e32 v9, 0xffff0000, v9
	v_mul_f32_e32 v8, 0xbfb8aa3b, v9
	v_exp_f32_e32 v15, v8
	v_lshlrev_b64 v[8:9], 11, v[10:11]
	v_pk_add_f32 v[12:13], v[12:13], 1.0 op_sel_hi:[1,0]
	v_lshl_add_u64 v[16:17], v[0:1], 0, v[8:9]
	ds_read_b128 v[8:11], v7
	v_min_f32_e32 v7, 0x7f7fffff, v13
	v_rcp_f32_e32 v18, v7
	v_pk_add_f32 v[14:15], v[14:15], 1.0 op_sel_hi:[1,0]
	v_fma_f32 v19, -v7, v18, 1.0
	v_fmac_f32_e32 v18, v19, v18
	v_fma_f32 v21, -v7, v18, 1.0
	v_fma_f32 v20, v21, v18, v18
	v_fma_f32 v7, -v7, v20, 1.0
	v_fma_f32 v13, v7, v18, v20
	v_min_f32_e32 v7, 0x7f7fffff, v12
	v_rcp_f32_e32 v18, v7
	s_nop 0
	v_fma_f32 v19, -v7, v18, 1.0
	v_fmac_f32_e32 v18, v19, v18
	v_fma_f32 v21, -v7, v18, 1.0
	v_fma_f32 v20, v21, v18, v18
	v_fma_f32 v7, -v7, v20, 1.0
	v_fma_f32 v12, v7, v18, v20
	v_min_f32_e32 v7, 0x7f7fffff, v15
	s_waitcnt lgkmcnt(0)
; DEVI float sigmoidf_(float x) { return 1.f / (1.f + __expf(-x)); }
; template <int BR, int IN, int OUT>
; DEVI void p6_branch(const Params& P, int pm, int pn, float* macc, char* smem, int tid) {
;     ...
; #pragma unroll 8
;   for (int q = 0; q < 16; ++q) {
;     const int id = tid + 256 * q, row = id >> 5, c4 = id & 31;
;     const long grow = (long)pm * 128 + row;
;     const int gcol = pn * 128 + c4 * 4;
;     float4 a = *reinterpret_cast<const float4*>(T + row * 128 + c4 * 4);
;     float g[4];
;     load4bf(Z + grow * NCOL + (9 + BR) * 1024 + gcol, g);
;     float v[4] = {sigmoidf_(g[0]) * a.x, sigmoidf_(g[1]) * a.y, sigmoidf_(g[2]) * a.z, sigmoidf_(g[3]) * a.w};
;     if (IN == 1) {
;       float mo[4]; load4bf(M + grow * 1024 + gcol, mo);
;       v[0] += mo[0]; v[1] += mo[1]; v[2] += mo[2]; v[3] += mo[3];
;     }
;     if (IN == 2) {
;       float4 mo = *reinterpret_cast<const float4*>(macc + grow * 1024 + gcol);
;       v[0] += mo.x; v[1] += mo.y; v[2] += mo.z; v[3] += mo.w;
;     }
;     if (OUT == 1) *reinterpret_cast<float4*>(macc + grow * 1024 + gcol) = make_float4(v[0], v[1], v[2], v[3]);
;     else store4bf(M + grow * 1024 + gcol, v);
	v_mov_b32_e32 v18, v8
	v_rcp_f32_e32 v8, v7
	v_mov_b32_e32 v19, v10
	v_pk_mul_f32 v[12:13], v[18:19], v[12:13]
	v_fma_f32 v10, -v7, v8, 1.0
	v_fmac_f32_e32 v8, v10, v8
	v_fma_f32 v19, -v7, v8, 1.0
	v_fma_f32 v18, v19, v8, v8
	v_fma_f32 v7, -v7, v18, 1.0
	v_fma_f32 v15, v7, v8, v18
	v_min_f32_e32 v7, 0x7f7fffff, v14
	v_rcp_f32_e32 v8, v7
	s_nop 0
	v_fma_f32 v10, -v7, v8, 1.0
	v_fmac_f32_e32 v8, v10, v8
	v_fma_f32 v19, -v7, v8, 1.0
	v_fma_f32 v18, v19, v8, v8
	v_fma_f32 v7, -v7, v18, 1.0
	v_fma_f32 v14, v7, v8, v18
	v_mov_b32_e32 v10, v9
	v_pk_mul_f32 v[8:9], v[10:11], v[14:15]
	v_and_b32_sdwa v10, v12, v95 dst_sel:DWORD dst_unused:UNUSED_PAD src0_sel:WORD_1 src1_sel:DWORD
	v_add3_u32 v10, v12, v10, s39
	v_and_b32_sdwa v11, v9, v95 dst_sel:DWORD dst_unused:UNUSED_PAD src0_sel:WORD_1 src1_sel:DWORD
	v_and_b32_sdwa v12, v8, v95 dst_sel:DWORD dst_unused:UNUSED_PAD src0_sel:WORD_1 src1_sel:DWORD
	v_and_b32_sdwa v7, v13, v95 dst_sel:DWORD dst_unused:UNUSED_PAD src0_sel:WORD_1 src1_sel:DWORD
	v_add3_u32 v9, v9, v11, s39
	v_add3_u32 v8, v8, v12, s39
	v_add3_u32 v7, v13, v7, s39
	v_and_b32_e32 v9, 0xffff0000, v9
	v_and_b32_e32 v8, 0xffff0000, v8
	v_or_b32_sdwa v9, v9, v7 dst_sel:DWORD dst_unused:UNUSED_PAD src0_sel:DWORD src1_sel:WORD_1
	v_or_b32_sdwa v8, v8, v10 dst_sel:DWORD dst_unused:UNUSED_PAD src0_sel:DWORD src1_sel:WORD_1
	v_add_u32_e32 v7, 0x300, v6
	global_store_dwordx2 v[16:17], v[8:9], off
	v_ashrrev_i32_e32 v8, 5, v7
	v_ashrrev_i32_e32 v9, 31, v8
	v_lshl_add_u64 v[10:11], s[74:75], 0, v[8:9]
	v_lshl_or_b32 v7, v8, 9, v169
	v_mad_u64_u32 v[8:9], s[50:51], v10, s22, v[4:5]
	v_mad_i32_i24 v9, v11, s22, v9
	v_lshl_add_u64 v[8:9], v[8:9], 0, v[2:3]
	v_add_co_u32_e32 v8, vcc, s36, v8
	s_nop 1
	v_addc_co_u32_e32 v9, vcc, 0, v9, vcc
	v_mov_b32_e32 v8, v226
	v_mov_b32_e32 v9, v227
	v_lshlrev_b32_e32 v12, 16, v8
	v_and_b32_e32 v8, 0xffff0000, v8
	v_lshlrev_b32_e32 v13, 16, v9
	v_mul_f32_e32 v8, 0xbfb8aa3b, v8
	v_mul_f32_e32 v12, 0xbfb8aa3b, v12
	v_exp_f32_e32 v14, v8
	v_mul_f32_e32 v8, 0xbfb8aa3b, v13
	v_exp_f32_e32 v12, v12
	v_exp_f32_e32 v13, v8
	v_and_b32_e32 v9, 0xffff0000, v9
	v_mul_f32_e32 v8, 0xbfb8aa3b, v9
	v_exp_f32_e32 v15, v8
	v_lshlrev_b64 v[8:9], 11, v[10:11]
	v_pk_add_f32 v[12:13], v[12:13], 1.0 op_sel_hi:[1,0]
	v_lshl_add_u64 v[16:17], v[0:1], 0, v[8:9]
	ds_read_b128 v[8:11], v7
	v_min_f32_e32 v7, 0x7f7fffff, v13
	v_rcp_f32_e32 v18, v7
	v_pk_add_f32 v[14:15], v[14:15], 1.0 op_sel_hi:[1,0]
	v_fma_f32 v19, -v7, v18, 1.0
	v_fmac_f32_e32 v18, v19, v18
	v_fma_f32 v21, -v7, v18, 1.0
	v_fma_f32 v20, v21, v18, v18
	v_fma_f32 v7, -v7, v20, 1.0
	v_fma_f32 v13, v7, v18, v20
	v_min_f32_e32 v7, 0x7f7fffff, v12
	v_rcp_f32_e32 v18, v7
	s_nop 0
	v_fma_f32 v19, -v7, v18, 1.0
	v_fmac_f32_e32 v18, v19, v18
	v_fma_f32 v21, -v7, v18, 1.0
	v_fma_f32 v20, v21, v18, v18
	v_fma_f32 v7, -v7, v20, 1.0
	v_fma_f32 v12, v7, v18, v20
	v_min_f32_e32 v7, 0x7f7fffff, v15
	s_waitcnt lgkmcnt(0)
	v_mov_b32_e32 v18, v8
	v_rcp_f32_e32 v8, v7
	v_mov_b32_e32 v19, v10
	v_pk_mul_f32 v[12:13], v[18:19], v[12:13]
	v_fma_f32 v10, -v7, v8, 1.0
	v_fmac_f32_e32 v8, v10, v8
	v_fma_f32 v19, -v7, v8, 1.0
	v_fma_f32 v18, v19, v8, v8
	v_fma_f32 v7, -v7, v18, 1.0
	v_fma_f32 v15, v7, v8, v18
	v_min_f32_e32 v7, 0x7f7fffff, v14
	v_rcp_f32_e32 v8, v7
	s_nop 0
	v_fma_f32 v10, -v7, v8, 1.0
	v_fmac_f32_e32 v8, v10, v8
	v_fma_f32 v19, -v7, v8, 1.0
	v_fma_f32 v18, v19, v8, v8
	v_fma_f32 v7, -v7, v18, 1.0
	v_fma_f32 v14, v7, v8, v18
	v_mov_b32_e32 v10, v9
	v_pk_mul_f32 v[8:9], v[10:11], v[14:15]
	v_and_b32_sdwa v10, v12, v95 dst_sel:DWORD dst_unused:UNUSED_PAD src0_sel:WORD_1 src1_sel:DWORD
	v_add3_u32 v10, v12, v10, s39
	v_and_b32_sdwa v11, v9, v95 dst_sel:DWORD dst_unused:UNUSED_PAD src0_sel:WORD_1 src1_sel:DWORD
	v_and_b32_sdwa v12, v8, v95 dst_sel:DWORD dst_unused:UNUSED_PAD src0_sel:WORD_1 src1_sel:DWORD
	v_and_b32_sdwa v7, v13, v95 dst_sel:DWORD dst_unused:UNUSED_PAD src0_sel:WORD_1 src1_sel:DWORD
	v_add3_u32 v9, v9, v11, s39
	v_add3_u32 v8, v8, v12, s39
	v_add3_u32 v7, v13, v7, s39
	v_and_b32_e32 v9, 0xffff0000, v9
	v_and_b32_e32 v8, 0xffff0000, v8
	v_or_b32_sdwa v9, v9, v7 dst_sel:DWORD dst_unused:UNUSED_PAD src0_sel:DWORD src1_sel:WORD_1
	v_or_b32_sdwa v8, v8, v10 dst_sel:DWORD dst_unused:UNUSED_PAD src0_sel:DWORD src1_sel:WORD_1
	v_add_u32_e32 v7, 0x400, v6
	global_store_dwordx2 v[16:17], v[8:9], off
	v_ashrrev_i32_e32 v8, 5, v7
	v_ashrrev_i32_e32 v9, 31, v8
	v_lshl_add_u64 v[10:11], s[74:75], 0, v[8:9]
	v_lshl_or_b32 v7, v8, 9, v169
	v_mad_u64_u32 v[8:9], s[50:51], v10, s22, v[4:5]
	v_mad_i32_i24 v9, v11, s22, v9
	v_lshl_add_u64 v[8:9], v[8:9], 0, v[2:3]
	v_add_co_u32_e32 v8, vcc, s36, v8
	s_nop 1
	v_addc_co_u32_e32 v9, vcc, 0, v9, vcc
	v_mov_b32_e32 v8, v228
	v_mov_b32_e32 v9, v229
	v_lshlrev_b32_e32 v12, 16, v8
	v_and_b32_e32 v8, 0xffff0000, v8
	v_lshlrev_b32_e32 v13, 16, v9
	v_mul_f32_e32 v8, 0xbfb8aa3b, v8
	v_mul_f32_e32 v12, 0xbfb8aa3b, v12
	v_exp_f32_e32 v14, v8
	v_mul_f32_e32 v8, 0xbfb8aa3b, v13
	v_exp_f32_e32 v12, v12
	v_exp_f32_e32 v13, v8
	v_and_b32_e32 v9, 0xffff0000, v9
	v_mul_f32_e32 v8, 0xbfb8aa3b, v9
	v_exp_f32_e32 v15, v8
	v_lshlrev_b64 v[8:9], 11, v[10:11]
	v_pk_add_f32 v[12:13], v[12:13], 1.0 op_sel_hi:[1,0]
	v_lshl_add_u64 v[16:17], v[0:1], 0, v[8:9]
	ds_read_b128 v[8:11], v7
	v_min_f32_e32 v7, 0x7f7fffff, v13
	v_rcp_f32_e32 v18, v7
	v_pk_add_f32 v[14:15], v[14:15], 1.0 op_sel_hi:[1,0]
	v_fma_f32 v19, -v7, v18, 1.0
	v_fmac_f32_e32 v18, v19, v18
	v_fma_f32 v21, -v7, v18, 1.0
	v_fma_f32 v20, v21, v18, v18
	v_fma_f32 v7, -v7, v20, 1.0
	v_fma_f32 v13, v7, v18, v20
	v_min_f32_e32 v7, 0x7f7fffff, v12
	v_rcp_f32_e32 v18, v7
	s_nop 0
	v_fma_f32 v19, -v7, v18, 1.0
	v_fmac_f32_e32 v18, v19, v18
	v_fma_f32 v21, -v7, v18, 1.0
	v_fma_f32 v20, v21, v18, v18
	v_fma_f32 v7, -v7, v20, 1.0
	v_fma_f32 v12, v7, v18, v20
	v_min_f32_e32 v7, 0x7f7fffff, v15
	s_waitcnt lgkmcnt(0)
; DEVI float sigmoidf_(float x) { return 1.f / (1.f + __expf(-x)); }
; template <int BR, int IN, int OUT>
; DEVI void p6_branch(const Params& P, int pm, int pn, float* macc, char* smem, int tid) {
;     ...
; #pragma unroll 8
;   for (int q = 0; q < 16; ++q) {
;     const int id = tid + 256 * q, row = id >> 5, c4 = id & 31;
;     const long grow = (long)pm * 128 + row;
;     const int gcol = pn * 128 + c4 * 4;
;     float4 a = *reinterpret_cast<const float4*>(T + row * 128 + c4 * 4);
;     float g[4];
;     load4bf(Z + grow * NCOL + (9 + BR) * 1024 + gcol, g);
;     float v[4] = {sigmoidf_(g[0]) * a.x, sigmoidf_(g[1]) * a.y, sigmoidf_(g[2]) * a.z, sigmoidf_(g[3]) * a.w};
;     if (IN == 1) {
;       float mo[4]; load4bf(M + grow * 1024 + gcol, mo);
;       v[0] += mo[0]; v[1] += mo[1]; v[2] += mo[2]; v[3] += mo[3];
;     }
;     if (IN == 2) {
;       float4 mo = *reinterpret_cast<const float4*>(macc + grow * 1024 + gcol);
;       v[0] += mo.x; v[1] += mo.y; v[2] += mo.z; v[3] += mo.w;
;     }
;     if (OUT == 1) *reinterpret_cast<float4*>(macc + grow * 1024 + gcol) = make_float4(v[0], v[1], v[2], v[3]);
;     else store4bf(M + grow * 1024 + gcol, v);
	v_mov_b32_e32 v18, v8
	v_rcp_f32_e32 v8, v7
	v_mov_b32_e32 v19, v10
	v_pk_mul_f32 v[12:13], v[18:19], v[12:13]
	v_fma_f32 v10, -v7, v8, 1.0
	v_fmac_f32_e32 v8, v10, v8
	v_fma_f32 v19, -v7, v8, 1.0
	v_fma_f32 v18, v19, v8, v8
	v_fma_f32 v7, -v7, v18, 1.0
	v_fma_f32 v15, v7, v8, v18
	v_min_f32_e32 v7, 0x7f7fffff, v14
	v_rcp_f32_e32 v8, v7
	s_nop 0
	v_fma_f32 v10, -v7, v8, 1.0
	v_fmac_f32_e32 v8, v10, v8
	v_fma_f32 v19, -v7, v8, 1.0
	v_fma_f32 v18, v19, v8, v8
	v_fma_f32 v7, -v7, v18, 1.0
	v_fma_f32 v14, v7, v8, v18
	v_mov_b32_e32 v10, v9
	v_pk_mul_f32 v[8:9], v[10:11], v[14:15]
	v_and_b32_sdwa v10, v12, v95 dst_sel:DWORD dst_unused:UNUSED_PAD src0_sel:WORD_1 src1_sel:DWORD
	v_add3_u32 v10, v12, v10, s39
	v_and_b32_sdwa v11, v9, v95 dst_sel:DWORD dst_unused:UNUSED_PAD src0_sel:WORD_1 src1_sel:DWORD
	v_and_b32_sdwa v12, v8, v95 dst_sel:DWORD dst_unused:UNUSED_PAD src0_sel:WORD_1 src1_sel:DWORD
	v_and_b32_sdwa v7, v13, v95 dst_sel:DWORD dst_unused:UNUSED_PAD src0_sel:WORD_1 src1_sel:DWORD
	v_add3_u32 v9, v9, v11, s39
	v_add3_u32 v8, v8, v12, s39
	v_add3_u32 v7, v13, v7, s39
	v_and_b32_e32 v9, 0xffff0000, v9
	v_and_b32_e32 v8, 0xffff0000, v8
	v_or_b32_sdwa v9, v9, v7 dst_sel:DWORD dst_unused:UNUSED_PAD src0_sel:DWORD src1_sel:WORD_1
	v_or_b32_sdwa v8, v8, v10 dst_sel:DWORD dst_unused:UNUSED_PAD src0_sel:DWORD src1_sel:WORD_1
	v_add_u32_e32 v7, 0x500, v6
	global_store_dwordx2 v[16:17], v[8:9], off
	v_ashrrev_i32_e32 v8, 5, v7
	v_ashrrev_i32_e32 v9, 31, v8
	v_lshl_add_u64 v[10:11], s[74:75], 0, v[8:9]
	v_lshl_or_b32 v7, v8, 9, v169
	v_mad_u64_u32 v[8:9], s[50:51], v10, s22, v[4:5]
	v_mad_i32_i24 v9, v11, s22, v9
	v_lshl_add_u64 v[8:9], v[8:9], 0, v[2:3]
	v_add_co_u32_e32 v8, vcc, s36, v8
	s_nop 1
	v_addc_co_u32_e32 v9, vcc, 0, v9, vcc
	v_mov_b32_e32 v8, v230
	v_mov_b32_e32 v9, v231
	v_lshlrev_b32_e32 v12, 16, v8
	v_and_b32_e32 v8, 0xffff0000, v8
	v_lshlrev_b32_e32 v13, 16, v9
	v_mul_f32_e32 v8, 0xbfb8aa3b, v8
	v_mul_f32_e32 v12, 0xbfb8aa3b, v12
	v_exp_f32_e32 v14, v8
	v_mul_f32_e32 v8, 0xbfb8aa3b, v13
	v_exp_f32_e32 v12, v12
	v_exp_f32_e32 v13, v8
	v_and_b32_e32 v9, 0xffff0000, v9
	v_mul_f32_e32 v8, 0xbfb8aa3b, v9
	v_exp_f32_e32 v15, v8
	v_lshlrev_b64 v[8:9], 11, v[10:11]
	v_pk_add_f32 v[12:13], v[12:13], 1.0 op_sel_hi:[1,0]
	v_lshl_add_u64 v[16:17], v[0:1], 0, v[8:9]
	ds_read_b128 v[8:11], v7
	v_min_f32_e32 v7, 0x7f7fffff, v13
	v_rcp_f32_e32 v18, v7
	v_pk_add_f32 v[14:15], v[14:15], 1.0 op_sel_hi:[1,0]
	v_fma_f32 v19, -v7, v18, 1.0
	v_fmac_f32_e32 v18, v19, v18
	v_fma_f32 v21, -v7, v18, 1.0
	v_fma_f32 v20, v21, v18, v18
	v_fma_f32 v7, -v7, v20, 1.0
	v_fma_f32 v13, v7, v18, v20
	v_min_f32_e32 v7, 0x7f7fffff, v12
	v_rcp_f32_e32 v18, v7
	s_nop 0
	v_fma_f32 v19, -v7, v18, 1.0
	v_fmac_f32_e32 v18, v19, v18
	v_fma_f32 v21, -v7, v18, 1.0
	v_fma_f32 v20, v21, v18, v18
	v_fma_f32 v7, -v7, v20, 1.0
	v_fma_f32 v12, v7, v18, v20
	v_min_f32_e32 v7, 0x7f7fffff, v15
	s_waitcnt lgkmcnt(0)
	v_mov_b32_e32 v18, v8
	v_rcp_f32_e32 v8, v7
	v_mov_b32_e32 v19, v10
	v_pk_mul_f32 v[12:13], v[18:19], v[12:13]
	v_fma_f32 v10, -v7, v8, 1.0
	v_fmac_f32_e32 v8, v10, v8
	v_fma_f32 v19, -v7, v8, 1.0
	v_fma_f32 v18, v19, v8, v8
	v_fma_f32 v7, -v7, v18, 1.0
	v_fma_f32 v15, v7, v8, v18
	v_min_f32_e32 v7, 0x7f7fffff, v14
	v_rcp_f32_e32 v8, v7
	s_nop 0
	v_fma_f32 v10, -v7, v8, 1.0
	v_fmac_f32_e32 v8, v10, v8
	v_fma_f32 v19, -v7, v8, 1.0
	v_fma_f32 v18, v19, v8, v8
	v_fma_f32 v7, -v7, v18, 1.0
	v_fma_f32 v14, v7, v8, v18
	v_mov_b32_e32 v10, v9
	v_pk_mul_f32 v[8:9], v[10:11], v[14:15]
	v_and_b32_sdwa v10, v12, v95 dst_sel:DWORD dst_unused:UNUSED_PAD src0_sel:WORD_1 src1_sel:DWORD
	v_add3_u32 v10, v12, v10, s39
	v_and_b32_sdwa v11, v9, v95 dst_sel:DWORD dst_unused:UNUSED_PAD src0_sel:WORD_1 src1_sel:DWORD
	v_and_b32_sdwa v12, v8, v95 dst_sel:DWORD dst_unused:UNUSED_PAD src0_sel:WORD_1 src1_sel:DWORD
	v_and_b32_sdwa v7, v13, v95 dst_sel:DWORD dst_unused:UNUSED_PAD src0_sel:WORD_1 src1_sel:DWORD
	v_add3_u32 v9, v9, v11, s39
	v_add3_u32 v8, v8, v12, s39
	v_add3_u32 v7, v13, v7, s39
	v_and_b32_e32 v9, 0xffff0000, v9
	v_and_b32_e32 v8, 0xffff0000, v8
	v_or_b32_sdwa v9, v9, v7 dst_sel:DWORD dst_unused:UNUSED_PAD src0_sel:DWORD src1_sel:WORD_1
	v_or_b32_sdwa v8, v8, v10 dst_sel:DWORD dst_unused:UNUSED_PAD src0_sel:DWORD src1_sel:WORD_1
	v_add_u32_e32 v7, 0x600, v6
	global_store_dwordx2 v[16:17], v[8:9], off
	v_ashrrev_i32_e32 v8, 5, v7
	v_ashrrev_i32_e32 v9, 31, v8
	v_lshl_add_u64 v[10:11], s[74:75], 0, v[8:9]
	v_lshl_or_b32 v7, v8, 9, v169
	v_mad_u64_u32 v[8:9], s[50:51], v10, s22, v[4:5]
	v_mad_i32_i24 v9, v11, s22, v9
	v_lshl_add_u64 v[8:9], v[8:9], 0, v[2:3]
	v_add_co_u32_e32 v8, vcc, s36, v8
	v_add_u32_e32 v6, 0x700, v6
	s_nop 0
	v_addc_co_u32_e32 v9, vcc, 0, v9, vcc
	v_mov_b32_e32 v8, v232
	v_mov_b32_e32 v9, v233
	v_lshlrev_b32_e32 v12, 16, v8
	v_and_b32_e32 v8, 0xffff0000, v8
	v_lshlrev_b32_e32 v13, 16, v9
	v_mul_f32_e32 v8, 0xbfb8aa3b, v8
	v_mul_f32_e32 v12, 0xbfb8aa3b, v12
	v_exp_f32_e32 v14, v8
	v_mul_f32_e32 v8, 0xbfb8aa3b, v13
	v_exp_f32_e32 v12, v12
	v_exp_f32_e32 v13, v8
	v_and_b32_e32 v9, 0xffff0000, v9
	v_mul_f32_e32 v8, 0xbfb8aa3b, v9
	v_exp_f32_e32 v15, v8
	v_lshlrev_b64 v[8:9], 11, v[10:11]
	v_pk_add_f32 v[12:13], v[12:13], 1.0 op_sel_hi:[1,0]
	v_lshl_add_u64 v[16:17], v[0:1], 0, v[8:9]
	ds_read_b128 v[8:11], v7
	v_min_f32_e32 v7, 0x7f7fffff, v13
	v_rcp_f32_e32 v18, v7
	v_pk_add_f32 v[14:15], v[14:15], 1.0 op_sel_hi:[1,0]
	v_fma_f32 v19, -v7, v18, 1.0
	v_fmac_f32_e32 v18, v19, v18
	v_fma_f32 v21, -v7, v18, 1.0
	v_fma_f32 v20, v21, v18, v18
	v_fma_f32 v7, -v7, v20, 1.0
	v_fma_f32 v13, v7, v18, v20
	v_min_f32_e32 v7, 0x7f7fffff, v12
	v_rcp_f32_e32 v18, v7
	s_nop 0
	v_fma_f32 v19, -v7, v18, 1.0
	v_fmac_f32_e32 v18, v19, v18
	v_fma_f32 v21, -v7, v18, 1.0
	v_fma_f32 v20, v21, v18, v18
	v_fma_f32 v7, -v7, v20, 1.0
	v_fma_f32 v12, v7, v18, v20
	v_min_f32_e32 v7, 0x7f7fffff, v15
	s_waitcnt lgkmcnt(0)
; DEVI float sigmoidf_(float x) { return 1.f / (1.f + __expf(-x)); }
; template <int BR, int IN, int OUT>
; DEVI void p6_branch(const Params& P, int pm, int pn, float* macc, char* smem, int tid) {
;     ...
; #pragma unroll 8
;   for (int q = 0; q < 16; ++q) {
;     const int id = tid + 256 * q, row = id >> 5, c4 = id & 31;
;     const long grow = (long)pm * 128 + row;
;     const int gcol = pn * 128 + c4 * 4;
;     float4 a = *reinterpret_cast<const float4*>(T + row * 128 + c4 * 4);
;     float g[4];
;     load4bf(Z + grow * NCOL + (9 + BR) * 1024 + gcol, g);
;     float v[4] = {sigmoidf_(g[0]) * a.x, sigmoidf_(g[1]) * a.y, sigmoidf_(g[2]) * a.z, sigmoidf_(g[3]) * a.w};
;     if (IN == 1) {
;       float mo[4]; load4bf(M + grow * 1024 + gcol, mo);
;       v[0] += mo[0]; v[1] += mo[1]; v[2] += mo[2]; v[3] += mo[3];
;     }
;     if (IN == 2) {
;       float4 mo = *reinterpret_cast<const float4*>(macc + grow * 1024 + gcol);
;       v[0] += mo.x; v[1] += mo.y; v[2] += mo.z; v[3] += mo.w;
;     }
;     if (OUT == 1) *reinterpret_cast<float4*>(macc + grow * 1024 + gcol) = make_float4(v[0], v[1], v[2], v[3]);
;     else store4bf(M + grow * 1024 + gcol, v);
	v_mov_b32_e32 v18, v8
	v_rcp_f32_e32 v8, v7
	v_mov_b32_e32 v19, v10
	v_pk_mul_f32 v[12:13], v[18:19], v[12:13]
	v_fma_f32 v10, -v7, v8, 1.0
	v_fmac_f32_e32 v8, v10, v8
	v_fma_f32 v19, -v7, v8, 1.0
	v_fma_f32 v18, v19, v8, v8
	v_fma_f32 v7, -v7, v18, 1.0
	v_fma_f32 v15, v7, v8, v18
	v_min_f32_e32 v7, 0x7f7fffff, v14
	v_rcp_f32_e32 v8, v7
	s_nop 0
	v_fma_f32 v10, -v7, v8, 1.0
	v_fmac_f32_e32 v8, v10, v8
	v_fma_f32 v19, -v7, v8, 1.0
	v_fma_f32 v18, v19, v8, v8
	v_fma_f32 v7, -v7, v18, 1.0
	v_fma_f32 v14, v7, v8, v18
	v_mov_b32_e32 v10, v9
	v_pk_mul_f32 v[8:9], v[10:11], v[14:15]
	v_and_b32_sdwa v10, v12, v95 dst_sel:DWORD dst_unused:UNUSED_PAD src0_sel:WORD_1 src1_sel:DWORD
	v_add3_u32 v10, v12, v10, s39
	v_and_b32_sdwa v11, v9, v95 dst_sel:DWORD dst_unused:UNUSED_PAD src0_sel:WORD_1 src1_sel:DWORD
	v_and_b32_sdwa v12, v8, v95 dst_sel:DWORD dst_unused:UNUSED_PAD src0_sel:WORD_1 src1_sel:DWORD
	v_and_b32_sdwa v7, v13, v95 dst_sel:DWORD dst_unused:UNUSED_PAD src0_sel:WORD_1 src1_sel:DWORD
	v_add3_u32 v9, v9, v11, s39
	v_add3_u32 v8, v8, v12, s39
	v_add3_u32 v7, v13, v7, s39
	v_and_b32_e32 v9, 0xffff0000, v9
	v_and_b32_e32 v8, 0xffff0000, v8
	v_or_b32_sdwa v9, v9, v7 dst_sel:DWORD dst_unused:UNUSED_PAD src0_sel:DWORD src1_sel:WORD_1
	v_or_b32_sdwa v8, v8, v10 dst_sel:DWORD dst_unused:UNUSED_PAD src0_sel:DWORD src1_sel:WORD_1
	global_store_dwordx2 v[16:17], v[8:9], off
	v_ashrrev_i32_e32 v8, 5, v6
	v_ashrrev_i32_e32 v9, 31, v8
	v_lshl_add_u64 v[6:7], s[74:75], 0, v[8:9]
	v_mad_u64_u32 v[4:5], s[50:51], v6, s22, v[4:5]
	v_mad_i32_i24 v5, v7, s22, v5
	v_lshl_add_u64 v[4:5], v[4:5], 0, v[2:3]
	v_add_co_u32_e32 v4, vcc, s36, v4
	v_lshl_or_b32 v8, v8, 9, v169
	s_nop 0
	v_addc_co_u32_e32 v5, vcc, 0, v5, vcc
	v_mov_b32_e32 v4, v234
	v_mov_b32_e32 v5, v235
	v_lshlrev_b32_e32 v9, 16, v4
	v_and_b32_e32 v4, 0xffff0000, v4
	v_lshlrev_b32_e32 v11, 16, v5
	v_mul_f32_e32 v4, 0xbfb8aa3b, v4
	v_mul_f32_e32 v9, 0xbfb8aa3b, v9
	v_exp_f32_e32 v12, v4
	v_mul_f32_e32 v4, 0xbfb8aa3b, v11
	v_exp_f32_e32 v10, v9
	v_exp_f32_e32 v11, v4
	v_and_b32_e32 v5, 0xffff0000, v5
	v_mul_f32_e32 v4, 0xbfb8aa3b, v5
	v_exp_f32_e32 v13, v4
	v_lshlrev_b64 v[4:5], 11, v[6:7]
	v_lshl_add_u64 v[14:15], v[0:1], 0, v[4:5]
	ds_read_b128 v[4:7], v8
	v_pk_add_f32 v[8:9], v[10:11], 1.0 op_sel_hi:[1,0]
	s_nop 0
	v_min_f32_e32 v10, 0x7f7fffff, v9
	v_rcp_f32_e32 v11, v10
	s_nop 0
	v_fma_f32 v16, -v10, v11, 1.0
	v_fmac_f32_e32 v11, v16, v11
	v_fma_f32 v18, -v10, v11, 1.0
	v_fma_f32 v17, v18, v11, v11
	v_fma_f32 v10, -v10, v17, 1.0
	v_fma_f32 v9, v10, v11, v17
	v_min_f32_e32 v10, 0x7f7fffff, v8
	v_rcp_f32_e32 v11, v10
	s_nop 0
	v_fma_f32 v16, -v10, v11, 1.0
	v_fmac_f32_e32 v11, v16, v11
	v_fma_f32 v18, -v10, v11, 1.0
	v_fma_f32 v17, v18, v11, v11
	v_fma_f32 v10, -v10, v17, 1.0
	v_fma_f32 v8, v10, v11, v17
	s_waitcnt lgkmcnt(0)
	v_mov_b32_e32 v10, v4
	v_mov_b32_e32 v11, v6
	v_pk_mul_f32 v[8:9], v[10:11], v[8:9]
	v_pk_add_f32 v[10:11], v[12:13], 1.0 op_sel_hi:[1,0]
	s_nop 0
	v_min_f32_e32 v4, 0x7f7fffff, v11
	v_rcp_f32_e32 v6, v4
	s_nop 0
	v_fma_f32 v12, -v4, v6, 1.0
	v_fmac_f32_e32 v6, v12, v6
	v_fma_f32 v16, -v4, v6, 1.0
	v_fma_f32 v13, v16, v6, v6
	v_fma_f32 v4, -v4, v13, 1.0
	v_fma_f32 v11, v4, v6, v13
	v_min_f32_e32 v4, 0x7f7fffff, v10
	v_rcp_f32_e32 v6, v4
	s_nop 0
	v_fma_f32 v12, -v4, v6, 1.0
	v_fmac_f32_e32 v6, v12, v6
	v_fma_f32 v16, -v4, v6, 1.0
	v_fma_f32 v13, v16, v6, v6
	v_fma_f32 v4, -v4, v13, 1.0
	v_fma_f32 v10, v4, v6, v13
	v_mov_b32_e32 v6, v5
	v_pk_mul_f32 v[4:5], v[6:7], v[10:11]
	v_and_b32_sdwa v6, v9, v95 dst_sel:DWORD dst_unused:UNUSED_PAD src0_sel:WORD_1 src1_sel:DWORD
	v_and_b32_sdwa v7, v8, v95 dst_sel:DWORD dst_unused:UNUSED_PAD src0_sel:WORD_1 src1_sel:DWORD
	v_add3_u32 v7, v8, v7, s39
	v_add3_u32 v6, v9, v6, s39
	v_and_b32_sdwa v8, v5, v95 dst_sel:DWORD dst_unused:UNUSED_PAD src0_sel:WORD_1 src1_sel:DWORD
	v_and_b32_sdwa v9, v4, v95 dst_sel:DWORD dst_unused:UNUSED_PAD src0_sel:WORD_1 src1_sel:DWORD
	v_add3_u32 v5, v5, v8, s39
	v_add3_u32 v4, v4, v9, s39
	v_and_b32_e32 v5, 0xffff0000, v5
	v_and_b32_e32 v4, 0xffff0000, v4
	v_or_b32_sdwa v5, v5, v6 dst_sel:DWORD dst_unused:UNUSED_PAD src0_sel:DWORD src1_sel:WORD_1
	v_or_b32_sdwa v4, v4, v7 dst_sel:DWORD dst_unused:UNUSED_PAD src0_sel:DWORD src1_sel:WORD_1
	global_store_dwordx2 v[14:15], v[4:5], off
	s_cbranch_scc1 .LBB0_513
	s_mov_b64 s[26:27], 0

; DEVI float b2f(bfu b) { return __uint_as_float(((unsigned)b) << 16); }
; DEVI float sigmoidf_(float x) { return 1.f / (1.f + __expf(-x)); }
; DEVI float siluf_(float x) { return x / (1.f + __expf(-x)); }
; DEVI void h3_item(const Params& P, int l, int ck, int h, char* smem, int tid) {
;     ...
;     float rel = 0.f;
; #pragma unroll 8
;     for (int t = Lh; t < L; ++t) {
;       float f = lb + (1.f - lb) * sigmoidf_(b2f(KT[t * 136 + d]));
;       float q = siluf_(b2f(QT[t * 136 + d]));
;       rel += __logf(f);
;       QT[t * 136 + d] = f2b(q * __expf(rel));
;       KT[t * 136 + d] = f2b((1.f - f) * __expf(fminf(-rel, 80.f)));
;     }
.LBB0_549:
	ds_read_u16 v3, v1 offset:17408
	s_add_i32 s59, s59, -1
	s_cmp_lg_u32 s59, 0
	s_waitcnt lgkmcnt(0)
	v_lshlrev_b32_e32 v3, 16, v3
	v_mul_f32_e32 v3, 0xbfb8aa3b, v3
	v_exp_f32_e32 v3, v3
	s_nop 0
	v_add_f32_e32 v3, 1.0, v3
	v_min_f32_e32 v4, 0x7f7fffff, v3
	v_rcp_f32_e32 v5, v4
	s_nop 0
	v_fma_f32 v6, -v4, v5, 1.0
	v_fmac_f32_e32 v5, v6, v5
	v_fma_f32 v8, -v4, v5, 1.0
	v_fma_f32 v7, v8, v5, v5
	v_fma_f32 v4, -v4, v7, 1.0
	v_fma_f32 v3, v4, v5, v7
	ds_read_u16 v4, v1
	v_fma_f32 v3, v0, v3, v58
	s_waitcnt lgkmcnt(0)
	v_lshlrev_b32_e32 v4, 16, v4
	v_mul_f32_e32 v5, 0xbfb8aa3b, v4
	v_exp_f32_e32 v5, v5
	s_nop 0
	v_add_f32_e32 v5, 1.0, v5
	v_min_f32_e32 v6, 0x7f7fffff, v5
	v_rcp_f32_e32 v7, v6
	s_nop 0
	v_fma_f32 v8, -v6, v7, 1.0
	v_fmac_f32_e32 v7, v8, v7
	v_mul_f32_e32 v9, v4, v7
	v_fma_f32 v10, -v6, v9, v4
	v_fmac_f32_e32 v9, v10, v7
	v_fma_f32 v6, -v6, v9, v4
	v_cmp_gt_f32_e32 vcc, s34, v3
	v_fma_f32 v4, v6, v7, v9
	s_nop 0
	v_cndmask_b32_e64 v5, 0, 32, vcc
	v_ldexp_f32 v5, v3, v5
	v_log_f32_e32 v5, v5
	v_sub_f32_e32 v3, 1.0, v3
	v_mul_f32_e32 v6, 0x3f317217, v5
	v_fma_f32 v6, v5, s38, -v6
	v_fmac_f32_e32 v6, 0x3377d1cf, v5
	v_fmac_f32_e32 v6, 0x3f317217, v5
	v_cmp_lt_f32_e64 s[82:83], |v5|, s20
	s_nop 1
	v_cndmask_b32_e64 v5, v5, v6, s[82:83]
	v_cndmask_b32_e32 v6, 0, v193, vcc
	v_sub_f32_e32 v5, v5, v6
	v_add_f32_e32 v2, v2, v5
	v_mul_f32_e32 v5, 0x3fb8aa3b, v2
	v_exp_f32_e32 v5, v5
	s_nop 0
	v_mul_f32_e32 v4, v4, v5
	v_bfe_u32 v5, v4, 16, 1
	v_add3_u32 v4, v4, v5, s39
	ds_write_b16_d16_hi v1, v4
	v_min_f32_e64 v4, -v2, s4
	v_mul_f32_e32 v4, 0x3fb8aa3b, v4
	v_exp_f32_e32 v4, v4
	s_nop 0
	v_mul_f32_e32 v3, v3, v4
	v_bfe_u32 v4, v3, 16, 1
	v_add3_u32 v3, v3, v4, s39
	ds_write_b16_d16_hi v1, v3 offset:17408
	v_add_u32_e32 v1, 0x110, v1
	s_cbranch_scc1 .LBB0_549
	s_mov_b32 s55, s58

; DEVI float b2f(bfu b) { return __uint_as_float(((unsigned)b) << 16); }
; DEVI float sigmoidf_(float x) { return 1.f / (1.f + __expf(-x)); }
; DEVI float siluf_(float x) { return x / (1.f + __expf(-x)); }
; DEVI void h3_item(const Params& P, int l, int ck, int h, char* smem, int tid) {
;     ...
;     float rel = 0.f;
; #pragma unroll 8
;     for (int t = Lh; t < L; ++t) {
;       float f = lb + (1.f - lb) * sigmoidf_(b2f(KT[t * 136 + d]));
;       float q = siluf_(b2f(QT[t * 136 + d]));
;       rel += __logf(f);
;       QT[t * 136 + d] = f2b(q * __expf(rel));
;       KT[t * 136 + d] = f2b((1.f - f) * __expf(fminf(-rel, 80.f)));
;     }
.LBB0_553:
	ds_read_u16 v3, v1 offset:17408
	s_add_i32 s55, s55, 8
	s_cmp_lt_u32 s55, s51
	s_waitcnt lgkmcnt(0)
	v_lshlrev_b32_e32 v3, 16, v3
	v_mul_f32_e32 v3, 0xbfb8aa3b, v3
	v_exp_f32_e32 v3, v3
	s_nop 0
	v_add_f32_e32 v3, 1.0, v3
	v_min_f32_e32 v4, 0x7f7fffff, v3
	v_rcp_f32_e32 v5, v4
	s_nop 0
	v_fma_f32 v6, -v4, v5, 1.0
	v_fmac_f32_e32 v5, v6, v5
	v_fma_f32 v8, -v4, v5, 1.0
	v_fma_f32 v7, v8, v5, v5
	v_fma_f32 v4, -v4, v7, 1.0
	v_fma_f32 v3, v4, v5, v7
	ds_read_u16 v4, v1
	v_fma_f32 v3, v0, v3, v58
	s_waitcnt lgkmcnt(0)
	v_lshlrev_b32_e32 v4, 16, v4
	v_mul_f32_e32 v5, 0xbfb8aa3b, v4
	v_exp_f32_e32 v5, v5
	s_nop 0
	v_add_f32_e32 v5, 1.0, v5
	v_min_f32_e32 v6, 0x7f7fffff, v5
	v_rcp_f32_e32 v7, v6
	s_nop 0
	v_fma_f32 v8, -v6, v7, 1.0
	v_fmac_f32_e32 v7, v8, v7
	v_mul_f32_e32 v9, v4, v7
	v_fma_f32 v10, -v6, v9, v4
	v_fmac_f32_e32 v9, v10, v7
	v_fma_f32 v6, -v6, v9, v4
	v_cmp_gt_f32_e32 vcc, s34, v3
	v_fma_f32 v4, v6, v7, v9
	s_nop 0
	v_cndmask_b32_e64 v5, 0, 32, vcc
	v_ldexp_f32 v5, v3, v5
	v_log_f32_e32 v5, v5
	v_sub_f32_e32 v3, 1.0, v3
	v_mul_f32_e32 v6, 0x3f317217, v5
	v_fma_f32 v6, v5, s38, -v6
	v_fmac_f32_e32 v6, 0x3377d1cf, v5
	v_fmac_f32_e32 v6, 0x3f317217, v5
	v_cmp_lt_f32_e64 s[82:83], |v5|, s20
	s_nop 1
	v_cndmask_b32_e64 v5, v5, v6, s[82:83]
	v_cndmask_b32_e32 v6, 0, v193, vcc
	v_sub_f32_e32 v5, v5, v6
	v_add_f32_e32 v2, v2, v5
	v_mul_f32_e32 v5, 0x3fb8aa3b, v2
	v_exp_f32_e32 v5, v5
	s_nop 0
	v_mul_f32_e32 v4, v4, v5
	v_bfe_u32 v5, v4, 16, 1
	v_add3_u32 v4, v4, v5, s39
	ds_write_b16_d16_hi v1, v4
	v_min_f32_e64 v4, -v2, s4
	v_mul_f32_e32 v4, 0x3fb8aa3b, v4
	v_exp_f32_e32 v4, v4
	s_nop 0
	v_mul_f32_e32 v3, v3, v4
	v_bfe_u32 v4, v3, 16, 1
	v_add3_u32 v3, v3, v4, s39
	ds_write_b16_d16_hi v1, v3 offset:17408
	ds_read_u16 v3, v1 offset:17680
	s_waitcnt lgkmcnt(0)
	v_lshlrev_b32_e32 v3, 16, v3
	v_mul_f32_e32 v3, 0xbfb8aa3b, v3
	v_exp_f32_e32 v3, v3
	s_nop 0
	v_add_f32_e32 v3, 1.0, v3
	v_min_f32_e32 v4, 0x7f7fffff, v3
	v_rcp_f32_e32 v5, v4
	s_nop 0
	v_fma_f32 v6, -v4, v5, 1.0
	v_fmac_f32_e32 v5, v6, v5
	v_fma_f32 v8, -v4, v5, 1.0
	v_fma_f32 v7, v8, v5, v5
	v_fma_f32 v4, -v4, v7, 1.0
	v_fma_f32 v3, v4, v5, v7
	ds_read_u16 v4, v1 offset:272
	v_fma_f32 v3, v0, v3, v58
	s_waitcnt lgkmcnt(0)
	v_lshlrev_b32_e32 v4, 16, v4
	v_mul_f32_e32 v5, 0xbfb8aa3b, v4
	v_exp_f32_e32 v5, v5
	s_nop 0
	v_add_f32_e32 v5, 1.0, v5
	v_min_f32_e32 v6, 0x7f7fffff, v5
	v_rcp_f32_e32 v7, v6
	s_nop 0
	v_fma_f32 v8, -v6, v7, 1.0
	v_fmac_f32_e32 v7, v8, v7
	v_mul_f32_e32 v9, v4, v7
	v_fma_f32 v10, -v6, v9, v4
	v_fmac_f32_e32 v9, v10, v7
	v_fma_f32 v6, -v6, v9, v4
	v_cmp_gt_f32_e32 vcc, s34, v3
	v_fma_f32 v4, v6, v7, v9
	s_nop 0
	v_cndmask_b32_e64 v5, 0, 32, vcc
	v_ldexp_f32 v5, v3, v5
	v_log_f32_e32 v5, v5
	v_sub_f32_e32 v3, 1.0, v3
	v_mul_f32_e32 v6, 0x3f317217, v5
	v_fma_f32 v6, v5, s38, -v6
	v_fmac_f32_e32 v6, 0x3377d1cf, v5
	v_fmac_f32_e32 v6, 0x3f317217, v5
	v_cmp_lt_f32_e64 s[82:83], |v5|, s20
	s_nop 1
	v_cndmask_b32_e64 v5, v5, v6, s[82:83]
	v_cndmask_b32_e32 v6, 0, v193, vcc
	v_sub_f32_e32 v5, v5, v6
	v_add_f32_e32 v2, v2, v5
	v_mul_f32_e32 v5, 0x3fb8aa3b, v2
	v_exp_f32_e32 v5, v5
	s_nop 0
	v_mul_f32_e32 v4, v4, v5
	v_bfe_u32 v5, v4, 16, 1
	v_add3_u32 v4, v4, v5, s39
	ds_write_b16_d16_hi v1, v4 offset:272
	v_min_f32_e64 v4, -v2, s4
	v_mul_f32_e32 v4, 0x3fb8aa3b, v4
	v_exp_f32_e32 v4, v4
	s_nop 0
	v_mul_f32_e32 v3, v3, v4
	v_bfe_u32 v4, v3, 16, 1
	v_add3_u32 v3, v3, v4, s39
	ds_write_b16_d16_hi v1, v3 offset:17680
	ds_read_u16 v3, v1 offset:17952
	s_waitcnt lgkmcnt(0)
	v_lshlrev_b32_e32 v3, 16, v3
	v_mul_f32_e32 v3, 0xbfb8aa3b, v3
	v_exp_f32_e32 v3, v3
	s_nop 0
	v_add_f32_e32 v3, 1.0, v3
	v_min_f32_e32 v4, 0x7f7fffff, v3
	v_rcp_f32_e32 v5, v4
	s_nop 0
	v_fma_f32 v6, -v4, v5, 1.0
	v_fmac_f32_e32 v5, v6, v5
	v_fma_f32 v8, -v4, v5, 1.0
	v_fma_f32 v7, v8, v5, v5
	v_fma_f32 v4, -v4, v7, 1.0
	v_fma_f32 v3, v4, v5, v7
	ds_read_u16 v4, v1 offset:544
	v_fma_f32 v3, v0, v3, v58
	s_waitcnt lgkmcnt(0)
	v_lshlrev_b32_e32 v4, 16, v4
	v_mul_f32_e32 v5, 0xbfb8aa3b, v4
	v_exp_f32_e32 v5, v5
	s_nop 0
	v_add_f32_e32 v5, 1.0, v5
	v_min_f32_e32 v6, 0x7f7fffff, v5
	v_rcp_f32_e32 v7, v6
	s_nop 0
	v_fma_f32 v8, -v6, v7, 1.0
	v_fmac_f32_e32 v7, v8, v7
	v_mul_f32_e32 v9, v4, v7
	v_fma_f32 v10, -v6, v9, v4
	v_fmac_f32_e32 v9, v10, v7
	v_fma_f32 v6, -v6, v9, v4
	v_cmp_gt_f32_e32 vcc, s34, v3
	v_fma_f32 v4, v6, v7, v9
	s_nop 0
	v_cndmask_b32_e64 v5, 0, 32, vcc
	v_ldexp_f32 v5, v3, v5
	v_log_f32_e32 v5, v5
	v_sub_f32_e32 v3, 1.0, v3
	v_mul_f32_e32 v6, 0x3f317217, v5
	v_fma_f32 v6, v5, s38, -v6
	v_fmac_f32_e32 v6, 0x3377d1cf, v5
	v_fmac_f32_e32 v6, 0x3f317217, v5
	v_cmp_lt_f32_e64 s[82:83], |v5|, s20
	s_nop 1
	v_cndmask_b32_e64 v5, v5, v6, s[82:83]
	v_cndmask_b32_e32 v6, 0, v193, vcc
	v_sub_f32_e32 v5, v5, v6
	v_add_f32_e32 v2, v2, v5
	v_mul_f32_e32 v5, 0x3fb8aa3b, v2
	v_exp_f32_e32 v5, v5
	s_nop 0
	v_mul_f32_e32 v4, v4, v5
	v_bfe_u32 v5, v4, 16, 1
	v_add3_u32 v4, v4, v5, s39
	ds_write_b16_d16_hi v1, v4 offset:544
	v_min_f32_e64 v4, -v2, s4
	v_mul_f32_e32 v4, 0x3fb8aa3b, v4
	v_exp_f32_e32 v4, v4
	s_nop 0
	v_mul_f32_e32 v3, v3, v4
	v_bfe_u32 v4, v3, 16, 1
	v_add3_u32 v3, v3, v4, s39
	ds_write_b16_d16_hi v1, v3 offset:17952
	ds_read_u16 v3, v1 offset:18224
	s_waitcnt lgkmcnt(0)
	v_lshlrev_b32_e32 v3, 16, v3
	v_mul_f32_e32 v3, 0xbfb8aa3b, v3
	v_exp_f32_e32 v3, v3
	s_nop 0
	v_add_f32_e32 v3, 1.0, v3
	v_min_f32_e32 v4, 0x7f7fffff, v3
	v_rcp_f32_e32 v5, v4
	s_nop 0
	v_fma_f32 v6, -v4, v5, 1.0
	v_fmac_f32_e32 v5, v6, v5
	v_fma_f32 v8, -v4, v5, 1.0
	v_fma_f32 v7, v8, v5, v5
	v_fma_f32 v4, -v4, v7, 1.0
	v_fma_f32 v3, v4, v5, v7
	ds_read_u16 v4, v1 offset:816
	v_fma_f32 v3, v0, v3, v58
	s_waitcnt lgkmcnt(0)
; DEVI float b2f(bfu b) { return __uint_as_float(((unsigned)b) << 16); }
; DEVI float sigmoidf_(float x) { return 1.f / (1.f + __expf(-x)); }
; DEVI float siluf_(float x) { return x / (1.f + __expf(-x)); }
; DEVI void h3_item(const Params& P, int l, int ck, int h, char* smem, int tid) {
;     ...
;     float rel = 0.f;
; #pragma unroll 8
;     for (int t = Lh; t < L; ++t) {
;       float f = lb + (1.f - lb) * sigmoidf_(b2f(KT[t * 136 + d]));
;       float q = siluf_(b2f(QT[t * 136 + d]));
;       rel += __logf(f);
;       QT[t * 136 + d] = f2b(q * __expf(rel));
;       KT[t * 136 + d] = f2b((1.f - f) * __expf(fminf(-rel, 80.f)));
;     }
	v_lshlrev_b32_e32 v4, 16, v4
	v_mul_f32_e32 v5, 0xbfb8aa3b, v4
	v_exp_f32_e32 v5, v5
	s_nop 0
	v_add_f32_e32 v5, 1.0, v5
	v_min_f32_e32 v6, 0x7f7fffff, v5
	v_rcp_f32_e32 v7, v6
	s_nop 0
	v_fma_f32 v8, -v6, v7, 1.0
	v_fmac_f32_e32 v7, v8, v7
	v_mul_f32_e32 v9, v4, v7
	v_fma_f32 v10, -v6, v9, v4
	v_fmac_f32_e32 v9, v10, v7
	v_fma_f32 v6, -v6, v9, v4
	v_cmp_gt_f32_e32 vcc, s34, v3
	v_fma_f32 v4, v6, v7, v9
	s_nop 0
	v_cndmask_b32_e64 v5, 0, 32, vcc
	v_ldexp_f32 v5, v3, v5
	v_log_f32_e32 v5, v5
	v_sub_f32_e32 v3, 1.0, v3
	v_mul_f32_e32 v6, 0x3f317217, v5
	v_fma_f32 v6, v5, s38, -v6
	v_fmac_f32_e32 v6, 0x3377d1cf, v5
	v_fmac_f32_e32 v6, 0x3f317217, v5
	v_cmp_lt_f32_e64 s[82:83], |v5|, s20
	s_nop 1
	v_cndmask_b32_e64 v5, v5, v6, s[82:83]
	v_cndmask_b32_e32 v6, 0, v193, vcc
	v_sub_f32_e32 v5, v5, v6
	v_add_f32_e32 v2, v2, v5
	v_mul_f32_e32 v5, 0x3fb8aa3b, v2
	v_exp_f32_e32 v5, v5
	s_nop 0
	v_mul_f32_e32 v4, v4, v5
	v_bfe_u32 v5, v4, 16, 1
	v_add3_u32 v4, v4, v5, s39
	ds_write_b16_d16_hi v1, v4 offset:816
	v_min_f32_e64 v4, -v2, s4
	v_mul_f32_e32 v4, 0x3fb8aa3b, v4
	v_exp_f32_e32 v4, v4
	s_nop 0
	v_mul_f32_e32 v3, v3, v4
	v_bfe_u32 v4, v3, 16, 1
	v_add3_u32 v3, v3, v4, s39
	ds_write_b16_d16_hi v1, v3 offset:18224
	ds_read_u16 v3, v1 offset:18496
	s_waitcnt lgkmcnt(0)
	v_lshlrev_b32_e32 v3, 16, v3
	v_mul_f32_e32 v3, 0xbfb8aa3b, v3
	v_exp_f32_e32 v3, v3
	s_nop 0
	v_add_f32_e32 v3, 1.0, v3
	v_min_f32_e32 v4, 0x7f7fffff, v3
	v_rcp_f32_e32 v5, v4
	s_nop 0
	v_fma_f32 v6, -v4, v5, 1.0
	v_fmac_f32_e32 v5, v6, v5
	v_fma_f32 v8, -v4, v5, 1.0
	v_fma_f32 v7, v8, v5, v5
	v_fma_f32 v4, -v4, v7, 1.0
	v_fma_f32 v3, v4, v5, v7
	ds_read_u16 v4, v1 offset:1088
	v_fma_f32 v3, v0, v3, v58
	s_waitcnt lgkmcnt(0)
	v_lshlrev_b32_e32 v4, 16, v4
	v_mul_f32_e32 v5, 0xbfb8aa3b, v4
	v_exp_f32_e32 v5, v5
	s_nop 0
	v_add_f32_e32 v5, 1.0, v5
	v_min_f32_e32 v6, 0x7f7fffff, v5
	v_rcp_f32_e32 v7, v6
	s_nop 0
	v_fma_f32 v8, -v6, v7, 1.0
	v_fmac_f32_e32 v7, v8, v7
	v_mul_f32_e32 v9, v4, v7
	v_fma_f32 v10, -v6, v9, v4
	v_fmac_f32_e32 v9, v10, v7
	v_fma_f32 v6, -v6, v9, v4
	v_cmp_gt_f32_e32 vcc, s34, v3
	v_fma_f32 v4, v6, v7, v9
	s_nop 0
	v_cndmask_b32_e64 v5, 0, 32, vcc
	v_ldexp_f32 v5, v3, v5
	v_log_f32_e32 v5, v5
	v_sub_f32_e32 v3, 1.0, v3
	v_mul_f32_e32 v6, 0x3f317217, v5
	v_fma_f32 v6, v5, s38, -v6
	v_fmac_f32_e32 v6, 0x3377d1cf, v5
	v_fmac_f32_e32 v6, 0x3f317217, v5
	v_cmp_lt_f32_e64 s[82:83], |v5|, s20
	s_nop 1
	v_cndmask_b32_e64 v5, v5, v6, s[82:83]
	v_cndmask_b32_e32 v6, 0, v193, vcc
	v_sub_f32_e32 v5, v5, v6
	v_add_f32_e32 v2, v2, v5
	v_mul_f32_e32 v5, 0x3fb8aa3b, v2
	v_exp_f32_e32 v5, v5
	s_nop 0
	v_mul_f32_e32 v4, v4, v5
	v_bfe_u32 v5, v4, 16, 1
	v_add3_u32 v4, v4, v5, s39
	ds_write_b16_d16_hi v1, v4 offset:1088
	v_min_f32_e64 v4, -v2, s4
	v_mul_f32_e32 v4, 0x3fb8aa3b, v4
	v_exp_f32_e32 v4, v4
	s_nop 0
	v_mul_f32_e32 v3, v3, v4
	v_bfe_u32 v4, v3, 16, 1
	v_add3_u32 v3, v3, v4, s39
	ds_write_b16_d16_hi v1, v3 offset:18496
	ds_read_u16 v3, v1 offset:18768
	s_waitcnt lgkmcnt(0)
	v_lshlrev_b32_e32 v3, 16, v3
	v_mul_f32_e32 v3, 0xbfb8aa3b, v3
	v_exp_f32_e32 v3, v3
	s_nop 0
	v_add_f32_e32 v3, 1.0, v3
	v_min_f32_e32 v4, 0x7f7fffff, v3
	v_rcp_f32_e32 v5, v4
	s_nop 0
	v_fma_f32 v6, -v4, v5, 1.0
	v_fmac_f32_e32 v5, v6, v5
	v_fma_f32 v8, -v4, v5, 1.0
	v_fma_f32 v7, v8, v5, v5
	v_fma_f32 v4, -v4, v7, 1.0
	v_fma_f32 v3, v4, v5, v7
	ds_read_u16 v4, v1 offset:1360
	v_fma_f32 v3, v0, v3, v58
	s_waitcnt lgkmcnt(0)
; DEVI float b2f(bfu b) { return __uint_as_float(((unsigned)b) << 16); }
; DEVI float sigmoidf_(float x) { return 1.f / (1.f + __expf(-x)); }
; DEVI float siluf_(float x) { return x / (1.f + __expf(-x)); }
; DEVI void h3_item(const Params& P, int l, int ck, int h, char* smem, int tid) {
;     ...
;     float rel = 0.f;
; #pragma unroll 8
;     for (int t = Lh; t < L; ++t) {
;       float f = lb + (1.f - lb) * sigmoidf_(b2f(KT[t * 136 + d]));
;       float q = siluf_(b2f(QT[t * 136 + d]));
;       rel += __logf(f);
;       QT[t * 136 + d] = f2b(q * __expf(rel));
;       KT[t * 136 + d] = f2b((1.f - f) * __expf(fminf(-rel, 80.f)));
;     }
	v_lshlrev_b32_e32 v4, 16, v4
	v_mul_f32_e32 v5, 0xbfb8aa3b, v4
	v_exp_f32_e32 v5, v5
	s_nop 0
	v_add_f32_e32 v5, 1.0, v5
	v_min_f32_e32 v6, 0x7f7fffff, v5
	v_rcp_f32_e32 v7, v6
	s_nop 0
	v_fma_f32 v8, -v6, v7, 1.0
	v_fmac_f32_e32 v7, v8, v7
	v_mul_f32_e32 v9, v4, v7
	v_fma_f32 v10, -v6, v9, v4
	v_fmac_f32_e32 v9, v10, v7
	v_fma_f32 v6, -v6, v9, v4
	v_cmp_gt_f32_e32 vcc, s34, v3
	v_fma_f32 v4, v6, v7, v9
	s_nop 0
	v_cndmask_b32_e64 v5, 0, 32, vcc
	v_ldexp_f32 v5, v3, v5
	v_log_f32_e32 v5, v5
	v_sub_f32_e32 v3, 1.0, v3
	v_mul_f32_e32 v6, 0x3f317217, v5
	v_fma_f32 v6, v5, s38, -v6
	v_fmac_f32_e32 v6, 0x3377d1cf, v5
	v_fmac_f32_e32 v6, 0x3f317217, v5
	v_cmp_lt_f32_e64 s[82:83], |v5|, s20
	s_nop 1
	v_cndmask_b32_e64 v5, v5, v6, s[82:83]
	v_cndmask_b32_e32 v6, 0, v193, vcc
	v_sub_f32_e32 v5, v5, v6
	v_add_f32_e32 v2, v2, v5
	v_mul_f32_e32 v5, 0x3fb8aa3b, v2
	v_exp_f32_e32 v5, v5
	s_nop 0
	v_mul_f32_e32 v4, v4, v5
	v_bfe_u32 v5, v4, 16, 1
	v_add3_u32 v4, v4, v5, s39
	ds_write_b16_d16_hi v1, v4 offset:1360
	v_min_f32_e64 v4, -v2, s4
	v_mul_f32_e32 v4, 0x3fb8aa3b, v4
	v_exp_f32_e32 v4, v4
	s_nop 0
	v_mul_f32_e32 v3, v3, v4
	v_bfe_u32 v4, v3, 16, 1
	v_add3_u32 v3, v3, v4, s39
	ds_write_b16_d16_hi v1, v3 offset:18768
	ds_read_u16 v3, v1 offset:19040
	s_waitcnt lgkmcnt(0)
	v_lshlrev_b32_e32 v3, 16, v3
	v_mul_f32_e32 v3, 0xbfb8aa3b, v3
	v_exp_f32_e32 v3, v3
	s_nop 0
	v_add_f32_e32 v3, 1.0, v3
	v_min_f32_e32 v4, 0x7f7fffff, v3
	v_rcp_f32_e32 v5, v4
	s_nop 0
	v_fma_f32 v6, -v4, v5, 1.0
	v_fmac_f32_e32 v5, v6, v5
	v_fma_f32 v8, -v4, v5, 1.0
	v_fma_f32 v7, v8, v5, v5
	v_fma_f32 v4, -v4, v7, 1.0
	v_fma_f32 v3, v4, v5, v7
	ds_read_u16 v4, v1 offset:1632
	v_fma_f32 v3, v0, v3, v58
	s_waitcnt lgkmcnt(0)
	v_lshlrev_b32_e32 v4, 16, v4
	v_mul_f32_e32 v5, 0xbfb8aa3b, v4
	v_exp_f32_e32 v5, v5
	s_nop 0
	v_add_f32_e32 v5, 1.0, v5
	v_min_f32_e32 v6, 0x7f7fffff, v5
	v_rcp_f32_e32 v7, v6
	s_nop 0
	v_fma_f32 v8, -v6, v7, 1.0
	v_fmac_f32_e32 v7, v8, v7
	v_mul_f32_e32 v9, v4, v7
	v_fma_f32 v10, -v6, v9, v4
	v_fmac_f32_e32 v9, v10, v7
	v_fma_f32 v6, -v6, v9, v4
	v_cmp_gt_f32_e32 vcc, s34, v3
	v_fma_f32 v4, v6, v7, v9
	s_nop 0
	v_cndmask_b32_e64 v5, 0, 32, vcc
	v_ldexp_f32 v5, v3, v5
	v_log_f32_e32 v5, v5
	v_sub_f32_e32 v3, 1.0, v3
	v_mul_f32_e32 v6, 0x3f317217, v5
	v_fma_f32 v6, v5, s38, -v6
	v_fmac_f32_e32 v6, 0x3377d1cf, v5
	v_fmac_f32_e32 v6, 0x3f317217, v5
	v_cmp_lt_f32_e64 s[82:83], |v5|, s20
	s_nop 1
	v_cndmask_b32_e64 v5, v5, v6, s[82:83]
	v_cndmask_b32_e32 v6, 0, v193, vcc
	v_sub_f32_e32 v5, v5, v6
	v_add_f32_e32 v2, v2, v5
	v_mul_f32_e32 v5, 0x3fb8aa3b, v2
	v_exp_f32_e32 v5, v5
	s_nop 0
	v_mul_f32_e32 v4, v4, v5
	v_bfe_u32 v5, v4, 16, 1
	v_add3_u32 v4, v4, v5, s39
	ds_write_b16_d16_hi v1, v4 offset:1632
	v_min_f32_e64 v4, -v2, s4
	v_mul_f32_e32 v4, 0x3fb8aa3b, v4
	v_exp_f32_e32 v4, v4
	s_nop 0
	v_mul_f32_e32 v3, v3, v4
	v_bfe_u32 v4, v3, 16, 1
	v_add3_u32 v3, v3, v4, s39
	ds_write_b16_d16_hi v1, v3 offset:19040
	ds_read_u16 v3, v1 offset:19312
	s_waitcnt lgkmcnt(0)
	v_lshlrev_b32_e32 v3, 16, v3
	v_mul_f32_e32 v3, 0xbfb8aa3b, v3
	v_exp_f32_e32 v3, v3
	s_nop 0
	v_add_f32_e32 v3, 1.0, v3
	v_min_f32_e32 v4, 0x7f7fffff, v3
	v_rcp_f32_e32 v5, v4
	s_nop 0
	v_fma_f32 v6, -v4, v5, 1.0
	v_fmac_f32_e32 v5, v6, v5
	v_fma_f32 v8, -v4, v5, 1.0
	v_fma_f32 v7, v8, v5, v5
	v_fma_f32 v4, -v4, v7, 1.0
	v_fma_f32 v3, v4, v5, v7
	ds_read_u16 v4, v1 offset:1904
	v_fma_f32 v3, v0, v3, v58
	s_waitcnt lgkmcnt(0)
	v_lshlrev_b32_e32 v4, 16, v4
	v_mul_f32_e32 v5, 0xbfb8aa3b, v4
	v_exp_f32_e32 v5, v5
	s_nop 0
	v_add_f32_e32 v5, 1.0, v5
	v_min_f32_e32 v6, 0x7f7fffff, v5
	v_rcp_f32_e32 v7, v6
	s_nop 0
	v_fma_f32 v8, -v6, v7, 1.0
	v_fmac_f32_e32 v7, v8, v7
	v_mul_f32_e32 v9, v4, v7
	v_fma_f32 v10, -v6, v9, v4
	v_fmac_f32_e32 v9, v10, v7
	v_fma_f32 v6, -v6, v9, v4
	v_cmp_gt_f32_e32 vcc, s34, v3
	v_fma_f32 v4, v6, v7, v9
	s_nop 0
	v_cndmask_b32_e64 v5, 0, 32, vcc
	v_ldexp_f32 v5, v3, v5
	v_log_f32_e32 v5, v5
	v_sub_f32_e32 v3, 1.0, v3
	v_mul_f32_e32 v6, 0x3f317217, v5
	v_fma_f32 v6, v5, s38, -v6
	v_fmac_f32_e32 v6, 0x3377d1cf, v5
	v_fmac_f32_e32 v6, 0x3f317217, v5
	v_cmp_lt_f32_e64 s[82:83], |v5|, s20
	s_nop 1
	v_cndmask_b32_e64 v5, v5, v6, s[82:83]
	v_cndmask_b32_e32 v6, 0, v193, vcc
	v_sub_f32_e32 v5, v5, v6
	v_add_f32_e32 v2, v2, v5
	v_mul_f32_e32 v5, 0x3fb8aa3b, v2
	v_exp_f32_e32 v5, v5
	s_nop 0
	v_mul_f32_e32 v4, v4, v5
	v_bfe_u32 v5, v4, 16, 1
	v_add3_u32 v4, v4, v5, s39
	ds_write_b16_d16_hi v1, v4 offset:1904
	v_min_f32_e64 v4, -v2, s4
	v_mul_f32_e32 v4, 0x3fb8aa3b, v4
	v_exp_f32_e32 v4, v4
	s_nop 0
	v_mul_f32_e32 v3, v3, v4
	v_bfe_u32 v4, v3, 16, 1
	v_add3_u32 v3, v3, v4, s39
	ds_write_b16_d16_hi v1, v3 offset:19312
	v_add_u32_e32 v1, 0x880, v1
	s_cbranch_scc1 .LBB0_553

; DEVI float b2f(bfu b) { return __uint_as_float(((unsigned)b) << 16); }
; DEVI float sigmoidf_(float x) { return 1.f / (1.f + __expf(-x)); }
; DEVI float siluf_(float x) { return x / (1.f + __expf(-x)); }
; DEVI void h3_item(const Params& P, int l, int ck, int h, char* smem, int tid) {
;     ...
;   if (hf == 0) {
;     float rel = 0.f;
; #pragma unroll 8
;     for (int t = Lh - 1; t >= 0; --t) {
;       float f = lb + (1.f - lb) * sigmoidf_(b2f(KT[t * 136 + d]));
;       float q = siluf_(b2f(QT[t * 136 + d]));
;       QT[t * 136 + d] = f2b(q * __expf(fminf(rel, 80.f)));
;       KT[t * 136 + d] = f2b((1.f - f) * __expf(-rel));
;       rel -= __logf(f);
;     }
;     bmid[d] = -rel;
.LBB0_556:
	v_add_u32_e32 v2, s55, v205
	ds_read_u16 v3, v2 offset:19312
	s_addk_i32 s55, 0xf780
	s_cmp_eq_u32 s55, 0
	s_waitcnt lgkmcnt(0)
	v_lshlrev_b32_e32 v3, 16, v3
	v_mul_f32_e32 v3, 0xbfb8aa3b, v3
	v_exp_f32_e32 v3, v3
	s_nop 0
	v_add_f32_e32 v3, 1.0, v3
	v_min_f32_e32 v4, 0x7f7fffff, v3
	v_rcp_f32_e32 v5, v4
	s_nop 0
	v_fma_f32 v6, -v4, v5, 1.0
	v_fmac_f32_e32 v5, v6, v5
	v_fma_f32 v8, -v4, v5, 1.0
	v_fma_f32 v7, v8, v5, v5
	v_fma_f32 v4, -v4, v7, 1.0
	v_fma_f32 v3, v4, v5, v7
	ds_read_u16 v4, v2 offset:1904
	v_fma_f32 v3, v0, v3, v58
	s_waitcnt lgkmcnt(0)
	v_lshlrev_b32_e32 v4, 16, v4
	v_mul_f32_e32 v5, 0xbfb8aa3b, v4
	v_exp_f32_e32 v5, v5
	s_nop 0
	v_add_f32_e32 v5, 1.0, v5
	v_min_f32_e32 v6, 0x7f7fffff, v5
	v_rcp_f32_e32 v7, v6
	s_nop 0
	v_fma_f32 v8, -v6, v7, 1.0
	v_fmac_f32_e32 v7, v8, v7
	v_mul_f32_e32 v9, v4, v7
	v_fma_f32 v10, -v6, v9, v4
	v_fmac_f32_e32 v9, v10, v7
	v_fma_f32 v6, -v6, v9, v4
	v_fma_f32 v4, v6, v7, v9
	v_max_f32_e32 v5, v1, v1
	v_min_f32_e32 v5, 0x42a00000, v5
	v_mul_f32_e32 v5, 0x3fb8aa3b, v5
	v_exp_f32_e32 v5, v5
	v_cmp_gt_f32_e32 vcc, s34, v3
	v_mul_f32_e32 v4, v5, v4
	v_bfe_u32 v5, v4, 16, 1
	v_add3_u32 v4, v4, v5, s39
	v_mul_f32_e32 v5, 0xbfb8aa3b, v1
	v_exp_f32_e32 v5, v5
	ds_write_b16_d16_hi v2, v4 offset:1904
	v_sub_f32_e32 v4, 1.0, v3
	v_mul_f32_e32 v4, v5, v4
	v_bfe_u32 v5, v4, 16, 1
	v_add3_u32 v4, v4, v5, s39
	ds_write_b16_d16_hi v2, v4 offset:19312
	v_cndmask_b32_e64 v4, 0, 32, vcc
	v_ldexp_f32 v3, v3, v4
	v_log_f32_e32 v3, v3
	s_nop 0
	v_mul_f32_e32 v4, 0x3f317217, v3
	v_fma_f32 v4, v3, s38, -v4
	v_fmac_f32_e32 v4, 0x3377d1cf, v3
	v_fmac_f32_e32 v4, 0x3f317217, v3
	v_cmp_lt_f32_e64 s[82:83], |v3|, s20
	s_nop 1
	v_cndmask_b32_e64 v3, v3, v4, s[82:83]
	v_cndmask_b32_e32 v4, 0, v193, vcc
	v_sub_f32_e32 v3, v3, v4
	v_sub_f32_e32 v1, v1, v3
	ds_read_u16 v3, v2 offset:19040
	s_waitcnt lgkmcnt(0)
	v_lshlrev_b32_e32 v3, 16, v3
	v_mul_f32_e32 v3, 0xbfb8aa3b, v3
	v_exp_f32_e32 v3, v3
	s_nop 0
	v_add_f32_e32 v3, 1.0, v3
	v_min_f32_e32 v4, 0x7f7fffff, v3
	v_rcp_f32_e32 v5, v4
	s_nop 0
	v_fma_f32 v6, -v4, v5, 1.0
	v_fmac_f32_e32 v5, v6, v5
	v_fma_f32 v8, -v4, v5, 1.0
	v_fma_f32 v7, v8, v5, v5
	v_fma_f32 v4, -v4, v7, 1.0
	v_fma_f32 v3, v4, v5, v7
	ds_read_u16 v4, v2 offset:1632
	v_fma_f32 v3, v0, v3, v58
	s_waitcnt lgkmcnt(0)
	v_lshlrev_b32_e32 v4, 16, v4
	v_mul_f32_e32 v5, 0xbfb8aa3b, v4
	v_exp_f32_e32 v5, v5
	s_nop 0
	v_add_f32_e32 v5, 1.0, v5
	v_min_f32_e32 v6, 0x7f7fffff, v5
	v_rcp_f32_e32 v7, v6
	s_nop 0
	v_fma_f32 v8, -v6, v7, 1.0
	v_fmac_f32_e32 v7, v8, v7
	v_mul_f32_e32 v9, v4, v7
	v_fma_f32 v10, -v6, v9, v4
	v_fmac_f32_e32 v9, v10, v7
	v_fma_f32 v6, -v6, v9, v4
	v_fma_f32 v4, v6, v7, v9
	v_min_f32_e32 v5, 0x42a00000, v1
	v_mul_f32_e32 v5, 0x3fb8aa3b, v5
	v_exp_f32_e32 v5, v5
	v_cmp_gt_f32_e32 vcc, s34, v3
	v_mul_f32_e32 v4, v5, v4
	v_bfe_u32 v5, v4, 16, 1
	v_add3_u32 v4, v4, v5, s39
	v_mul_f32_e32 v5, 0xbfb8aa3b, v1
	v_exp_f32_e32 v5, v5
	ds_write_b16_d16_hi v2, v4 offset:1632
	v_sub_f32_e32 v4, 1.0, v3
	v_mul_f32_e32 v4, v5, v4
	v_bfe_u32 v5, v4, 16, 1
	v_add3_u32 v4, v4, v5, s39
	ds_write_b16_d16_hi v2, v4 offset:19040
	v_cndmask_b32_e64 v4, 0, 32, vcc
	v_ldexp_f32 v3, v3, v4
	v_log_f32_e32 v3, v3
	s_nop 0
	v_mul_f32_e32 v4, 0x3f317217, v3
	v_fma_f32 v4, v3, s38, -v4
	v_fmac_f32_e32 v4, 0x3377d1cf, v3
	v_fmac_f32_e32 v4, 0x3f317217, v3
	v_cmp_lt_f32_e64 s[82:83], |v3|, s20
	s_nop 1
	v_cndmask_b32_e64 v3, v3, v4, s[82:83]
	v_cndmask_b32_e32 v4, 0, v193, vcc
	v_sub_f32_e32 v3, v3, v4
	v_sub_f32_e32 v1, v1, v3
	ds_read_u16 v3, v2 offset:18768
	s_waitcnt lgkmcnt(0)
	v_lshlrev_b32_e32 v3, 16, v3
	v_mul_f32_e32 v3, 0xbfb8aa3b, v3
	v_exp_f32_e32 v3, v3
	s_nop 0
	v_add_f32_e32 v3, 1.0, v3
	v_min_f32_e32 v4, 0x7f7fffff, v3
	v_rcp_f32_e32 v5, v4
	s_nop 0
	v_fma_f32 v6, -v4, v5, 1.0
	v_fmac_f32_e32 v5, v6, v5
	v_fma_f32 v8, -v4, v5, 1.0
	v_fma_f32 v7, v8, v5, v5
	v_fma_f32 v4, -v4, v7, 1.0
	v_fma_f32 v3, v4, v5, v7
	ds_read_u16 v4, v2 offset:1360
	v_fma_f32 v3, v0, v3, v58
	s_waitcnt lgkmcnt(0)
	v_lshlrev_b32_e32 v4, 16, v4
	v_mul_f32_e32 v5, 0xbfb8aa3b, v4
	v_exp_f32_e32 v5, v5
	s_nop 0
	v_add_f32_e32 v5, 1.0, v5
	v_min_f32_e32 v6, 0x7f7fffff, v5
	v_rcp_f32_e32 v7, v6
	s_nop 0
	v_fma_f32 v8, -v6, v7, 1.0
	v_fmac_f32_e32 v7, v8, v7
	v_mul_f32_e32 v9, v4, v7
	v_fma_f32 v10, -v6, v9, v4
	v_fmac_f32_e32 v9, v10, v7
	v_fma_f32 v6, -v6, v9, v4
	v_fma_f32 v4, v6, v7, v9
	v_min_f32_e32 v5, 0x42a00000, v1
	v_mul_f32_e32 v5, 0x3fb8aa3b, v5
	v_exp_f32_e32 v5, v5
	v_cmp_gt_f32_e32 vcc, s34, v3
	v_mul_f32_e32 v4, v5, v4
	v_bfe_u32 v5, v4, 16, 1
	v_add3_u32 v4, v4, v5, s39
	v_mul_f32_e32 v5, 0xbfb8aa3b, v1
	v_exp_f32_e32 v5, v5
	ds_write_b16_d16_hi v2, v4 offset:1360
	v_sub_f32_e32 v4, 1.0, v3
	v_mul_f32_e32 v4, v5, v4
	v_bfe_u32 v5, v4, 16, 1
	v_add3_u32 v4, v4, v5, s39
	ds_write_b16_d16_hi v2, v4 offset:18768
	v_cndmask_b32_e64 v4, 0, 32, vcc
	v_ldexp_f32 v3, v3, v4
	v_log_f32_e32 v3, v3
	s_nop 0
	v_mul_f32_e32 v4, 0x3f317217, v3
	v_fma_f32 v4, v3, s38, -v4
	v_fmac_f32_e32 v4, 0x3377d1cf, v3
	v_fmac_f32_e32 v4, 0x3f317217, v3
	v_cmp_lt_f32_e64 s[82:83], |v3|, s20
	s_nop 1
	v_cndmask_b32_e64 v3, v3, v4, s[82:83]
	v_cndmask_b32_e32 v4, 0, v193, vcc
	v_sub_f32_e32 v3, v3, v4
	v_sub_f32_e32 v1, v1, v3
	ds_read_u16 v3, v2 offset:18496
	s_waitcnt lgkmcnt(0)
	v_lshlrev_b32_e32 v3, 16, v3
	v_mul_f32_e32 v3, 0xbfb8aa3b, v3
	v_exp_f32_e32 v3, v3
	s_nop 0
	v_add_f32_e32 v3, 1.0, v3
	v_min_f32_e32 v4, 0x7f7fffff, v3
	v_rcp_f32_e32 v5, v4
	s_nop 0
	v_fma_f32 v6, -v4, v5, 1.0
	v_fmac_f32_e32 v5, v6, v5
	v_fma_f32 v8, -v4, v5, 1.0
	v_fma_f32 v7, v8, v5, v5
	v_fma_f32 v4, -v4, v7, 1.0
	v_fma_f32 v3, v4, v5, v7
	ds_read_u16 v4, v2 offset:1088
	v_fma_f32 v3, v0, v3, v58
	s_waitcnt lgkmcnt(0)
; DEVI float b2f(bfu b) { return __uint_as_float(((unsigned)b) << 16); }
; DEVI float sigmoidf_(float x) { return 1.f / (1.f + __expf(-x)); }
; DEVI float siluf_(float x) { return x / (1.f + __expf(-x)); }
; DEVI void h3_item(const Params& P, int l, int ck, int h, char* smem, int tid) {
;     ...
;   if (hf == 0) {
;     float rel = 0.f;
; #pragma unroll 8
;     for (int t = Lh - 1; t >= 0; --t) {
;       float f = lb + (1.f - lb) * sigmoidf_(b2f(KT[t * 136 + d]));
;       float q = siluf_(b2f(QT[t * 136 + d]));
;       QT[t * 136 + d] = f2b(q * __expf(fminf(rel, 80.f)));
;       KT[t * 136 + d] = f2b((1.f - f) * __expf(-rel));
;       rel -= __logf(f);
;     }
;     bmid[d] = -rel;
	v_lshlrev_b32_e32 v4, 16, v4
	v_mul_f32_e32 v5, 0xbfb8aa3b, v4
	v_exp_f32_e32 v5, v5
	s_nop 0
	v_add_f32_e32 v5, 1.0, v5
	v_min_f32_e32 v6, 0x7f7fffff, v5
	v_rcp_f32_e32 v7, v6
	s_nop 0
	v_fma_f32 v8, -v6, v7, 1.0
	v_fmac_f32_e32 v7, v8, v7
	v_mul_f32_e32 v9, v4, v7
	v_fma_f32 v10, -v6, v9, v4
	v_fmac_f32_e32 v9, v10, v7
	v_fma_f32 v6, -v6, v9, v4
	v_fma_f32 v4, v6, v7, v9
	v_min_f32_e32 v5, 0x42a00000, v1
	v_mul_f32_e32 v5, 0x3fb8aa3b, v5
	v_exp_f32_e32 v5, v5
	v_cmp_gt_f32_e32 vcc, s34, v3
	v_mul_f32_e32 v4, v5, v4
	v_bfe_u32 v5, v4, 16, 1
	v_add3_u32 v4, v4, v5, s39
	v_mul_f32_e32 v5, 0xbfb8aa3b, v1
	v_exp_f32_e32 v5, v5
	ds_write_b16_d16_hi v2, v4 offset:1088
	v_sub_f32_e32 v4, 1.0, v3
	v_mul_f32_e32 v4, v5, v4
	v_bfe_u32 v5, v4, 16, 1
	v_add3_u32 v4, v4, v5, s39
	ds_write_b16_d16_hi v2, v4 offset:18496
	v_cndmask_b32_e64 v4, 0, 32, vcc
	v_ldexp_f32 v3, v3, v4
	v_log_f32_e32 v3, v3
	s_nop 0
	v_mul_f32_e32 v4, 0x3f317217, v3
	v_fma_f32 v4, v3, s38, -v4
	v_fmac_f32_e32 v4, 0x3377d1cf, v3
	v_fmac_f32_e32 v4, 0x3f317217, v3
	v_cmp_lt_f32_e64 s[82:83], |v3|, s20
	s_nop 1
	v_cndmask_b32_e64 v3, v3, v4, s[82:83]
	v_cndmask_b32_e32 v4, 0, v193, vcc
	v_sub_f32_e32 v3, v3, v4
	v_sub_f32_e32 v1, v1, v3
	ds_read_u16 v3, v2 offset:18224
	s_waitcnt lgkmcnt(0)
	v_lshlrev_b32_e32 v3, 16, v3
	v_mul_f32_e32 v3, 0xbfb8aa3b, v3
	v_exp_f32_e32 v3, v3
	s_nop 0
	v_add_f32_e32 v3, 1.0, v3
	v_min_f32_e32 v4, 0x7f7fffff, v3
	v_rcp_f32_e32 v5, v4
	s_nop 0
	v_fma_f32 v6, -v4, v5, 1.0
	v_fmac_f32_e32 v5, v6, v5
	v_fma_f32 v8, -v4, v5, 1.0
	v_fma_f32 v7, v8, v5, v5
	v_fma_f32 v4, -v4, v7, 1.0
	v_fma_f32 v3, v4, v5, v7
	ds_read_u16 v4, v2 offset:816
	v_fma_f32 v3, v0, v3, v58
	s_waitcnt lgkmcnt(0)
	v_lshlrev_b32_e32 v4, 16, v4
	v_mul_f32_e32 v5, 0xbfb8aa3b, v4
	v_exp_f32_e32 v5, v5
	s_nop 0
	v_add_f32_e32 v5, 1.0, v5
	v_min_f32_e32 v6, 0x7f7fffff, v5
	v_rcp_f32_e32 v7, v6
	s_nop 0
	v_fma_f32 v8, -v6, v7, 1.0
	v_fmac_f32_e32 v7, v8, v7
	v_mul_f32_e32 v9, v4, v7
	v_fma_f32 v10, -v6, v9, v4
	v_fmac_f32_e32 v9, v10, v7
	v_fma_f32 v6, -v6, v9, v4
	v_fma_f32 v4, v6, v7, v9
	v_min_f32_e32 v5, 0x42a00000, v1
	v_mul_f32_e32 v5, 0x3fb8aa3b, v5
	v_exp_f32_e32 v5, v5
	v_cmp_gt_f32_e32 vcc, s34, v3
	v_mul_f32_e32 v4, v5, v4
	v_bfe_u32 v5, v4, 16, 1
	v_add3_u32 v4, v4, v5, s39
	v_mul_f32_e32 v5, 0xbfb8aa3b, v1
	v_exp_f32_e32 v5, v5
	ds_write_b16_d16_hi v2, v4 offset:816
	v_sub_f32_e32 v4, 1.0, v3
	v_mul_f32_e32 v4, v5, v4
	v_bfe_u32 v5, v4, 16, 1
	v_add3_u32 v4, v4, v5, s39
	ds_write_b16_d16_hi v2, v4 offset:18224
	v_cndmask_b32_e64 v4, 0, 32, vcc
	v_ldexp_f32 v3, v3, v4
	v_log_f32_e32 v3, v3
	s_nop 0
	v_mul_f32_e32 v4, 0x3f317217, v3
	v_fma_f32 v4, v3, s38, -v4
	v_fmac_f32_e32 v4, 0x3377d1cf, v3
	v_fmac_f32_e32 v4, 0x3f317217, v3
	v_cmp_lt_f32_e64 s[82:83], |v3|, s20
	s_nop 1
	v_cndmask_b32_e64 v3, v3, v4, s[82:83]
	v_cndmask_b32_e32 v4, 0, v193, vcc
	v_sub_f32_e32 v3, v3, v4
	v_sub_f32_e32 v1, v1, v3
	ds_read_u16 v3, v2 offset:17952
	s_waitcnt lgkmcnt(0)
	v_lshlrev_b32_e32 v3, 16, v3
	v_mul_f32_e32 v3, 0xbfb8aa3b, v3
	v_exp_f32_e32 v3, v3
	s_nop 0
	v_add_f32_e32 v3, 1.0, v3
	v_min_f32_e32 v4, 0x7f7fffff, v3
	v_rcp_f32_e32 v5, v4
	s_nop 0
	v_fma_f32 v6, -v4, v5, 1.0
	v_fmac_f32_e32 v5, v6, v5
	v_fma_f32 v8, -v4, v5, 1.0
	v_fma_f32 v7, v8, v5, v5
	v_fma_f32 v4, -v4, v7, 1.0
	v_fma_f32 v3, v4, v5, v7
	ds_read_u16 v4, v2 offset:544
	v_fma_f32 v3, v0, v3, v58
	s_waitcnt lgkmcnt(0)
	v_lshlrev_b32_e32 v4, 16, v4
	v_mul_f32_e32 v5, 0xbfb8aa3b, v4
	v_exp_f32_e32 v5, v5
	s_nop 0
	v_add_f32_e32 v5, 1.0, v5
	v_min_f32_e32 v6, 0x7f7fffff, v5
	v_rcp_f32_e32 v7, v6
	s_nop 0
	v_fma_f32 v8, -v6, v7, 1.0
	v_fmac_f32_e32 v7, v8, v7
	v_mul_f32_e32 v9, v4, v7
	v_fma_f32 v10, -v6, v9, v4
	v_fmac_f32_e32 v9, v10, v7
	v_fma_f32 v6, -v6, v9, v4
	v_fma_f32 v4, v6, v7, v9
	v_min_f32_e32 v5, 0x42a00000, v1
	v_mul_f32_e32 v5, 0x3fb8aa3b, v5
	v_exp_f32_e32 v5, v5
	v_cmp_gt_f32_e32 vcc, s34, v3
	v_mul_f32_e32 v4, v5, v4
	v_bfe_u32 v5, v4, 16, 1
	v_add3_u32 v4, v4, v5, s39
	v_mul_f32_e32 v5, 0xbfb8aa3b, v1
	v_exp_f32_e32 v5, v5
	ds_write_b16_d16_hi v2, v4 offset:544
	v_sub_f32_e32 v4, 1.0, v3
	v_mul_f32_e32 v4, v5, v4
	v_bfe_u32 v5, v4, 16, 1
	v_add3_u32 v4, v4, v5, s39
	ds_write_b16_d16_hi v2, v4 offset:17952
	v_cndmask_b32_e64 v4, 0, 32, vcc
	v_ldexp_f32 v3, v3, v4
	v_log_f32_e32 v3, v3
	s_nop 0
	v_mul_f32_e32 v4, 0x3f317217, v3
	v_fma_f32 v4, v3, s38, -v4
	v_fmac_f32_e32 v4, 0x3377d1cf, v3
	v_fmac_f32_e32 v4, 0x3f317217, v3
	v_cmp_lt_f32_e64 s[82:83], |v3|, s20
	s_nop 1
	v_cndmask_b32_e64 v3, v3, v4, s[82:83]
	v_cndmask_b32_e32 v4, 0, v193, vcc
	v_sub_f32_e32 v3, v3, v4
	v_sub_f32_e32 v1, v1, v3
	ds_read_u16 v3, v2 offset:17680
	s_waitcnt lgkmcnt(0)
; DEVI float b2f(bfu b) { return __uint_as_float(((unsigned)b) << 16); }
; DEVI float sigmoidf_(float x) { return 1.f / (1.f + __expf(-x)); }
; DEVI float siluf_(float x) { return x / (1.f + __expf(-x)); }
; DEVI void h3_item(const Params& P, int l, int ck, int h, char* smem, int tid) {
;     ...
;   if (hf == 0) {
;     float rel = 0.f;
; #pragma unroll 8
;     for (int t = Lh - 1; t >= 0; --t) {
;       float f = lb + (1.f - lb) * sigmoidf_(b2f(KT[t * 136 + d]));
;       float q = siluf_(b2f(QT[t * 136 + d]));
;       QT[t * 136 + d] = f2b(q * __expf(fminf(rel, 80.f)));
;       KT[t * 136 + d] = f2b((1.f - f) * __expf(-rel));
;       rel -= __logf(f);
;     }
;     bmid[d] = -rel;
	v_lshlrev_b32_e32 v3, 16, v3
	v_mul_f32_e32 v3, 0xbfb8aa3b, v3
	v_exp_f32_e32 v3, v3
	s_nop 0
	v_add_f32_e32 v3, 1.0, v3
	v_min_f32_e32 v4, 0x7f7fffff, v3
	v_rcp_f32_e32 v5, v4
	s_nop 0
	v_fma_f32 v6, -v4, v5, 1.0
	v_fmac_f32_e32 v5, v6, v5
	v_fma_f32 v8, -v4, v5, 1.0
	v_fma_f32 v7, v8, v5, v5
	v_fma_f32 v4, -v4, v7, 1.0
	v_fma_f32 v3, v4, v5, v7
	ds_read_u16 v4, v2 offset:272
	v_fma_f32 v3, v0, v3, v58
	s_waitcnt lgkmcnt(0)
	v_lshlrev_b32_e32 v4, 16, v4
	v_mul_f32_e32 v5, 0xbfb8aa3b, v4
	v_exp_f32_e32 v5, v5
	s_nop 0
	v_add_f32_e32 v5, 1.0, v5
	v_min_f32_e32 v6, 0x7f7fffff, v5
	v_rcp_f32_e32 v7, v6
	s_nop 0
	v_fma_f32 v8, -v6, v7, 1.0
	v_fmac_f32_e32 v7, v8, v7
	v_mul_f32_e32 v9, v4, v7
	v_fma_f32 v10, -v6, v9, v4
	v_fmac_f32_e32 v9, v10, v7
	v_fma_f32 v6, -v6, v9, v4
	v_fma_f32 v4, v6, v7, v9
	v_min_f32_e32 v5, 0x42a00000, v1
	v_mul_f32_e32 v5, 0x3fb8aa3b, v5
	v_exp_f32_e32 v5, v5
	v_cmp_gt_f32_e32 vcc, s34, v3
	v_mul_f32_e32 v4, v5, v4
	v_bfe_u32 v5, v4, 16, 1
	v_add3_u32 v4, v4, v5, s39
	v_mul_f32_e32 v5, 0xbfb8aa3b, v1
	v_exp_f32_e32 v5, v5
	ds_write_b16_d16_hi v2, v4 offset:272
	v_sub_f32_e32 v4, 1.0, v3
	v_mul_f32_e32 v4, v5, v4
	v_bfe_u32 v5, v4, 16, 1
	v_add3_u32 v4, v4, v5, s39
	ds_write_b16_d16_hi v2, v4 offset:17680
	v_cndmask_b32_e64 v4, 0, 32, vcc
	v_ldexp_f32 v3, v3, v4
	v_log_f32_e32 v3, v3
	s_nop 0
	v_mul_f32_e32 v4, 0x3f317217, v3
	v_fma_f32 v4, v3, s38, -v4
	v_fmac_f32_e32 v4, 0x3377d1cf, v3
	v_fmac_f32_e32 v4, 0x3f317217, v3
	v_cmp_lt_f32_e64 s[82:83], |v3|, s20
	s_nop 1
	v_cndmask_b32_e64 v3, v3, v4, s[82:83]
	v_cndmask_b32_e32 v4, 0, v193, vcc
	v_sub_f32_e32 v3, v3, v4
	v_sub_f32_e32 v1, v1, v3
	ds_read_u16 v3, v2 offset:17408
	s_waitcnt lgkmcnt(0)
	v_lshlrev_b32_e32 v3, 16, v3
	v_mul_f32_e32 v3, 0xbfb8aa3b, v3
	v_exp_f32_e32 v3, v3
	s_nop 0
	v_add_f32_e32 v3, 1.0, v3
	v_min_f32_e32 v4, 0x7f7fffff, v3
	v_rcp_f32_e32 v5, v4
	s_nop 0
	v_fma_f32 v6, -v4, v5, 1.0
	v_fmac_f32_e32 v5, v6, v5
	v_fma_f32 v8, -v4, v5, 1.0
	v_fma_f32 v7, v8, v5, v5
	v_fma_f32 v4, -v4, v7, 1.0
	v_fma_f32 v3, v4, v5, v7
	ds_read_u16 v4, v2
	v_fma_f32 v3, v0, v3, v58
	s_waitcnt lgkmcnt(0)
	v_lshlrev_b32_e32 v4, 16, v4
	v_mul_f32_e32 v5, 0xbfb8aa3b, v4
	v_exp_f32_e32 v5, v5
	s_nop 0
	v_add_f32_e32 v5, 1.0, v5
	v_min_f32_e32 v6, 0x7f7fffff, v5
	v_rcp_f32_e32 v7, v6
	s_nop 0
	v_fma_f32 v8, -v6, v7, 1.0
	v_fmac_f32_e32 v7, v8, v7
	v_mul_f32_e32 v9, v4, v7
	v_fma_f32 v10, -v6, v9, v4
	v_fmac_f32_e32 v9, v10, v7
	v_fma_f32 v6, -v6, v9, v4
	v_fma_f32 v4, v6, v7, v9
	v_min_f32_e32 v5, 0x42a00000, v1
	v_mul_f32_e32 v5, 0x3fb8aa3b, v5
	v_exp_f32_e32 v5, v5
	v_cmp_gt_f32_e32 vcc, s34, v3
	v_mul_f32_e32 v4, v5, v4
	v_bfe_u32 v5, v4, 16, 1
	v_add3_u32 v4, v4, v5, s39
	v_mul_f32_e32 v5, 0xbfb8aa3b, v1
	v_exp_f32_e32 v5, v5
	ds_write_b16_d16_hi v2, v4
	v_sub_f32_e32 v4, 1.0, v3
	v_mul_f32_e32 v4, v5, v4
	v_bfe_u32 v5, v4, 16, 1
	v_add3_u32 v4, v4, v5, s39
	ds_write_b16_d16_hi v2, v4 offset:17408
	v_cndmask_b32_e64 v2, 0, 32, vcc
	v_ldexp_f32 v2, v3, v2
	v_log_f32_e32 v2, v2
	s_nop 0
	v_mul_f32_e32 v3, 0x3f317217, v2
	v_fma_f32 v3, v2, s38, -v3
	v_fmac_f32_e32 v3, 0x3377d1cf, v2
	v_fmac_f32_e32 v3, 0x3f317217, v2
	v_cmp_lt_f32_e64 s[82:83], |v2|, s20
	s_nop 1
	v_cndmask_b32_e64 v2, v2, v3, s[82:83]
	v_cndmask_b32_e32 v3, 0, v193, vcc
	v_sub_f32_e32 v2, v2, v3
	v_sub_f32_e32 v1, v1, v2
	s_cbranch_scc0 .LBB0_556
	v_xor_b32_e32 v0, 0x80000000, v1
	ds_write_b32 v199, v0 offset:62464

; DEVI float b2f(bfu b) { return __uint_as_float(((unsigned)b) << 16); }
; DEVI void h3_item(const Params& P, int l, int ck, int h, char* smem, int tid) {
;     ...
; #pragma unroll
;     for (int kk = 0; kk < 2; ++kk) {
; #pragma unroll
;       for (int n = 0; n < 8; ++n) {
;         bf16x8 b = *reinterpret_cast<const bf16x8*>(BS + (n * 16 + fr) * 72 + kk * 32 + fq * 8);
;         o[n] = __builtin_amdgcn_mfma_f32_16x16x32_bf16(aq[sl * 2 + kk], b, o[n], 0, 0, 0);
;       }
;     }
;   }
;   float rinv[4];
; #pragma unroll
;   for (int j = 0; j < 4; ++j) {
;     float ss = 0.f;
; #pragma unroll
;     for (int n = 0; n < 8; ++n) ss += o[n][j] * o[n][j];
;     ss += __shfl_xor(ss, 1); ss += __shfl_xor(ss, 2); ss += __shfl_xor(ss, 4); ss += __shfl_xor(ss, 8);
;     rinv[j] = rsqrtf(ss * (1.f / 128.f) + 1e-6f);
;   }
;   const float* ng = P.in[17] + l * 128;
;   bfu* UC = (bfu*)(P.ws + O_UC);
; #pragma unroll
;   for (int n = 0; n < 8; ++n)
; #pragma unroll
;     for (int j = 0; j < 4; ++j) {
;       int t = 16 * w + fq * 4 + j, e = n * 16 + fr;
;       if (t < L) {
;         float g = b2f(QT[t * 136 + e]);
.LBB0_580:
	s_waitcnt vmcnt(0)
	s_waitcnt lgkmcnt(0)
	s_barrier
	ds_read_b128 v[40:43], v217 offset:44032
	s_brev_b32 s4, 60
	s_waitcnt lgkmcnt(0)
	v_mfma_f32_16x16x32_bf16 v[12:15], v[4:7], v[40:43], v[12:15]
	ds_read_b128 v[40:43], v217 offset:46336
	s_lshl_b32 s24, s24, 1
	v_cmp_gt_i32_e64 s[74:75], s51, v201
	s_waitcnt lgkmcnt(0)
	v_mfma_f32_16x16x32_bf16 v[16:19], v[4:7], v[40:43], v[16:19]
	ds_read_b128 v[40:43], v217 offset:48640
	s_waitcnt lgkmcnt(0)
	v_mfma_f32_16x16x32_bf16 v[20:23], v[4:7], v[40:43], v[20:23]
	ds_read_b128 v[40:43], v217 offset:50944
	s_waitcnt lgkmcnt(0)
	v_mfma_f32_16x16x32_bf16 v[40:43], v[4:7], v[40:43], v[24:27]
	s_nop 2
	ds_read_b128 v[24:27], v217 offset:53248
	s_waitcnt lgkmcnt(0)
	v_mfma_f32_16x16x32_bf16 v[44:47], v[4:7], v[24:27], v[28:31]
	ds_read_b128 v[24:27], v217 offset:55552
	s_waitcnt lgkmcnt(0)
	v_mfma_f32_16x16x32_bf16 v[32:35], v[4:7], v[24:27], v[32:35]
	ds_read_b128 v[24:27], v217 offset:57856
	s_waitcnt lgkmcnt(0)
	v_mfma_f32_16x16x32_bf16 v[36:39], v[4:7], v[24:27], v[36:39]
	ds_read_b128 v[24:27], v217 offset:60160
	s_waitcnt lgkmcnt(0)
	v_mfma_f32_16x16x32_bf16 v[48:51], v[4:7], v[24:27], v[8:11]
	ds_read_b128 v[4:7], v217 offset:44096
	s_waitcnt lgkmcnt(0)
	v_mfma_f32_16x16x32_bf16 v[28:31], v[0:3], v[4:7], v[12:15]
	ds_read_b128 v[4:7], v217 offset:46400
	s_waitcnt lgkmcnt(0)
	v_mfma_f32_16x16x32_bf16 v[24:27], v[0:3], v[4:7], v[16:19]
	ds_read_b128 v[4:7], v217 offset:48704
	s_waitcnt lgkmcnt(0)
	v_mfma_f32_16x16x32_bf16 v[20:23], v[0:3], v[4:7], v[20:23]
	ds_read_b128 v[4:7], v217 offset:51008
	s_waitcnt lgkmcnt(0)
	v_mfma_f32_16x16x32_bf16 v[16:19], v[0:3], v[4:7], v[40:43]
	ds_read_b128 v[4:7], v217 offset:53312
	s_nop 1
	v_pk_mul_f32 v[42:43], v[24:25], v[24:25]
	v_pk_mul_f32 v[40:41], v[26:27], v[26:27]
	s_waitcnt lgkmcnt(0)
	v_mfma_f32_16x16x32_bf16 v[12:15], v[0:3], v[4:7], v[44:47]
	ds_read_b128 v[4:7], v217 offset:55616
	v_pk_fma_f32 v[42:43], v[28:29], v[28:29], v[42:43]
	v_pk_fma_f32 v[40:41], v[30:31], v[30:31], v[40:41]
	s_waitcnt lgkmcnt(0)
	v_mfma_f32_16x16x32_bf16 v[8:11], v[0:3], v[4:7], v[32:35]
	ds_read_b128 v[4:7], v217 offset:57920
	s_nop 1
	ds_read_b128 v[32:35], v217 offset:60224
	v_mov_b32_e32 v44, v13
	s_waitcnt lgkmcnt(1)
	v_mfma_f32_16x16x32_bf16 v[4:7], v[0:3], v[4:7], v[36:39]
	s_nop 0
	v_mov_b32_e32 v45, v9
	s_nop 0
	v_mov_b32_e32 v38, v21
	v_mov_b32_e32 v39, v17
	s_waitcnt lgkmcnt(0)
	v_mfma_f32_16x16x32_bf16 v[0:3], v[0:3], v[32:35], v[48:51]
	v_and_b32_e32 v33, 64, v187
	v_xor_b32_e32 v32, 1, v187
	v_add_u32_e32 v33, 64, v33
	v_cmp_lt_i32_e32 vcc, v32, v33
	v_pk_mul_f32 v[38:39], v[38:39], v[38:39]
	v_mov_b32_e32 v34, v12
	v_cndmask_b32_e32 v32, v187, v32, vcc
	v_lshlrev_b32_e32 v52, 2, v32
	v_xor_b32_e32 v32, 2, v187
	v_cmp_lt_i32_e32 vcc, v32, v33
	v_mov_b32_e32 v35, v8
	v_mov_b32_e32 v48, v38
	v_cndmask_b32_e32 v32, v187, v32, vcc
	v_lshlrev_b32_e32 v53, 2, v32
	v_xor_b32_e32 v32, 4, v187
	v_cmp_lt_i32_e32 vcc, v32, v33
	v_pk_mul_f32 v[34:35], v[34:35], v[34:35]
	v_pk_mul_f32 v[44:45], v[44:45], v[44:45]
	v_cndmask_b32_e32 v32, v187, v32, vcc
	v_lshlrev_b32_e32 v54, 2, v32
	v_xor_b32_e32 v32, 8, v187
	v_cmp_lt_i32_e32 vcc, v32, v33
	v_mov_b32_e32 v33, v16
	v_mov_b32_e32 v36, v4
	v_cndmask_b32_e32 v32, v187, v32, vcc
	v_lshlrev_b32_e32 v55, 2, v32
	v_mov_b32_e32 v32, v20
	v_pk_mul_f32 v[32:33], v[32:33], v[32:33]
	v_mov_b32_e32 v37, v0
	v_mov_b32_e32 v49, v32
	v_pk_add_f32 v[42:43], v[42:43], v[48:49] op_sel:[1,0] op_sel_hi:[0,1]
	v_mov_b32_e32 v32, v39
	v_mov_b32_e32 v46, v5
	v_mov_b32_e32 v47, v1
	v_pk_add_f32 v[32:33], v[42:43], v[32:33]
	v_mov_b32_e32 v38, v44
	v_mov_b32_e32 v39, v34
	v_pk_mul_f32 v[36:37], v[36:37], v[36:37]
	v_pk_mul_f32 v[46:47], v[46:47], v[46:47]
	v_pk_add_f32 v[32:33], v[32:33], v[38:39]
	v_mov_b32_e32 v34, v45
	v_pk_add_f32 v[32:33], v[32:33], v[34:35]
	v_mov_b32_e32 v34, v46
	v_mov_b32_e32 v35, v36
	v_pk_add_f32 v[32:33], v[32:33], v[34:35]
	v_mov_b32_e32 v36, v47
	v_pk_add_f32 v[32:33], v[32:33], v[36:37]
	ds_bpermute_b32 v35, v52, v33
	ds_bpermute_b32 v34, v52, v32
	v_mov_b32_e32 v44, v23
	v_mov_b32_e32 v45, v19
	v_pk_mul_f32 v[44:45], v[44:45], v[44:45]
	v_mov_b32_e32 v46, v15
	s_waitcnt lgkmcnt(0)
	v_pk_add_f32 v[32:33], v[32:33], v[34:35]
	ds_bpermute_b32 v35, v53, v33
	ds_bpermute_b32 v34, v53, v32
	v_mov_b32_e32 v47, v11
	v_mov_b32_e32 v50, v44
	v_pk_mul_f32 v[46:47], v[46:47], v[46:47]
	v_mov_b32_e32 v38, v6
	s_waitcnt lgkmcnt(0)
	v_pk_add_f32 v[32:33], v[32:33], v[34:35]
	ds_bpermute_b32 v35, v54, v33
	ds_bpermute_b32 v34, v54, v32
	v_mov_b32_e32 v39, v2
	v_mov_b32_e32 v48, v7
	v_mov_b32_e32 v49, v3
	v_pk_mul_f32 v[38:39], v[38:39], v[38:39]
	s_waitcnt lgkmcnt(0)
	v_pk_add_f32 v[32:33], v[32:33], v[34:35]
	ds_bpermute_b32 v35, v55, v33
	ds_bpermute_b32 v34, v55, v32
	v_pk_mul_f32 v[48:49], v[48:49], v[48:49]
	s_waitcnt lgkmcnt(0)
	v_pk_add_f32 v[32:33], v[32:33], v[34:35]
	s_nop 0
	v_pk_fma_f32 v[36:37], v[32:33], s[4:5], v[90:91] op_sel_hi:[1,0,0]
	v_mov_b32_e32 v34, v14
	v_mul_f32_e32 v32, 0x4b800000, v37
	v_cmp_gt_f32_e32 vcc, s34, v37
	v_mov_b32_e32 v35, v10
	v_pk_mul_f32 v[34:35], v[34:35], v[34:35]
	v_cndmask_b32_e32 v32, v37, v32, vcc
	v_rsq_f32_e32 v32, v32
	v_cmp_gt_f32_e64 s[76:77], s34, v36
	v_mul_f32_e32 v33, 0x45800000, v32
	v_cndmask_b32_e32 v42, v32, v33, vcc
	v_mov_b32_e32 v32, v22
	v_mov_b32_e32 v33, v18
	v_pk_mul_f32 v[32:33], v[32:33], v[32:33]
	s_nop 0
	v_mov_b32_e32 v51, v32
	v_pk_add_f32 v[40:41], v[40:41], v[50:51] op_sel:[1,0] op_sel_hi:[0,1]
	v_mov_b32_e32 v32, v45
	v_pk_add_f32 v[32:33], v[40:41], v[32:33]
	v_mov_b32_e32 v40, v46
	v_mov_b32_e32 v41, v34
	v_pk_add_f32 v[32:33], v[32:33], v[40:41]
	v_mov_b32_e32 v34, v47
	v_pk_add_f32 v[32:33], v[32:33], v[34:35]
	v_mov_b32_e32 v34, v48
	v_mov_b32_e32 v35, v38
	v_pk_add_f32 v[32:33], v[32:33], v[34:35]
	v_mov_b32_e32 v38, v49
	v_pk_add_f32 v[32:33], v[32:33], v[38:39]
	ds_bpermute_b32 v35, v52, v33
	ds_bpermute_b32 v34, v52, v32
	s_waitcnt lgkmcnt(0)
	v_pk_add_f32 v[32:33], v[32:33], v[34:35]
	ds_bpermute_b32 v35, v53, v33
	ds_bpermute_b32 v34, v53, v32
	s_waitcnt lgkmcnt(0)
	v_pk_add_f32 v[32:33], v[32:33], v[34:35]
	ds_bpermute_b32 v35, v54, v33
	ds_bpermute_b32 v34, v54, v32
	s_waitcnt lgkmcnt(0)
	v_pk_add_f32 v[38:39], v[32:33], v[34:35]
	ds_bpermute_b32 v41, v55, v39
	ds_bpermute_b32 v40, v55, v38
	v_add_u32_e32 v34, s50, v201
	v_lshl_add_u64 v[32:33], v[120:121], 0, s[24:25]
	v_ashrrev_i32_e32 v35, 31, v34
	s_and_saveexec_b64 s[26:27], s[74:75]
	s_cbranch_execz .LBB0_582
; DEVI float b2f(bfu b) { return __uint_as_float(((unsigned)b) << 16); }
; DEVI float siluf_(float x) { return x / (1.f + __expf(-x)); }
; DEVI void h3_item(const Params& P, int l, int ck, int h, char* smem, int tid) {
;     ...
;   bfu* UC = (bfu*)(P.ws + O_UC);
; #pragma unroll
;   for (int n = 0; n < 8; ++n)
; #pragma unroll
;     for (int j = 0; j < 4; ++j) {
;       int t = 16 * w + fq * 4 + j, e = n * 16 + fr;
;       if (t < L) {
;         float g = b2f(QT[t * 136 + e]);
;         UC[(long)(ci.lt0 + t) * 1024 + h * 128 + e] = f2b(o[n][j] * rinv[j] * ng[e] * siluf_(g));
;       }
;     }
	ds_read_u16 v37, v218
	v_mul_f32_e32 v28, v28, v42
	s_waitcnt lgkmcnt(0)
	v_lshlrev_b32_e32 v37, 16, v37
	v_mul_f32_e32 v28, v28, v219
	v_mul_f32_e32 v43, 0xbfb8aa3b, v37
	v_exp_f32_e32 v43, v43
	s_nop 0
	v_add_f32_e32 v43, 1.0, v43
	v_min_f32_e32 v44, 0x7f7fffff, v43
	v_rcp_f32_e32 v45, v44
	s_nop 0
	v_fma_f32 v46, -v44, v45, 1.0
	v_fmac_f32_e32 v45, v46, v45
	v_mul_f32_e32 v47, v37, v45
	v_fma_f32 v48, -v44, v47, v37
	v_fmac_f32_e32 v47, v48, v45
	v_fma_f32 v44, -v44, v47, v37
	v_fma_f32 v37, v44, v45, v47
	v_mul_f32_e32 v28, v28, v37
	v_bfe_u32 v37, v28, 16, 1
	v_lshlrev_b64 v[44:45], 11, v[34:35]
	v_add3_u32 v28, v28, v37, s39
	v_lshl_add_u64 v[44:45], v[32:33], 0, v[44:45]
	global_store_short_d16_hi v[44:45], v28, off
.LBB0_582:
	s_or_b64 exec, exec, s[26:27]
	v_mul_f32_e32 v28, 0x4b800000, v36
	v_cndmask_b32_e64 v28, v36, v28, s[76:77]
	v_rsq_f32_e32 v28, v28
	s_nop 0
	v_mul_f32_e32 v36, 0x45800000, v28
	v_cndmask_b32_e64 v43, v28, v36, s[76:77]
	v_add_u32_e32 v36, s50, v202
	v_cmp_gt_i32_e64 s[76:77], s51, v202
	v_ashrrev_i32_e32 v37, 31, v36
	s_and_saveexec_b64 s[26:27], s[76:77]
	s_cbranch_execz .LBB0_584
	ds_read_u16 v28, v218 offset:272
	v_mul_f32_e32 v29, v29, v43
	s_waitcnt lgkmcnt(0)
	v_lshlrev_b32_e32 v28, 16, v28
	v_mul_f32_e32 v29, v29, v219
	v_mul_f32_e32 v44, 0xbfb8aa3b, v28
	v_exp_f32_e32 v44, v44
	s_nop 0
	v_add_f32_e32 v44, 1.0, v44
	v_min_f32_e32 v45, 0x7f7fffff, v44
	v_rcp_f32_e32 v46, v45
	s_nop 0
	v_fma_f32 v47, -v45, v46, 1.0
	v_fmac_f32_e32 v46, v47, v46
	v_mul_f32_e32 v48, v28, v46
	v_fma_f32 v49, -v45, v48, v28
	v_fmac_f32_e32 v48, v49, v46
	v_fma_f32 v45, -v45, v48, v28
	v_fma_f32 v28, v45, v46, v48
	v_mul_f32_e32 v28, v29, v28
	v_bfe_u32 v29, v28, 16, 1
	v_add3_u32 v44, v28, v29, s39
	v_lshlrev_b64 v[28:29], 11, v[36:37]
	v_lshl_add_u64 v[28:29], v[32:33], 0, v[28:29]
	global_store_short_d16_hi v[28:29], v44, off
.LBB0_584:
	s_or_b64 exec, exec, s[26:27]
	s_waitcnt lgkmcnt(0)
	v_pk_add_f32 v[28:29], v[38:39], v[40:41]
	v_cmp_gt_i32_e64 s[78:79], s51, v203
	v_pk_fma_f32 v[38:39], v[28:29], s[4:5], v[90:91] op_sel_hi:[1,0,0]
	s_nop 0
	v_mul_f32_e32 v28, 0x4b800000, v39
	v_cmp_gt_f32_e32 vcc, s34, v39
	v_cmp_gt_f32_e64 s[80:81], s34, v38
	s_nop 0
	v_cndmask_b32_e32 v28, v39, v28, vcc
	v_rsq_f32_e32 v28, v28
	s_nop 0
	v_mul_f32_e32 v29, 0x45800000, v28
	v_cndmask_b32_e32 v40, v28, v29, vcc
	v_add_u32_e32 v28, s50, v203
	v_ashrrev_i32_e32 v29, 31, v28
	s_and_saveexec_b64 s[26:27], s[78:79]
	s_cbranch_execz .LBB0_586
	ds_read_u16 v39, v218 offset:544
	v_mul_f32_e32 v30, v30, v40
	s_waitcnt lgkmcnt(0)
	v_lshlrev_b32_e32 v39, 16, v39
	v_mul_f32_e32 v30, v30, v219
	v_mul_f32_e32 v41, 0xbfb8aa3b, v39
	v_exp_f32_e32 v41, v41
	s_nop 0
	v_add_f32_e32 v41, 1.0, v41
	v_min_f32_e32 v44, 0x7f7fffff, v41
	v_rcp_f32_e32 v45, v44
	s_nop 0
	v_fma_f32 v46, -v44, v45, 1.0
	v_fmac_f32_e32 v45, v46, v45
	v_mul_f32_e32 v47, v39, v45
	v_fma_f32 v48, -v44, v47, v39
	v_fmac_f32_e32 v47, v48, v45
	v_fma_f32 v44, -v44, v47, v39
	v_fma_f32 v39, v44, v45, v47
	v_mul_f32_e32 v30, v30, v39
	v_bfe_u32 v39, v30, 16, 1
	v_lshlrev_b64 v[44:45], 11, v[28:29]
	v_add3_u32 v30, v30, v39, s39
	v_lshl_add_u64 v[44:45], v[32:33], 0, v[44:45]
	global_store_short_d16_hi v[44:45], v30, off
.LBB0_586:
	s_or_b64 exec, exec, s[26:27]
	v_mul_f32_e32 v30, 0x4b800000, v38
	v_cndmask_b32_e64 v30, v38, v30, s[80:81]
	v_rsq_f32_e32 v30, v30
	s_nop 0
	v_mul_f32_e32 v38, 0x45800000, v30
	v_cndmask_b32_e64 v30, v30, v38, s[80:81]
	v_add_u32_e32 v38, s50, v204
	v_cmp_gt_i32_e64 s[80:81], s51, v204
	v_ashrrev_i32_e32 v39, 31, v38
	s_and_saveexec_b64 s[26:27], s[80:81]
	s_cbranch_execz .LBB0_617
	ds_read_u16 v41, v218 offset:816
	v_mul_f32_e32 v31, v31, v30
	s_waitcnt lgkmcnt(0)
	v_lshlrev_b32_e32 v41, 16, v41
	v_mul_f32_e32 v31, v31, v219
	v_mul_f32_e32 v44, 0xbfb8aa3b, v41
	v_exp_f32_e32 v44, v44
	s_nop 0
	v_add_f32_e32 v44, 1.0, v44
	v_min_f32_e32 v45, 0x7f7fffff, v44
	v_rcp_f32_e32 v46, v45
	s_nop 0
	v_fma_f32 v47, -v45, v46, 1.0
	v_fmac_f32_e32 v46, v47, v46
	v_mul_f32_e32 v48, v41, v46
	v_fma_f32 v49, -v45, v48, v41
	v_fmac_f32_e32 v48, v49, v46
	v_fma_f32 v45, -v45, v48, v41
	v_fma_f32 v41, v45, v46, v48
	v_mul_f32_e32 v31, v31, v41
	v_bfe_u32 v41, v31, 16, 1
	v_lshlrev_b64 v[44:45], 11, v[38:39]
	v_add3_u32 v31, v31, v41, s39
	v_lshl_add_u64 v[44:45], v[32:33], 0, v[44:45]
	global_store_short_d16_hi v[44:45], v31, off
	s_or_b64 exec, exec, s[26:27]
	s_and_saveexec_b64 s[26:27], s[74:75]
	s_cbranch_execnz .LBB0_618

; DEVI float b2f(bfu b) { return __uint_as_float(((unsigned)b) << 16); }
; DEVI float siluf_(float x) { return x / (1.f + __expf(-x)); }
; DEVI void h3_item(const Params& P, int l, int ck, int h, char* smem, int tid) {
;     ...
;   for (int n = 0; n < 8; ++n)
; #pragma unroll
;     for (int j = 0; j < 4; ++j) {
;       int t = 16 * w + fq * 4 + j, e = n * 16 + fr;
;       if (t < L) {
;         float g = b2f(QT[t * 136 + e]);
;         UC[(long)(ci.lt0 + t) * 1024 + h * 128 + e] = f2b(o[n][j] * rinv[j] * ng[e] * siluf_(g));
;       }
;     }
.LBB0_589:
	ds_read_u16 v24, v218 offset:304
	v_mul_f32_e32 v25, v25, v43
	s_waitcnt lgkmcnt(0)
	v_lshlrev_b32_e32 v24, 16, v24
	v_mul_f32_e32 v25, v25, v220
	v_mul_f32_e32 v31, 0xbfb8aa3b, v24
	v_exp_f32_e32 v31, v31
	s_nop 0
	v_add_f32_e32 v31, 1.0, v31
	v_min_f32_e32 v41, 0x7f7fffff, v31
	v_rcp_f32_e32 v44, v41
	s_nop 0
	v_fma_f32 v45, -v41, v44, 1.0
	v_fmac_f32_e32 v44, v45, v44
	v_mul_f32_e32 v46, v24, v44
	v_fma_f32 v47, -v41, v46, v24
	v_fmac_f32_e32 v46, v47, v44
	v_fma_f32 v41, -v41, v46, v24
	v_fma_f32 v24, v41, v44, v46
	v_mul_f32_e32 v24, v25, v24
	v_bfe_u32 v25, v24, 16, 1
	v_add3_u32 v31, v24, v25, s39
	v_lshlrev_b64 v[24:25], 11, v[36:37]
	v_lshl_add_u64 v[24:25], v[32:33], 0, v[24:25]
	global_store_short_d16_hi v[24:25], v31, off offset:32
	s_or_b64 exec, exec, s[26:27]
	s_and_saveexec_b64 s[26:27], s[78:79]
	s_cbranch_execnz .LBB0_620

; DEVI float b2f(bfu b) { return __uint_as_float(((unsigned)b) << 16); }
; DEVI float siluf_(float x) { return x / (1.f + __expf(-x)); }
; DEVI void h3_item(const Params& P, int l, int ck, int h, char* smem, int tid) {
;     ...
;   for (int n = 0; n < 8; ++n)
; #pragma unroll
;     for (int j = 0; j < 4; ++j) {
;       int t = 16 * w + fq * 4 + j, e = n * 16 + fr;
;       if (t < L) {
;         float g = b2f(QT[t * 136 + e]);
;         UC[(long)(ci.lt0 + t) * 1024 + h * 128 + e] = f2b(o[n][j] * rinv[j] * ng[e] * siluf_(g));
;       }
;     }
.LBB0_591:
	ds_read_u16 v24, v218 offset:848
	v_mul_f32_e32 v25, v27, v30
	s_waitcnt lgkmcnt(0)
	v_lshlrev_b32_e32 v24, 16, v24
	v_mul_f32_e32 v25, v25, v220
	v_mul_f32_e32 v26, 0xbfb8aa3b, v24
	v_exp_f32_e32 v26, v26
	s_nop 0
	v_add_f32_e32 v26, 1.0, v26
	v_min_f32_e32 v27, 0x7f7fffff, v26
	v_rcp_f32_e32 v31, v27
	s_nop 0
	v_fma_f32 v41, -v27, v31, 1.0
	v_fmac_f32_e32 v31, v41, v31
	v_mul_f32_e32 v44, v24, v31
	v_fma_f32 v45, -v27, v44, v24
	v_fmac_f32_e32 v44, v45, v31
	v_fma_f32 v27, -v27, v44, v24
	v_fma_f32 v24, v27, v31, v44
	v_mul_f32_e32 v24, v25, v24
	v_bfe_u32 v25, v24, 16, 1
	v_add3_u32 v26, v24, v25, s39
	v_lshlrev_b64 v[24:25], 11, v[38:39]
	v_lshl_add_u64 v[24:25], v[32:33], 0, v[24:25]
	global_store_short_d16_hi v[24:25], v26, off offset:32
	s_or_b64 exec, exec, s[26:27]
	s_and_saveexec_b64 s[26:27], s[74:75]
	s_cbranch_execnz .LBB0_622

; DEVI float b2f(bfu b) { return __uint_as_float(((unsigned)b) << 16); }
; DEVI float siluf_(float x) { return x / (1.f + __expf(-x)); }
; DEVI void h3_item(const Params& P, int l, int ck, int h, char* smem, int tid) {
;     ...
;   for (int n = 0; n < 8; ++n)
; #pragma unroll
;     for (int j = 0; j < 4; ++j) {
;       int t = 16 * w + fq * 4 + j, e = n * 16 + fr;
;       if (t < L) {
;         float g = b2f(QT[t * 136 + e]);
;         UC[(long)(ci.lt0 + t) * 1024 + h * 128 + e] = f2b(o[n][j] * rinv[j] * ng[e] * siluf_(g));
;       }
;     }
.LBB0_593:
	ds_read_u16 v20, v218 offset:336
	v_mul_f32_e32 v21, v21, v43
	s_waitcnt lgkmcnt(0)
	v_lshlrev_b32_e32 v20, 16, v20
	v_mul_f32_e32 v21, v21, v221
	v_mul_f32_e32 v24, 0xbfb8aa3b, v20
	v_exp_f32_e32 v24, v24
	s_nop 0
	v_add_f32_e32 v24, 1.0, v24
	v_min_f32_e32 v25, 0x7f7fffff, v24
	v_rcp_f32_e32 v26, v25
	s_nop 0
	v_fma_f32 v27, -v25, v26, 1.0
	v_fmac_f32_e32 v26, v27, v26
	v_mul_f32_e32 v31, v20, v26
	v_fma_f32 v41, -v25, v31, v20
	v_fmac_f32_e32 v31, v41, v26
	v_fma_f32 v25, -v25, v31, v20
	v_fma_f32 v20, v25, v26, v31
	v_mul_f32_e32 v20, v21, v20
	v_bfe_u32 v21, v20, 16, 1
	v_add3_u32 v24, v20, v21, s39
	v_lshlrev_b64 v[20:21], 11, v[36:37]
	v_lshl_add_u64 v[20:21], v[32:33], 0, v[20:21]
	global_store_short_d16_hi v[20:21], v24, off offset:64
	s_or_b64 exec, exec, s[26:27]
	s_and_saveexec_b64 s[26:27], s[78:79]
	s_cbranch_execnz .LBB0_624

; DEVI float b2f(bfu b) { return __uint_as_float(((unsigned)b) << 16); }
; DEVI float siluf_(float x) { return x / (1.f + __expf(-x)); }
; DEVI void h3_item(const Params& P, int l, int ck, int h, char* smem, int tid) {
;     ...
;   for (int n = 0; n < 8; ++n)
; #pragma unroll
;     for (int j = 0; j < 4; ++j) {
;       int t = 16 * w + fq * 4 + j, e = n * 16 + fr;
;       if (t < L) {
;         float g = b2f(QT[t * 136 + e]);
;         UC[(long)(ci.lt0 + t) * 1024 + h * 128 + e] = f2b(o[n][j] * rinv[j] * ng[e] * siluf_(g));
;       }
;     }
.LBB0_595:
	ds_read_u16 v20, v218 offset:880
	v_mul_f32_e32 v21, v23, v30
	s_waitcnt lgkmcnt(0)
	v_lshlrev_b32_e32 v20, 16, v20
	v_mul_f32_e32 v21, v21, v221
	v_mul_f32_e32 v22, 0xbfb8aa3b, v20
	v_exp_f32_e32 v22, v22
	s_nop 0
	v_add_f32_e32 v22, 1.0, v22
	v_min_f32_e32 v23, 0x7f7fffff, v22
	v_rcp_f32_e32 v24, v23
	s_nop 0
	v_fma_f32 v25, -v23, v24, 1.0
	v_fmac_f32_e32 v24, v25, v24
	v_mul_f32_e32 v26, v20, v24
	v_fma_f32 v27, -v23, v26, v20
	v_fmac_f32_e32 v26, v27, v24
	v_fma_f32 v23, -v23, v26, v20
	v_fma_f32 v20, v23, v24, v26
	v_mul_f32_e32 v20, v21, v20
	v_bfe_u32 v21, v20, 16, 1
	v_add3_u32 v22, v20, v21, s39
	v_lshlrev_b64 v[20:21], 11, v[38:39]
	v_lshl_add_u64 v[20:21], v[32:33], 0, v[20:21]
	global_store_short_d16_hi v[20:21], v22, off offset:64
	s_or_b64 exec, exec, s[26:27]
	s_and_saveexec_b64 s[26:27], s[74:75]
	s_cbranch_execnz .LBB0_626

; DEVI float b2f(bfu b) { return __uint_as_float(((unsigned)b) << 16); }
; DEVI float siluf_(float x) { return x / (1.f + __expf(-x)); }
; DEVI void h3_item(const Params& P, int l, int ck, int h, char* smem, int tid) {
;     ...
;   for (int n = 0; n < 8; ++n)
; #pragma unroll
;     for (int j = 0; j < 4; ++j) {
;       int t = 16 * w + fq * 4 + j, e = n * 16 + fr;
;       if (t < L) {
;         float g = b2f(QT[t * 136 + e]);
;         UC[(long)(ci.lt0 + t) * 1024 + h * 128 + e] = f2b(o[n][j] * rinv[j] * ng[e] * siluf_(g));
;       }
;     }
.LBB0_597:
	ds_read_u16 v16, v218 offset:368
	v_mul_f32_e32 v17, v17, v43
	s_waitcnt lgkmcnt(0)
	v_lshlrev_b32_e32 v16, 16, v16
	v_mul_f32_e32 v17, v17, v222
	v_mul_f32_e32 v20, 0xbfb8aa3b, v16
	v_exp_f32_e32 v20, v20
	s_nop 0
	v_add_f32_e32 v20, 1.0, v20
	v_min_f32_e32 v21, 0x7f7fffff, v20
	v_rcp_f32_e32 v22, v21
	s_nop 0
	v_fma_f32 v23, -v21, v22, 1.0
	v_fmac_f32_e32 v22, v23, v22
	v_mul_f32_e32 v24, v16, v22
	v_fma_f32 v25, -v21, v24, v16
	v_fmac_f32_e32 v24, v25, v22
	v_fma_f32 v21, -v21, v24, v16
	v_fma_f32 v16, v21, v22, v24
	v_mul_f32_e32 v16, v17, v16
	v_bfe_u32 v17, v16, 16, 1
	v_add3_u32 v20, v16, v17, s39
	v_lshlrev_b64 v[16:17], 11, v[36:37]
	v_lshl_add_u64 v[16:17], v[32:33], 0, v[16:17]
	global_store_short_d16_hi v[16:17], v20, off offset:96
	s_or_b64 exec, exec, s[26:27]
	s_and_saveexec_b64 s[26:27], s[78:79]
	s_cbranch_execnz .LBB0_628

; DEVI float b2f(bfu b) { return __uint_as_float(((unsigned)b) << 16); }
; DEVI float siluf_(float x) { return x / (1.f + __expf(-x)); }
; DEVI void h3_item(const Params& P, int l, int ck, int h, char* smem, int tid) {
;     ...
;   for (int n = 0; n < 8; ++n)
; #pragma unroll
;     for (int j = 0; j < 4; ++j) {
;       int t = 16 * w + fq * 4 + j, e = n * 16 + fr;
;       if (t < L) {
;         float g = b2f(QT[t * 136 + e]);
;         UC[(long)(ci.lt0 + t) * 1024 + h * 128 + e] = f2b(o[n][j] * rinv[j] * ng[e] * siluf_(g));
;       }
;     }
.LBB0_599:
	ds_read_u16 v16, v218 offset:912
	v_mul_f32_e32 v17, v19, v30
	s_waitcnt lgkmcnt(0)
	v_lshlrev_b32_e32 v16, 16, v16
	v_mul_f32_e32 v17, v17, v222
	v_mul_f32_e32 v18, 0xbfb8aa3b, v16
	v_exp_f32_e32 v18, v18
	s_nop 0
	v_add_f32_e32 v18, 1.0, v18
	v_min_f32_e32 v19, 0x7f7fffff, v18
	v_rcp_f32_e32 v20, v19
	s_nop 0
	v_fma_f32 v21, -v19, v20, 1.0
	v_fmac_f32_e32 v20, v21, v20
	v_mul_f32_e32 v22, v16, v20
	v_fma_f32 v23, -v19, v22, v16
	v_fmac_f32_e32 v22, v23, v20
	v_fma_f32 v19, -v19, v22, v16
	v_fma_f32 v16, v19, v20, v22
	v_mul_f32_e32 v16, v17, v16
	v_bfe_u32 v17, v16, 16, 1
	v_add3_u32 v18, v16, v17, s39
	v_lshlrev_b64 v[16:17], 11, v[38:39]
	v_lshl_add_u64 v[16:17], v[32:33], 0, v[16:17]
	global_store_short_d16_hi v[16:17], v18, off offset:96
	s_or_b64 exec, exec, s[26:27]
	s_and_saveexec_b64 s[26:27], s[74:75]
	s_cbranch_execnz .LBB0_630

; DEVI float b2f(bfu b) { return __uint_as_float(((unsigned)b) << 16); }
; DEVI float siluf_(float x) { return x / (1.f + __expf(-x)); }
; DEVI void h3_item(const Params& P, int l, int ck, int h, char* smem, int tid) {
;     ...
;   for (int n = 0; n < 8; ++n)
; #pragma unroll
;     for (int j = 0; j < 4; ++j) {
;       int t = 16 * w + fq * 4 + j, e = n * 16 + fr;
;       if (t < L) {
;         float g = b2f(QT[t * 136 + e]);
;         UC[(long)(ci.lt0 + t) * 1024 + h * 128 + e] = f2b(o[n][j] * rinv[j] * ng[e] * siluf_(g));
;       }
;     }
.LBB0_601:
	ds_read_u16 v12, v218 offset:400
	v_mul_f32_e32 v13, v13, v43
	s_waitcnt lgkmcnt(0)
	v_lshlrev_b32_e32 v12, 16, v12
	v_mul_f32_e32 v13, v13, v223
	v_mul_f32_e32 v16, 0xbfb8aa3b, v12
	v_exp_f32_e32 v16, v16
	s_nop 0
	v_add_f32_e32 v16, 1.0, v16
	v_min_f32_e32 v17, 0x7f7fffff, v16
	v_rcp_f32_e32 v18, v17
	s_nop 0
	v_fma_f32 v19, -v17, v18, 1.0
	v_fmac_f32_e32 v18, v19, v18
	v_mul_f32_e32 v20, v12, v18
	v_fma_f32 v21, -v17, v20, v12
	v_fmac_f32_e32 v20, v21, v18
	v_fma_f32 v17, -v17, v20, v12
	v_fma_f32 v12, v17, v18, v20
	v_mul_f32_e32 v12, v13, v12
	v_bfe_u32 v13, v12, 16, 1
	v_add3_u32 v16, v12, v13, s39
	v_lshlrev_b64 v[12:13], 11, v[36:37]
	v_lshl_add_u64 v[12:13], v[32:33], 0, v[12:13]
	global_store_short_d16_hi v[12:13], v16, off offset:128
	s_or_b64 exec, exec, s[26:27]
	s_and_saveexec_b64 s[26:27], s[78:79]
	s_cbranch_execnz .LBB0_632

; DEVI float b2f(bfu b) { return __uint_as_float(((unsigned)b) << 16); }
; DEVI float siluf_(float x) { return x / (1.f + __expf(-x)); }
; DEVI void h3_item(const Params& P, int l, int ck, int h, char* smem, int tid) {
;     ...
;   for (int n = 0; n < 8; ++n)
; #pragma unroll
;     for (int j = 0; j < 4; ++j) {
;       int t = 16 * w + fq * 4 + j, e = n * 16 + fr;
;       if (t < L) {
;         float g = b2f(QT[t * 136 + e]);
;         UC[(long)(ci.lt0 + t) * 1024 + h * 128 + e] = f2b(o[n][j] * rinv[j] * ng[e] * siluf_(g));
;       }
;     }
.LBB0_603:
	ds_read_u16 v12, v218 offset:944
	v_mul_f32_e32 v13, v15, v30
	s_waitcnt lgkmcnt(0)
	v_lshlrev_b32_e32 v12, 16, v12
	v_mul_f32_e32 v13, v13, v223
	v_mul_f32_e32 v14, 0xbfb8aa3b, v12
	v_exp_f32_e32 v14, v14
	s_nop 0
	v_add_f32_e32 v14, 1.0, v14
	v_min_f32_e32 v15, 0x7f7fffff, v14
	v_rcp_f32_e32 v16, v15
	s_nop 0
	v_fma_f32 v17, -v15, v16, 1.0
	v_fmac_f32_e32 v16, v17, v16
	v_mul_f32_e32 v18, v12, v16
	v_fma_f32 v19, -v15, v18, v12
	v_fmac_f32_e32 v18, v19, v16
	v_fma_f32 v15, -v15, v18, v12
	v_fma_f32 v12, v15, v16, v18
	v_mul_f32_e32 v12, v13, v12
	v_bfe_u32 v13, v12, 16, 1
	v_add3_u32 v14, v12, v13, s39
	v_lshlrev_b64 v[12:13], 11, v[38:39]
	v_lshl_add_u64 v[12:13], v[32:33], 0, v[12:13]
	global_store_short_d16_hi v[12:13], v14, off offset:128
	s_or_b64 exec, exec, s[26:27]
	s_and_saveexec_b64 s[26:27], s[74:75]
	s_cbranch_execnz .LBB0_634

; DEVI float b2f(bfu b) { return __uint_as_float(((unsigned)b) << 16); }
; DEVI float siluf_(float x) { return x / (1.f + __expf(-x)); }
; DEVI void h3_item(const Params& P, int l, int ck, int h, char* smem, int tid) {
;     ...
;   for (int n = 0; n < 8; ++n)
; #pragma unroll
;     for (int j = 0; j < 4; ++j) {
;       int t = 16 * w + fq * 4 + j, e = n * 16 + fr;
;       if (t < L) {
;         float g = b2f(QT[t * 136 + e]);
;         UC[(long)(ci.lt0 + t) * 1024 + h * 128 + e] = f2b(o[n][j] * rinv[j] * ng[e] * siluf_(g));
;       }
;     }
.LBB0_605:
	ds_read_u16 v8, v218 offset:432
	v_mul_f32_e32 v9, v9, v43
	s_waitcnt lgkmcnt(0)
	v_lshlrev_b32_e32 v8, 16, v8
	v_mul_f32_e32 v9, v9, v224
	v_mul_f32_e32 v12, 0xbfb8aa3b, v8
	v_exp_f32_e32 v12, v12
	s_nop 0
	v_add_f32_e32 v12, 1.0, v12
	v_min_f32_e32 v13, 0x7f7fffff, v12
	v_rcp_f32_e32 v14, v13
	s_nop 0
	v_fma_f32 v15, -v13, v14, 1.0
	v_fmac_f32_e32 v14, v15, v14
	v_mul_f32_e32 v16, v8, v14
	v_fma_f32 v17, -v13, v16, v8
	v_fmac_f32_e32 v16, v17, v14
	v_fma_f32 v13, -v13, v16, v8
	v_fma_f32 v8, v13, v14, v16
	v_mul_f32_e32 v8, v9, v8
	v_bfe_u32 v9, v8, 16, 1
	v_add3_u32 v12, v8, v9, s39
	v_lshlrev_b64 v[8:9], 11, v[36:37]
	v_lshl_add_u64 v[8:9], v[32:33], 0, v[8:9]
	global_store_short_d16_hi v[8:9], v12, off offset:160
	s_or_b64 exec, exec, s[26:27]
	s_and_saveexec_b64 s[26:27], s[78:79]
	s_cbranch_execnz .LBB0_636

; DEVI float b2f(bfu b) { return __uint_as_float(((unsigned)b) << 16); }
; DEVI float siluf_(float x) { return x / (1.f + __expf(-x)); }
; DEVI void h3_item(const Params& P, int l, int ck, int h, char* smem, int tid) {
;     ...
;   for (int n = 0; n < 8; ++n)
; #pragma unroll
;     for (int j = 0; j < 4; ++j) {
;       int t = 16 * w + fq * 4 + j, e = n * 16 + fr;
;       if (t < L) {
;         float g = b2f(QT[t * 136 + e]);
;         UC[(long)(ci.lt0 + t) * 1024 + h * 128 + e] = f2b(o[n][j] * rinv[j] * ng[e] * siluf_(g));
;       }
;     }
.LBB0_607:
	ds_read_u16 v8, v218 offset:976
	v_mul_f32_e32 v9, v11, v30
	s_waitcnt lgkmcnt(0)
	v_lshlrev_b32_e32 v8, 16, v8
	v_mul_f32_e32 v9, v9, v224
	v_mul_f32_e32 v10, 0xbfb8aa3b, v8
	v_exp_f32_e32 v10, v10
	s_nop 0
	v_add_f32_e32 v10, 1.0, v10
	v_min_f32_e32 v11, 0x7f7fffff, v10
	v_rcp_f32_e32 v12, v11
	s_nop 0
	v_fma_f32 v13, -v11, v12, 1.0
	v_fmac_f32_e32 v12, v13, v12
	v_mul_f32_e32 v14, v8, v12
	v_fma_f32 v15, -v11, v14, v8
	v_fmac_f32_e32 v14, v15, v12
	v_fma_f32 v11, -v11, v14, v8
	v_fma_f32 v8, v11, v12, v14
	v_mul_f32_e32 v8, v9, v8
	v_bfe_u32 v9, v8, 16, 1
	v_add3_u32 v10, v8, v9, s39
	v_lshlrev_b64 v[8:9], 11, v[38:39]
	v_lshl_add_u64 v[8:9], v[32:33], 0, v[8:9]
	global_store_short_d16_hi v[8:9], v10, off offset:160
	s_or_b64 exec, exec, s[26:27]
	s_and_saveexec_b64 s[26:27], s[74:75]
	s_cbranch_execnz .LBB0_638

; DEVI float b2f(bfu b) { return __uint_as_float(((unsigned)b) << 16); }
; DEVI float siluf_(float x) { return x / (1.f + __expf(-x)); }
; DEVI void h3_item(const Params& P, int l, int ck, int h, char* smem, int tid) {
;     ...
;   for (int n = 0; n < 8; ++n)
; #pragma unroll
;     for (int j = 0; j < 4; ++j) {
;       int t = 16 * w + fq * 4 + j, e = n * 16 + fr;
;       if (t < L) {
;         float g = b2f(QT[t * 136 + e]);
;         UC[(long)(ci.lt0 + t) * 1024 + h * 128 + e] = f2b(o[n][j] * rinv[j] * ng[e] * siluf_(g));
;       }
;     }
.LBB0_609:
	ds_read_u16 v4, v218 offset:464
	v_mul_f32_e32 v5, v5, v43
	s_waitcnt lgkmcnt(0)
	v_lshlrev_b32_e32 v4, 16, v4
	v_mul_f32_e32 v5, v5, v225
	v_mul_f32_e32 v8, 0xbfb8aa3b, v4
	v_exp_f32_e32 v8, v8
	s_nop 0
	v_add_f32_e32 v8, 1.0, v8
	v_min_f32_e32 v9, 0x7f7fffff, v8
	v_rcp_f32_e32 v10, v9
	s_nop 0
	v_fma_f32 v11, -v9, v10, 1.0
	v_fmac_f32_e32 v10, v11, v10
	v_mul_f32_e32 v12, v4, v10
	v_fma_f32 v13, -v9, v12, v4
	v_fmac_f32_e32 v12, v13, v10
	v_fma_f32 v9, -v9, v12, v4
	v_fma_f32 v4, v9, v10, v12
	v_mul_f32_e32 v4, v5, v4
	v_bfe_u32 v5, v4, 16, 1
	v_add3_u32 v8, v4, v5, s39
	v_lshlrev_b64 v[4:5], 11, v[36:37]
	v_lshl_add_u64 v[4:5], v[32:33], 0, v[4:5]
	global_store_short_d16_hi v[4:5], v8, off offset:192
	s_or_b64 exec, exec, s[26:27]
	s_and_saveexec_b64 s[26:27], s[78:79]
	s_cbranch_execnz .LBB0_640

; DEVI float b2f(bfu b) { return __uint_as_float(((unsigned)b) << 16); }
; DEVI float siluf_(float x) { return x / (1.f + __expf(-x)); }
; DEVI void h3_item(const Params& P, int l, int ck, int h, char* smem, int tid) {
;     ...
;   for (int n = 0; n < 8; ++n)
; #pragma unroll
;     for (int j = 0; j < 4; ++j) {
;       int t = 16 * w + fq * 4 + j, e = n * 16 + fr;
;       if (t < L) {
;         float g = b2f(QT[t * 136 + e]);
;         UC[(long)(ci.lt0 + t) * 1024 + h * 128 + e] = f2b(o[n][j] * rinv[j] * ng[e] * siluf_(g));
;       }
;     }
.LBB0_611:
	ds_read_u16 v4, v218 offset:1008
	v_mul_f32_e32 v5, v7, v30
	s_waitcnt lgkmcnt(0)
	v_lshlrev_b32_e32 v4, 16, v4
	v_mul_f32_e32 v5, v5, v225
	v_mul_f32_e32 v6, 0xbfb8aa3b, v4
	v_exp_f32_e32 v6, v6
	s_nop 0
	v_add_f32_e32 v6, 1.0, v6
	v_min_f32_e32 v7, 0x7f7fffff, v6
	v_rcp_f32_e32 v8, v7
	s_nop 0
	v_fma_f32 v9, -v7, v8, 1.0
	v_fmac_f32_e32 v8, v9, v8
	v_mul_f32_e32 v10, v4, v8
	v_fma_f32 v11, -v7, v10, v4
	v_fmac_f32_e32 v10, v11, v8
	v_fma_f32 v7, -v7, v10, v4
	v_fma_f32 v4, v7, v8, v10
	v_mul_f32_e32 v4, v5, v4
	v_bfe_u32 v5, v4, 16, 1
	v_add3_u32 v6, v4, v5, s39
	v_lshlrev_b64 v[4:5], 11, v[38:39]
	v_lshl_add_u64 v[4:5], v[32:33], 0, v[4:5]
	global_store_short_d16_hi v[4:5], v6, off offset:192
	s_or_b64 exec, exec, s[26:27]
	s_and_saveexec_b64 s[26:27], s[74:75]
	s_cbranch_execnz .LBB0_642

; DEVI float b2f(bfu b) { return __uint_as_float(((unsigned)b) << 16); }
; DEVI float siluf_(float x) { return x / (1.f + __expf(-x)); }
; DEVI void h3_item(const Params& P, int l, int ck, int h, char* smem, int tid) {
;     ...
;   for (int n = 0; n < 8; ++n)
; #pragma unroll
;     for (int j = 0; j < 4; ++j) {
;       int t = 16 * w + fq * 4 + j, e = n * 16 + fr;
;       if (t < L) {
;         float g = b2f(QT[t * 136 + e]);
;         UC[(long)(ci.lt0 + t) * 1024 + h * 128 + e] = f2b(o[n][j] * rinv[j] * ng[e] * siluf_(g));
;       }
;     }
.LBB0_613:
	ds_read_u16 v0, v218 offset:496
	v_mul_f32_e32 v1, v1, v43
	s_waitcnt lgkmcnt(0)
	v_lshlrev_b32_e32 v0, 16, v0
	v_mul_f32_e32 v1, v1, v226
	v_mul_f32_e32 v4, 0xbfb8aa3b, v0
	v_exp_f32_e32 v4, v4
	s_nop 0
	v_add_f32_e32 v4, 1.0, v4
	v_min_f32_e32 v5, 0x7f7fffff, v4
	v_rcp_f32_e32 v6, v5
	s_nop 0
	v_fma_f32 v7, -v5, v6, 1.0
	v_fmac_f32_e32 v6, v7, v6
	v_mul_f32_e32 v8, v0, v6
	v_fma_f32 v9, -v5, v8, v0
	v_fmac_f32_e32 v8, v9, v6
	v_fma_f32 v5, -v5, v8, v0
	v_fma_f32 v0, v5, v6, v8
	v_mul_f32_e32 v0, v1, v0
	v_bfe_u32 v1, v0, 16, 1
	v_add3_u32 v4, v0, v1, s39
	v_lshlrev_b64 v[0:1], 11, v[36:37]
	v_lshl_add_u64 v[0:1], v[32:33], 0, v[0:1]
	global_store_short_d16_hi v[0:1], v4, off offset:224
	s_or_b64 exec, exec, s[26:27]
	s_and_saveexec_b64 s[26:27], s[78:79]
	s_cbranch_execnz .LBB0_644

; DEVI float b2f(bfu b) { return __uint_as_float(((unsigned)b) << 16); }
; DEVI float siluf_(float x) { return x / (1.f + __expf(-x)); }
; DEVI void h3_item(const Params& P, int l, int ck, int h, char* smem, int tid) {
;     ...
;   for (int n = 0; n < 8; ++n)
; #pragma unroll
;     for (int j = 0; j < 4; ++j) {
;       int t = 16 * w + fq * 4 + j, e = n * 16 + fr;
;       if (t < L) {
;         float g = b2f(QT[t * 136 + e]);
;         UC[(long)(ci.lt0 + t) * 1024 + h * 128 + e] = f2b(o[n][j] * rinv[j] * ng[e] * siluf_(g));
;       }
;     }
.LBB0_615:
	ds_read_u16 v0, v218 offset:1040
	v_mul_f32_e32 v1, v3, v30
	s_waitcnt lgkmcnt(0)
	v_lshlrev_b32_e32 v0, 16, v0
	v_mul_f32_e32 v1, v1, v226
	v_mul_f32_e32 v2, 0xbfb8aa3b, v0
	v_exp_f32_e32 v2, v2
	s_nop 0
	v_add_f32_e32 v2, 1.0, v2
	v_min_f32_e32 v3, 0x7f7fffff, v2
	v_rcp_f32_e32 v4, v3
	s_nop 0
	v_fma_f32 v5, -v3, v4, 1.0
	v_fmac_f32_e32 v4, v5, v4
	v_mul_f32_e32 v6, v0, v4
	v_fma_f32 v7, -v3, v6, v0
	v_fmac_f32_e32 v6, v7, v4
	v_fma_f32 v3, -v3, v6, v0
	v_fma_f32 v0, v3, v4, v6
	v_mul_f32_e32 v0, v1, v0
	v_bfe_u32 v1, v0, 16, 1
	v_add3_u32 v2, v0, v1, s39
	v_lshlrev_b64 v[0:1], 11, v[38:39]
	v_lshl_add_u64 v[0:1], v[32:33], 0, v[0:1]
	global_store_short_d16_hi v[0:1], v2, off offset:224

; DEVI float b2f(bfu b) { return __uint_as_float(((unsigned)b) << 16); }
; DEVI float siluf_(float x) { return x / (1.f + __expf(-x)); }
; DEVI void h3_item(const Params& P, int l, int ck, int h, char* smem, int tid) {
;     ...
;   for (int n = 0; n < 8; ++n)
; #pragma unroll
;     for (int j = 0; j < 4; ++j) {
;       int t = 16 * w + fq * 4 + j, e = n * 16 + fr;
;       if (t < L) {
;         float g = b2f(QT[t * 136 + e]);
;         UC[(long)(ci.lt0 + t) * 1024 + h * 128 + e] = f2b(o[n][j] * rinv[j] * ng[e] * siluf_(g));
;       }
;     }
.LBB0_618:
	ds_read_u16 v31, v218 offset:32
	v_mul_f32_e32 v24, v24, v42
	s_waitcnt lgkmcnt(0)
	v_lshlrev_b32_e32 v31, 16, v31
	v_mul_f32_e32 v24, v24, v220
	v_mul_f32_e32 v41, 0xbfb8aa3b, v31
	v_exp_f32_e32 v41, v41
	s_nop 0
	v_add_f32_e32 v41, 1.0, v41
	v_min_f32_e32 v44, 0x7f7fffff, v41
	v_rcp_f32_e32 v45, v44
	s_nop 0
	v_fma_f32 v46, -v44, v45, 1.0
	v_fmac_f32_e32 v45, v46, v45
	v_mul_f32_e32 v47, v31, v45
	v_fma_f32 v48, -v44, v47, v31
	v_fmac_f32_e32 v47, v48, v45
	v_fma_f32 v44, -v44, v47, v31
	v_fma_f32 v31, v44, v45, v47
	v_mul_f32_e32 v24, v24, v31
	v_bfe_u32 v31, v24, 16, 1
	v_lshlrev_b64 v[44:45], 11, v[34:35]
	v_add3_u32 v24, v24, v31, s39
	v_lshl_add_u64 v[44:45], v[32:33], 0, v[44:45]
	global_store_short_d16_hi v[44:45], v24, off offset:32
	s_or_b64 exec, exec, s[26:27]
	s_and_saveexec_b64 s[26:27], s[76:77]
	s_cbranch_execnz .LBB0_589

; DEVI float b2f(bfu b) { return __uint_as_float(((unsigned)b) << 16); }
; DEVI float siluf_(float x) { return x / (1.f + __expf(-x)); }
; DEVI void h3_item(const Params& P, int l, int ck, int h, char* smem, int tid) {
;     ...
;   for (int n = 0; n < 8; ++n)
; #pragma unroll
;     for (int j = 0; j < 4; ++j) {
;       int t = 16 * w + fq * 4 + j, e = n * 16 + fr;
;       if (t < L) {
;         float g = b2f(QT[t * 136 + e]);
;         UC[(long)(ci.lt0 + t) * 1024 + h * 128 + e] = f2b(o[n][j] * rinv[j] * ng[e] * siluf_(g));
;       }
;     }
.LBB0_620:
	v_mul_f32_e32 v25, v26, v40
	ds_read_u16 v24, v218 offset:576
	s_waitcnt lgkmcnt(0)
	v_lshlrev_b32_e32 v24, 16, v24
	v_mul_f32_e32 v25, v25, v220
	v_mul_f32_e32 v26, 0xbfb8aa3b, v24
	v_exp_f32_e32 v26, v26
	s_nop 0
	v_add_f32_e32 v26, 1.0, v26
	v_min_f32_e32 v31, 0x7f7fffff, v26
	v_rcp_f32_e32 v41, v31
	s_nop 0
	v_fma_f32 v44, -v31, v41, 1.0
	v_fmac_f32_e32 v41, v44, v41
	v_mul_f32_e32 v45, v24, v41
	v_fma_f32 v46, -v31, v45, v24
	v_fmac_f32_e32 v45, v46, v41
	v_fma_f32 v31, -v31, v45, v24
	v_fma_f32 v24, v31, v41, v45
	v_mul_f32_e32 v24, v25, v24
	v_bfe_u32 v25, v24, 16, 1
	v_add3_u32 v26, v24, v25, s39
	v_lshlrev_b64 v[24:25], 11, v[28:29]
	v_lshl_add_u64 v[24:25], v[32:33], 0, v[24:25]
	global_store_short_d16_hi v[24:25], v26, off offset:32
	s_or_b64 exec, exec, s[26:27]
	s_and_saveexec_b64 s[26:27], s[80:81]
	s_cbranch_execnz .LBB0_591

; DEVI float b2f(bfu b) { return __uint_as_float(((unsigned)b) << 16); }
; DEVI float siluf_(float x) { return x / (1.f + __expf(-x)); }
; DEVI void h3_item(const Params& P, int l, int ck, int h, char* smem, int tid) {
;     ...
;   for (int n = 0; n < 8; ++n)
; #pragma unroll
;     for (int j = 0; j < 4; ++j) {
;       int t = 16 * w + fq * 4 + j, e = n * 16 + fr;
;       if (t < L) {
;         float g = b2f(QT[t * 136 + e]);
;         UC[(long)(ci.lt0 + t) * 1024 + h * 128 + e] = f2b(o[n][j] * rinv[j] * ng[e] * siluf_(g));
;       }
;     }
.LBB0_622:
	ds_read_u16 v24, v218 offset:64
	v_mul_f32_e32 v20, v20, v42
	s_waitcnt lgkmcnt(0)
	v_lshlrev_b32_e32 v24, 16, v24
	v_mul_f32_e32 v20, v20, v221
	v_mul_f32_e32 v25, 0xbfb8aa3b, v24
	v_exp_f32_e32 v25, v25
	s_nop 0
	v_add_f32_e32 v25, 1.0, v25
	v_min_f32_e32 v26, 0x7f7fffff, v25
	v_rcp_f32_e32 v27, v26
	s_nop 0
	v_fma_f32 v31, -v26, v27, 1.0
	v_fmac_f32_e32 v27, v31, v27
	v_mul_f32_e32 v41, v24, v27
	v_fma_f32 v44, -v26, v41, v24
	v_fmac_f32_e32 v41, v44, v27
	v_fma_f32 v26, -v26, v41, v24
	v_fma_f32 v24, v26, v27, v41
	v_mul_f32_e32 v20, v20, v24
	v_bfe_u32 v24, v20, 16, 1
	v_add3_u32 v20, v20, v24, s39
	v_lshlrev_b64 v[24:25], 11, v[34:35]
	v_lshl_add_u64 v[24:25], v[32:33], 0, v[24:25]
	global_store_short_d16_hi v[24:25], v20, off offset:64
	s_or_b64 exec, exec, s[26:27]
	s_and_saveexec_b64 s[26:27], s[76:77]
	s_cbranch_execnz .LBB0_593

; DEVI float b2f(bfu b) { return __uint_as_float(((unsigned)b) << 16); }
; DEVI float siluf_(float x) { return x / (1.f + __expf(-x)); }
; DEVI void h3_item(const Params& P, int l, int ck, int h, char* smem, int tid) {
;     ...
;   for (int n = 0; n < 8; ++n)
; #pragma unroll
;     for (int j = 0; j < 4; ++j) {
;       int t = 16 * w + fq * 4 + j, e = n * 16 + fr;
;       if (t < L) {
;         float g = b2f(QT[t * 136 + e]);
;         UC[(long)(ci.lt0 + t) * 1024 + h * 128 + e] = f2b(o[n][j] * rinv[j] * ng[e] * siluf_(g));
;       }
;     }
.LBB0_624:
	v_mul_f32_e32 v21, v22, v40
	ds_read_u16 v20, v218 offset:608
	s_waitcnt lgkmcnt(0)
	v_lshlrev_b32_e32 v20, 16, v20
	v_mul_f32_e32 v21, v21, v221
	v_mul_f32_e32 v22, 0xbfb8aa3b, v20
	v_exp_f32_e32 v22, v22
	s_nop 0
	v_add_f32_e32 v22, 1.0, v22
	v_min_f32_e32 v24, 0x7f7fffff, v22
	v_rcp_f32_e32 v25, v24
	s_nop 0
	v_fma_f32 v26, -v24, v25, 1.0
	v_fmac_f32_e32 v25, v26, v25
	v_mul_f32_e32 v27, v20, v25
	v_fma_f32 v31, -v24, v27, v20
	v_fmac_f32_e32 v27, v31, v25
	v_fma_f32 v24, -v24, v27, v20
	v_fma_f32 v20, v24, v25, v27
	v_mul_f32_e32 v20, v21, v20
	v_bfe_u32 v21, v20, 16, 1
	v_add3_u32 v22, v20, v21, s39
	v_lshlrev_b64 v[20:21], 11, v[28:29]
	v_lshl_add_u64 v[20:21], v[32:33], 0, v[20:21]
	global_store_short_d16_hi v[20:21], v22, off offset:64
	s_or_b64 exec, exec, s[26:27]
	s_and_saveexec_b64 s[26:27], s[80:81]
	s_cbranch_execnz .LBB0_595

; DEVI float b2f(bfu b) { return __uint_as_float(((unsigned)b) << 16); }
; DEVI float siluf_(float x) { return x / (1.f + __expf(-x)); }
; DEVI void h3_item(const Params& P, int l, int ck, int h, char* smem, int tid) {
;     ...
;   for (int n = 0; n < 8; ++n)
; #pragma unroll
;     for (int j = 0; j < 4; ++j) {
;       int t = 16 * w + fq * 4 + j, e = n * 16 + fr;
;       if (t < L) {
;         float g = b2f(QT[t * 136 + e]);
;         UC[(long)(ci.lt0 + t) * 1024 + h * 128 + e] = f2b(o[n][j] * rinv[j] * ng[e] * siluf_(g));
;       }
;     }
.LBB0_626:
	ds_read_u16 v20, v218 offset:96
	v_mul_f32_e32 v16, v16, v42
	s_waitcnt lgkmcnt(0)
	v_lshlrev_b32_e32 v20, 16, v20
	v_mul_f32_e32 v16, v16, v222
	v_mul_f32_e32 v21, 0xbfb8aa3b, v20
	v_exp_f32_e32 v21, v21
	s_nop 0
	v_add_f32_e32 v21, 1.0, v21
	v_min_f32_e32 v22, 0x7f7fffff, v21
	v_rcp_f32_e32 v23, v22
	s_nop 0
	v_fma_f32 v24, -v22, v23, 1.0
	v_fmac_f32_e32 v23, v24, v23
	v_mul_f32_e32 v25, v20, v23
	v_fma_f32 v26, -v22, v25, v20
	v_fmac_f32_e32 v25, v26, v23
	v_fma_f32 v22, -v22, v25, v20
	v_fma_f32 v20, v22, v23, v25
	v_mul_f32_e32 v16, v16, v20
	v_bfe_u32 v20, v16, 16, 1
	v_add3_u32 v16, v16, v20, s39
	v_lshlrev_b64 v[20:21], 11, v[34:35]
	v_lshl_add_u64 v[20:21], v[32:33], 0, v[20:21]
	global_store_short_d16_hi v[20:21], v16, off offset:96
	s_or_b64 exec, exec, s[26:27]
	s_and_saveexec_b64 s[26:27], s[76:77]
	s_cbranch_execnz .LBB0_597

; DEVI float b2f(bfu b) { return __uint_as_float(((unsigned)b) << 16); }
; DEVI float siluf_(float x) { return x / (1.f + __expf(-x)); }
; DEVI void h3_item(const Params& P, int l, int ck, int h, char* smem, int tid) {
;     ...
;   for (int n = 0; n < 8; ++n)
; #pragma unroll
;     for (int j = 0; j < 4; ++j) {
;       int t = 16 * w + fq * 4 + j, e = n * 16 + fr;
;       if (t < L) {
;         float g = b2f(QT[t * 136 + e]);
;         UC[(long)(ci.lt0 + t) * 1024 + h * 128 + e] = f2b(o[n][j] * rinv[j] * ng[e] * siluf_(g));
;       }
;     }
.LBB0_628:
	v_mul_f32_e32 v17, v18, v40
	ds_read_u16 v16, v218 offset:640
	s_waitcnt lgkmcnt(0)
	v_lshlrev_b32_e32 v16, 16, v16
	v_mul_f32_e32 v17, v17, v222
	v_mul_f32_e32 v18, 0xbfb8aa3b, v16
	v_exp_f32_e32 v18, v18
	s_nop 0
	v_add_f32_e32 v18, 1.0, v18
	v_min_f32_e32 v20, 0x7f7fffff, v18
	v_rcp_f32_e32 v21, v20
	s_nop 0
	v_fma_f32 v22, -v20, v21, 1.0
	v_fmac_f32_e32 v21, v22, v21
	v_mul_f32_e32 v23, v16, v21
	v_fma_f32 v24, -v20, v23, v16
	v_fmac_f32_e32 v23, v24, v21
	v_fma_f32 v20, -v20, v23, v16
	v_fma_f32 v16, v20, v21, v23
	v_mul_f32_e32 v16, v17, v16
	v_bfe_u32 v17, v16, 16, 1
	v_add3_u32 v18, v16, v17, s39
	v_lshlrev_b64 v[16:17], 11, v[28:29]
	v_lshl_add_u64 v[16:17], v[32:33], 0, v[16:17]
	global_store_short_d16_hi v[16:17], v18, off offset:96
	s_or_b64 exec, exec, s[26:27]
	s_and_saveexec_b64 s[26:27], s[80:81]
	s_cbranch_execnz .LBB0_599

; DEVI float b2f(bfu b) { return __uint_as_float(((unsigned)b) << 16); }
; DEVI float siluf_(float x) { return x / (1.f + __expf(-x)); }
; DEVI void h3_item(const Params& P, int l, int ck, int h, char* smem, int tid) {
;     ...
;   for (int n = 0; n < 8; ++n)
; #pragma unroll
;     for (int j = 0; j < 4; ++j) {
;       int t = 16 * w + fq * 4 + j, e = n * 16 + fr;
;       if (t < L) {
;         float g = b2f(QT[t * 136 + e]);
;         UC[(long)(ci.lt0 + t) * 1024 + h * 128 + e] = f2b(o[n][j] * rinv[j] * ng[e] * siluf_(g));
;       }
;     }
.LBB0_630:
	ds_read_u16 v16, v218 offset:128
	v_mul_f32_e32 v12, v12, v42
	s_waitcnt lgkmcnt(0)
	v_lshlrev_b32_e32 v16, 16, v16
	v_mul_f32_e32 v12, v12, v223
	v_mul_f32_e32 v17, 0xbfb8aa3b, v16
	v_exp_f32_e32 v17, v17
	s_nop 0
	v_add_f32_e32 v17, 1.0, v17
	v_min_f32_e32 v18, 0x7f7fffff, v17
	v_rcp_f32_e32 v19, v18
	s_nop 0
	v_fma_f32 v20, -v18, v19, 1.0
	v_fmac_f32_e32 v19, v20, v19
	v_mul_f32_e32 v21, v16, v19
	v_fma_f32 v22, -v18, v21, v16
	v_fmac_f32_e32 v21, v22, v19
	v_fma_f32 v18, -v18, v21, v16
	v_fma_f32 v16, v18, v19, v21
	v_mul_f32_e32 v12, v12, v16
	v_bfe_u32 v16, v12, 16, 1
	v_add3_u32 v12, v12, v16, s39
	v_lshlrev_b64 v[16:17], 11, v[34:35]
	v_lshl_add_u64 v[16:17], v[32:33], 0, v[16:17]
	global_store_short_d16_hi v[16:17], v12, off offset:128
	s_or_b64 exec, exec, s[26:27]
	s_and_saveexec_b64 s[26:27], s[76:77]
	s_cbranch_execnz .LBB0_601

; DEVI float b2f(bfu b) { return __uint_as_float(((unsigned)b) << 16); }
; DEVI float siluf_(float x) { return x / (1.f + __expf(-x)); }
; DEVI void h3_item(const Params& P, int l, int ck, int h, char* smem, int tid) {
;     ...
;   for (int n = 0; n < 8; ++n)
; #pragma unroll
;     for (int j = 0; j < 4; ++j) {
;       int t = 16 * w + fq * 4 + j, e = n * 16 + fr;
;       if (t < L) {
;         float g = b2f(QT[t * 136 + e]);
;         UC[(long)(ci.lt0 + t) * 1024 + h * 128 + e] = f2b(o[n][j] * rinv[j] * ng[e] * siluf_(g));
;       }
;     }
.LBB0_632:
	v_mul_f32_e32 v13, v14, v40
	ds_read_u16 v12, v218 offset:672
	s_waitcnt lgkmcnt(0)
	v_lshlrev_b32_e32 v12, 16, v12
	v_mul_f32_e32 v13, v13, v223
	v_mul_f32_e32 v14, 0xbfb8aa3b, v12
	v_exp_f32_e32 v14, v14
	s_nop 0
	v_add_f32_e32 v14, 1.0, v14
	v_min_f32_e32 v16, 0x7f7fffff, v14
	v_rcp_f32_e32 v17, v16
	s_nop 0
	v_fma_f32 v18, -v16, v17, 1.0
	v_fmac_f32_e32 v17, v18, v17
	v_mul_f32_e32 v19, v12, v17
	v_fma_f32 v20, -v16, v19, v12
	v_fmac_f32_e32 v19, v20, v17
	v_fma_f32 v16, -v16, v19, v12
	v_fma_f32 v12, v16, v17, v19
	v_mul_f32_e32 v12, v13, v12
	v_bfe_u32 v13, v12, 16, 1
	v_add3_u32 v14, v12, v13, s39
	v_lshlrev_b64 v[12:13], 11, v[28:29]
	v_lshl_add_u64 v[12:13], v[32:33], 0, v[12:13]
	global_store_short_d16_hi v[12:13], v14, off offset:128
	s_or_b64 exec, exec, s[26:27]
	s_and_saveexec_b64 s[26:27], s[80:81]
	s_cbranch_execnz .LBB0_603

; DEVI float b2f(bfu b) { return __uint_as_float(((unsigned)b) << 16); }
; DEVI float siluf_(float x) { return x / (1.f + __expf(-x)); }
; DEVI void h3_item(const Params& P, int l, int ck, int h, char* smem, int tid) {
;     ...
;   for (int n = 0; n < 8; ++n)
; #pragma unroll
;     for (int j = 0; j < 4; ++j) {
;       int t = 16 * w + fq * 4 + j, e = n * 16 + fr;
;       if (t < L) {
;         float g = b2f(QT[t * 136 + e]);
;         UC[(long)(ci.lt0 + t) * 1024 + h * 128 + e] = f2b(o[n][j] * rinv[j] * ng[e] * siluf_(g));
;       }
;     }
.LBB0_634:
	ds_read_u16 v12, v218 offset:160
	v_mul_f32_e32 v8, v8, v42
	s_waitcnt lgkmcnt(0)
	v_lshlrev_b32_e32 v12, 16, v12
	v_mul_f32_e32 v8, v8, v224
	v_mul_f32_e32 v13, 0xbfb8aa3b, v12
	v_exp_f32_e32 v13, v13
	s_nop 0
	v_add_f32_e32 v13, 1.0, v13
	v_min_f32_e32 v14, 0x7f7fffff, v13
	v_rcp_f32_e32 v15, v14
	s_nop 0
	v_fma_f32 v16, -v14, v15, 1.0
	v_fmac_f32_e32 v15, v16, v15
	v_mul_f32_e32 v17, v12, v15
	v_fma_f32 v18, -v14, v17, v12
	v_fmac_f32_e32 v17, v18, v15
	v_fma_f32 v14, -v14, v17, v12
	v_fma_f32 v12, v14, v15, v17
	v_mul_f32_e32 v8, v8, v12
	v_bfe_u32 v12, v8, 16, 1
	v_add3_u32 v8, v8, v12, s39
	v_lshlrev_b64 v[12:13], 11, v[34:35]
	v_lshl_add_u64 v[12:13], v[32:33], 0, v[12:13]
	global_store_short_d16_hi v[12:13], v8, off offset:160
	s_or_b64 exec, exec, s[26:27]
	s_and_saveexec_b64 s[26:27], s[76:77]
	s_cbranch_execnz .LBB0_605

; DEVI float b2f(bfu b) { return __uint_as_float(((unsigned)b) << 16); }
; DEVI float siluf_(float x) { return x / (1.f + __expf(-x)); }
; DEVI void h3_item(const Params& P, int l, int ck, int h, char* smem, int tid) {
;     ...
;   for (int n = 0; n < 8; ++n)
; #pragma unroll
;     for (int j = 0; j < 4; ++j) {
;       int t = 16 * w + fq * 4 + j, e = n * 16 + fr;
;       if (t < L) {
;         float g = b2f(QT[t * 136 + e]);
;         UC[(long)(ci.lt0 + t) * 1024 + h * 128 + e] = f2b(o[n][j] * rinv[j] * ng[e] * siluf_(g));
;       }
;     }
.LBB0_636:
	v_mul_f32_e32 v9, v10, v40
	ds_read_u16 v8, v218 offset:704
	s_waitcnt lgkmcnt(0)
	v_lshlrev_b32_e32 v8, 16, v8
	v_mul_f32_e32 v9, v9, v224
	v_mul_f32_e32 v10, 0xbfb8aa3b, v8
	v_exp_f32_e32 v10, v10
	s_nop 0
	v_add_f32_e32 v10, 1.0, v10
	v_min_f32_e32 v12, 0x7f7fffff, v10
	v_rcp_f32_e32 v13, v12
	s_nop 0
	v_fma_f32 v14, -v12, v13, 1.0
	v_fmac_f32_e32 v13, v14, v13
	v_mul_f32_e32 v15, v8, v13
	v_fma_f32 v16, -v12, v15, v8
	v_fmac_f32_e32 v15, v16, v13
	v_fma_f32 v12, -v12, v15, v8
	v_fma_f32 v8, v12, v13, v15
	v_mul_f32_e32 v8, v9, v8
	v_bfe_u32 v9, v8, 16, 1
	v_add3_u32 v10, v8, v9, s39
	v_lshlrev_b64 v[8:9], 11, v[28:29]
	v_lshl_add_u64 v[8:9], v[32:33], 0, v[8:9]
	global_store_short_d16_hi v[8:9], v10, off offset:160
	s_or_b64 exec, exec, s[26:27]
	s_and_saveexec_b64 s[26:27], s[80:81]
	s_cbranch_execnz .LBB0_607

; DEVI float b2f(bfu b) { return __uint_as_float(((unsigned)b) << 16); }
; DEVI float siluf_(float x) { return x / (1.f + __expf(-x)); }
; DEVI void h3_item(const Params& P, int l, int ck, int h, char* smem, int tid) {
;     ...
;   for (int n = 0; n < 8; ++n)
; #pragma unroll
;     for (int j = 0; j < 4; ++j) {
;       int t = 16 * w + fq * 4 + j, e = n * 16 + fr;
;       if (t < L) {
;         float g = b2f(QT[t * 136 + e]);
;         UC[(long)(ci.lt0 + t) * 1024 + h * 128 + e] = f2b(o[n][j] * rinv[j] * ng[e] * siluf_(g));
;       }
;     }
.LBB0_638:
	ds_read_u16 v8, v218 offset:192
	v_mul_f32_e32 v4, v4, v42
	s_waitcnt lgkmcnt(0)
	v_lshlrev_b32_e32 v8, 16, v8
	v_mul_f32_e32 v4, v4, v225
	v_mul_f32_e32 v9, 0xbfb8aa3b, v8
	v_exp_f32_e32 v9, v9
	s_nop 0
	v_add_f32_e32 v9, 1.0, v9
	v_min_f32_e32 v10, 0x7f7fffff, v9
	v_rcp_f32_e32 v11, v10
	s_nop 0
	v_fma_f32 v12, -v10, v11, 1.0
	v_fmac_f32_e32 v11, v12, v11
	v_mul_f32_e32 v13, v8, v11
	v_fma_f32 v14, -v10, v13, v8
	v_fmac_f32_e32 v13, v14, v11
	v_fma_f32 v10, -v10, v13, v8
	v_fma_f32 v8, v10, v11, v13
	v_mul_f32_e32 v4, v4, v8
	v_bfe_u32 v8, v4, 16, 1
	v_add3_u32 v4, v4, v8, s39
	v_lshlrev_b64 v[8:9], 11, v[34:35]
	v_lshl_add_u64 v[8:9], v[32:33], 0, v[8:9]
	global_store_short_d16_hi v[8:9], v4, off offset:192
	s_or_b64 exec, exec, s[26:27]
	s_and_saveexec_b64 s[26:27], s[76:77]
	s_cbranch_execnz .LBB0_609

; DEVI float b2f(bfu b) { return __uint_as_float(((unsigned)b) << 16); }
; DEVI float siluf_(float x) { return x / (1.f + __expf(-x)); }
; DEVI void h3_item(const Params& P, int l, int ck, int h, char* smem, int tid) {
;     ...
;   for (int n = 0; n < 8; ++n)
; #pragma unroll
;     for (int j = 0; j < 4; ++j) {
;       int t = 16 * w + fq * 4 + j, e = n * 16 + fr;
;       if (t < L) {
;         float g = b2f(QT[t * 136 + e]);
;         UC[(long)(ci.lt0 + t) * 1024 + h * 128 + e] = f2b(o[n][j] * rinv[j] * ng[e] * siluf_(g));
;       }
;     }
.LBB0_640:
	v_mul_f32_e32 v5, v6, v40
	ds_read_u16 v4, v218 offset:736
	s_waitcnt lgkmcnt(0)
	v_lshlrev_b32_e32 v4, 16, v4
	v_mul_f32_e32 v5, v5, v225
	v_mul_f32_e32 v6, 0xbfb8aa3b, v4
	v_exp_f32_e32 v6, v6
	s_nop 0
	v_add_f32_e32 v6, 1.0, v6
	v_min_f32_e32 v8, 0x7f7fffff, v6
	v_rcp_f32_e32 v9, v8
	s_nop 0
	v_fma_f32 v10, -v8, v9, 1.0
	v_fmac_f32_e32 v9, v10, v9
	v_mul_f32_e32 v11, v4, v9
	v_fma_f32 v12, -v8, v11, v4
	v_fmac_f32_e32 v11, v12, v9
	v_fma_f32 v8, -v8, v11, v4
	v_fma_f32 v4, v8, v9, v11
	v_mul_f32_e32 v4, v5, v4
	v_bfe_u32 v5, v4, 16, 1
	v_add3_u32 v6, v4, v5, s39
	v_lshlrev_b64 v[4:5], 11, v[28:29]
	v_lshl_add_u64 v[4:5], v[32:33], 0, v[4:5]
	global_store_short_d16_hi v[4:5], v6, off offset:192
	s_or_b64 exec, exec, s[26:27]
	s_and_saveexec_b64 s[26:27], s[80:81]
	s_cbranch_execnz .LBB0_611

; DEVI float b2f(bfu b) { return __uint_as_float(((unsigned)b) << 16); }
; DEVI float siluf_(float x) { return x / (1.f + __expf(-x)); }
; DEVI void h3_item(const Params& P, int l, int ck, int h, char* smem, int tid) {
;     ...
;   for (int n = 0; n < 8; ++n)
; #pragma unroll
;     for (int j = 0; j < 4; ++j) {
;       int t = 16 * w + fq * 4 + j, e = n * 16 + fr;
;       if (t < L) {
;         float g = b2f(QT[t * 136 + e]);
;         UC[(long)(ci.lt0 + t) * 1024 + h * 128 + e] = f2b(o[n][j] * rinv[j] * ng[e] * siluf_(g));
;       }
;     }
.LBB0_642:
	ds_read_u16 v4, v218 offset:224
	v_mul_f32_e32 v0, v0, v42
	s_waitcnt lgkmcnt(0)
	v_lshlrev_b32_e32 v4, 16, v4
	v_mul_f32_e32 v0, v0, v226
	v_mul_f32_e32 v5, 0xbfb8aa3b, v4
	v_exp_f32_e32 v5, v5
	s_nop 0
	v_add_f32_e32 v5, 1.0, v5
	v_min_f32_e32 v6, 0x7f7fffff, v5
	v_rcp_f32_e32 v7, v6
	s_nop 0
	v_fma_f32 v8, -v6, v7, 1.0
	v_fmac_f32_e32 v7, v8, v7
	v_mul_f32_e32 v9, v4, v7
	v_fma_f32 v10, -v6, v9, v4
	v_fmac_f32_e32 v9, v10, v7
	v_fma_f32 v6, -v6, v9, v4
	v_fma_f32 v4, v6, v7, v9
	v_mul_f32_e32 v0, v0, v4
	v_bfe_u32 v4, v0, 16, 1
	v_add3_u32 v0, v0, v4, s39
	v_lshlrev_b64 v[4:5], 11, v[34:35]
	v_lshl_add_u64 v[4:5], v[32:33], 0, v[4:5]
	global_store_short_d16_hi v[4:5], v0, off offset:224
	s_or_b64 exec, exec, s[26:27]
	s_and_saveexec_b64 s[26:27], s[76:77]
	s_cbranch_execnz .LBB0_613

; DEVI float b2f(bfu b) { return __uint_as_float(((unsigned)b) << 16); }
; DEVI float siluf_(float x) { return x / (1.f + __expf(-x)); }
; DEVI void h3_item(const Params& P, int l, int ck, int h, char* smem, int tid) {
;     ...
;   for (int n = 0; n < 8; ++n)
; #pragma unroll
;     for (int j = 0; j < 4; ++j) {
;       int t = 16 * w + fq * 4 + j, e = n * 16 + fr;
;       if (t < L) {
;         float g = b2f(QT[t * 136 + e]);
;         UC[(long)(ci.lt0 + t) * 1024 + h * 128 + e] = f2b(o[n][j] * rinv[j] * ng[e] * siluf_(g));
;       }
;     }
.LBB0_644:
	v_mul_f32_e32 v1, v2, v40
	ds_read_u16 v0, v218 offset:768
	s_waitcnt lgkmcnt(0)
	v_lshlrev_b32_e32 v0, 16, v0
	v_mul_f32_e32 v1, v1, v226
	v_mul_f32_e32 v2, 0xbfb8aa3b, v0
	v_exp_f32_e32 v2, v2
	s_nop 0
	v_add_f32_e32 v2, 1.0, v2
	v_min_f32_e32 v4, 0x7f7fffff, v2
	v_rcp_f32_e32 v5, v4
	s_nop 0
	v_fma_f32 v6, -v4, v5, 1.0
	v_fmac_f32_e32 v5, v6, v5
	v_mul_f32_e32 v7, v0, v5
	v_fma_f32 v8, -v4, v7, v0
	v_fmac_f32_e32 v7, v8, v5
	v_fma_f32 v4, -v4, v7, v0
	v_fma_f32 v0, v4, v5, v7
	v_mul_f32_e32 v0, v1, v0
	v_bfe_u32 v1, v0, 16, 1
	v_add3_u32 v2, v0, v1, s39
	v_lshlrev_b64 v[0:1], 11, v[28:29]
	v_lshl_add_u64 v[0:1], v[32:33], 0, v[0:1]
	global_store_short_d16_hi v[0:1], v2, off offset:224
	s_or_b64 exec, exec, s[26:27]
	s_and_saveexec_b64 s[26:27], s[80:81]
	s_cbranch_execnz .LBB0_615
	s_branch .LBB0_616

; DEVI float sigmoidf_(float x) { return 1.f / (1.f + __expf(-x)); }
; template <int BR, int IN, int OUT>
; DEVI void p6_branch(const Params& P, int pm, int pn, float* macc, char* smem, int tid) {
;     ...
;   for (int q = 0; q < 16; ++q) {
;     const int id = tid + 256 * q, row = id >> 5, c4 = id & 31;
;     const long grow = (long)pm * 128 + row;
;     const int gcol = pn * 128 + c4 * 4;
;     float4 a = *reinterpret_cast<const float4*>(T + row * 128 + c4 * 4);
;     float g[4];
;     load4bf(Z + grow * NCOL + (9 + BR) * 1024 + gcol, g);
;     float v[4] = {sigmoidf_(g[0]) * a.x, sigmoidf_(g[1]) * a.y, sigmoidf_(g[2]) * a.z, sigmoidf_(g[3]) * a.w};
;     if (IN == 1) {
;       float mo[4]; load4bf(M + grow * 1024 + gcol, mo);
;       v[0] += mo[0]; v[1] += mo[1]; v[2] += mo[2]; v[3] += mo[3];
;     }
;     if (IN == 2) {
;       float4 mo = *reinterpret_cast<const float4*>(macc + grow * 1024 + gcol);
.LBB0_737:
	v_add_u32_e32 v242, s24, v91
	v_ashrrev_i32_e32 v240, 5, v242
	v_ashrrev_i32_e32 v241, 31, v240
	v_lshl_add_u64 v[244:245], s[46:47], 0, v[240:241]
	v_mov_b64_e32 v[240:241], s[44:45]
	v_mad_u64_u32 v[246:247], s[48:49], v244, s22, v[240:241]
	v_mad_i32_i24 v247, v245, s22, v247
	v_lshl_add_u64 v[246:247], v[246:247], 0, v[4:5]
	v_add_co_u32_e32 v246, vcc, 0x5000, v246
	s_nop 1
	v_addc_co_u32_e32 v247, vcc, 0, v247, vcc
	global_load_dwordx2 v[208:209], v[246:247], off offset:2048
	v_add_u32_e32 v242, s24, v91
	v_ashrrev_i32_e32 v240, 5, v242
	v_ashrrev_i32_e32 v241, 31, v240
	v_lshl_add_u64 v[244:245], s[46:47], 0, v[240:241]
	v_lshlrev_b64 v[246:247], 11, v[244:245]
	v_lshl_add_u64 v[246:247], v[0:1], 0, v[246:247]
	global_load_dwordx2 v[210:211], v[246:247], off
	v_add_u32_e32 v242, s24, v91
	v_mov_b64_e32 v[240:241], s[44:45]
	v_add_u32_e32 v243, 0x100, v242
	v_ashrrev_i32_e32 v244, 5, v243
	v_ashrrev_i32_e32 v245, 31, v244
	v_lshl_add_u64 v[246:247], s[46:47], 0, v[244:245]
	v_mad_u64_u32 v[244:245], s[48:49], v246, s22, v[240:241]
	v_mad_i32_i24 v245, v247, s22, v245
	v_lshl_add_u64 v[244:245], v[244:245], 0, v[4:5]
	v_add_co_u32_e32 v244, vcc, s21, v244
	s_nop 1
	v_addc_co_u32_e32 v245, vcc, 0, v245, vcc
	global_load_dwordx2 v[212:213], v[244:245], off offset:2048
	v_add_u32_e32 v240, s24, v91
	v_add_u32_e32 v241, 0x100, v240
	v_ashrrev_i32_e32 v242, 5, v241
	v_ashrrev_i32_e32 v243, 31, v242
	v_lshl_add_u64 v[244:245], s[46:47], 0, v[242:243]
	v_lshlrev_b64 v[242:243], 11, v[244:245]
	v_lshl_add_u64 v[242:243], v[0:1], 0, v[242:243]
	global_load_dwordx2 v[214:215], v[242:243], off
	v_add_u32_e32 v242, s24, v91
	v_mov_b64_e32 v[240:241], s[44:45]
	v_add_u32_e32 v243, 0x200, v242
	v_ashrrev_i32_e32 v244, 5, v243
	v_ashrrev_i32_e32 v245, 31, v244
	v_lshl_add_u64 v[246:247], s[46:47], 0, v[244:245]
	v_mad_u64_u32 v[244:245], s[48:49], v246, s22, v[240:241]
	v_mad_i32_i24 v245, v247, s22, v245
	v_lshl_add_u64 v[244:245], v[244:245], 0, v[4:5]
	v_add_co_u32_e32 v244, vcc, s21, v244
	s_nop 1
	v_addc_co_u32_e32 v245, vcc, 0, v245, vcc
	global_load_dwordx2 v[216:217], v[244:245], off offset:2048
	v_add_u32_e32 v240, s24, v91
	v_add_u32_e32 v241, 0x200, v240
	v_ashrrev_i32_e32 v242, 5, v241
	v_ashrrev_i32_e32 v243, 31, v242
	v_lshl_add_u64 v[244:245], s[46:47], 0, v[242:243]
	v_lshlrev_b64 v[242:243], 11, v[244:245]
	v_lshl_add_u64 v[242:243], v[0:1], 0, v[242:243]
	global_load_dwordx2 v[218:219], v[242:243], off
	v_add_u32_e32 v242, s24, v91
	v_mov_b64_e32 v[240:241], s[44:45]
	v_add_u32_e32 v243, 0x300, v242
	v_ashrrev_i32_e32 v244, 5, v243
	v_ashrrev_i32_e32 v245, 31, v244
	v_lshl_add_u64 v[246:247], s[46:47], 0, v[244:245]
	v_mad_u64_u32 v[244:245], s[48:49], v246, s22, v[240:241]
	v_mad_i32_i24 v245, v247, s22, v245
	v_lshl_add_u64 v[244:245], v[244:245], 0, v[4:5]
	v_add_co_u32_e32 v244, vcc, s21, v244
	s_nop 1
	v_addc_co_u32_e32 v245, vcc, 0, v245, vcc
	global_load_dwordx2 v[220:221], v[244:245], off offset:2048
	v_add_u32_e32 v240, s24, v91
	v_add_u32_e32 v241, 0x300, v240
	v_ashrrev_i32_e32 v242, 5, v241
	v_ashrrev_i32_e32 v243, 31, v242
	v_lshl_add_u64 v[244:245], s[46:47], 0, v[242:243]
	v_lshlrev_b64 v[242:243], 11, v[244:245]
	v_lshl_add_u64 v[242:243], v[0:1], 0, v[242:243]
	global_load_dwordx2 v[222:223], v[242:243], off
	v_add_u32_e32 v242, s24, v91
	v_mov_b64_e32 v[240:241], s[44:45]
	v_add_u32_e32 v243, 0x400, v242
	v_ashrrev_i32_e32 v244, 5, v243
	v_ashrrev_i32_e32 v245, 31, v244
	v_lshl_add_u64 v[246:247], s[46:47], 0, v[244:245]
	v_mad_u64_u32 v[244:245], s[48:49], v246, s22, v[240:241]
	v_mad_i32_i24 v245, v247, s22, v245
	v_lshl_add_u64 v[244:245], v[244:245], 0, v[4:5]
	v_add_co_u32_e32 v244, vcc, s21, v244
	s_nop 1
	v_addc_co_u32_e32 v245, vcc, 0, v245, vcc
	global_load_dwordx2 v[224:225], v[244:245], off offset:2048
	v_add_u32_e32 v240, s24, v91
	v_add_u32_e32 v241, 0x400, v240
	v_ashrrev_i32_e32 v242, 5, v241
	v_ashrrev_i32_e32 v243, 31, v242
	v_lshl_add_u64 v[244:245], s[46:47], 0, v[242:243]
	v_lshlrev_b64 v[242:243], 11, v[244:245]
	v_lshl_add_u64 v[242:243], v[0:1], 0, v[242:243]
	global_load_dwordx2 v[226:227], v[242:243], off
	v_add_u32_e32 v242, s24, v91
	v_mov_b64_e32 v[240:241], s[44:45]
	v_add_u32_e32 v243, 0x500, v242
	v_ashrrev_i32_e32 v244, 5, v243
	v_ashrrev_i32_e32 v245, 31, v244
	v_lshl_add_u64 v[246:247], s[46:47], 0, v[244:245]
	v_mad_u64_u32 v[244:245], s[48:49], v246, s22, v[240:241]
	v_mad_i32_i24 v245, v247, s22, v245
	v_lshl_add_u64 v[244:245], v[244:245], 0, v[4:5]
	v_add_co_u32_e32 v244, vcc, s21, v244
	s_nop 1
	v_addc_co_u32_e32 v245, vcc, 0, v245, vcc
	global_load_dwordx2 v[228:229], v[244:245], off offset:2048
	v_add_u32_e32 v240, s24, v91
	v_add_u32_e32 v241, 0x500, v240
	v_ashrrev_i32_e32 v242, 5, v241
	v_ashrrev_i32_e32 v243, 31, v242
	v_lshl_add_u64 v[244:245], s[46:47], 0, v[242:243]
	v_lshlrev_b64 v[242:243], 11, v[244:245]
	v_lshl_add_u64 v[242:243], v[0:1], 0, v[242:243]
	global_load_dwordx2 v[230:231], v[242:243], off
	v_add_u32_e32 v242, s24, v91
	v_mov_b64_e32 v[240:241], s[44:45]
	v_add_u32_e32 v243, 0x600, v242
	v_ashrrev_i32_e32 v244, 5, v243
	v_ashrrev_i32_e32 v245, 31, v244
	v_lshl_add_u64 v[246:247], s[46:47], 0, v[244:245]
	v_mad_u64_u32 v[244:245], s[48:49], v246, s22, v[240:241]
	v_mad_i32_i24 v245, v247, s22, v245
	v_lshl_add_u64 v[244:245], v[244:245], 0, v[4:5]
	v_add_co_u32_e32 v244, vcc, s21, v244
	s_nop 1
	v_addc_co_u32_e32 v245, vcc, 0, v245, vcc
	global_load_dwordx2 v[232:233], v[244:245], off offset:2048
	v_add_u32_e32 v240, s24, v91
	v_add_u32_e32 v241, 0x600, v240
	v_ashrrev_i32_e32 v242, 5, v241
	v_ashrrev_i32_e32 v243, 31, v242
	v_lshl_add_u64 v[244:245], s[46:47], 0, v[242:243]
	v_lshlrev_b64 v[242:243], 11, v[244:245]
	v_lshl_add_u64 v[242:243], v[0:1], 0, v[242:243]
	global_load_dwordx2 v[234:235], v[242:243], off
	v_add_u32_e32 v242, s24, v91
	v_mov_b64_e32 v[240:241], s[44:45]
	v_add_u32_e32 v242, 0x700, v242
	v_ashrrev_i32_e32 v242, 5, v242
	v_ashrrev_i32_e32 v243, 31, v242
	v_lshl_add_u64 v[244:245], s[46:47], 0, v[242:243]
	v_mad_u64_u32 v[240:241], s[48:49], v244, s22, v[240:241]
	v_mad_i32_i24 v241, v245, s22, v241
	v_lshl_add_u64 v[240:241], v[240:241], 0, v[4:5]
	v_add_co_u32_e32 v240, vcc, s21, v240
	s_nop 1
	v_addc_co_u32_e32 v241, vcc, 0, v241, vcc
	global_load_dwordx2 v[236:237], v[240:241], off offset:2048
	v_add_u32_e32 v242, s24, v91
	v_add_u32_e32 v242, 0x700, v242
	v_ashrrev_i32_e32 v242, 5, v242
	v_ashrrev_i32_e32 v243, 31, v242
	v_lshl_add_u64 v[244:245], s[46:47], 0, v[242:243]
	v_lshlrev_b64 v[240:241], 11, v[244:245]
	v_lshl_add_u64 v[240:241], v[0:1], 0, v[240:241]
	global_load_dwordx2 v[238:239], v[240:241], off
	s_waitcnt vmcnt(0)
; DEVI float sigmoidf_(float x) { return 1.f / (1.f + __expf(-x)); }
; template <int BR, int IN, int OUT>
; DEVI void p6_branch(const Params& P, int pm, int pn, float* macc, char* smem, int tid) {
;     ...
;   for (int q = 0; q < 16; ++q) {
;     const int id = tid + 256 * q, row = id >> 5, c4 = id & 31;
;     const long grow = (long)pm * 128 + row;
;     const int gcol = pn * 128 + c4 * 4;
;     float4 a = *reinterpret_cast<const float4*>(T + row * 128 + c4 * 4);
;     float g[4];
;     load4bf(Z + grow * NCOL + (9 + BR) * 1024 + gcol, g);
;     float v[4] = {sigmoidf_(g[0]) * a.x, sigmoidf_(g[1]) * a.y, sigmoidf_(g[2]) * a.z, sigmoidf_(g[3]) * a.w};
;     if (IN == 1) {
;       float mo[4]; load4bf(M + grow * 1024 + gcol, mo);
;       v[0] += mo[0]; v[1] += mo[1]; v[2] += mo[2]; v[3] += mo[3];
;     }
;     if (IN == 2) {
;       float4 mo = *reinterpret_cast<const float4*>(macc + grow * 1024 + gcol);
;       v[0] += mo.x; v[1] += mo.y; v[2] += mo.z; v[3] += mo.w;
;     }
;     if (OUT == 1) *reinterpret_cast<float4*>(macc + grow * 1024 + gcol) = make_float4(v[0], v[1], v[2], v[3]);
	s_nop 0
	v_add_u32_e32 v8, s24, v91
	v_ashrrev_i32_e32 v6, 5, v8
	v_ashrrev_i32_e32 v7, 31, v6
	v_lshl_add_u64 v[10:11], s[46:47], 0, v[6:7]
	v_lshl_or_b32 v9, v6, 9, v152
	v_mov_b64_e32 v[6:7], s[44:45]
	v_mad_u64_u32 v[12:13], s[48:49], v10, s22, v[6:7]
	v_mad_i32_i24 v13, v11, s22, v13
	v_lshl_add_u64 v[12:13], v[12:13], 0, v[4:5]
	v_add_co_u32_e32 v12, vcc, 0x5000, v12
	s_addk_i32 s24, 0x800
	s_nop 0
	v_addc_co_u32_e32 v13, vcc, 0, v13, vcc
	v_mov_b32_e32 v12, v208
	v_mov_b32_e32 v13, v209
	s_cmpk_lg_i32 s24, 0x1000
	v_lshlrev_b32_e32 v14, 16, v12
	v_and_b32_e32 v12, 0xffff0000, v12
	v_lshlrev_b32_e32 v16, 16, v13
	v_mul_f32_e32 v12, 0xbfb8aa3b, v12
	v_and_b32_e32 v13, 0xffff0000, v13
	v_exp_f32_e32 v15, v12
	v_mul_f32_e32 v12, 0xbfb8aa3b, v16
	v_exp_f32_e32 v16, v12
	v_mul_f32_e32 v12, 0xbfb8aa3b, v13
	v_exp_f32_e32 v17, v12
	v_lshlrev_b64 v[12:13], 11, v[10:11]
	v_lshl_add_u64 v[12:13], v[0:1], 0, v[12:13]
	v_mov_b32_e32 v12, v210
	v_mov_b32_e32 v13, v211
	v_mul_f32_e32 v14, 0xbfb8aa3b, v14
	v_exp_f32_e32 v14, v14
	v_lshlrev_b64 v[10:11], 12, v[10:11]
	v_lshl_add_u64 v[22:23], v[2:3], 0, v[10:11]
	v_pk_add_f32 v[14:15], v[14:15], 1.0 op_sel_hi:[1,0]
	v_lshlrev_b32_e32 v18, 16, v12
	v_and_b32_e32 v19, 0xffff0000, v12
	v_lshlrev_b32_e32 v20, 16, v13
	v_and_b32_e32 v21, 0xffff0000, v13
	ds_read_b128 v[10:13], v9
	v_min_f32_e32 v9, 0x7f7fffff, v15
	v_rcp_f32_e32 v24, v9
	s_nop 0
	v_fma_f32 v25, -v9, v24, 1.0
	v_fmac_f32_e32 v24, v25, v24
	v_fma_f32 v27, -v9, v24, 1.0
	v_fma_f32 v26, v27, v24, v24
	v_fma_f32 v9, -v9, v26, 1.0
	v_fma_f32 v15, v9, v24, v26
	v_min_f32_e32 v9, 0x7f7fffff, v14
	v_rcp_f32_e32 v24, v9
	s_nop 0
	v_fma_f32 v25, -v9, v24, 1.0
	v_fmac_f32_e32 v24, v25, v24
	v_fma_f32 v27, -v9, v24, 1.0
	v_fma_f32 v26, v27, v24, v24
	v_fma_f32 v9, -v9, v26, 1.0
	v_fma_f32 v14, v9, v24, v26
	s_waitcnt lgkmcnt(0)
	v_pk_fma_f32 v[10:11], v[10:11], v[14:15], v[18:19]
	v_pk_add_f32 v[14:15], v[16:17], 1.0 op_sel_hi:[1,0]
	s_nop 0
	v_min_f32_e32 v9, 0x7f7fffff, v15
	v_rcp_f32_e32 v16, v9
	s_nop 0
	v_fma_f32 v17, -v9, v16, 1.0
	v_fmac_f32_e32 v16, v17, v16
	v_fma_f32 v19, -v9, v16, 1.0
	v_fma_f32 v18, v19, v16, v16
	v_fma_f32 v9, -v9, v18, 1.0
	v_fma_f32 v15, v9, v16, v18
	v_min_f32_e32 v9, 0x7f7fffff, v14
	v_rcp_f32_e32 v16, v9
	s_nop 0
	v_fma_f32 v17, -v9, v16, 1.0
	v_fmac_f32_e32 v16, v17, v16
	v_fma_f32 v19, -v9, v16, 1.0
	v_fma_f32 v18, v19, v16, v16
	v_fma_f32 v9, -v9, v18, 1.0
	v_fma_f32 v14, v9, v16, v18
	v_pk_fma_f32 v[12:13], v[12:13], v[14:15], v[20:21]
	v_add_u32_e32 v9, 0x100, v8
	global_store_dwordx4 v[22:23], v[10:13], off
	s_nop 1
	v_ashrrev_i32_e32 v10, 5, v9
	v_ashrrev_i32_e32 v11, 31, v10
	v_lshl_add_u64 v[12:13], s[46:47], 0, v[10:11]
	v_lshl_or_b32 v9, v10, 9, v152
	v_mad_u64_u32 v[10:11], s[48:49], v12, s22, v[6:7]
	v_mad_i32_i24 v11, v13, s22, v11
	v_lshl_add_u64 v[10:11], v[10:11], 0, v[4:5]
	v_add_co_u32_e32 v10, vcc, s21, v10
	s_nop 1
	v_addc_co_u32_e32 v11, vcc, 0, v11, vcc
	v_mov_b32_e32 v10, v212
	v_mov_b32_e32 v11, v213
	v_lshlrev_b32_e32 v14, 16, v10
	v_and_b32_e32 v10, 0xffff0000, v10
	v_lshlrev_b32_e32 v16, 16, v11
	v_mul_f32_e32 v10, 0xbfb8aa3b, v10
	v_and_b32_e32 v11, 0xffff0000, v11
	v_exp_f32_e32 v15, v10
	v_mul_f32_e32 v10, 0xbfb8aa3b, v16
	v_exp_f32_e32 v16, v10
	v_mul_f32_e32 v10, 0xbfb8aa3b, v11
	v_exp_f32_e32 v17, v10
	v_lshlrev_b64 v[10:11], 11, v[12:13]
	v_lshl_add_u64 v[10:11], v[0:1], 0, v[10:11]
	v_mov_b32_e32 v10, v214
	v_mov_b32_e32 v11, v215
	v_mul_f32_e32 v14, 0xbfb8aa3b, v14
	v_exp_f32_e32 v14, v14
	v_lshlrev_b32_e32 v18, 16, v10
	v_and_b32_e32 v19, 0xffff0000, v10
	v_lshlrev_b32_e32 v20, 16, v11
	v_and_b32_e32 v21, 0xffff0000, v11
	v_lshlrev_b64 v[10:11], 12, v[12:13]
	v_pk_add_f32 v[14:15], v[14:15], 1.0 op_sel_hi:[1,0]
	v_lshl_add_u64 v[22:23], v[2:3], 0, v[10:11]
	ds_read_b128 v[10:13], v9
	v_min_f32_e32 v9, 0x7f7fffff, v15
	v_rcp_f32_e32 v24, v9
	s_nop 0
	v_fma_f32 v25, -v9, v24, 1.0
	v_fmac_f32_e32 v24, v25, v24
	v_fma_f32 v27, -v9, v24, 1.0
	v_fma_f32 v26, v27, v24, v24
	v_fma_f32 v9, -v9, v26, 1.0
	v_fma_f32 v15, v9, v24, v26
	v_min_f32_e32 v9, 0x7f7fffff, v14
	v_rcp_f32_e32 v24, v9
	s_nop 0
	v_fma_f32 v25, -v9, v24, 1.0
	v_fmac_f32_e32 v24, v25, v24
	v_fma_f32 v27, -v9, v24, 1.0
	v_fma_f32 v26, v27, v24, v24
	v_fma_f32 v9, -v9, v26, 1.0
	v_fma_f32 v14, v9, v24, v26
	s_waitcnt lgkmcnt(0)
	v_pk_fma_f32 v[10:11], v[10:11], v[14:15], v[18:19]
	v_pk_add_f32 v[14:15], v[16:17], 1.0 op_sel_hi:[1,0]
	s_nop 0
	v_min_f32_e32 v9, 0x7f7fffff, v15
	v_rcp_f32_e32 v16, v9
	s_nop 0
	v_fma_f32 v17, -v9, v16, 1.0
	v_fmac_f32_e32 v16, v17, v16
	v_fma_f32 v19, -v9, v16, 1.0
	v_fma_f32 v18, v19, v16, v16
	v_fma_f32 v9, -v9, v18, 1.0
	v_fma_f32 v15, v9, v16, v18
	v_min_f32_e32 v9, 0x7f7fffff, v14
	v_rcp_f32_e32 v16, v9
	s_nop 0
	v_fma_f32 v17, -v9, v16, 1.0
	v_fmac_f32_e32 v16, v17, v16
	v_fma_f32 v19, -v9, v16, 1.0
	v_fma_f32 v18, v19, v16, v16
	v_fma_f32 v9, -v9, v18, 1.0
	v_fma_f32 v14, v9, v16, v18
	v_pk_fma_f32 v[12:13], v[12:13], v[14:15], v[20:21]
	v_add_u32_e32 v9, 0x200, v8
	global_store_dwordx4 v[22:23], v[10:13], off
	s_nop 1
	v_ashrrev_i32_e32 v10, 5, v9
	v_ashrrev_i32_e32 v11, 31, v10
	v_lshl_add_u64 v[12:13], s[46:47], 0, v[10:11]
	v_lshl_or_b32 v9, v10, 9, v152
	v_mad_u64_u32 v[10:11], s[48:49], v12, s22, v[6:7]
	v_mad_i32_i24 v11, v13, s22, v11
	v_lshl_add_u64 v[10:11], v[10:11], 0, v[4:5]
	v_add_co_u32_e32 v10, vcc, s21, v10
	s_nop 1
	v_addc_co_u32_e32 v11, vcc, 0, v11, vcc
	v_mov_b32_e32 v10, v216
	v_mov_b32_e32 v11, v217
	v_lshlrev_b32_e32 v14, 16, v10
	v_and_b32_e32 v10, 0xffff0000, v10
	v_lshlrev_b32_e32 v16, 16, v11
	v_mul_f32_e32 v10, 0xbfb8aa3b, v10
	v_and_b32_e32 v11, 0xffff0000, v11
	v_exp_f32_e32 v15, v10
	v_mul_f32_e32 v10, 0xbfb8aa3b, v16
	v_exp_f32_e32 v16, v10
	v_mul_f32_e32 v10, 0xbfb8aa3b, v11
	v_exp_f32_e32 v17, v10
	v_lshlrev_b64 v[10:11], 11, v[12:13]
	v_lshl_add_u64 v[10:11], v[0:1], 0, v[10:11]
	v_mov_b32_e32 v10, v218
	v_mov_b32_e32 v11, v219
	v_mul_f32_e32 v14, 0xbfb8aa3b, v14
	v_exp_f32_e32 v14, v14
	v_lshlrev_b32_e32 v18, 16, v10
	v_and_b32_e32 v19, 0xffff0000, v10
	v_lshlrev_b32_e32 v20, 16, v11
	v_and_b32_e32 v21, 0xffff0000, v11
	v_lshlrev_b64 v[10:11], 12, v[12:13]
	v_pk_add_f32 v[14:15], v[14:15], 1.0 op_sel_hi:[1,0]
	v_lshl_add_u64 v[22:23], v[2:3], 0, v[10:11]
	ds_read_b128 v[10:13], v9
	v_min_f32_e32 v9, 0x7f7fffff, v15
	v_rcp_f32_e32 v24, v9
	s_nop 0
	v_fma_f32 v25, -v9, v24, 1.0
	v_fmac_f32_e32 v24, v25, v24
	v_fma_f32 v27, -v9, v24, 1.0
	v_fma_f32 v26, v27, v24, v24
	v_fma_f32 v9, -v9, v26, 1.0
	v_fma_f32 v15, v9, v24, v26
	v_min_f32_e32 v9, 0x7f7fffff, v14
	v_rcp_f32_e32 v24, v9
	s_nop 0
	v_fma_f32 v25, -v9, v24, 1.0
	v_fmac_f32_e32 v24, v25, v24
	v_fma_f32 v27, -v9, v24, 1.0
	v_fma_f32 v26, v27, v24, v24
	v_fma_f32 v9, -v9, v26, 1.0
	v_fma_f32 v14, v9, v24, v26
	s_waitcnt lgkmcnt(0)
; DEVI float sigmoidf_(float x) { return 1.f / (1.f + __expf(-x)); }
; template <int BR, int IN, int OUT>
; DEVI void p6_branch(const Params& P, int pm, int pn, float* macc, char* smem, int tid) {
;     ...
;   for (int q = 0; q < 16; ++q) {
;     const int id = tid + 256 * q, row = id >> 5, c4 = id & 31;
;     const long grow = (long)pm * 128 + row;
;     const int gcol = pn * 128 + c4 * 4;
;     float4 a = *reinterpret_cast<const float4*>(T + row * 128 + c4 * 4);
;     float g[4];
;     load4bf(Z + grow * NCOL + (9 + BR) * 1024 + gcol, g);
;     float v[4] = {sigmoidf_(g[0]) * a.x, sigmoidf_(g[1]) * a.y, sigmoidf_(g[2]) * a.z, sigmoidf_(g[3]) * a.w};
;     if (IN == 1) {
;       float mo[4]; load4bf(M + grow * 1024 + gcol, mo);
;       v[0] += mo[0]; v[1] += mo[1]; v[2] += mo[2]; v[3] += mo[3];
;     }
;     if (IN == 2) {
;       float4 mo = *reinterpret_cast<const float4*>(macc + grow * 1024 + gcol);
;       v[0] += mo.x; v[1] += mo.y; v[2] += mo.z; v[3] += mo.w;
;     }
;     if (OUT == 1) *reinterpret_cast<float4*>(macc + grow * 1024 + gcol) = make_float4(v[0], v[1], v[2], v[3]);
	v_pk_fma_f32 v[10:11], v[10:11], v[14:15], v[18:19]
	v_pk_add_f32 v[14:15], v[16:17], 1.0 op_sel_hi:[1,0]
	s_nop 0
	v_min_f32_e32 v9, 0x7f7fffff, v15
	v_rcp_f32_e32 v16, v9
	s_nop 0
	v_fma_f32 v17, -v9, v16, 1.0
	v_fmac_f32_e32 v16, v17, v16
	v_fma_f32 v19, -v9, v16, 1.0
	v_fma_f32 v18, v19, v16, v16
	v_fma_f32 v9, -v9, v18, 1.0
	v_fma_f32 v15, v9, v16, v18
	v_min_f32_e32 v9, 0x7f7fffff, v14
	v_rcp_f32_e32 v16, v9
	s_nop 0
	v_fma_f32 v17, -v9, v16, 1.0
	v_fmac_f32_e32 v16, v17, v16
	v_fma_f32 v19, -v9, v16, 1.0
	v_fma_f32 v18, v19, v16, v16
	v_fma_f32 v9, -v9, v18, 1.0
	v_fma_f32 v14, v9, v16, v18
	v_pk_fma_f32 v[12:13], v[12:13], v[14:15], v[20:21]
	v_add_u32_e32 v9, 0x300, v8
	global_store_dwordx4 v[22:23], v[10:13], off
	s_nop 1
	v_ashrrev_i32_e32 v10, 5, v9
	v_ashrrev_i32_e32 v11, 31, v10
	v_lshl_add_u64 v[12:13], s[46:47], 0, v[10:11]
	v_lshl_or_b32 v9, v10, 9, v152
	v_mad_u64_u32 v[10:11], s[48:49], v12, s22, v[6:7]
	v_mad_i32_i24 v11, v13, s22, v11
	v_lshl_add_u64 v[10:11], v[10:11], 0, v[4:5]
	v_add_co_u32_e32 v10, vcc, s21, v10
	s_nop 1
	v_addc_co_u32_e32 v11, vcc, 0, v11, vcc
	v_mov_b32_e32 v10, v220
	v_mov_b32_e32 v11, v221
	v_lshlrev_b32_e32 v14, 16, v10
	v_and_b32_e32 v10, 0xffff0000, v10
	v_lshlrev_b32_e32 v16, 16, v11
	v_mul_f32_e32 v10, 0xbfb8aa3b, v10
	v_and_b32_e32 v11, 0xffff0000, v11
	v_exp_f32_e32 v15, v10
	v_mul_f32_e32 v10, 0xbfb8aa3b, v16
	v_exp_f32_e32 v16, v10
	v_mul_f32_e32 v10, 0xbfb8aa3b, v11
	v_exp_f32_e32 v17, v10
	v_lshlrev_b64 v[10:11], 11, v[12:13]
	v_lshl_add_u64 v[10:11], v[0:1], 0, v[10:11]
	v_mov_b32_e32 v10, v222
	v_mov_b32_e32 v11, v223
	v_mul_f32_e32 v14, 0xbfb8aa3b, v14
	v_exp_f32_e32 v14, v14
	v_lshlrev_b32_e32 v18, 16, v10
	v_and_b32_e32 v19, 0xffff0000, v10
	v_lshlrev_b32_e32 v20, 16, v11
	v_and_b32_e32 v21, 0xffff0000, v11
	v_lshlrev_b64 v[10:11], 12, v[12:13]
	v_pk_add_f32 v[14:15], v[14:15], 1.0 op_sel_hi:[1,0]
	v_lshl_add_u64 v[22:23], v[2:3], 0, v[10:11]
	ds_read_b128 v[10:13], v9
	v_min_f32_e32 v9, 0x7f7fffff, v15
	v_rcp_f32_e32 v24, v9
	s_nop 0
	v_fma_f32 v25, -v9, v24, 1.0
	v_fmac_f32_e32 v24, v25, v24
	v_fma_f32 v27, -v9, v24, 1.0
	v_fma_f32 v26, v27, v24, v24
	v_fma_f32 v9, -v9, v26, 1.0
	v_fma_f32 v15, v9, v24, v26
	v_min_f32_e32 v9, 0x7f7fffff, v14
	v_rcp_f32_e32 v24, v9
	s_nop 0
	v_fma_f32 v25, -v9, v24, 1.0
	v_fmac_f32_e32 v24, v25, v24
	v_fma_f32 v27, -v9, v24, 1.0
	v_fma_f32 v26, v27, v24, v24
	v_fma_f32 v9, -v9, v26, 1.0
	v_fma_f32 v14, v9, v24, v26
	s_waitcnt lgkmcnt(0)
	v_pk_fma_f32 v[10:11], v[10:11], v[14:15], v[18:19]
	v_pk_add_f32 v[14:15], v[16:17], 1.0 op_sel_hi:[1,0]
	s_nop 0
	v_min_f32_e32 v9, 0x7f7fffff, v15
	v_rcp_f32_e32 v16, v9
	s_nop 0
	v_fma_f32 v17, -v9, v16, 1.0
	v_fmac_f32_e32 v16, v17, v16
	v_fma_f32 v19, -v9, v16, 1.0
	v_fma_f32 v18, v19, v16, v16
	v_fma_f32 v9, -v9, v18, 1.0
	v_fma_f32 v15, v9, v16, v18
	v_min_f32_e32 v9, 0x7f7fffff, v14
	v_rcp_f32_e32 v16, v9
	s_nop 0
	v_fma_f32 v17, -v9, v16, 1.0
	v_fmac_f32_e32 v16, v17, v16
	v_fma_f32 v19, -v9, v16, 1.0
	v_fma_f32 v18, v19, v16, v16
	v_fma_f32 v9, -v9, v18, 1.0
	v_fma_f32 v14, v9, v16, v18
	v_pk_fma_f32 v[12:13], v[12:13], v[14:15], v[20:21]
	v_add_u32_e32 v9, 0x400, v8
	global_store_dwordx4 v[22:23], v[10:13], off
	s_nop 1
	v_ashrrev_i32_e32 v10, 5, v9
	v_ashrrev_i32_e32 v11, 31, v10
	v_lshl_add_u64 v[12:13], s[46:47], 0, v[10:11]
	v_lshl_or_b32 v9, v10, 9, v152
	v_mad_u64_u32 v[10:11], s[48:49], v12, s22, v[6:7]
	v_mad_i32_i24 v11, v13, s22, v11
	v_lshl_add_u64 v[10:11], v[10:11], 0, v[4:5]
	v_add_co_u32_e32 v10, vcc, s21, v10
	s_nop 1
	v_addc_co_u32_e32 v11, vcc, 0, v11, vcc
	v_mov_b32_e32 v10, v224
	v_mov_b32_e32 v11, v225
	v_lshlrev_b32_e32 v14, 16, v10
	v_and_b32_e32 v10, 0xffff0000, v10
	v_lshlrev_b32_e32 v16, 16, v11
	v_mul_f32_e32 v10, 0xbfb8aa3b, v10
	v_and_b32_e32 v11, 0xffff0000, v11
	v_exp_f32_e32 v15, v10
	v_mul_f32_e32 v10, 0xbfb8aa3b, v16
	v_exp_f32_e32 v16, v10
	v_mul_f32_e32 v10, 0xbfb8aa3b, v11
	v_exp_f32_e32 v17, v10
	v_lshlrev_b64 v[10:11], 11, v[12:13]
	v_lshl_add_u64 v[10:11], v[0:1], 0, v[10:11]
	v_mov_b32_e32 v10, v226
	v_mov_b32_e32 v11, v227
	v_mul_f32_e32 v14, 0xbfb8aa3b, v14
	v_exp_f32_e32 v14, v14
	v_lshlrev_b32_e32 v18, 16, v10
	v_and_b32_e32 v19, 0xffff0000, v10
	v_lshlrev_b32_e32 v20, 16, v11
	v_and_b32_e32 v21, 0xffff0000, v11
	v_lshlrev_b64 v[10:11], 12, v[12:13]
	v_pk_add_f32 v[14:15], v[14:15], 1.0 op_sel_hi:[1,0]
	v_lshl_add_u64 v[22:23], v[2:3], 0, v[10:11]
	ds_read_b128 v[10:13], v9
	v_min_f32_e32 v9, 0x7f7fffff, v15
	v_rcp_f32_e32 v24, v9
	s_nop 0
	v_fma_f32 v25, -v9, v24, 1.0
	v_fmac_f32_e32 v24, v25, v24
	v_fma_f32 v27, -v9, v24, 1.0
	v_fma_f32 v26, v27, v24, v24
	v_fma_f32 v9, -v9, v26, 1.0
	v_fma_f32 v15, v9, v24, v26
	v_min_f32_e32 v9, 0x7f7fffff, v14
	v_rcp_f32_e32 v24, v9
	s_nop 0
	v_fma_f32 v25, -v9, v24, 1.0
	v_fmac_f32_e32 v24, v25, v24
	v_fma_f32 v27, -v9, v24, 1.0
	v_fma_f32 v26, v27, v24, v24
	v_fma_f32 v9, -v9, v26, 1.0
	v_fma_f32 v14, v9, v24, v26
	s_waitcnt lgkmcnt(0)
; DEVI float sigmoidf_(float x) { return 1.f / (1.f + __expf(-x)); }
; template <int BR, int IN, int OUT>
; DEVI void p6_branch(const Params& P, int pm, int pn, float* macc, char* smem, int tid) {
;     ...
;   for (int q = 0; q < 16; ++q) {
;     const int id = tid + 256 * q, row = id >> 5, c4 = id & 31;
;     const long grow = (long)pm * 128 + row;
;     const int gcol = pn * 128 + c4 * 4;
;     float4 a = *reinterpret_cast<const float4*>(T + row * 128 + c4 * 4);
;     float g[4];
;     load4bf(Z + grow * NCOL + (9 + BR) * 1024 + gcol, g);
;     float v[4] = {sigmoidf_(g[0]) * a.x, sigmoidf_(g[1]) * a.y, sigmoidf_(g[2]) * a.z, sigmoidf_(g[3]) * a.w};
;     if (IN == 1) {
;       float mo[4]; load4bf(M + grow * 1024 + gcol, mo);
;       v[0] += mo[0]; v[1] += mo[1]; v[2] += mo[2]; v[3] += mo[3];
;     }
;     if (IN == 2) {
;       float4 mo = *reinterpret_cast<const float4*>(macc + grow * 1024 + gcol);
;       v[0] += mo.x; v[1] += mo.y; v[2] += mo.z; v[3] += mo.w;
;     }
;     if (OUT == 1) *reinterpret_cast<float4*>(macc + grow * 1024 + gcol) = make_float4(v[0], v[1], v[2], v[3]);
	v_pk_fma_f32 v[10:11], v[10:11], v[14:15], v[18:19]
	v_pk_add_f32 v[14:15], v[16:17], 1.0 op_sel_hi:[1,0]
	s_nop 0
	v_min_f32_e32 v9, 0x7f7fffff, v15
	v_rcp_f32_e32 v16, v9
	s_nop 0
	v_fma_f32 v17, -v9, v16, 1.0
	v_fmac_f32_e32 v16, v17, v16
	v_fma_f32 v19, -v9, v16, 1.0
	v_fma_f32 v18, v19, v16, v16
	v_fma_f32 v9, -v9, v18, 1.0
	v_fma_f32 v15, v9, v16, v18
	v_min_f32_e32 v9, 0x7f7fffff, v14
	v_rcp_f32_e32 v16, v9
	s_nop 0
	v_fma_f32 v17, -v9, v16, 1.0
	v_fmac_f32_e32 v16, v17, v16
	v_fma_f32 v19, -v9, v16, 1.0
	v_fma_f32 v18, v19, v16, v16
	v_fma_f32 v9, -v9, v18, 1.0
	v_fma_f32 v14, v9, v16, v18
	v_pk_fma_f32 v[12:13], v[12:13], v[14:15], v[20:21]
	v_add_u32_e32 v9, 0x500, v8
	global_store_dwordx4 v[22:23], v[10:13], off
	s_nop 1
	v_ashrrev_i32_e32 v10, 5, v9
	v_ashrrev_i32_e32 v11, 31, v10
	v_lshl_add_u64 v[12:13], s[46:47], 0, v[10:11]
	v_lshl_or_b32 v9, v10, 9, v152
	v_mad_u64_u32 v[10:11], s[48:49], v12, s22, v[6:7]
	v_mad_i32_i24 v11, v13, s22, v11
	v_lshl_add_u64 v[10:11], v[10:11], 0, v[4:5]
	v_add_co_u32_e32 v10, vcc, s21, v10
	s_nop 1
	v_addc_co_u32_e32 v11, vcc, 0, v11, vcc
	v_mov_b32_e32 v10, v228
	v_mov_b32_e32 v11, v229
	v_lshlrev_b32_e32 v14, 16, v10
	v_and_b32_e32 v10, 0xffff0000, v10
	v_lshlrev_b32_e32 v16, 16, v11
	v_mul_f32_e32 v10, 0xbfb8aa3b, v10
	v_and_b32_e32 v11, 0xffff0000, v11
	v_exp_f32_e32 v15, v10
	v_mul_f32_e32 v10, 0xbfb8aa3b, v16
	v_exp_f32_e32 v16, v10
	v_mul_f32_e32 v10, 0xbfb8aa3b, v11
	v_exp_f32_e32 v17, v10
	v_lshlrev_b64 v[10:11], 11, v[12:13]
	v_lshl_add_u64 v[10:11], v[0:1], 0, v[10:11]
	v_mov_b32_e32 v10, v230
	v_mov_b32_e32 v11, v231
	v_mul_f32_e32 v14, 0xbfb8aa3b, v14
	v_exp_f32_e32 v14, v14
	v_lshlrev_b32_e32 v18, 16, v10
	v_and_b32_e32 v19, 0xffff0000, v10
	v_lshlrev_b32_e32 v20, 16, v11
	v_and_b32_e32 v21, 0xffff0000, v11
	v_lshlrev_b64 v[10:11], 12, v[12:13]
	v_pk_add_f32 v[14:15], v[14:15], 1.0 op_sel_hi:[1,0]
	v_lshl_add_u64 v[22:23], v[2:3], 0, v[10:11]
	ds_read_b128 v[10:13], v9
	v_min_f32_e32 v9, 0x7f7fffff, v15
	v_rcp_f32_e32 v24, v9
	s_nop 0
	v_fma_f32 v25, -v9, v24, 1.0
	v_fmac_f32_e32 v24, v25, v24
	v_fma_f32 v27, -v9, v24, 1.0
	v_fma_f32 v26, v27, v24, v24
	v_fma_f32 v9, -v9, v26, 1.0
	v_fma_f32 v15, v9, v24, v26
	v_min_f32_e32 v9, 0x7f7fffff, v14
	v_rcp_f32_e32 v24, v9
	s_nop 0
	v_fma_f32 v25, -v9, v24, 1.0
	v_fmac_f32_e32 v24, v25, v24
	v_fma_f32 v27, -v9, v24, 1.0
	v_fma_f32 v26, v27, v24, v24
	v_fma_f32 v9, -v9, v26, 1.0
	v_fma_f32 v14, v9, v24, v26
	s_waitcnt lgkmcnt(0)
	v_pk_fma_f32 v[10:11], v[10:11], v[14:15], v[18:19]
	v_pk_add_f32 v[14:15], v[16:17], 1.0 op_sel_hi:[1,0]
	s_nop 0
	v_min_f32_e32 v9, 0x7f7fffff, v15
	v_rcp_f32_e32 v16, v9
	s_nop 0
	v_fma_f32 v17, -v9, v16, 1.0
	v_fmac_f32_e32 v16, v17, v16
	v_fma_f32 v19, -v9, v16, 1.0
	v_fma_f32 v18, v19, v16, v16
	v_fma_f32 v9, -v9, v18, 1.0
	v_fma_f32 v15, v9, v16, v18
	v_min_f32_e32 v9, 0x7f7fffff, v14
	v_rcp_f32_e32 v16, v9
	s_nop 0
	v_fma_f32 v17, -v9, v16, 1.0
	v_fmac_f32_e32 v16, v17, v16
	v_fma_f32 v19, -v9, v16, 1.0
	v_fma_f32 v18, v19, v16, v16
	v_fma_f32 v9, -v9, v18, 1.0
	v_fma_f32 v14, v9, v16, v18
	v_pk_fma_f32 v[12:13], v[12:13], v[14:15], v[20:21]
	v_add_u32_e32 v9, 0x600, v8
	global_store_dwordx4 v[22:23], v[10:13], off
	v_add_u32_e32 v8, 0x700, v8
	v_ashrrev_i32_e32 v8, 5, v8
	v_ashrrev_i32_e32 v10, 5, v9
	v_ashrrev_i32_e32 v11, 31, v10
	v_lshl_add_u64 v[12:13], s[46:47], 0, v[10:11]
	v_lshl_or_b32 v9, v10, 9, v152
	v_mad_u64_u32 v[10:11], s[48:49], v12, s22, v[6:7]
	v_mad_i32_i24 v11, v13, s22, v11
	v_lshl_add_u64 v[10:11], v[10:11], 0, v[4:5]
	v_add_co_u32_e32 v10, vcc, s21, v10
	s_nop 1
	v_addc_co_u32_e32 v11, vcc, 0, v11, vcc
	v_mov_b32_e32 v10, v232
	v_mov_b32_e32 v11, v233
	v_lshlrev_b32_e32 v14, 16, v10
	v_and_b32_e32 v10, 0xffff0000, v10
	v_lshlrev_b32_e32 v16, 16, v11
	v_mul_f32_e32 v10, 0xbfb8aa3b, v10
	v_and_b32_e32 v11, 0xffff0000, v11
	v_exp_f32_e32 v15, v10
	v_mul_f32_e32 v10, 0xbfb8aa3b, v16
	v_exp_f32_e32 v16, v10
	v_mul_f32_e32 v10, 0xbfb8aa3b, v11
	v_exp_f32_e32 v17, v10
	v_lshlrev_b64 v[10:11], 11, v[12:13]
	v_lshl_add_u64 v[10:11], v[0:1], 0, v[10:11]
	v_mov_b32_e32 v10, v234
	v_mov_b32_e32 v11, v235
	v_mul_f32_e32 v14, 0xbfb8aa3b, v14
	v_exp_f32_e32 v14, v14
	v_lshlrev_b32_e32 v18, 16, v10
	v_and_b32_e32 v19, 0xffff0000, v10
	v_lshlrev_b32_e32 v20, 16, v11
	v_and_b32_e32 v21, 0xffff0000, v11
	v_lshlrev_b64 v[10:11], 12, v[12:13]
	v_pk_add_f32 v[14:15], v[14:15], 1.0 op_sel_hi:[1,0]
	v_lshl_add_u64 v[22:23], v[2:3], 0, v[10:11]
	ds_read_b128 v[10:13], v9
	v_min_f32_e32 v9, 0x7f7fffff, v15
	v_rcp_f32_e32 v24, v9
	s_nop 0
	v_fma_f32 v25, -v9, v24, 1.0
	v_fmac_f32_e32 v24, v25, v24
	v_fma_f32 v27, -v9, v24, 1.0
	v_fma_f32 v26, v27, v24, v24
	v_fma_f32 v9, -v9, v26, 1.0
	v_fma_f32 v15, v9, v24, v26
	v_min_f32_e32 v9, 0x7f7fffff, v14
	v_rcp_f32_e32 v24, v9
	s_nop 0
	v_fma_f32 v25, -v9, v24, 1.0
	v_fmac_f32_e32 v24, v25, v24
	v_fma_f32 v27, -v9, v24, 1.0
	v_fma_f32 v26, v27, v24, v24
	v_fma_f32 v9, -v9, v26, 1.0
	v_fma_f32 v14, v9, v24, v26
	s_waitcnt lgkmcnt(0)
; DEVI float sigmoidf_(float x) { return 1.f / (1.f + __expf(-x)); }
; DEVI char* wsp(const Params& P, size_t off) { asm volatile("" : "+s"(off)); return P.ws + off; }
; #define ZERO_ACC(a) _Pragma("unroll") for (int m_ = 0; m_ < 4; ++m_) _Pragma("unroll") for (int n_ = 0; n_ < 4; ++n_) a[m_][n_] = f32x4{0.f, 0.f, 0.f, 0.f}
; template <int BR, int IN, int OUT>
; DEVI void p6_branch(const Params& P, int pm, int pn, float* macc, char* smem, int tid) {
;     ...
;   const bfu* A = (const bfu*)wsp(P, BR == 0 ? O_UA : BR == 1 ? O_UB : O_UC) + (long)pm * 128 * 1024;
;   const bfu* B = (const bfu*)wsp(P, BR == 0 ? O_WOA : BR == 1 ? O_WOB : O_WOC) + (long)pn * 128 * 1024;
;   f32x4 acc[4][4]; ZERO_ACC(acc);
;   gemm_core(acc, A, 1024, B, 1024, 1024, smem, tid);
;     ...
;   for (int q = 0; q < 16; ++q) {
;     const int id = tid + 256 * q, row = id >> 5, c4 = id & 31;
;     const long grow = (long)pm * 128 + row;
;     const int gcol = pn * 128 + c4 * 4;
;     float4 a = *reinterpret_cast<const float4*>(T + row * 128 + c4 * 4);
;     float g[4];
;     load4bf(Z + grow * NCOL + (9 + BR) * 1024 + gcol, g);
;     float v[4] = {sigmoidf_(g[0]) * a.x, sigmoidf_(g[1]) * a.y, sigmoidf_(g[2]) * a.z, sigmoidf_(g[3]) * a.w};
;     if (IN == 1) {
;       float mo[4]; load4bf(M + grow * 1024 + gcol, mo);
;       v[0] += mo[0]; v[1] += mo[1]; v[2] += mo[2]; v[3] += mo[3];
;     }
;     if (IN == 2) {
;       float4 mo = *reinterpret_cast<const float4*>(macc + grow * 1024 + gcol);
;       v[0] += mo.x; v[1] += mo.y; v[2] += mo.z; v[3] += mo.w;
;     }
;     if (OUT == 1) *reinterpret_cast<float4*>(macc + grow * 1024 + gcol) = make_float4(v[0], v[1], v[2], v[3]);
	v_pk_fma_f32 v[10:11], v[10:11], v[14:15], v[18:19]
	v_pk_add_f32 v[14:15], v[16:17], 1.0 op_sel_hi:[1,0]
	s_nop 0
	v_min_f32_e32 v9, 0x7f7fffff, v15
	v_rcp_f32_e32 v16, v9
	s_nop 0
	v_fma_f32 v17, -v9, v16, 1.0
	v_fmac_f32_e32 v16, v17, v16
	v_fma_f32 v19, -v9, v16, 1.0
	v_fma_f32 v18, v19, v16, v16
	v_fma_f32 v9, -v9, v18, 1.0
	v_fma_f32 v15, v9, v16, v18
	v_min_f32_e32 v9, 0x7f7fffff, v14
	v_rcp_f32_e32 v16, v9
	s_nop 0
	v_fma_f32 v17, -v9, v16, 1.0
	v_fmac_f32_e32 v16, v17, v16
	v_fma_f32 v19, -v9, v16, 1.0
	v_fma_f32 v18, v19, v16, v16
	v_fma_f32 v9, -v9, v18, 1.0
	v_fma_f32 v14, v9, v16, v18
	v_pk_fma_f32 v[12:13], v[12:13], v[14:15], v[20:21]
	v_ashrrev_i32_e32 v9, 31, v8
	global_store_dwordx4 v[22:23], v[10:13], off
	s_nop 1
	v_lshl_add_u64 v[10:11], s[46:47], 0, v[8:9]
	v_mad_u64_u32 v[6:7], s[48:49], v10, s22, v[6:7]
	v_mad_i32_i24 v7, v11, s22, v7
	v_lshl_add_u64 v[6:7], v[6:7], 0, v[4:5]
	v_add_co_u32_e32 v6, vcc, s21, v6
	v_lshl_or_b32 v8, v8, 9, v152
	s_nop 0
	v_addc_co_u32_e32 v7, vcc, 0, v7, vcc
	v_mov_b32_e32 v6, v236
	v_mov_b32_e32 v7, v237
	v_lshlrev_b32_e32 v9, 16, v6
	v_and_b32_e32 v6, 0xffff0000, v6
	v_lshlrev_b32_e32 v14, 16, v7
	v_mul_f32_e32 v6, 0xbfb8aa3b, v6
	v_and_b32_e32 v7, 0xffff0000, v7
	v_exp_f32_e32 v13, v6
	v_mul_f32_e32 v6, 0xbfb8aa3b, v14
	v_exp_f32_e32 v14, v6
	v_mul_f32_e32 v6, 0xbfb8aa3b, v7
	v_exp_f32_e32 v15, v6
	v_lshlrev_b64 v[6:7], 11, v[10:11]
	v_lshl_add_u64 v[6:7], v[0:1], 0, v[6:7]
	v_mov_b32_e32 v6, v238
	v_mov_b32_e32 v7, v239
	v_mul_f32_e32 v9, 0xbfb8aa3b, v9
	v_exp_f32_e32 v12, v9
	v_lshlrev_b32_e32 v16, 16, v6
	v_pk_add_f32 v[12:13], v[12:13], 1.0 op_sel_hi:[1,0]
	v_and_b32_e32 v17, 0xffff0000, v6
	v_min_f32_e32 v20, 0x7f7fffff, v13
	v_rcp_f32_e32 v21, v20
	v_lshlrev_b32_e32 v18, 16, v7
	v_and_b32_e32 v19, 0xffff0000, v7
	v_lshlrev_b64 v[6:7], 12, v[10:11]
	v_fma_f32 v22, -v20, v21, 1.0
	v_fmac_f32_e32 v21, v22, v21
	v_fma_f32 v24, -v20, v21, 1.0
	v_fma_f32 v23, v24, v21, v21
	v_fma_f32 v20, -v20, v23, 1.0
	v_fma_f32 v13, v20, v21, v23
	v_min_f32_e32 v20, 0x7f7fffff, v12
	v_rcp_f32_e32 v21, v20
	v_lshl_add_u64 v[10:11], v[2:3], 0, v[6:7]
	ds_read_b128 v[6:9], v8
	v_fma_f32 v22, -v20, v21, 1.0
	v_fmac_f32_e32 v21, v22, v21
	v_fma_f32 v24, -v20, v21, 1.0
	v_fma_f32 v23, v24, v21, v21
	v_fma_f32 v20, -v20, v23, 1.0
	v_fma_f32 v12, v20, v21, v23
	s_waitcnt lgkmcnt(0)
	v_pk_fma_f32 v[6:7], v[6:7], v[12:13], v[16:17]
	v_pk_add_f32 v[12:13], v[14:15], 1.0 op_sel_hi:[1,0]
	s_nop 0
	v_min_f32_e32 v14, 0x7f7fffff, v13
	v_rcp_f32_e32 v15, v14
	s_nop 0
	v_fma_f32 v16, -v14, v15, 1.0
	v_fmac_f32_e32 v15, v16, v15
	v_fma_f32 v20, -v14, v15, 1.0
	v_fma_f32 v17, v20, v15, v15
	v_fma_f32 v14, -v14, v17, 1.0
	v_fma_f32 v13, v14, v15, v17
	v_min_f32_e32 v14, 0x7f7fffff, v12
	v_rcp_f32_e32 v15, v14
	s_nop 0
	v_fma_f32 v16, -v14, v15, 1.0
	v_fmac_f32_e32 v15, v16, v15
	v_fma_f32 v20, -v14, v15, 1.0
	v_fma_f32 v17, v20, v15, v15
	v_fma_f32 v14, -v14, v17, 1.0
	v_fma_f32 v12, v14, v15, v17
	v_pk_fma_f32 v[8:9], v[8:9], v[12:13], v[18:19]
	global_store_dwordx4 v[10:11], v[6:9], off
	s_cbranch_scc1 .LBB0_737
	s_ashr_i32 s41, s40, 31
	s_ashr_i32 s27, s26, 31
	s_mov_b64 s[44:45], 0x8582000
	s_mov_b64 s[46:47], 0x17d02000
	s_mov_b64 s[48:49], 0x15c02000
	s_lshl_b64 s[50:51], s[40:41], 18
	s_lshl_b64 s[54:55], s[26:27], 18
	s_add_u32 s24, s30, s48
	s_addc_u32 s27, s31, s49
	s_add_u32 s56, s24, s50
	s_mov_b64 s[52:53], 0x1a00000
	s_addc_u32 s57, s27, s51
	s_add_u32 s24, s30, s52
	s_addc_u32 s27, s31, s53
	s_add_u32 s58, s24, s54
	v_lshl_add_u64 v[0:1], s[56:57], 0, v[116:117]
	v_readfirstlane_b32 s24, v101
	v_lshl_add_u64 v[0:1], v[0:1], 0, v[88:89]
	s_mov_b32 m0, s24
	s_barrier
; DEVI void stage_tile(const bfu* __restrict__ g, int ld, int k0, char* lds, int tid) {
; #pragma unroll
;   for (int i = 0; i < 4; ++i) {
;     int b = tid * 16 + i * 4096;
;     int r = b >> 7, cp = (b >> 4) & 7, gc = cp ^ (r & 7);
;     __builtin_amdgcn_global_load_lds((const unsigned*)(g + (long)r * ld + k0 + gc * 8),
;                                      (unsigned*)(lds + b), 16, 0, 0);
;   }
; }
	global_load_lds_dwordx4 v[0:1], off
	v_lshl_add_u64 v[0:1], s[56:57], 0, v[118:119]
	v_mov_b32_e32 v125, v89
	v_readfirstlane_b32 s24, v103
	v_lshl_add_u64 v[0:1], v[0:1], 0, v[124:125]
	s_mov_b32 m0, s24
	v_mov_b32_e32 v127, v89
	global_load_lds_dwordx4 v[0:1], off
	v_lshl_add_u64 v[0:1], s[56:57], 0, v[120:121]
	v_readfirstlane_b32 s24, v105
	v_lshl_add_u64 v[0:1], v[0:1], 0, v[126:127]
	s_mov_b32 m0, s24
	v_mov_b32_e32 v129, v89
	global_load_lds_dwordx4 v[0:1], off
	v_lshl_add_u64 v[0:1], s[56:57], 0, v[122:123]
	v_readfirstlane_b32 s24, v107
	s_addc_u32 s59, s27, s55
	v_lshl_add_u64 v[0:1], v[0:1], 0, v[128:129]
	s_mov_b32 m0, s24
	v_readfirstlane_b32 s24, v153
	global_load_lds_dwordx4 v[0:1], off
	v_lshl_add_u64 v[0:1], s[58:59], 0, v[116:117]
	v_lshl_add_u64 v[0:1], v[0:1], 0, v[88:89]
	s_mov_b32 m0, s24
	v_readfirstlane_b32 s24, v154
	global_load_lds_dwordx4 v[0:1], off
	v_lshl_add_u64 v[0:1], s[58:59], 0, v[118:119]
	v_lshl_add_u64 v[0:1], v[0:1], 0, v[124:125]
	s_mov_b32 m0, s24
	v_readfirstlane_b32 s24, v155
	global_load_lds_dwordx4 v[0:1], off
	v_lshl_add_u64 v[0:1], s[58:59], 0, v[120:121]
	v_lshl_add_u64 v[0:1], v[0:1], 0, v[126:127]
	s_mov_b32 m0, s24
	v_readfirstlane_b32 s24, v156
	global_load_lds_dwordx4 v[0:1], off
	v_lshl_add_u64 v[0:1], s[58:59], 0, v[122:123]
	v_lshl_add_u64 v[0:1], v[0:1], 0, v[128:129]
	s_mov_b32 m0, s24
	s_add_u32 s48, s48, s50
	global_load_lds_dwordx4 v[0:1], off
	s_addc_u32 s49, s49, s51
	v_lshl_add_u64 v[124:125], v[108:109], 0, s[48:49]
	v_lshl_add_u64 v[126:127], v[110:111], 0, s[48:49]
	v_lshl_add_u64 v[128:129], v[112:113], 0, s[48:49]
	v_lshl_add_u64 v[130:131], v[114:115], 0, s[48:49]
	s_add_u32 s48, s52, s54
	s_addc_u32 s49, s53, s55
	v_mov_b32_e32 v0, 0
	v_lshl_add_u64 v[132:133], v[108:109], 0, s[48:49]
	v_lshl_add_u64 v[134:135], v[110:111], 0, s[48:49]
	v_lshl_add_u64 v[136:137], v[112:113], 0, s[48:49]
	v_lshl_add_u64 v[138:139], v[114:115], 0, s[48:49]
	s_mov_b64 s[48:49], 0
	s_mov_b32 s24, 0x8000
	v_mov_b32_e32 v1, v0
	v_mov_b32_e32 v2, v0
	v_mov_b32_e32 v3, v0
	v_mov_b32_e32 v4, v0
	v_mov_b32_e32 v5, v0
	v_mov_b32_e32 v6, v0
	v_mov_b32_e32 v7, v0
	v_mov_b32_e32 v8, v0
	v_mov_b32_e32 v9, v0
	v_mov_b32_e32 v10, v0
	v_mov_b32_e32 v11, v0
	v_mov_b32_e32 v12, v0
	v_mov_b32_e32 v13, v0
	v_mov_b32_e32 v14, v0
	v_mov_b32_e32 v15, v0
	v_mov_b32_e32 v16, v0
	v_mov_b32_e32 v17, v0
	v_mov_b32_e32 v18, v0
	v_mov_b32_e32 v19, v0
	v_mov_b32_e32 v20, v0
	v_mov_b32_e32 v21, v0
	v_mov_b32_e32 v22, v0
	v_mov_b32_e32 v23, v0
	v_mov_b32_e32 v24, v0
	v_mov_b32_e32 v25, v0
	v_mov_b32_e32 v26, v0
	v_mov_b32_e32 v27, v0
	v_mov_b32_e32 v28, v0
	v_mov_b32_e32 v29, v0
	v_mov_b32_e32 v30, v0
	v_mov_b32_e32 v31, v0
	v_mov_b32_e32 v32, v0
	v_mov_b32_e32 v33, v0
	v_mov_b32_e32 v34, v0
	v_mov_b32_e32 v35, v0
	v_mov_b32_e32 v36, v0
	v_mov_b32_e32 v37, v0
	v_mov_b32_e32 v38, v0
	v_mov_b32_e32 v39, v0
	v_mov_b32_e32 v40, v0
	v_mov_b32_e32 v41, v0
	v_mov_b32_e32 v42, v0
	v_mov_b32_e32 v43, v0
	v_mov_b32_e32 v44, v0
	v_mov_b32_e32 v45, v0
	v_mov_b32_e32 v46, v0
	v_mov_b32_e32 v47, v0
	v_mov_b32_e32 v48, v0
	v_mov_b32_e32 v49, v0
	v_mov_b32_e32 v50, v0
	v_mov_b32_e32 v51, v0
	v_mov_b32_e32 v52, v0
	v_mov_b32_e32 v53, v0
	v_mov_b32_e32 v54, v0
	v_mov_b32_e32 v55, v0
	v_mov_b32_e32 v56, v0
	v_mov_b32_e32 v57, v0
	v_mov_b32_e32 v58, v0
	v_mov_b32_e32 v59, v0
	v_mov_b32_e32 v60, v0
	v_mov_b32_e32 v61, v0
	v_mov_b32_e32 v62, v0
	v_mov_b32_e32 v63, v0

; DEVI float sigmoidf_(float x) { return 1.f / (1.f + __expf(-x)); }
; template <int BR, int IN, int OUT>
; DEVI void p6_branch(const Params& P, int pm, int pn, float* macc, char* smem, int tid) {
;     ...
;   for (int q = 0; q < 16; ++q) {
;     const int id = tid + 256 * q, row = id >> 5, c4 = id & 31;
;     const long grow = (long)pm * 128 + row;
;     const int gcol = pn * 128 + c4 * 4;
;     float4 a = *reinterpret_cast<const float4*>(T + row * 128 + c4 * 4);
;     float g[4];
;     load4bf(Z + grow * NCOL + (9 + BR) * 1024 + gcol, g);
;     float v[4] = {sigmoidf_(g[0]) * a.x, sigmoidf_(g[1]) * a.y, sigmoidf_(g[2]) * a.z, sigmoidf_(g[3]) * a.w};
;     if (IN == 1) {
;       float mo[4]; load4bf(M + grow * 1024 + gcol, mo);
;       v[0] += mo[0]; v[1] += mo[1]; v[2] += mo[2]; v[3] += mo[3];
;     }
;     if (IN == 2) {
;       float4 mo = *reinterpret_cast<const float4*>(macc + grow * 1024 + gcol);
.LBB0_741:
	v_add_u32_e32 v238, s24, v91
	v_ashrrev_i32_e32 v236, 5, v238
	v_ashrrev_i32_e32 v237, 31, v236
	v_lshl_add_u64 v[240:241], s[40:41], 0, v[236:237]
	v_mov_b64_e32 v[236:237], s[44:45]
	v_mad_u64_u32 v[242:243], s[26:27], v240, s22, v[236:237]
	v_mad_i32_i24 v243, v241, s22, v243
	v_lshl_add_u64 v[242:243], v[242:243], 0, v[4:5]
	v_add_co_u32_e32 v242, vcc, 0x5000, v242
	s_nop 1
	v_addc_co_u32_e32 v243, vcc, 0, v243, vcc
	global_load_dwordx2 v[154:155], v[242:243], off
	v_add_u32_e32 v238, s24, v91
	v_ashrrev_i32_e32 v236, 5, v238
	v_ashrrev_i32_e32 v237, 31, v236
	v_lshl_add_u64 v[240:241], s[40:41], 0, v[236:237]
	v_lshlrev_b64 v[242:243], 12, v[240:241]
	v_lshl_add_u64 v[244:245], v[0:1], 0, v[242:243]
	global_load_dwordx4 v[156:159], v[244:245], off
	v_add_u32_e32 v238, s24, v91
	v_mov_b64_e32 v[236:237], s[44:45]
	v_add_u32_e32 v239, 0x100, v238
	v_ashrrev_i32_e32 v240, 5, v239
	v_ashrrev_i32_e32 v241, 31, v240
	v_lshl_add_u64 v[242:243], s[40:41], 0, v[240:241]
	v_mad_u64_u32 v[240:241], s[26:27], v242, s22, v[236:237]
	v_mad_i32_i24 v241, v243, s22, v241
	v_lshl_add_u64 v[240:241], v[240:241], 0, v[4:5]
	v_add_co_u32_e32 v240, vcc, s21, v240
	s_nop 1
	v_addc_co_u32_e32 v241, vcc, 0, v241, vcc
	global_load_dwordx2 v[160:161], v[240:241], off
	v_add_u32_e32 v236, s24, v91
	v_add_u32_e32 v237, 0x100, v236
	v_ashrrev_i32_e32 v238, 5, v237
	v_ashrrev_i32_e32 v239, 31, v238
	v_lshl_add_u64 v[240:241], s[40:41], 0, v[238:239]
	v_lshlrev_b64 v[238:239], 12, v[240:241]
	v_lshl_add_u64 v[242:243], v[0:1], 0, v[238:239]
	global_load_dwordx4 v[164:167], v[242:243], off
	v_add_u32_e32 v238, s24, v91
	v_mov_b64_e32 v[236:237], s[44:45]
	v_add_u32_e32 v239, 0x200, v238
	v_ashrrev_i32_e32 v240, 5, v239
	v_ashrrev_i32_e32 v241, 31, v240
	v_lshl_add_u64 v[242:243], s[40:41], 0, v[240:241]
	v_mad_u64_u32 v[240:241], s[26:27], v242, s22, v[236:237]
	v_mad_i32_i24 v241, v243, s22, v241
	v_lshl_add_u64 v[240:241], v[240:241], 0, v[4:5]
	v_add_co_u32_e32 v240, vcc, s21, v240
	s_nop 1
	v_addc_co_u32_e32 v241, vcc, 0, v241, vcc
	global_load_dwordx2 v[162:163], v[240:241], off
	v_add_u32_e32 v236, s24, v91
	v_add_u32_e32 v237, 0x200, v236
	v_ashrrev_i32_e32 v238, 5, v237
	v_ashrrev_i32_e32 v239, 31, v238
	v_lshl_add_u64 v[240:241], s[40:41], 0, v[238:239]
	v_lshlrev_b64 v[238:239], 12, v[240:241]
	v_lshl_add_u64 v[242:243], v[0:1], 0, v[238:239]
	global_load_dwordx4 v[168:171], v[242:243], off
	v_add_u32_e32 v238, s24, v91
	v_mov_b64_e32 v[236:237], s[44:45]
	v_add_u32_e32 v239, 0x300, v238
	v_ashrrev_i32_e32 v240, 5, v239
	v_ashrrev_i32_e32 v241, 31, v240
	v_lshl_add_u64 v[242:243], s[40:41], 0, v[240:241]
	v_mad_u64_u32 v[240:241], s[26:27], v242, s22, v[236:237]
	v_mad_i32_i24 v241, v243, s22, v241
	v_lshl_add_u64 v[240:241], v[240:241], 0, v[4:5]
	v_add_co_u32_e32 v240, vcc, s21, v240
	s_nop 1
	v_addc_co_u32_e32 v241, vcc, 0, v241, vcc
	global_load_dwordx2 v[172:173], v[240:241], off
	v_add_u32_e32 v236, s24, v91
	v_add_u32_e32 v237, 0x300, v236
	v_ashrrev_i32_e32 v238, 5, v237
	v_ashrrev_i32_e32 v239, 31, v238
	v_lshl_add_u64 v[240:241], s[40:41], 0, v[238:239]
	v_lshlrev_b64 v[238:239], 12, v[240:241]
	v_lshl_add_u64 v[242:243], v[0:1], 0, v[238:239]
	global_load_dwordx4 v[176:179], v[242:243], off
	v_add_u32_e32 v238, s24, v91
	v_mov_b64_e32 v[236:237], s[44:45]
	v_add_u32_e32 v239, 0x400, v238
	v_ashrrev_i32_e32 v240, 5, v239
	v_ashrrev_i32_e32 v241, 31, v240
	v_lshl_add_u64 v[242:243], s[40:41], 0, v[240:241]
	v_mad_u64_u32 v[240:241], s[26:27], v242, s22, v[236:237]
	v_mad_i32_i24 v241, v243, s22, v241
	v_lshl_add_u64 v[240:241], v[240:241], 0, v[4:5]
	v_add_co_u32_e32 v240, vcc, s21, v240
	s_nop 1
	v_addc_co_u32_e32 v241, vcc, 0, v241, vcc
	global_load_dwordx2 v[174:175], v[240:241], off
	v_add_u32_e32 v236, s24, v91
	v_add_u32_e32 v237, 0x400, v236
	v_ashrrev_i32_e32 v238, 5, v237
	v_ashrrev_i32_e32 v239, 31, v238
	v_lshl_add_u64 v[240:241], s[40:41], 0, v[238:239]
	v_lshlrev_b64 v[238:239], 12, v[240:241]
	v_lshl_add_u64 v[242:243], v[0:1], 0, v[238:239]
	global_load_dwordx4 v[180:183], v[242:243], off
	v_add_u32_e32 v238, s24, v91
	v_mov_b64_e32 v[236:237], s[44:45]
	v_add_u32_e32 v239, 0x500, v238
	v_ashrrev_i32_e32 v240, 5, v239
	v_ashrrev_i32_e32 v241, 31, v240
	v_lshl_add_u64 v[242:243], s[40:41], 0, v[240:241]
	v_mad_u64_u32 v[240:241], s[26:27], v242, s22, v[236:237]
	v_mad_i32_i24 v241, v243, s22, v241
	v_lshl_add_u64 v[240:241], v[240:241], 0, v[4:5]
	v_add_co_u32_e32 v240, vcc, s21, v240
	s_nop 1
	v_addc_co_u32_e32 v241, vcc, 0, v241, vcc
	global_load_dwordx2 v[208:209], v[240:241], off
	v_add_u32_e32 v236, s24, v91
	v_add_u32_e32 v237, 0x500, v236
	v_ashrrev_i32_e32 v238, 5, v237
	v_ashrrev_i32_e32 v239, 31, v238
	v_lshl_add_u64 v[240:241], s[40:41], 0, v[238:239]
	v_lshlrev_b64 v[238:239], 12, v[240:241]
	v_lshl_add_u64 v[242:243], v[0:1], 0, v[238:239]
	global_load_dwordx4 v[212:215], v[242:243], off
	v_add_u32_e32 v238, s24, v91
	v_mov_b64_e32 v[236:237], s[44:45]
	v_add_u32_e32 v239, 0x600, v238
	v_ashrrev_i32_e32 v240, 5, v239
	v_ashrrev_i32_e32 v241, 31, v240
	v_lshl_add_u64 v[242:243], s[40:41], 0, v[240:241]
	v_mad_u64_u32 v[240:241], s[26:27], v242, s22, v[236:237]
	v_mad_i32_i24 v241, v243, s22, v241
	v_lshl_add_u64 v[240:241], v[240:241], 0, v[4:5]
	v_add_co_u32_e32 v240, vcc, s21, v240
	s_nop 1
	v_addc_co_u32_e32 v241, vcc, 0, v241, vcc
	global_load_dwordx2 v[210:211], v[240:241], off
	v_add_u32_e32 v236, s24, v91
	v_add_u32_e32 v237, 0x600, v236
	v_ashrrev_i32_e32 v238, 5, v237
	v_ashrrev_i32_e32 v239, 31, v238
	v_lshl_add_u64 v[240:241], s[40:41], 0, v[238:239]
	v_lshlrev_b64 v[238:239], 12, v[240:241]
	v_lshl_add_u64 v[242:243], v[0:1], 0, v[238:239]
	global_load_dwordx4 v[216:219], v[242:243], off
	v_add_u32_e32 v238, s24, v91
	v_mov_b64_e32 v[236:237], s[44:45]
	v_add_u32_e32 v238, 0x700, v238
	v_ashrrev_i32_e32 v238, 5, v238
	v_ashrrev_i32_e32 v239, 31, v238
	v_lshl_add_u64 v[240:241], s[40:41], 0, v[238:239]
	v_mad_u64_u32 v[236:237], s[26:27], v240, s22, v[236:237]
	v_mad_i32_i24 v237, v241, s22, v237
	v_lshl_add_u64 v[236:237], v[236:237], 0, v[4:5]
	v_add_co_u32_e32 v236, vcc, s21, v236
	s_nop 1
	v_addc_co_u32_e32 v237, vcc, 0, v237, vcc
	global_load_dwordx2 v[220:221], v[236:237], off
	v_add_u32_e32 v238, s24, v91
	v_add_u32_e32 v238, 0x700, v238
	v_ashrrev_i32_e32 v238, 5, v238
	v_ashrrev_i32_e32 v239, 31, v238
	v_lshl_add_u64 v[240:241], s[40:41], 0, v[238:239]
	v_lshlrev_b64 v[236:237], 12, v[240:241]
	v_lshl_add_u64 v[242:243], v[0:1], 0, v[236:237]
	global_load_dwordx4 v[224:227], v[242:243], off
	s_waitcnt vmcnt(0)
; DEVI float sigmoidf_(float x) { return 1.f / (1.f + __expf(-x)); }
; DEVI void store4bf(bfu* p, const float (&v)[4]) {
;   uint2 r;
;   r.x = f2b(v[0]) | ((unsigned)f2b(v[1]) << 16);
;   r.y = f2b(v[2]) | ((unsigned)f2b(v[3]) << 16);
;   *reinterpret_cast<uint2*>(p) = r;
; }
; template <int BR, int IN, int OUT>
; DEVI void p6_branch(const Params& P, int pm, int pn, float* macc, char* smem, int tid) {
;     ...
;   for (int q = 0; q < 16; ++q) {
;     const int id = tid + 256 * q, row = id >> 5, c4 = id & 31;
;     const long grow = (long)pm * 128 + row;
;     const int gcol = pn * 128 + c4 * 4;
;     float4 a = *reinterpret_cast<const float4*>(T + row * 128 + c4 * 4);
;     float g[4];
;     load4bf(Z + grow * NCOL + (9 + BR) * 1024 + gcol, g);
;     float v[4] = {sigmoidf_(g[0]) * a.x, sigmoidf_(g[1]) * a.y, sigmoidf_(g[2]) * a.z, sigmoidf_(g[3]) * a.w};
;     if (IN == 1) {
;       float mo[4]; load4bf(M + grow * 1024 + gcol, mo);
;       v[0] += mo[0]; v[1] += mo[1]; v[2] += mo[2]; v[3] += mo[3];
;     }
;     if (IN == 2) {
;       float4 mo = *reinterpret_cast<const float4*>(macc + grow * 1024 + gcol);
;       v[0] += mo.x; v[1] += mo.y; v[2] += mo.z; v[3] += mo.w;
;     }
;     if (OUT == 1) *reinterpret_cast<float4*>(macc + grow * 1024 + gcol) = make_float4(v[0], v[1], v[2], v[3]);
;     else store4bf(M + grow * 1024 + gcol, v);
	v_add_u32_e32 v8, s24, v91
	v_ashrrev_i32_e32 v6, 5, v8
	v_ashrrev_i32_e32 v7, 31, v6
	v_lshl_add_u64 v[10:11], s[40:41], 0, v[6:7]
	v_lshl_or_b32 v9, v6, 9, v152
	v_mov_b64_e32 v[6:7], s[44:45]
	v_mad_u64_u32 v[12:13], s[26:27], v10, s22, v[6:7]
	v_mad_i32_i24 v13, v11, s22, v13
	v_lshl_add_u64 v[12:13], v[12:13], 0, v[4:5]
	v_add_co_u32_e32 v12, vcc, 0x5000, v12
	s_addk_i32 s24, 0x800
	s_nop 0
	v_addc_co_u32_e32 v13, vcc, 0, v13, vcc
	v_mov_b32_e32 v12, v154
	v_mov_b32_e32 v13, v155
	s_cmpk_lg_i32 s24, 0x1000
	v_lshlrev_b32_e32 v14, 16, v12
	v_and_b32_e32 v12, 0xffff0000, v12
	v_lshlrev_b32_e32 v15, 16, v13
	v_mul_f32_e32 v12, 0xbfb8aa3b, v12
	v_mul_f32_e32 v14, 0xbfb8aa3b, v14
	v_exp_f32_e32 v16, v12
	v_mul_f32_e32 v12, 0xbfb8aa3b, v15
	v_exp_f32_e32 v14, v14
	v_exp_f32_e32 v15, v12
	v_and_b32_e32 v13, 0xffff0000, v13
	v_mul_f32_e32 v12, 0xbfb8aa3b, v13
	v_exp_f32_e32 v17, v12
	v_lshlrev_b64 v[12:13], 12, v[10:11]
	v_lshlrev_b64 v[10:11], 11, v[10:11]
	v_pk_add_f32 v[14:15], v[14:15], 1.0 op_sel_hi:[1,0]
	v_lshl_add_u64 v[18:19], v[0:1], 0, v[12:13]
	v_lshl_add_u64 v[20:21], v[2:3], 0, v[10:11]
	ds_read_b128 v[10:13], v9
	v_min_f32_e32 v9, 0x7f7fffff, v15
	v_rcp_f32_e32 v22, v9
	s_nop 0
	v_fma_f32 v23, -v9, v22, 1.0
	v_fmac_f32_e32 v22, v23, v22
	v_fma_f32 v25, -v9, v22, 1.0
	v_fma_f32 v24, v25, v22, v22
	v_fma_f32 v9, -v9, v24, 1.0
	v_fma_f32 v23, v9, v22, v24
	v_min_f32_e32 v9, 0x7f7fffff, v14
	v_rcp_f32_e32 v15, v9
	s_nop 0
	v_fma_f32 v22, -v9, v15, 1.0
	v_fmac_f32_e32 v15, v22, v15
	v_fma_f32 v25, -v9, v15, 1.0
	v_fma_f32 v24, v25, v15, v15
	v_fma_f32 v9, -v9, v24, 1.0
	v_fma_f32 v22, v9, v15, v24
	v_pk_add_f32 v[14:15], v[16:17], 1.0 op_sel_hi:[1,0]
	s_waitcnt lgkmcnt(0)
	v_mov_b32_e32 v24, v10
	v_min_f32_e32 v9, 0x7f7fffff, v15
	v_rcp_f32_e32 v10, v9
	v_mov_b32_e32 v25, v12
	v_fma_f32 v12, -v9, v10, 1.0
	v_fmac_f32_e32 v10, v12, v10
	v_fma_f32 v17, -v9, v10, 1.0
	v_fma_f32 v16, v17, v10, v10
	v_fma_f32 v9, -v9, v16, 1.0
	v_fma_f32 v27, v9, v10, v16
	v_min_f32_e32 v9, 0x7f7fffff, v14
	v_rcp_f32_e32 v10, v9
	s_nop 0
	v_fma_f32 v12, -v9, v10, 1.0
	v_fmac_f32_e32 v10, v12, v10
	v_fma_f32 v16, -v9, v10, 1.0
	v_fma_f32 v15, v16, v10, v10
	v_fma_f32 v9, -v9, v15, 1.0
	v_fma_f32 v26, v9, v10, v15
	v_mov_b32_e32 v14, v156
	v_mov_b32_e32 v15, v157
	v_mov_b32_e32 v16, v158
	v_mov_b32_e32 v17, v159
	v_mov_b32_e32 v12, v11
	v_mov_b32_e32 v10, v14
	v_mov_b32_e32 v11, v16
	v_pk_fma_f32 v[10:11], v[24:25], v[22:23], v[10:11]
	v_mov_b32_e32 v16, v15
	v_pk_fma_f32 v[12:13], v[12:13], v[26:27], v[16:17]
	v_and_b32_sdwa v9, v11, v95 dst_sel:DWORD dst_unused:UNUSED_PAD src0_sel:WORD_1 src1_sel:DWORD
	v_and_b32_sdwa v14, v10, v95 dst_sel:DWORD dst_unused:UNUSED_PAD src0_sel:WORD_1 src1_sel:DWORD
	v_add3_u32 v10, v10, v14, s39
	v_add3_u32 v9, v11, v9, s39
	v_and_b32_sdwa v11, v13, v95 dst_sel:DWORD dst_unused:UNUSED_PAD src0_sel:WORD_1 src1_sel:DWORD
	v_and_b32_sdwa v14, v12, v95 dst_sel:DWORD dst_unused:UNUSED_PAD src0_sel:WORD_1 src1_sel:DWORD
	v_add3_u32 v11, v13, v11, s39
	v_add3_u32 v12, v12, v14, s39
	v_and_b32_e32 v11, 0xffff0000, v11
	v_and_b32_e32 v12, 0xffff0000, v12
	v_or_b32_sdwa v11, v11, v9 dst_sel:DWORD dst_unused:UNUSED_PAD src0_sel:DWORD src1_sel:WORD_1
	v_or_b32_sdwa v10, v12, v10 dst_sel:DWORD dst_unused:UNUSED_PAD src0_sel:DWORD src1_sel:WORD_1
	v_add_u32_e32 v9, 0x100, v8
	global_store_dwordx2 v[20:21], v[10:11], off
	v_ashrrev_i32_e32 v10, 5, v9
	v_ashrrev_i32_e32 v11, 31, v10
	v_lshl_add_u64 v[12:13], s[40:41], 0, v[10:11]
	v_lshl_or_b32 v9, v10, 9, v152
	v_mad_u64_u32 v[10:11], s[26:27], v12, s22, v[6:7]
	v_mad_i32_i24 v11, v13, s22, v11
	v_lshl_add_u64 v[10:11], v[10:11], 0, v[4:5]
	v_add_co_u32_e32 v10, vcc, s21, v10
	s_nop 1
	v_addc_co_u32_e32 v11, vcc, 0, v11, vcc
	v_mov_b32_e32 v10, v160
	v_mov_b32_e32 v11, v161
	v_lshlrev_b32_e32 v14, 16, v10
	v_and_b32_e32 v10, 0xffff0000, v10
	v_lshlrev_b32_e32 v15, 16, v11
	v_mul_f32_e32 v10, 0xbfb8aa3b, v10
	v_mul_f32_e32 v14, 0xbfb8aa3b, v14
	v_exp_f32_e32 v16, v10
	v_mul_f32_e32 v10, 0xbfb8aa3b, v15
	v_exp_f32_e32 v14, v14
	v_exp_f32_e32 v15, v10
	v_and_b32_e32 v11, 0xffff0000, v11
	v_mul_f32_e32 v10, 0xbfb8aa3b, v11
	v_exp_f32_e32 v17, v10
	v_lshlrev_b64 v[10:11], 12, v[12:13]
	v_lshl_add_u64 v[18:19], v[0:1], 0, v[10:11]
	v_lshlrev_b64 v[10:11], 11, v[12:13]
	v_pk_add_f32 v[14:15], v[14:15], 1.0 op_sel_hi:[1,0]
	v_lshl_add_u64 v[20:21], v[2:3], 0, v[10:11]
	ds_read_b128 v[10:13], v9
	v_min_f32_e32 v9, 0x7f7fffff, v15
	v_rcp_f32_e32 v22, v9
	s_nop 0
	v_fma_f32 v23, -v9, v22, 1.0
	v_fmac_f32_e32 v22, v23, v22
	v_fma_f32 v25, -v9, v22, 1.0
	v_fma_f32 v24, v25, v22, v22
	v_fma_f32 v9, -v9, v24, 1.0
	v_fma_f32 v23, v9, v22, v24
	v_min_f32_e32 v9, 0x7f7fffff, v14
	v_rcp_f32_e32 v15, v9
	s_nop 0
	v_fma_f32 v22, -v9, v15, 1.0
	v_fmac_f32_e32 v15, v22, v15
	v_fma_f32 v25, -v9, v15, 1.0
	v_fma_f32 v24, v25, v15, v15
	v_fma_f32 v9, -v9, v24, 1.0
	v_fma_f32 v22, v9, v15, v24
	v_pk_add_f32 v[14:15], v[16:17], 1.0 op_sel_hi:[1,0]
	s_waitcnt lgkmcnt(0)
; DEVI float sigmoidf_(float x) { return 1.f / (1.f + __expf(-x)); }
; DEVI void store4bf(bfu* p, const float (&v)[4]) {
;   uint2 r;
;   r.x = f2b(v[0]) | ((unsigned)f2b(v[1]) << 16);
;   r.y = f2b(v[2]) | ((unsigned)f2b(v[3]) << 16);
;   *reinterpret_cast<uint2*>(p) = r;
; }
; template <int BR, int IN, int OUT>
; DEVI void p6_branch(const Params& P, int pm, int pn, float* macc, char* smem, int tid) {
;     ...
;   for (int q = 0; q < 16; ++q) {
;     const int id = tid + 256 * q, row = id >> 5, c4 = id & 31;
;     const long grow = (long)pm * 128 + row;
;     const int gcol = pn * 128 + c4 * 4;
;     float4 a = *reinterpret_cast<const float4*>(T + row * 128 + c4 * 4);
;     float g[4];
;     load4bf(Z + grow * NCOL + (9 + BR) * 1024 + gcol, g);
;     float v[4] = {sigmoidf_(g[0]) * a.x, sigmoidf_(g[1]) * a.y, sigmoidf_(g[2]) * a.z, sigmoidf_(g[3]) * a.w};
;     if (IN == 1) {
;       float mo[4]; load4bf(M + grow * 1024 + gcol, mo);
;       v[0] += mo[0]; v[1] += mo[1]; v[2] += mo[2]; v[3] += mo[3];
;     }
;     if (IN == 2) {
;       float4 mo = *reinterpret_cast<const float4*>(macc + grow * 1024 + gcol);
;       v[0] += mo.x; v[1] += mo.y; v[2] += mo.z; v[3] += mo.w;
;     }
;     if (OUT == 1) *reinterpret_cast<float4*>(macc + grow * 1024 + gcol) = make_float4(v[0], v[1], v[2], v[3]);
;     else store4bf(M + grow * 1024 + gcol, v);
	v_mov_b32_e32 v24, v10
	v_min_f32_e32 v9, 0x7f7fffff, v15
	v_rcp_f32_e32 v10, v9
	v_mov_b32_e32 v25, v12
	v_fma_f32 v12, -v9, v10, 1.0
	v_fmac_f32_e32 v10, v12, v10
	v_fma_f32 v17, -v9, v10, 1.0
	v_fma_f32 v16, v17, v10, v10
	v_fma_f32 v9, -v9, v16, 1.0
	v_fma_f32 v27, v9, v10, v16
	v_min_f32_e32 v9, 0x7f7fffff, v14
	v_rcp_f32_e32 v10, v9
	s_nop 0
	v_fma_f32 v12, -v9, v10, 1.0
	v_fmac_f32_e32 v10, v12, v10
	v_fma_f32 v16, -v9, v10, 1.0
	v_fma_f32 v15, v16, v10, v10
	v_fma_f32 v9, -v9, v15, 1.0
	v_fma_f32 v26, v9, v10, v15
	v_mov_b32_e32 v14, v164
	v_mov_b32_e32 v15, v165
	v_mov_b32_e32 v16, v166
	v_mov_b32_e32 v17, v167
	v_mov_b32_e32 v12, v11
	v_mov_b32_e32 v10, v14
	v_mov_b32_e32 v11, v16
	v_pk_fma_f32 v[10:11], v[24:25], v[22:23], v[10:11]
	v_mov_b32_e32 v16, v15
	v_pk_fma_f32 v[12:13], v[12:13], v[26:27], v[16:17]
	v_and_b32_sdwa v9, v11, v95 dst_sel:DWORD dst_unused:UNUSED_PAD src0_sel:WORD_1 src1_sel:DWORD
	v_and_b32_sdwa v14, v10, v95 dst_sel:DWORD dst_unused:UNUSED_PAD src0_sel:WORD_1 src1_sel:DWORD
	v_add3_u32 v10, v10, v14, s39
	v_add3_u32 v9, v11, v9, s39
	v_and_b32_sdwa v11, v13, v95 dst_sel:DWORD dst_unused:UNUSED_PAD src0_sel:WORD_1 src1_sel:DWORD
	v_and_b32_sdwa v14, v12, v95 dst_sel:DWORD dst_unused:UNUSED_PAD src0_sel:WORD_1 src1_sel:DWORD
	v_add3_u32 v11, v13, v11, s39
	v_add3_u32 v12, v12, v14, s39
	v_and_b32_e32 v11, 0xffff0000, v11
	v_and_b32_e32 v12, 0xffff0000, v12
	v_or_b32_sdwa v11, v11, v9 dst_sel:DWORD dst_unused:UNUSED_PAD src0_sel:DWORD src1_sel:WORD_1
	v_or_b32_sdwa v10, v12, v10 dst_sel:DWORD dst_unused:UNUSED_PAD src0_sel:DWORD src1_sel:WORD_1
	v_add_u32_e32 v9, 0x200, v8
	global_store_dwordx2 v[20:21], v[10:11], off
	v_ashrrev_i32_e32 v10, 5, v9
	v_ashrrev_i32_e32 v11, 31, v10
	v_lshl_add_u64 v[12:13], s[40:41], 0, v[10:11]
	v_lshl_or_b32 v9, v10, 9, v152
	v_mad_u64_u32 v[10:11], s[26:27], v12, s22, v[6:7]
	v_mad_i32_i24 v11, v13, s22, v11
	v_lshl_add_u64 v[10:11], v[10:11], 0, v[4:5]
	v_add_co_u32_e32 v10, vcc, s21, v10
	s_nop 1
	v_addc_co_u32_e32 v11, vcc, 0, v11, vcc
	v_mov_b32_e32 v10, v162
	v_mov_b32_e32 v11, v163
	v_lshlrev_b32_e32 v14, 16, v10
	v_and_b32_e32 v10, 0xffff0000, v10
	v_lshlrev_b32_e32 v15, 16, v11
	v_mul_f32_e32 v10, 0xbfb8aa3b, v10
	v_mul_f32_e32 v14, 0xbfb8aa3b, v14
	v_exp_f32_e32 v16, v10
	v_mul_f32_e32 v10, 0xbfb8aa3b, v15
	v_exp_f32_e32 v14, v14
	v_exp_f32_e32 v15, v10
	v_and_b32_e32 v11, 0xffff0000, v11
	v_mul_f32_e32 v10, 0xbfb8aa3b, v11
	v_exp_f32_e32 v17, v10
	v_lshlrev_b64 v[10:11], 12, v[12:13]
	v_lshl_add_u64 v[18:19], v[0:1], 0, v[10:11]
	v_lshlrev_b64 v[10:11], 11, v[12:13]
	v_pk_add_f32 v[14:15], v[14:15], 1.0 op_sel_hi:[1,0]
	v_lshl_add_u64 v[20:21], v[2:3], 0, v[10:11]
	ds_read_b128 v[10:13], v9
	v_min_f32_e32 v9, 0x7f7fffff, v15
	v_rcp_f32_e32 v22, v9
	s_nop 0
	v_fma_f32 v23, -v9, v22, 1.0
	v_fmac_f32_e32 v22, v23, v22
	v_fma_f32 v25, -v9, v22, 1.0
	v_fma_f32 v24, v25, v22, v22
	v_fma_f32 v9, -v9, v24, 1.0
	v_fma_f32 v23, v9, v22, v24
	v_min_f32_e32 v9, 0x7f7fffff, v14
	v_rcp_f32_e32 v15, v9
	s_nop 0
	v_fma_f32 v22, -v9, v15, 1.0
	v_fmac_f32_e32 v15, v22, v15
	v_fma_f32 v25, -v9, v15, 1.0
	v_fma_f32 v24, v25, v15, v15
	v_fma_f32 v9, -v9, v24, 1.0
	v_fma_f32 v22, v9, v15, v24
	v_pk_add_f32 v[14:15], v[16:17], 1.0 op_sel_hi:[1,0]
	s_waitcnt lgkmcnt(0)
	v_mov_b32_e32 v24, v10
	v_min_f32_e32 v9, 0x7f7fffff, v15
	v_rcp_f32_e32 v10, v9
	v_mov_b32_e32 v25, v12
	v_fma_f32 v12, -v9, v10, 1.0
	v_fmac_f32_e32 v10, v12, v10
	v_fma_f32 v17, -v9, v10, 1.0
	v_fma_f32 v16, v17, v10, v10
	v_fma_f32 v9, -v9, v16, 1.0
	v_fma_f32 v27, v9, v10, v16
	v_min_f32_e32 v9, 0x7f7fffff, v14
	v_rcp_f32_e32 v10, v9
	s_nop 0
	v_fma_f32 v12, -v9, v10, 1.0
	v_fmac_f32_e32 v10, v12, v10
	v_fma_f32 v16, -v9, v10, 1.0
	v_fma_f32 v15, v16, v10, v10
	v_fma_f32 v9, -v9, v15, 1.0
	v_fma_f32 v26, v9, v10, v15
	v_mov_b32_e32 v14, v168
	v_mov_b32_e32 v15, v169
	v_mov_b32_e32 v16, v170
	v_mov_b32_e32 v17, v171
	v_mov_b32_e32 v12, v11
	v_mov_b32_e32 v10, v14
	v_mov_b32_e32 v11, v16
	v_pk_fma_f32 v[10:11], v[24:25], v[22:23], v[10:11]
	v_mov_b32_e32 v16, v15
	v_pk_fma_f32 v[12:13], v[12:13], v[26:27], v[16:17]
	v_and_b32_sdwa v9, v11, v95 dst_sel:DWORD dst_unused:UNUSED_PAD src0_sel:WORD_1 src1_sel:DWORD
	v_and_b32_sdwa v14, v10, v95 dst_sel:DWORD dst_unused:UNUSED_PAD src0_sel:WORD_1 src1_sel:DWORD
	v_add3_u32 v10, v10, v14, s39
	v_add3_u32 v9, v11, v9, s39
	v_and_b32_sdwa v11, v13, v95 dst_sel:DWORD dst_unused:UNUSED_PAD src0_sel:WORD_1 src1_sel:DWORD
	v_and_b32_sdwa v14, v12, v95 dst_sel:DWORD dst_unused:UNUSED_PAD src0_sel:WORD_1 src1_sel:DWORD
	v_add3_u32 v11, v13, v11, s39
	v_add3_u32 v12, v12, v14, s39
	v_and_b32_e32 v11, 0xffff0000, v11
	v_and_b32_e32 v12, 0xffff0000, v12
	v_or_b32_sdwa v11, v11, v9 dst_sel:DWORD dst_unused:UNUSED_PAD src0_sel:DWORD src1_sel:WORD_1
	v_or_b32_sdwa v10, v12, v10 dst_sel:DWORD dst_unused:UNUSED_PAD src0_sel:DWORD src1_sel:WORD_1
	v_add_u32_e32 v9, 0x300, v8
	global_store_dwordx2 v[20:21], v[10:11], off
	v_ashrrev_i32_e32 v10, 5, v9
	v_ashrrev_i32_e32 v11, 31, v10
	v_lshl_add_u64 v[12:13], s[40:41], 0, v[10:11]
	v_lshl_or_b32 v9, v10, 9, v152
	v_mad_u64_u32 v[10:11], s[26:27], v12, s22, v[6:7]
	v_mad_i32_i24 v11, v13, s22, v11
	v_lshl_add_u64 v[10:11], v[10:11], 0, v[4:5]
	v_add_co_u32_e32 v10, vcc, s21, v10
	s_nop 1
	v_addc_co_u32_e32 v11, vcc, 0, v11, vcc
	v_mov_b32_e32 v10, v172
	v_mov_b32_e32 v11, v173
	v_lshlrev_b32_e32 v14, 16, v10
	v_and_b32_e32 v10, 0xffff0000, v10
	v_lshlrev_b32_e32 v15, 16, v11
	v_mul_f32_e32 v10, 0xbfb8aa3b, v10
	v_mul_f32_e32 v14, 0xbfb8aa3b, v14
	v_exp_f32_e32 v16, v10
	v_mul_f32_e32 v10, 0xbfb8aa3b, v15
	v_exp_f32_e32 v14, v14
	v_exp_f32_e32 v15, v10
	v_and_b32_e32 v11, 0xffff0000, v11
	v_mul_f32_e32 v10, 0xbfb8aa3b, v11
	v_exp_f32_e32 v17, v10
	v_lshlrev_b64 v[10:11], 12, v[12:13]
	v_lshl_add_u64 v[18:19], v[0:1], 0, v[10:11]
	v_lshlrev_b64 v[10:11], 11, v[12:13]
	v_pk_add_f32 v[14:15], v[14:15], 1.0 op_sel_hi:[1,0]
	v_lshl_add_u64 v[20:21], v[2:3], 0, v[10:11]
	ds_read_b128 v[10:13], v9
	v_min_f32_e32 v9, 0x7f7fffff, v15
	v_rcp_f32_e32 v22, v9
	s_nop 0
	v_fma_f32 v23, -v9, v22, 1.0
	v_fmac_f32_e32 v22, v23, v22
	v_fma_f32 v25, -v9, v22, 1.0
	v_fma_f32 v24, v25, v22, v22
	v_fma_f32 v9, -v9, v24, 1.0
	v_fma_f32 v23, v9, v22, v24
	v_min_f32_e32 v9, 0x7f7fffff, v14
	v_rcp_f32_e32 v15, v9
	s_nop 0
	v_fma_f32 v22, -v9, v15, 1.0
	v_fmac_f32_e32 v15, v22, v15
	v_fma_f32 v25, -v9, v15, 1.0
	v_fma_f32 v24, v25, v15, v15
	v_fma_f32 v9, -v9, v24, 1.0
	v_fma_f32 v22, v9, v15, v24
	v_pk_add_f32 v[14:15], v[16:17], 1.0 op_sel_hi:[1,0]
	s_waitcnt lgkmcnt(0)
; DEVI float sigmoidf_(float x) { return 1.f / (1.f + __expf(-x)); }
; DEVI void store4bf(bfu* p, const float (&v)[4]) {
;   uint2 r;
;   r.x = f2b(v[0]) | ((unsigned)f2b(v[1]) << 16);
;   r.y = f2b(v[2]) | ((unsigned)f2b(v[3]) << 16);
;   *reinterpret_cast<uint2*>(p) = r;
; }
; template <int BR, int IN, int OUT>
; DEVI void p6_branch(const Params& P, int pm, int pn, float* macc, char* smem, int tid) {
;     ...
;   for (int q = 0; q < 16; ++q) {
;     const int id = tid + 256 * q, row = id >> 5, c4 = id & 31;
;     const long grow = (long)pm * 128 + row;
;     const int gcol = pn * 128 + c4 * 4;
;     float4 a = *reinterpret_cast<const float4*>(T + row * 128 + c4 * 4);
;     float g[4];
;     load4bf(Z + grow * NCOL + (9 + BR) * 1024 + gcol, g);
;     float v[4] = {sigmoidf_(g[0]) * a.x, sigmoidf_(g[1]) * a.y, sigmoidf_(g[2]) * a.z, sigmoidf_(g[3]) * a.w};
;     if (IN == 1) {
;       float mo[4]; load4bf(M + grow * 1024 + gcol, mo);
;       v[0] += mo[0]; v[1] += mo[1]; v[2] += mo[2]; v[3] += mo[3];
;     }
;     if (IN == 2) {
;       float4 mo = *reinterpret_cast<const float4*>(macc + grow * 1024 + gcol);
;       v[0] += mo.x; v[1] += mo.y; v[2] += mo.z; v[3] += mo.w;
;     }
;     if (OUT == 1) *reinterpret_cast<float4*>(macc + grow * 1024 + gcol) = make_float4(v[0], v[1], v[2], v[3]);
;     else store4bf(M + grow * 1024 + gcol, v);
	v_mov_b32_e32 v24, v10
	v_min_f32_e32 v9, 0x7f7fffff, v15
	v_rcp_f32_e32 v10, v9
	v_mov_b32_e32 v25, v12
	v_fma_f32 v12, -v9, v10, 1.0
	v_fmac_f32_e32 v10, v12, v10
	v_fma_f32 v17, -v9, v10, 1.0
	v_fma_f32 v16, v17, v10, v10
	v_fma_f32 v9, -v9, v16, 1.0
	v_fma_f32 v27, v9, v10, v16
	v_min_f32_e32 v9, 0x7f7fffff, v14
	v_rcp_f32_e32 v10, v9
	s_nop 0
	v_fma_f32 v12, -v9, v10, 1.0
	v_fmac_f32_e32 v10, v12, v10
	v_fma_f32 v16, -v9, v10, 1.0
	v_fma_f32 v15, v16, v10, v10
	v_fma_f32 v9, -v9, v15, 1.0
	v_fma_f32 v26, v9, v10, v15
	v_mov_b32_e32 v14, v176
	v_mov_b32_e32 v15, v177
	v_mov_b32_e32 v16, v178
	v_mov_b32_e32 v17, v179
	v_mov_b32_e32 v12, v11
	v_mov_b32_e32 v10, v14
	v_mov_b32_e32 v11, v16
	v_pk_fma_f32 v[10:11], v[24:25], v[22:23], v[10:11]
	v_mov_b32_e32 v16, v15
	v_pk_fma_f32 v[12:13], v[12:13], v[26:27], v[16:17]
	v_and_b32_sdwa v9, v11, v95 dst_sel:DWORD dst_unused:UNUSED_PAD src0_sel:WORD_1 src1_sel:DWORD
	v_and_b32_sdwa v14, v10, v95 dst_sel:DWORD dst_unused:UNUSED_PAD src0_sel:WORD_1 src1_sel:DWORD
	v_add3_u32 v10, v10, v14, s39
	v_add3_u32 v9, v11, v9, s39
	v_and_b32_sdwa v11, v13, v95 dst_sel:DWORD dst_unused:UNUSED_PAD src0_sel:WORD_1 src1_sel:DWORD
	v_and_b32_sdwa v14, v12, v95 dst_sel:DWORD dst_unused:UNUSED_PAD src0_sel:WORD_1 src1_sel:DWORD
	v_add3_u32 v11, v13, v11, s39
	v_add3_u32 v12, v12, v14, s39
	v_and_b32_e32 v11, 0xffff0000, v11
	v_and_b32_e32 v12, 0xffff0000, v12
	v_or_b32_sdwa v11, v11, v9 dst_sel:DWORD dst_unused:UNUSED_PAD src0_sel:DWORD src1_sel:WORD_1
	v_or_b32_sdwa v10, v12, v10 dst_sel:DWORD dst_unused:UNUSED_PAD src0_sel:DWORD src1_sel:WORD_1
	v_add_u32_e32 v9, 0x400, v8
	global_store_dwordx2 v[20:21], v[10:11], off
	v_ashrrev_i32_e32 v10, 5, v9
	v_ashrrev_i32_e32 v11, 31, v10
	v_lshl_add_u64 v[12:13], s[40:41], 0, v[10:11]
	v_lshl_or_b32 v9, v10, 9, v152
	v_mad_u64_u32 v[10:11], s[26:27], v12, s22, v[6:7]
	v_mad_i32_i24 v11, v13, s22, v11
	v_lshl_add_u64 v[10:11], v[10:11], 0, v[4:5]
	v_add_co_u32_e32 v10, vcc, s21, v10
	s_nop 1
	v_addc_co_u32_e32 v11, vcc, 0, v11, vcc
	v_mov_b32_e32 v10, v174
	v_mov_b32_e32 v11, v175
	v_lshlrev_b32_e32 v14, 16, v10
	v_and_b32_e32 v10, 0xffff0000, v10
	v_lshlrev_b32_e32 v15, 16, v11
	v_mul_f32_e32 v10, 0xbfb8aa3b, v10
	v_mul_f32_e32 v14, 0xbfb8aa3b, v14
	v_exp_f32_e32 v16, v10
	v_mul_f32_e32 v10, 0xbfb8aa3b, v15
	v_exp_f32_e32 v14, v14
	v_exp_f32_e32 v15, v10
	v_and_b32_e32 v11, 0xffff0000, v11
	v_mul_f32_e32 v10, 0xbfb8aa3b, v11
	v_exp_f32_e32 v17, v10
	v_lshlrev_b64 v[10:11], 12, v[12:13]
	v_lshl_add_u64 v[18:19], v[0:1], 0, v[10:11]
	v_lshlrev_b64 v[10:11], 11, v[12:13]
	v_pk_add_f32 v[14:15], v[14:15], 1.0 op_sel_hi:[1,0]
	v_lshl_add_u64 v[20:21], v[2:3], 0, v[10:11]
	ds_read_b128 v[10:13], v9
	v_min_f32_e32 v9, 0x7f7fffff, v15
	v_rcp_f32_e32 v22, v9
	s_nop 0
	v_fma_f32 v23, -v9, v22, 1.0
	v_fmac_f32_e32 v22, v23, v22
	v_fma_f32 v25, -v9, v22, 1.0
	v_fma_f32 v24, v25, v22, v22
	v_fma_f32 v9, -v9, v24, 1.0
	v_fma_f32 v23, v9, v22, v24
	v_min_f32_e32 v9, 0x7f7fffff, v14
	v_rcp_f32_e32 v15, v9
	s_nop 0
	v_fma_f32 v22, -v9, v15, 1.0
	v_fmac_f32_e32 v15, v22, v15
	v_fma_f32 v25, -v9, v15, 1.0
	v_fma_f32 v24, v25, v15, v15
	v_fma_f32 v9, -v9, v24, 1.0
	v_fma_f32 v22, v9, v15, v24
	v_pk_add_f32 v[14:15], v[16:17], 1.0 op_sel_hi:[1,0]
	s_waitcnt lgkmcnt(0)
	v_mov_b32_e32 v24, v10
	v_min_f32_e32 v9, 0x7f7fffff, v15
	v_rcp_f32_e32 v10, v9
	v_mov_b32_e32 v25, v12
	v_fma_f32 v12, -v9, v10, 1.0
	v_fmac_f32_e32 v10, v12, v10
	v_fma_f32 v17, -v9, v10, 1.0
	v_fma_f32 v16, v17, v10, v10
	v_fma_f32 v9, -v9, v16, 1.0
	v_fma_f32 v27, v9, v10, v16
	v_min_f32_e32 v9, 0x7f7fffff, v14
	v_rcp_f32_e32 v10, v9
	s_nop 0
	v_fma_f32 v12, -v9, v10, 1.0
	v_fmac_f32_e32 v10, v12, v10
	v_fma_f32 v16, -v9, v10, 1.0
	v_fma_f32 v15, v16, v10, v10
	v_fma_f32 v9, -v9, v15, 1.0
	v_fma_f32 v26, v9, v10, v15
	v_mov_b32_e32 v14, v180
	v_mov_b32_e32 v15, v181
	v_mov_b32_e32 v16, v182
	v_mov_b32_e32 v17, v183
	v_mov_b32_e32 v12, v11
	v_mov_b32_e32 v10, v14
	v_mov_b32_e32 v11, v16
	v_pk_fma_f32 v[10:11], v[24:25], v[22:23], v[10:11]
	v_mov_b32_e32 v16, v15
	v_pk_fma_f32 v[12:13], v[12:13], v[26:27], v[16:17]
	v_and_b32_sdwa v9, v11, v95 dst_sel:DWORD dst_unused:UNUSED_PAD src0_sel:WORD_1 src1_sel:DWORD
	v_and_b32_sdwa v14, v10, v95 dst_sel:DWORD dst_unused:UNUSED_PAD src0_sel:WORD_1 src1_sel:DWORD
	v_add3_u32 v10, v10, v14, s39
	v_add3_u32 v9, v11, v9, s39
	v_and_b32_sdwa v11, v13, v95 dst_sel:DWORD dst_unused:UNUSED_PAD src0_sel:WORD_1 src1_sel:DWORD
	v_and_b32_sdwa v14, v12, v95 dst_sel:DWORD dst_unused:UNUSED_PAD src0_sel:WORD_1 src1_sel:DWORD
	v_add3_u32 v11, v13, v11, s39
	v_add3_u32 v12, v12, v14, s39
	v_and_b32_e32 v11, 0xffff0000, v11
	v_and_b32_e32 v12, 0xffff0000, v12
	v_or_b32_sdwa v11, v11, v9 dst_sel:DWORD dst_unused:UNUSED_PAD src0_sel:DWORD src1_sel:WORD_1
	v_or_b32_sdwa v10, v12, v10 dst_sel:DWORD dst_unused:UNUSED_PAD src0_sel:DWORD src1_sel:WORD_1
	v_add_u32_e32 v9, 0x500, v8
	global_store_dwordx2 v[20:21], v[10:11], off
	v_ashrrev_i32_e32 v10, 5, v9
	v_ashrrev_i32_e32 v11, 31, v10
	v_lshl_add_u64 v[12:13], s[40:41], 0, v[10:11]
	v_lshl_or_b32 v9, v10, 9, v152
	v_mad_u64_u32 v[10:11], s[26:27], v12, s22, v[6:7]
	v_mad_i32_i24 v11, v13, s22, v11
	v_lshl_add_u64 v[10:11], v[10:11], 0, v[4:5]
	v_add_co_u32_e32 v10, vcc, s21, v10
	s_nop 1
	v_addc_co_u32_e32 v11, vcc, 0, v11, vcc
	v_mov_b32_e32 v10, v208
	v_mov_b32_e32 v11, v209
	v_lshlrev_b32_e32 v14, 16, v10
	v_and_b32_e32 v10, 0xffff0000, v10
	v_lshlrev_b32_e32 v15, 16, v11
	v_mul_f32_e32 v10, 0xbfb8aa3b, v10
	v_mul_f32_e32 v14, 0xbfb8aa3b, v14
	v_exp_f32_e32 v16, v10
	v_mul_f32_e32 v10, 0xbfb8aa3b, v15
	v_exp_f32_e32 v14, v14
	v_exp_f32_e32 v15, v10
	v_and_b32_e32 v11, 0xffff0000, v11
	v_mul_f32_e32 v10, 0xbfb8aa3b, v11
	v_exp_f32_e32 v17, v10
	v_lshlrev_b64 v[10:11], 12, v[12:13]
	v_lshl_add_u64 v[18:19], v[0:1], 0, v[10:11]
	v_lshlrev_b64 v[10:11], 11, v[12:13]
	v_pk_add_f32 v[14:15], v[14:15], 1.0 op_sel_hi:[1,0]
	v_lshl_add_u64 v[20:21], v[2:3], 0, v[10:11]
	ds_read_b128 v[10:13], v9
	v_min_f32_e32 v9, 0x7f7fffff, v15
	v_rcp_f32_e32 v22, v9
	s_nop 0
	v_fma_f32 v23, -v9, v22, 1.0
	v_fmac_f32_e32 v22, v23, v22
	v_fma_f32 v25, -v9, v22, 1.0
	v_fma_f32 v24, v25, v22, v22
	v_fma_f32 v9, -v9, v24, 1.0
	v_fma_f32 v23, v9, v22, v24
	v_min_f32_e32 v9, 0x7f7fffff, v14
	v_rcp_f32_e32 v15, v9
	s_nop 0
	v_fma_f32 v22, -v9, v15, 1.0
	v_fmac_f32_e32 v15, v22, v15
	v_fma_f32 v25, -v9, v15, 1.0
	v_fma_f32 v24, v25, v15, v15
	v_fma_f32 v9, -v9, v24, 1.0
	v_fma_f32 v22, v9, v15, v24
	v_pk_add_f32 v[14:15], v[16:17], 1.0 op_sel_hi:[1,0]
	s_waitcnt lgkmcnt(0)
; DEVI float sigmoidf_(float x) { return 1.f / (1.f + __expf(-x)); }
; DEVI void store4bf(bfu* p, const float (&v)[4]) {
;   uint2 r;
;   r.x = f2b(v[0]) | ((unsigned)f2b(v[1]) << 16);
;   r.y = f2b(v[2]) | ((unsigned)f2b(v[3]) << 16);
;   *reinterpret_cast<uint2*>(p) = r;
; }
; template <int BR, int IN, int OUT>
; DEVI void p6_branch(const Params& P, int pm, int pn, float* macc, char* smem, int tid) {
;     ...
;   for (int q = 0; q < 16; ++q) {
;     const int id = tid + 256 * q, row = id >> 5, c4 = id & 31;
;     const long grow = (long)pm * 128 + row;
;     const int gcol = pn * 128 + c4 * 4;
;     float4 a = *reinterpret_cast<const float4*>(T + row * 128 + c4 * 4);
;     float g[4];
;     load4bf(Z + grow * NCOL + (9 + BR) * 1024 + gcol, g);
;     float v[4] = {sigmoidf_(g[0]) * a.x, sigmoidf_(g[1]) * a.y, sigmoidf_(g[2]) * a.z, sigmoidf_(g[3]) * a.w};
;     if (IN == 1) {
;       float mo[4]; load4bf(M + grow * 1024 + gcol, mo);
;       v[0] += mo[0]; v[1] += mo[1]; v[2] += mo[2]; v[3] += mo[3];
;     }
;     if (IN == 2) {
;       float4 mo = *reinterpret_cast<const float4*>(macc + grow * 1024 + gcol);
;       v[0] += mo.x; v[1] += mo.y; v[2] += mo.z; v[3] += mo.w;
;     }
;     if (OUT == 1) *reinterpret_cast<float4*>(macc + grow * 1024 + gcol) = make_float4(v[0], v[1], v[2], v[3]);
;     else store4bf(M + grow * 1024 + gcol, v);
	v_mov_b32_e32 v24, v10
	v_min_f32_e32 v9, 0x7f7fffff, v15
	v_rcp_f32_e32 v10, v9
	v_mov_b32_e32 v25, v12
	v_fma_f32 v12, -v9, v10, 1.0
	v_fmac_f32_e32 v10, v12, v10
	v_fma_f32 v17, -v9, v10, 1.0
	v_fma_f32 v16, v17, v10, v10
	v_fma_f32 v9, -v9, v16, 1.0
	v_fma_f32 v27, v9, v10, v16
	v_min_f32_e32 v9, 0x7f7fffff, v14
	v_rcp_f32_e32 v10, v9
	s_nop 0
	v_fma_f32 v12, -v9, v10, 1.0
	v_fmac_f32_e32 v10, v12, v10
	v_fma_f32 v16, -v9, v10, 1.0
	v_fma_f32 v15, v16, v10, v10
	v_fma_f32 v9, -v9, v15, 1.0
	v_fma_f32 v26, v9, v10, v15
	v_mov_b32_e32 v14, v212
	v_mov_b32_e32 v15, v213
	v_mov_b32_e32 v16, v214
	v_mov_b32_e32 v17, v215
	v_mov_b32_e32 v12, v11
	v_mov_b32_e32 v10, v14
	v_mov_b32_e32 v11, v16
	v_pk_fma_f32 v[10:11], v[24:25], v[22:23], v[10:11]
	v_mov_b32_e32 v16, v15
	v_pk_fma_f32 v[12:13], v[12:13], v[26:27], v[16:17]
	v_and_b32_sdwa v9, v11, v95 dst_sel:DWORD dst_unused:UNUSED_PAD src0_sel:WORD_1 src1_sel:DWORD
	v_and_b32_sdwa v14, v10, v95 dst_sel:DWORD dst_unused:UNUSED_PAD src0_sel:WORD_1 src1_sel:DWORD
	v_add3_u32 v10, v10, v14, s39
	v_add3_u32 v9, v11, v9, s39
	v_and_b32_sdwa v11, v13, v95 dst_sel:DWORD dst_unused:UNUSED_PAD src0_sel:WORD_1 src1_sel:DWORD
	v_and_b32_sdwa v14, v12, v95 dst_sel:DWORD dst_unused:UNUSED_PAD src0_sel:WORD_1 src1_sel:DWORD
	v_add3_u32 v11, v13, v11, s39
	v_add3_u32 v12, v12, v14, s39
	v_and_b32_e32 v11, 0xffff0000, v11
	v_and_b32_e32 v12, 0xffff0000, v12
	v_or_b32_sdwa v11, v11, v9 dst_sel:DWORD dst_unused:UNUSED_PAD src0_sel:DWORD src1_sel:WORD_1
	v_or_b32_sdwa v10, v12, v10 dst_sel:DWORD dst_unused:UNUSED_PAD src0_sel:DWORD src1_sel:WORD_1
	v_add_u32_e32 v9, 0x600, v8
	global_store_dwordx2 v[20:21], v[10:11], off
	v_ashrrev_i32_e32 v10, 5, v9
	v_ashrrev_i32_e32 v11, 31, v10
	v_lshl_add_u64 v[12:13], s[40:41], 0, v[10:11]
	v_lshl_or_b32 v9, v10, 9, v152
	v_mad_u64_u32 v[10:11], s[26:27], v12, s22, v[6:7]
	v_mad_i32_i24 v11, v13, s22, v11
	v_lshl_add_u64 v[10:11], v[10:11], 0, v[4:5]
	v_add_co_u32_e32 v10, vcc, s21, v10
	v_add_u32_e32 v8, 0x700, v8
	s_nop 0
	v_addc_co_u32_e32 v11, vcc, 0, v11, vcc
	v_mov_b32_e32 v10, v210
	v_mov_b32_e32 v11, v211
	v_ashrrev_i32_e32 v8, 5, v8
	v_lshlrev_b32_e32 v14, 16, v10
	v_and_b32_e32 v10, 0xffff0000, v10
	v_lshlrev_b32_e32 v15, 16, v11
	v_mul_f32_e32 v10, 0xbfb8aa3b, v10
	v_mul_f32_e32 v14, 0xbfb8aa3b, v14
	v_exp_f32_e32 v16, v10
	v_mul_f32_e32 v10, 0xbfb8aa3b, v15
	v_exp_f32_e32 v14, v14
	v_exp_f32_e32 v15, v10
	v_and_b32_e32 v11, 0xffff0000, v11
	v_mul_f32_e32 v10, 0xbfb8aa3b, v11
	v_exp_f32_e32 v17, v10
	v_lshlrev_b64 v[10:11], 12, v[12:13]
	v_lshl_add_u64 v[18:19], v[0:1], 0, v[10:11]
	v_lshlrev_b64 v[10:11], 11, v[12:13]
	v_pk_add_f32 v[14:15], v[14:15], 1.0 op_sel_hi:[1,0]
	v_lshl_add_u64 v[20:21], v[2:3], 0, v[10:11]
	ds_read_b128 v[10:13], v9
	v_min_f32_e32 v9, 0x7f7fffff, v15
	v_rcp_f32_e32 v22, v9
	s_nop 0
	v_fma_f32 v23, -v9, v22, 1.0
	v_fmac_f32_e32 v22, v23, v22
	v_fma_f32 v25, -v9, v22, 1.0
	v_fma_f32 v24, v25, v22, v22
	v_fma_f32 v9, -v9, v24, 1.0
	v_fma_f32 v23, v9, v22, v24
	v_min_f32_e32 v9, 0x7f7fffff, v14
	v_rcp_f32_e32 v15, v9
	s_nop 0
	v_fma_f32 v22, -v9, v15, 1.0
	v_fmac_f32_e32 v15, v22, v15
	v_fma_f32 v25, -v9, v15, 1.0
	v_fma_f32 v24, v25, v15, v15
	v_fma_f32 v9, -v9, v24, 1.0
	v_fma_f32 v22, v9, v15, v24
	v_pk_add_f32 v[14:15], v[16:17], 1.0 op_sel_hi:[1,0]
	s_waitcnt lgkmcnt(0)
; DEVI float sigmoidf_(float x) { return 1.f / (1.f + __expf(-x)); }
; template <int BR, int IN, int OUT>
; DEVI void p6_branch(const Params& P, int pm, int pn, float* macc, char* smem, int tid) {
;     ...
; #pragma unroll 8
;   for (int q = 0; q < 16; ++q) {
;     const int id = tid + 256 * q, row = id >> 5, c4 = id & 31;
;     const long grow = (long)pm * 128 + row;
;     const int gcol = pn * 128 + c4 * 4;
;     float4 a = *reinterpret_cast<const float4*>(T + row * 128 + c4 * 4);
;     float g[4];
;     load4bf(Z + grow * NCOL + (9 + BR) * 1024 + gcol, g);
;     float v[4] = {sigmoidf_(g[0]) * a.x, sigmoidf_(g[1]) * a.y, sigmoidf_(g[2]) * a.z, sigmoidf_(g[3]) * a.w};
;     if (IN == 1) {
;       float mo[4]; load4bf(M + grow * 1024 + gcol, mo);
;       v[0] += mo[0]; v[1] += mo[1]; v[2] += mo[2]; v[3] += mo[3];
;     }
;     if (IN == 2) {
;       float4 mo = *reinterpret_cast<const float4*>(macc + grow * 1024 + gcol);
;       v[0] += mo.x; v[1] += mo.y; v[2] += mo.z; v[3] += mo.w;
;     }
;     if (OUT == 1) *reinterpret_cast<float4*>(macc + grow * 1024 + gcol) = make_float4(v[0], v[1], v[2], v[3]);
;     else store4bf(M + grow * 1024 + gcol, v);
;   }
	v_mov_b32_e32 v24, v10
	v_min_f32_e32 v9, 0x7f7fffff, v15
	v_rcp_f32_e32 v10, v9
	v_mov_b32_e32 v25, v12
	v_fma_f32 v12, -v9, v10, 1.0
	v_fmac_f32_e32 v10, v12, v10
	v_fma_f32 v17, -v9, v10, 1.0
	v_fma_f32 v16, v17, v10, v10
	v_fma_f32 v9, -v9, v16, 1.0
	v_fma_f32 v27, v9, v10, v16
	v_min_f32_e32 v9, 0x7f7fffff, v14
	v_rcp_f32_e32 v10, v9
	s_nop 0
	v_fma_f32 v12, -v9, v10, 1.0
	v_fmac_f32_e32 v10, v12, v10
	v_fma_f32 v16, -v9, v10, 1.0
	v_fma_f32 v15, v16, v10, v10
	v_fma_f32 v9, -v9, v15, 1.0
	v_fma_f32 v26, v9, v10, v15
	v_mov_b32_e32 v14, v216
	v_mov_b32_e32 v15, v217
	v_mov_b32_e32 v16, v218
	v_mov_b32_e32 v17, v219
	v_mov_b32_e32 v12, v11
	v_mov_b32_e32 v10, v14
	v_mov_b32_e32 v11, v16
	v_pk_fma_f32 v[10:11], v[24:25], v[22:23], v[10:11]
	v_mov_b32_e32 v16, v15
	v_pk_fma_f32 v[12:13], v[12:13], v[26:27], v[16:17]
	v_and_b32_sdwa v9, v11, v95 dst_sel:DWORD dst_unused:UNUSED_PAD src0_sel:WORD_1 src1_sel:DWORD
	v_and_b32_sdwa v14, v10, v95 dst_sel:DWORD dst_unused:UNUSED_PAD src0_sel:WORD_1 src1_sel:DWORD
	v_add3_u32 v10, v10, v14, s39
	v_add3_u32 v9, v11, v9, s39
	v_and_b32_sdwa v11, v13, v95 dst_sel:DWORD dst_unused:UNUSED_PAD src0_sel:WORD_1 src1_sel:DWORD
	v_and_b32_sdwa v14, v12, v95 dst_sel:DWORD dst_unused:UNUSED_PAD src0_sel:WORD_1 src1_sel:DWORD
	v_add3_u32 v11, v13, v11, s39
	v_add3_u32 v12, v12, v14, s39
	v_and_b32_e32 v11, 0xffff0000, v11
	v_and_b32_e32 v12, 0xffff0000, v12
	v_or_b32_sdwa v11, v11, v9 dst_sel:DWORD dst_unused:UNUSED_PAD src0_sel:DWORD src1_sel:WORD_1
	v_or_b32_sdwa v10, v12, v10 dst_sel:DWORD dst_unused:UNUSED_PAD src0_sel:DWORD src1_sel:WORD_1
	v_ashrrev_i32_e32 v9, 31, v8
	global_store_dwordx2 v[20:21], v[10:11], off
	v_lshl_add_u64 v[10:11], s[40:41], 0, v[8:9]
	v_mad_u64_u32 v[6:7], s[26:27], v10, s22, v[6:7]
	v_mad_i32_i24 v7, v11, s22, v7
	v_lshl_add_u64 v[6:7], v[6:7], 0, v[4:5]
	v_add_co_u32_e32 v6, vcc, s21, v6
	v_lshl_or_b32 v8, v8, 9, v152
	s_nop 0
	v_addc_co_u32_e32 v7, vcc, 0, v7, vcc
	v_mov_b32_e32 v6, v220
	v_mov_b32_e32 v7, v221
	v_lshlrev_b32_e32 v9, 16, v6
	v_and_b32_e32 v6, 0xffff0000, v6
	v_lshlrev_b32_e32 v13, 16, v7
	v_mul_f32_e32 v6, 0xbfb8aa3b, v6
	v_mul_f32_e32 v9, 0xbfb8aa3b, v9
	v_exp_f32_e32 v14, v6
	v_mul_f32_e32 v6, 0xbfb8aa3b, v13
	v_exp_f32_e32 v12, v9
	v_exp_f32_e32 v13, v6
	v_and_b32_e32 v7, 0xffff0000, v7
	v_mul_f32_e32 v6, 0xbfb8aa3b, v7
	v_exp_f32_e32 v15, v6
	v_lshlrev_b64 v[6:7], 12, v[10:11]
	v_lshl_add_u64 v[16:17], v[0:1], 0, v[6:7]
	v_lshlrev_b64 v[6:7], 11, v[10:11]
	v_pk_add_f32 v[10:11], v[12:13], 1.0 op_sel_hi:[1,0]
	v_lshl_add_u64 v[18:19], v[2:3], 0, v[6:7]
	v_min_f32_e32 v12, 0x7f7fffff, v11
	v_rcp_f32_e32 v13, v12
	ds_read_b128 v[6:9], v8
	v_fma_f32 v20, -v12, v13, 1.0
	v_fmac_f32_e32 v13, v20, v13
	v_fma_f32 v22, -v12, v13, 1.0
	v_fma_f32 v21, v22, v13, v13
	v_fma_f32 v12, -v12, v21, 1.0
	v_fma_f32 v21, v12, v13, v21
	v_min_f32_e32 v11, 0x7f7fffff, v10
	v_rcp_f32_e32 v12, v11
	s_waitcnt lgkmcnt(0)
	v_mov_b32_e32 v23, v8
	v_fma_f32 v13, -v11, v12, 1.0
	v_fmac_f32_e32 v12, v13, v12
	v_fma_f32 v22, -v11, v12, 1.0
	v_fma_f32 v20, v22, v12, v12
	v_fma_f32 v11, -v11, v20, 1.0
	v_fma_f32 v20, v11, v12, v20
	v_pk_add_f32 v[10:11], v[14:15], 1.0 op_sel_hi:[1,0]
	v_mov_b32_e32 v22, v6
	v_min_f32_e32 v6, 0x7f7fffff, v11
	v_rcp_f32_e32 v8, v6
	s_nop 0
	v_fma_f32 v12, -v6, v8, 1.0
	v_fmac_f32_e32 v8, v12, v8
	v_fma_f32 v14, -v6, v8, 1.0
	v_fma_f32 v13, v14, v8, v8
	v_fma_f32 v6, -v6, v13, 1.0
	v_fma_f32 v15, v6, v8, v13
	v_min_f32_e32 v6, 0x7f7fffff, v10
	v_rcp_f32_e32 v8, v6
	s_nop 0
	v_fma_f32 v11, -v6, v8, 1.0
	v_fmac_f32_e32 v8, v11, v8
	v_fma_f32 v13, -v6, v8, 1.0
	v_fma_f32 v12, v13, v8, v8
	v_fma_f32 v6, -v6, v12, 1.0
	v_fma_f32 v14, v6, v8, v12
	v_mov_b32_e32 v10, v224
	v_mov_b32_e32 v11, v225
	v_mov_b32_e32 v12, v226
	v_mov_b32_e32 v13, v227
	v_mov_b32_e32 v8, v7
	v_mov_b32_e32 v6, v10
	v_mov_b32_e32 v7, v12
	v_pk_fma_f32 v[6:7], v[22:23], v[20:21], v[6:7]
	v_mov_b32_e32 v12, v11
	v_pk_fma_f32 v[8:9], v[8:9], v[14:15], v[12:13]
	v_and_b32_sdwa v10, v7, v95 dst_sel:DWORD dst_unused:UNUSED_PAD src0_sel:WORD_1 src1_sel:DWORD
	v_and_b32_sdwa v11, v6, v95 dst_sel:DWORD dst_unused:UNUSED_PAD src0_sel:WORD_1 src1_sel:DWORD
	v_add3_u32 v6, v6, v11, s39
	v_add3_u32 v7, v7, v10, s39
	v_and_b32_sdwa v10, v9, v95 dst_sel:DWORD dst_unused:UNUSED_PAD src0_sel:WORD_1 src1_sel:DWORD
	v_and_b32_sdwa v11, v8, v95 dst_sel:DWORD dst_unused:UNUSED_PAD src0_sel:WORD_1 src1_sel:DWORD
	v_add3_u32 v9, v9, v10, s39
	v_add3_u32 v8, v8, v11, s39
	v_and_b32_e32 v9, 0xffff0000, v9
	v_and_b32_e32 v8, 0xffff0000, v8
	v_or_b32_sdwa v7, v9, v7 dst_sel:DWORD dst_unused:UNUSED_PAD src0_sel:DWORD src1_sel:WORD_1
	v_or_b32_sdwa v6, v8, v6 dst_sel:DWORD dst_unused:UNUSED_PAD src0_sel:DWORD src1_sel:WORD_1
	global_store_dwordx2 v[18:19], v[6:7], off
	s_cbranch_scc1 .LBB0_741
	s_add_i32 s2, s2, s23
	s_cmp_lt_i32 s2, s1
	s_cbranch_scc1 .LBB0_730
